# c18: c16 + code placement: all K-loop MFMAs on 8-byte boundaries (satisfied in-segment lgkmcnt waits dropped, .p2align 3 at each MFMA segment head)
# speedup vs baseline: 1.0042x; 1.0042x over previous
.LBB0_343:
	s_ashr_i32 s11, s10, 31
	s_lshl_b64 s[12:13], s[10:11], 20
	s_add_u32 s12, s26, s12
	s_addc_u32 s13, s27, s13
	s_and_b64 s[14:15], s[2:3], exec
	s_cselect_b32 s11, s13, s21
	s_cselect_b32 s75, s12, s20
	s_ashr_i32 s9, s8, 31
	s_lshl_b64 s[14:15], s[8:9], 20
	s_add_u32 s14, s28, s14
	s_addc_u32 s15, s29, s15
	s_and_b64 s[22:23], s[2:3], exec
	s_cselect_b32 s9, s15, s19
	s_cselect_b32 s76, s14, s18
	s_add_u32 s77, s18, 0x100
	s_addc_u32 s78, s19, 0
	s_add_u32 s18, s20, 0x80080
	s_addc_u32 s19, s21, 0
	s_add_u32 s79, s20, 0x100
	s_addc_u32 s80, s21, 0
	s_mov_b32 s81, -2
	ds_read_b128 v[148:151], v143
	ds_read_b128 v[152:155], v143 offset:1024
	ds_read_b128 v[156:159], v143 offset:2048
	ds_read_b128 v[160:163], v143 offset:3072
	ds_read_b128 v[164:167], v144
	ds_read_b128 v[168:171], v144 offset:1024
	ds_read_b128 v[172:175], v144 offset:2048
	ds_read_b128 v[176:179], v144 offset:3072
	s_cmp_eq_u32 s81, 28
	s_cselect_b32 s21, s9, s78
	s_cselect_b32 s20, s76, s77
	s_cselect_b32 s23, s11, s80
	s_cselect_b32 s22, s75, s79
	ds_read_b128 v[180:183], v145
	ds_read_b128 v[184:187], v145 offset:1024
	ds_read_b128 v[188:191], v145 offset:2048
	ds_read_b128 v[192:195], v145 offset:3072
	ds_read_b128 v[196:199], v145 offset:4096
	ds_read_b128 v[200:203], v145 offset:5120
	ds_read_b128 v[204:207], v145 offset:6144
	ds_read_b128 v[208:211], v145 offset:7168
	s_add_u32 s82, s18, 0xfff80000
	s_addc_u32 s83, s19, -1
	s_mov_b32 s86, m0
	s_mov_b32 m0, s64
	s_nop 0
	global_load_lds_dwordx4 v138, s[82:83]
	s_mov_b32 m0, s86
	s_nop 0
	s_mov_b32 s86, m0
	s_mov_b32 m0, s67
	s_nop 0
	global_load_lds_dwordx4 v140, s[82:83]
	s_mov_b32 m0, s86
	s_mov_b32 s82, m0
	s_mov_b32 m0, s65
	s_nop 0
	global_load_lds_dwordx4 v138, s[18:19]
	s_mov_b32 m0, s82
	s_nop 0
	s_mov_b32 s82, m0
	s_mov_b32 m0, s73
	s_nop 0
	global_load_lds_dwordx4 v140, s[18:19]
	s_mov_b32 m0, s82
	s_waitcnt vmcnt(8)
	s_waitcnt lgkmcnt(0)
	s_barrier
	s_setprio 1
	.p2align 3
	v_mfma_f32_16x16x32_bf16 v[126:129], v[148:151], v[180:183], 0
	v_mfma_f32_16x16x32_bf16 v[126:129], v[152:155], v[184:187], v[126:129]
	v_mfma_f32_16x16x32_bf16 v[122:125], v[156:159], v[180:183], 0
	v_mfma_f32_16x16x32_bf16 v[122:125], v[160:163], v[184:187], v[122:125]
	v_mfma_f32_16x16x32_bf16 v[106:109], v[156:159], v[188:191], 0
	v_mfma_f32_16x16x32_bf16 v[106:109], v[160:163], v[192:195], v[106:109]
	v_mfma_f32_16x16x32_bf16 v[110:113], v[148:151], v[188:191], 0
	v_mfma_f32_16x16x32_bf16 v[110:113], v[152:155], v[192:195], v[110:113]
	v_mfma_f32_16x16x32_bf16 v[94:97], v[148:151], v[196:199], 0
	v_mfma_f32_16x16x32_bf16 v[94:97], v[152:155], v[200:203], v[94:97]
	v_mfma_f32_16x16x32_bf16 v[90:93], v[156:159], v[196:199], 0
	v_mfma_f32_16x16x32_bf16 v[90:93], v[160:163], v[200:203], v[90:93]
	v_mfma_f32_16x16x32_bf16 v[74:77], v[156:159], v[204:207], 0
	v_mfma_f32_16x16x32_bf16 v[74:77], v[160:163], v[208:211], v[74:77]
	v_mfma_f32_16x16x32_bf16 v[78:81], v[148:151], v[204:207], 0
	v_mfma_f32_16x16x32_bf16 v[78:81], v[152:155], v[208:211], v[78:81]
	s_setprio 0
	s_setprio 1
	v_mfma_f32_16x16x32_bf16 v[118:121], v[164:167], v[180:183], 0
	v_mfma_f32_16x16x32_bf16 v[118:121], v[168:171], v[184:187], v[118:121]
	v_mfma_f32_16x16x32_bf16 v[114:117], v[172:175], v[180:183], 0
	v_mfma_f32_16x16x32_bf16 v[114:117], v[176:179], v[184:187], v[114:117]
	v_mfma_f32_16x16x32_bf16 v[98:101], v[172:175], v[188:191], 0
	v_mfma_f32_16x16x32_bf16 v[98:101], v[176:179], v[192:195], v[98:101]
	v_mfma_f32_16x16x32_bf16 v[102:105], v[164:167], v[188:191], 0
	v_mfma_f32_16x16x32_bf16 v[102:105], v[168:171], v[192:195], v[102:105]
	v_mfma_f32_16x16x32_bf16 v[86:89], v[164:167], v[196:199], 0
	v_mfma_f32_16x16x32_bf16 v[86:89], v[168:171], v[200:203], v[86:89]
	v_mfma_f32_16x16x32_bf16 v[82:85], v[172:175], v[196:199], 0
	v_mfma_f32_16x16x32_bf16 v[82:85], v[176:179], v[200:203], v[82:85]
	v_mfma_f32_16x16x32_bf16 v[66:69], v[172:175], v[204:207], 0
	v_mfma_f32_16x16x32_bf16 v[66:69], v[176:179], v[208:211], v[66:69]
	s_setprio 2
	s_barrier
	v_mfma_f32_16x16x32_bf16 v[70:73], v[164:167], v[204:207], 0
	v_mfma_f32_16x16x32_bf16 v[70:73], v[168:171], v[208:211], v[70:73]
	s_setprio 0
	ds_read_b128 v[180:183], v145 offset:16384
	ds_read_b128 v[184:187], v145 offset:17408
	ds_read_b128 v[188:191], v145 offset:18432
	ds_read_b128 v[192:195], v145 offset:19456
	ds_read_b128 v[196:199], v145 offset:20480
	ds_read_b128 v[200:203], v145 offset:21504
	ds_read_b128 v[204:207], v145 offset:22528
	ds_read_b128 v[208:211], v145 offset:23552
	s_mov_b32 s82, m0
	s_mov_b32 m0, s35
	s_nop 0
	global_load_lds_dwordx4 v139, s[20:21]
	s_mov_b32 m0, s82
	s_nop 0
	s_mov_b32 s82, m0
	s_mov_b32 m0, s36
	s_nop 0
	global_load_lds_dwordx4 v141, s[20:21]
	s_mov_b32 m0, s82
	s_add_u32 s82, s20, 0x80000
	s_addc_u32 s83, s21, 0
	s_mov_b32 s86, m0
	s_mov_b32 m0, s37
	s_nop 0
	global_load_lds_dwordx4 v139, s[82:83]
	s_mov_b32 m0, s86
	s_nop 0
	s_mov_b32 s86, m0
	s_mov_b32 m0, s42
	s_nop 0
	global_load_lds_dwordx4 v141, s[82:83]
	s_mov_b32 m0, s86
	s_waitcnt vmcnt(4)
	s_waitcnt lgkmcnt(0)
	s_barrier
	s_setprio 1
	.p2align 3
	v_mfma_f32_16x16x32_bf16 v[62:65], v[148:151], v[180:183], 0
	v_mfma_f32_16x16x32_bf16 v[62:65], v[152:155], v[184:187], v[62:65]
	v_mfma_f32_16x16x32_bf16 v[58:61], v[156:159], v[180:183], 0
	v_mfma_f32_16x16x32_bf16 v[58:61], v[160:163], v[184:187], v[58:61]
	v_mfma_f32_16x16x32_bf16 v[42:45], v[156:159], v[188:191], 0
	v_mfma_f32_16x16x32_bf16 v[42:45], v[160:163], v[192:195], v[42:45]
	v_mfma_f32_16x16x32_bf16 v[46:49], v[148:151], v[188:191], 0
	v_mfma_f32_16x16x32_bf16 v[46:49], v[152:155], v[192:195], v[46:49]
	v_mfma_f32_16x16x32_bf16 v[30:33], v[148:151], v[196:199], 0
	v_mfma_f32_16x16x32_bf16 v[30:33], v[152:155], v[200:203], v[30:33]
	v_mfma_f32_16x16x32_bf16 v[26:29], v[156:159], v[196:199], 0
	v_mfma_f32_16x16x32_bf16 v[26:29], v[160:163], v[200:203], v[26:29]
	v_mfma_f32_16x16x32_bf16 v[10:13], v[156:159], v[204:207], 0
	v_mfma_f32_16x16x32_bf16 v[10:13], v[160:163], v[208:211], v[10:13]
	v_mfma_f32_16x16x32_bf16 v[14:17], v[148:151], v[204:207], 0
	v_mfma_f32_16x16x32_bf16 v[14:17], v[152:155], v[208:211], v[14:17]
	s_setprio 0
	s_setprio 1
	v_mfma_f32_16x16x32_bf16 v[54:57], v[164:167], v[180:183], 0
	v_mfma_f32_16x16x32_bf16 v[54:57], v[168:171], v[184:187], v[54:57]
	v_mfma_f32_16x16x32_bf16 v[50:53], v[172:175], v[180:183], 0
	v_mfma_f32_16x16x32_bf16 v[50:53], v[176:179], v[184:187], v[50:53]
	v_mfma_f32_16x16x32_bf16 v[34:37], v[172:175], v[188:191], 0
	v_mfma_f32_16x16x32_bf16 v[34:37], v[176:179], v[192:195], v[34:37]
	v_mfma_f32_16x16x32_bf16 v[38:41], v[164:167], v[188:191], 0
	v_mfma_f32_16x16x32_bf16 v[38:41], v[168:171], v[192:195], v[38:41]
	v_mfma_f32_16x16x32_bf16 v[22:25], v[164:167], v[196:199], 0
	v_mfma_f32_16x16x32_bf16 v[22:25], v[168:171], v[200:203], v[22:25]
	v_mfma_f32_16x16x32_bf16 v[18:21], v[172:175], v[196:199], 0
	v_mfma_f32_16x16x32_bf16 v[18:21], v[176:179], v[200:203], v[18:21]
	v_mfma_f32_16x16x32_bf16 v[2:5], v[172:175], v[204:207], 0
	v_mfma_f32_16x16x32_bf16 v[2:5], v[176:179], v[208:211], v[2:5]
	s_setprio 2
	s_barrier
	v_mfma_f32_16x16x32_bf16 v[6:9], v[164:167], v[204:207], 0
	v_mfma_f32_16x16x32_bf16 v[6:9], v[168:171], v[208:211], v[6:9]
	s_setprio 0
	ds_read_b128 v[148:151], v146
	ds_read_b128 v[152:155], v146 offset:1024
	ds_read_b128 v[156:159], v146 offset:2048
	ds_read_b128 v[160:163], v146 offset:3072
	ds_read_b128 v[164:167], v147
	ds_read_b128 v[168:171], v147 offset:1024
	ds_read_b128 v[172:175], v147 offset:2048
	ds_read_b128 v[176:179], v147 offset:3072
	ds_read_b128 v[180:183], v145 offset:32768
	ds_read_b128 v[184:187], v145 offset:33792
	ds_read_b128 v[188:191], v145 offset:34816
	ds_read_b128 v[192:195], v145 offset:35840
	ds_read_b128 v[196:199], v145 offset:36864
	ds_read_b128 v[200:203], v145 offset:37888
	ds_read_b128 v[204:207], v145 offset:38912
	ds_read_b128 v[208:211], v145 offset:39936
	s_mov_b32 s82, m0
	s_mov_b32 m0, s31
	s_nop 0
	global_load_lds_dwordx4 v138, s[22:23]
	s_mov_b32 m0, s82
	s_nop 0
	s_mov_b32 s82, m0
	s_mov_b32 m0, s43
	s_nop 0
	global_load_lds_dwordx4 v140, s[22:23]
	s_mov_b32 m0, s82
	s_add_u32 s22, s22, 0x80000
	s_addc_u32 s23, s23, 0
	s_mov_b32 s82, m0
	s_mov_b32 m0, s46
	s_nop 0
	global_load_lds_dwordx4 v138, s[22:23]
	s_mov_b32 m0, s82
	s_nop 0
	s_mov_b32 s82, m0
	s_mov_b32 m0, s47
	s_nop 0
	global_load_lds_dwordx4 v140, s[22:23]
	s_mov_b32 m0, s82
	s_waitcnt vmcnt(8)
	s_waitcnt lgkmcnt(0)
	s_barrier
	s_setprio 1
	.p2align 3
	v_mfma_f32_16x16x32_bf16 v[126:129], v[148:151], v[180:183], v[126:129]
	v_mfma_f32_16x16x32_bf16 v[126:129], v[152:155], v[184:187], v[126:129]
	v_mfma_f32_16x16x32_bf16 v[122:125], v[156:159], v[180:183], v[122:125]
	v_mfma_f32_16x16x32_bf16 v[122:125], v[160:163], v[184:187], v[122:125]
	v_mfma_f32_16x16x32_bf16 v[106:109], v[156:159], v[188:191], v[106:109]
	v_mfma_f32_16x16x32_bf16 v[106:109], v[160:163], v[192:195], v[106:109]
	v_mfma_f32_16x16x32_bf16 v[110:113], v[148:151], v[188:191], v[110:113]
	v_mfma_f32_16x16x32_bf16 v[110:113], v[152:155], v[192:195], v[110:113]
	v_mfma_f32_16x16x32_bf16 v[94:97], v[148:151], v[196:199], v[94:97]
	v_mfma_f32_16x16x32_bf16 v[94:97], v[152:155], v[200:203], v[94:97]
	v_mfma_f32_16x16x32_bf16 v[90:93], v[156:159], v[196:199], v[90:93]
	v_mfma_f32_16x16x32_bf16 v[90:93], v[160:163], v[200:203], v[90:93]
	v_mfma_f32_16x16x32_bf16 v[74:77], v[156:159], v[204:207], v[74:77]
	v_mfma_f32_16x16x32_bf16 v[74:77], v[160:163], v[208:211], v[74:77]
	v_mfma_f32_16x16x32_bf16 v[78:81], v[148:151], v[204:207], v[78:81]
	v_mfma_f32_16x16x32_bf16 v[78:81], v[152:155], v[208:211], v[78:81]
	s_setprio 0
	s_setprio 1
	v_mfma_f32_16x16x32_bf16 v[118:121], v[164:167], v[180:183], v[118:121]
	v_mfma_f32_16x16x32_bf16 v[118:121], v[168:171], v[184:187], v[118:121]
	v_mfma_f32_16x16x32_bf16 v[114:117], v[172:175], v[180:183], v[114:117]
	v_mfma_f32_16x16x32_bf16 v[114:117], v[176:179], v[184:187], v[114:117]
	v_mfma_f32_16x16x32_bf16 v[98:101], v[172:175], v[188:191], v[98:101]
	v_mfma_f32_16x16x32_bf16 v[98:101], v[176:179], v[192:195], v[98:101]
	v_mfma_f32_16x16x32_bf16 v[102:105], v[164:167], v[188:191], v[102:105]
	v_mfma_f32_16x16x32_bf16 v[102:105], v[168:171], v[192:195], v[102:105]
	v_mfma_f32_16x16x32_bf16 v[86:89], v[164:167], v[196:199], v[86:89]
	v_mfma_f32_16x16x32_bf16 v[86:89], v[168:171], v[200:203], v[86:89]
	v_mfma_f32_16x16x32_bf16 v[82:85], v[172:175], v[196:199], v[82:85]
	v_mfma_f32_16x16x32_bf16 v[82:85], v[176:179], v[200:203], v[82:85]
	v_mfma_f32_16x16x32_bf16 v[66:69], v[172:175], v[204:207], v[66:69]
	v_mfma_f32_16x16x32_bf16 v[66:69], v[176:179], v[208:211], v[66:69]
	s_setprio 2
	s_barrier
	v_mfma_f32_16x16x32_bf16 v[70:73], v[164:167], v[204:207], v[70:73]
	v_mfma_f32_16x16x32_bf16 v[70:73], v[168:171], v[208:211], v[70:73]
	s_setprio 0
	ds_read_b128 v[180:183], v145 offset:49152
	ds_read_b128 v[184:187], v145 offset:50176
	ds_read_b128 v[188:191], v145 offset:51200
	ds_read_b128 v[192:195], v145 offset:52224
	ds_read_b128 v[196:199], v145 offset:53248
	ds_read_b128 v[200:203], v145 offset:54272
	ds_read_b128 v[204:207], v145 offset:55296
	ds_read_b128 v[208:211], v145 offset:56320
	s_add_u32 s22, s20, 0x80
	s_addc_u32 s23, s21, 0
	s_mov_b32 s82, m0
	s_mov_b32 m0, s48
	s_nop 0
	global_load_lds_dwordx4 v139, s[22:23]
	s_mov_b32 m0, s82
	s_add_u32 s20, s20, 0x80080
	s_mov_b32 s82, m0
	s_mov_b32 m0, s49
	s_nop 0
	global_load_lds_dwordx4 v141, s[22:23]
	s_mov_b32 m0, s82
	s_addc_u32 s21, s21, 0
	s_mov_b32 s22, m0
	s_mov_b32 m0, s56
	s_nop 0
	global_load_lds_dwordx4 v139, s[20:21]
	s_mov_b32 m0, s22
	s_nop 0
	s_mov_b32 s22, m0
	s_mov_b32 m0, s57
	s_nop 0
	global_load_lds_dwordx4 v141, s[20:21]
	s_mov_b32 m0, s22
	s_waitcnt vmcnt(4)
	s_waitcnt lgkmcnt(0)
	s_barrier
	s_setprio 1
	.p2align 3
	v_mfma_f32_16x16x32_bf16 v[62:65], v[148:151], v[180:183], v[62:65]
	v_mfma_f32_16x16x32_bf16 v[62:65], v[152:155], v[184:187], v[62:65]
	v_mfma_f32_16x16x32_bf16 v[58:61], v[156:159], v[180:183], v[58:61]
	v_mfma_f32_16x16x32_bf16 v[58:61], v[160:163], v[184:187], v[58:61]
	v_mfma_f32_16x16x32_bf16 v[42:45], v[156:159], v[188:191], v[42:45]
	v_mfma_f32_16x16x32_bf16 v[42:45], v[160:163], v[192:195], v[42:45]
	v_mfma_f32_16x16x32_bf16 v[46:49], v[148:151], v[188:191], v[46:49]
	v_mfma_f32_16x16x32_bf16 v[46:49], v[152:155], v[192:195], v[46:49]
	v_mfma_f32_16x16x32_bf16 v[30:33], v[148:151], v[196:199], v[30:33]
	v_mfma_f32_16x16x32_bf16 v[30:33], v[152:155], v[200:203], v[30:33]
	v_mfma_f32_16x16x32_bf16 v[26:29], v[156:159], v[196:199], v[26:29]
	v_mfma_f32_16x16x32_bf16 v[26:29], v[160:163], v[200:203], v[26:29]
	v_mfma_f32_16x16x32_bf16 v[10:13], v[156:159], v[204:207], v[10:13]
	v_mfma_f32_16x16x32_bf16 v[10:13], v[160:163], v[208:211], v[10:13]
	v_mfma_f32_16x16x32_bf16 v[14:17], v[148:151], v[204:207], v[14:17]
	v_mfma_f32_16x16x32_bf16 v[14:17], v[152:155], v[208:211], v[14:17]
	s_setprio 0
	s_setprio 1
	v_mfma_f32_16x16x32_bf16 v[54:57], v[164:167], v[180:183], v[54:57]
	v_mfma_f32_16x16x32_bf16 v[54:57], v[168:171], v[184:187], v[54:57]
	v_mfma_f32_16x16x32_bf16 v[50:53], v[172:175], v[180:183], v[50:53]
	v_mfma_f32_16x16x32_bf16 v[50:53], v[176:179], v[184:187], v[50:53]
	v_mfma_f32_16x16x32_bf16 v[34:37], v[172:175], v[188:191], v[34:37]
	v_mfma_f32_16x16x32_bf16 v[34:37], v[176:179], v[192:195], v[34:37]
	v_mfma_f32_16x16x32_bf16 v[38:41], v[164:167], v[188:191], v[38:41]
	v_mfma_f32_16x16x32_bf16 v[38:41], v[168:171], v[192:195], v[38:41]
	v_mfma_f32_16x16x32_bf16 v[22:25], v[164:167], v[196:199], v[22:25]
	v_mfma_f32_16x16x32_bf16 v[22:25], v[168:171], v[200:203], v[22:25]
	v_mfma_f32_16x16x32_bf16 v[18:21], v[172:175], v[196:199], v[18:21]
	v_mfma_f32_16x16x32_bf16 v[18:21], v[176:179], v[200:203], v[18:21]
	v_mfma_f32_16x16x32_bf16 v[2:5], v[172:175], v[204:207], v[2:5]
	v_mfma_f32_16x16x32_bf16 v[2:5], v[176:179], v[208:211], v[2:5]
	s_setprio 2
	s_barrier
	v_mfma_f32_16x16x32_bf16 v[6:9], v[164:167], v[204:207], v[6:9]
	v_mfma_f32_16x16x32_bf16 v[6:9], v[168:171], v[208:211], v[6:9]
	s_setprio 0
	s_add_i32 s81, s81, 2
	s_add_u32 s77, s77, 0x100
	s_addc_u32 s78, s78, 0
	s_add_u32 s18, s18, 0x100
	s_addc_u32 s19, s19, 0
	s_add_u32 s79, s79, 0x100
	s_addc_u32 s80, s80, 0
	s_cmp_gt_u32 s81, 29
	.p2align 6
.LBB0_344:
	ds_read_b128 v[148:151], v143
	ds_read_b128 v[152:155], v143 offset:1024
	ds_read_b128 v[156:159], v143 offset:2048
	ds_read_b128 v[160:163], v143 offset:3072
	ds_read_b128 v[164:167], v144
	ds_read_b128 v[168:171], v144 offset:1024
	ds_read_b128 v[172:175], v144 offset:2048
	ds_read_b128 v[176:179], v144 offset:3072
	s_cmp_eq_u32 s81, 28
	s_cselect_b32 s21, s9, s78
	s_cselect_b32 s20, s76, s77
	s_cselect_b32 s23, s11, s80
	s_cselect_b32 s22, s75, s79
	ds_read_b128 v[180:183], v145
	ds_read_b128 v[184:187], v145 offset:1024
	ds_read_b128 v[188:191], v145 offset:2048
	ds_read_b128 v[192:195], v145 offset:3072
	ds_read_b128 v[196:199], v145 offset:4096
	ds_read_b128 v[200:203], v145 offset:5120
	ds_read_b128 v[204:207], v145 offset:6144
	ds_read_b128 v[208:211], v145 offset:7168
	s_add_u32 s82, s18, 0xfff80000
	s_addc_u32 s83, s19, -1
	s_mov_b32 s86, m0
	s_mov_b32 m0, s64
	s_nop 0
	global_load_lds_dwordx4 v138, s[82:83]
	s_mov_b32 m0, s86
	s_nop 0
	s_mov_b32 s86, m0
	s_mov_b32 m0, s67
	s_nop 0
	global_load_lds_dwordx4 v140, s[82:83]
	s_mov_b32 m0, s86
	s_mov_b32 s82, m0
	s_mov_b32 m0, s65
	s_nop 0
	global_load_lds_dwordx4 v138, s[18:19]
	s_mov_b32 m0, s82
	s_nop 0
	s_mov_b32 s82, m0
	s_mov_b32 m0, s73
	s_nop 0
	global_load_lds_dwordx4 v140, s[18:19]
	s_mov_b32 m0, s82
	s_waitcnt vmcnt(8)
	s_waitcnt lgkmcnt(0)
	s_barrier
	s_setprio 1
	.p2align 3
	v_mfma_f32_16x16x32_bf16 v[126:129], v[148:151], v[180:183], v[126:129]
	v_mfma_f32_16x16x32_bf16 v[126:129], v[152:155], v[184:187], v[126:129]
	v_mfma_f32_16x16x32_bf16 v[122:125], v[156:159], v[180:183], v[122:125]
	v_mfma_f32_16x16x32_bf16 v[122:125], v[160:163], v[184:187], v[122:125]
	v_mfma_f32_16x16x32_bf16 v[106:109], v[156:159], v[188:191], v[106:109]
	v_mfma_f32_16x16x32_bf16 v[106:109], v[160:163], v[192:195], v[106:109]
	v_mfma_f32_16x16x32_bf16 v[110:113], v[148:151], v[188:191], v[110:113]
	v_mfma_f32_16x16x32_bf16 v[110:113], v[152:155], v[192:195], v[110:113]
	v_mfma_f32_16x16x32_bf16 v[94:97], v[148:151], v[196:199], v[94:97]
	v_mfma_f32_16x16x32_bf16 v[94:97], v[152:155], v[200:203], v[94:97]
	v_mfma_f32_16x16x32_bf16 v[90:93], v[156:159], v[196:199], v[90:93]
	v_mfma_f32_16x16x32_bf16 v[90:93], v[160:163], v[200:203], v[90:93]
	v_mfma_f32_16x16x32_bf16 v[74:77], v[156:159], v[204:207], v[74:77]
	v_mfma_f32_16x16x32_bf16 v[74:77], v[160:163], v[208:211], v[74:77]
	v_mfma_f32_16x16x32_bf16 v[78:81], v[148:151], v[204:207], v[78:81]
	v_mfma_f32_16x16x32_bf16 v[78:81], v[152:155], v[208:211], v[78:81]
	s_setprio 0
	s_setprio 1
	v_mfma_f32_16x16x32_bf16 v[118:121], v[164:167], v[180:183], v[118:121]
	v_mfma_f32_16x16x32_bf16 v[118:121], v[168:171], v[184:187], v[118:121]
	v_mfma_f32_16x16x32_bf16 v[114:117], v[172:175], v[180:183], v[114:117]
	v_mfma_f32_16x16x32_bf16 v[114:117], v[176:179], v[184:187], v[114:117]
	v_mfma_f32_16x16x32_bf16 v[98:101], v[172:175], v[188:191], v[98:101]
	v_mfma_f32_16x16x32_bf16 v[98:101], v[176:179], v[192:195], v[98:101]
	v_mfma_f32_16x16x32_bf16 v[102:105], v[164:167], v[188:191], v[102:105]
	v_mfma_f32_16x16x32_bf16 v[102:105], v[168:171], v[192:195], v[102:105]
	v_mfma_f32_16x16x32_bf16 v[86:89], v[164:167], v[196:199], v[86:89]
	v_mfma_f32_16x16x32_bf16 v[86:89], v[168:171], v[200:203], v[86:89]
	v_mfma_f32_16x16x32_bf16 v[82:85], v[172:175], v[196:199], v[82:85]
	v_mfma_f32_16x16x32_bf16 v[82:85], v[176:179], v[200:203], v[82:85]
	v_mfma_f32_16x16x32_bf16 v[66:69], v[172:175], v[204:207], v[66:69]
	v_mfma_f32_16x16x32_bf16 v[66:69], v[176:179], v[208:211], v[66:69]
	s_setprio 2
	s_barrier
	v_mfma_f32_16x16x32_bf16 v[70:73], v[164:167], v[204:207], v[70:73]
	v_mfma_f32_16x16x32_bf16 v[70:73], v[168:171], v[208:211], v[70:73]
	s_setprio 0
	ds_read_b128 v[180:183], v145 offset:16384
	ds_read_b128 v[184:187], v145 offset:17408
	ds_read_b128 v[188:191], v145 offset:18432
	ds_read_b128 v[192:195], v145 offset:19456
	ds_read_b128 v[196:199], v145 offset:20480
	ds_read_b128 v[200:203], v145 offset:21504
	ds_read_b128 v[204:207], v145 offset:22528
	ds_read_b128 v[208:211], v145 offset:23552
	s_mov_b32 s82, m0
	s_mov_b32 m0, s35
	s_nop 0
	global_load_lds_dwordx4 v139, s[20:21]
	s_mov_b32 m0, s82
	s_nop 0
	s_mov_b32 s82, m0
	s_mov_b32 m0, s36
	s_nop 0
	global_load_lds_dwordx4 v141, s[20:21]
	s_mov_b32 m0, s82
	s_add_u32 s82, s20, 0x80000
	s_addc_u32 s83, s21, 0
	s_mov_b32 s86, m0
	s_mov_b32 m0, s37
	s_nop 0
	global_load_lds_dwordx4 v139, s[82:83]
	s_mov_b32 m0, s86
	s_nop 0
	s_mov_b32 s86, m0
	s_mov_b32 m0, s42
	s_nop 0
	global_load_lds_dwordx4 v141, s[82:83]
	s_mov_b32 m0, s86
	s_waitcnt vmcnt(4)
	s_waitcnt lgkmcnt(0)
	s_barrier
	s_setprio 1
	.p2align 3
	v_mfma_f32_16x16x32_bf16 v[62:65], v[148:151], v[180:183], v[62:65]
	v_mfma_f32_16x16x32_bf16 v[62:65], v[152:155], v[184:187], v[62:65]
	v_mfma_f32_16x16x32_bf16 v[58:61], v[156:159], v[180:183], v[58:61]
	v_mfma_f32_16x16x32_bf16 v[58:61], v[160:163], v[184:187], v[58:61]
	v_mfma_f32_16x16x32_bf16 v[42:45], v[156:159], v[188:191], v[42:45]
	v_mfma_f32_16x16x32_bf16 v[42:45], v[160:163], v[192:195], v[42:45]
	v_mfma_f32_16x16x32_bf16 v[46:49], v[148:151], v[188:191], v[46:49]
	v_mfma_f32_16x16x32_bf16 v[46:49], v[152:155], v[192:195], v[46:49]
	v_mfma_f32_16x16x32_bf16 v[30:33], v[148:151], v[196:199], v[30:33]
	v_mfma_f32_16x16x32_bf16 v[30:33], v[152:155], v[200:203], v[30:33]
	v_mfma_f32_16x16x32_bf16 v[26:29], v[156:159], v[196:199], v[26:29]
	v_mfma_f32_16x16x32_bf16 v[26:29], v[160:163], v[200:203], v[26:29]
	v_mfma_f32_16x16x32_bf16 v[10:13], v[156:159], v[204:207], v[10:13]
	v_mfma_f32_16x16x32_bf16 v[10:13], v[160:163], v[208:211], v[10:13]
	v_mfma_f32_16x16x32_bf16 v[14:17], v[148:151], v[204:207], v[14:17]
	v_mfma_f32_16x16x32_bf16 v[14:17], v[152:155], v[208:211], v[14:17]
	s_setprio 0
	s_setprio 1
	v_mfma_f32_16x16x32_bf16 v[54:57], v[164:167], v[180:183], v[54:57]
	v_mfma_f32_16x16x32_bf16 v[54:57], v[168:171], v[184:187], v[54:57]
	v_mfma_f32_16x16x32_bf16 v[50:53], v[172:175], v[180:183], v[50:53]
	v_mfma_f32_16x16x32_bf16 v[50:53], v[176:179], v[184:187], v[50:53]
	v_mfma_f32_16x16x32_bf16 v[34:37], v[172:175], v[188:191], v[34:37]
	v_mfma_f32_16x16x32_bf16 v[34:37], v[176:179], v[192:195], v[34:37]
	v_mfma_f32_16x16x32_bf16 v[38:41], v[164:167], v[188:191], v[38:41]
	v_mfma_f32_16x16x32_bf16 v[38:41], v[168:171], v[192:195], v[38:41]
	v_mfma_f32_16x16x32_bf16 v[22:25], v[164:167], v[196:199], v[22:25]
	v_mfma_f32_16x16x32_bf16 v[22:25], v[168:171], v[200:203], v[22:25]
	v_mfma_f32_16x16x32_bf16 v[18:21], v[172:175], v[196:199], v[18:21]
	v_mfma_f32_16x16x32_bf16 v[18:21], v[176:179], v[200:203], v[18:21]
	v_mfma_f32_16x16x32_bf16 v[2:5], v[172:175], v[204:207], v[2:5]
	v_mfma_f32_16x16x32_bf16 v[2:5], v[176:179], v[208:211], v[2:5]
	s_setprio 2
	s_barrier
	v_mfma_f32_16x16x32_bf16 v[6:9], v[164:167], v[204:207], v[6:9]
	v_mfma_f32_16x16x32_bf16 v[6:9], v[168:171], v[208:211], v[6:9]
	s_setprio 0
	ds_read_b128 v[148:151], v146
	ds_read_b128 v[152:155], v146 offset:1024
	ds_read_b128 v[156:159], v146 offset:2048
	ds_read_b128 v[160:163], v146 offset:3072
	ds_read_b128 v[164:167], v147
	ds_read_b128 v[168:171], v147 offset:1024
	ds_read_b128 v[172:175], v147 offset:2048
	ds_read_b128 v[176:179], v147 offset:3072
	ds_read_b128 v[180:183], v145 offset:32768
	ds_read_b128 v[184:187], v145 offset:33792
	ds_read_b128 v[188:191], v145 offset:34816
	ds_read_b128 v[192:195], v145 offset:35840
	ds_read_b128 v[196:199], v145 offset:36864
	ds_read_b128 v[200:203], v145 offset:37888
	ds_read_b128 v[204:207], v145 offset:38912
	ds_read_b128 v[208:211], v145 offset:39936
	s_mov_b32 s82, m0
	s_mov_b32 m0, s31
	s_nop 0
	global_load_lds_dwordx4 v138, s[22:23]
	s_mov_b32 m0, s82
	s_nop 0
	s_mov_b32 s82, m0
	s_mov_b32 m0, s43
	s_nop 0
	global_load_lds_dwordx4 v140, s[22:23]
	s_mov_b32 m0, s82
	s_add_u32 s22, s22, 0x80000
	s_addc_u32 s23, s23, 0
	s_mov_b32 s82, m0
	s_mov_b32 m0, s46
	s_nop 0
	global_load_lds_dwordx4 v138, s[22:23]
	s_mov_b32 m0, s82
	s_nop 0
	s_mov_b32 s82, m0
	s_mov_b32 m0, s47
	s_nop 0
	global_load_lds_dwordx4 v140, s[22:23]
	s_mov_b32 m0, s82
	s_waitcnt vmcnt(8)
	s_waitcnt lgkmcnt(0)
	s_barrier
	s_setprio 1
	.p2align 3
	v_mfma_f32_16x16x32_bf16 v[126:129], v[148:151], v[180:183], v[126:129]
	v_mfma_f32_16x16x32_bf16 v[126:129], v[152:155], v[184:187], v[126:129]
	v_mfma_f32_16x16x32_bf16 v[122:125], v[156:159], v[180:183], v[122:125]
	v_mfma_f32_16x16x32_bf16 v[122:125], v[160:163], v[184:187], v[122:125]
	v_mfma_f32_16x16x32_bf16 v[106:109], v[156:159], v[188:191], v[106:109]
	v_mfma_f32_16x16x32_bf16 v[106:109], v[160:163], v[192:195], v[106:109]
	v_mfma_f32_16x16x32_bf16 v[110:113], v[148:151], v[188:191], v[110:113]
	v_mfma_f32_16x16x32_bf16 v[110:113], v[152:155], v[192:195], v[110:113]
	v_mfma_f32_16x16x32_bf16 v[94:97], v[148:151], v[196:199], v[94:97]
	v_mfma_f32_16x16x32_bf16 v[94:97], v[152:155], v[200:203], v[94:97]
	v_mfma_f32_16x16x32_bf16 v[90:93], v[156:159], v[196:199], v[90:93]
	v_mfma_f32_16x16x32_bf16 v[90:93], v[160:163], v[200:203], v[90:93]
	v_mfma_f32_16x16x32_bf16 v[74:77], v[156:159], v[204:207], v[74:77]
	v_mfma_f32_16x16x32_bf16 v[74:77], v[160:163], v[208:211], v[74:77]
	v_mfma_f32_16x16x32_bf16 v[78:81], v[148:151], v[204:207], v[78:81]
	v_mfma_f32_16x16x32_bf16 v[78:81], v[152:155], v[208:211], v[78:81]
	s_setprio 0
	s_setprio 1
	v_mfma_f32_16x16x32_bf16 v[118:121], v[164:167], v[180:183], v[118:121]
	v_mfma_f32_16x16x32_bf16 v[118:121], v[168:171], v[184:187], v[118:121]
	v_mfma_f32_16x16x32_bf16 v[114:117], v[172:175], v[180:183], v[114:117]
	v_mfma_f32_16x16x32_bf16 v[114:117], v[176:179], v[184:187], v[114:117]
	v_mfma_f32_16x16x32_bf16 v[98:101], v[172:175], v[188:191], v[98:101]
	v_mfma_f32_16x16x32_bf16 v[98:101], v[176:179], v[192:195], v[98:101]
	v_mfma_f32_16x16x32_bf16 v[102:105], v[164:167], v[188:191], v[102:105]
	v_mfma_f32_16x16x32_bf16 v[102:105], v[168:171], v[192:195], v[102:105]
	v_mfma_f32_16x16x32_bf16 v[86:89], v[164:167], v[196:199], v[86:89]
	v_mfma_f32_16x16x32_bf16 v[86:89], v[168:171], v[200:203], v[86:89]
	v_mfma_f32_16x16x32_bf16 v[82:85], v[172:175], v[196:199], v[82:85]
	v_mfma_f32_16x16x32_bf16 v[82:85], v[176:179], v[200:203], v[82:85]
	v_mfma_f32_16x16x32_bf16 v[66:69], v[172:175], v[204:207], v[66:69]
	v_mfma_f32_16x16x32_bf16 v[66:69], v[176:179], v[208:211], v[66:69]
	s_setprio 2
	s_barrier
	v_mfma_f32_16x16x32_bf16 v[70:73], v[164:167], v[204:207], v[70:73]
	v_mfma_f32_16x16x32_bf16 v[70:73], v[168:171], v[208:211], v[70:73]
	s_setprio 0
	ds_read_b128 v[180:183], v145 offset:49152
	ds_read_b128 v[184:187], v145 offset:50176
	ds_read_b128 v[188:191], v145 offset:51200
	ds_read_b128 v[192:195], v145 offset:52224
	ds_read_b128 v[196:199], v145 offset:53248
	ds_read_b128 v[200:203], v145 offset:54272
	ds_read_b128 v[204:207], v145 offset:55296
	ds_read_b128 v[208:211], v145 offset:56320
	s_add_u32 s22, s20, 0x80
	s_addc_u32 s23, s21, 0
	s_mov_b32 s82, m0
	s_mov_b32 m0, s48
	s_nop 0
	global_load_lds_dwordx4 v139, s[22:23]
	s_mov_b32 m0, s82
	s_add_u32 s20, s20, 0x80080
	s_mov_b32 s82, m0
	s_mov_b32 m0, s49
	s_nop 0
	global_load_lds_dwordx4 v141, s[22:23]
	s_mov_b32 m0, s82
	s_addc_u32 s21, s21, 0
	s_mov_b32 s22, m0
	s_mov_b32 m0, s56
	s_nop 0
	global_load_lds_dwordx4 v139, s[20:21]
	s_mov_b32 m0, s22
	s_nop 0
	s_mov_b32 s22, m0
	s_mov_b32 m0, s57
	s_nop 0
	global_load_lds_dwordx4 v141, s[20:21]
	s_mov_b32 m0, s22
	s_waitcnt vmcnt(4)
	s_waitcnt lgkmcnt(0)
	s_barrier
	s_setprio 1
	.p2align 3
	v_mfma_f32_16x16x32_bf16 v[62:65], v[148:151], v[180:183], v[62:65]
	v_mfma_f32_16x16x32_bf16 v[62:65], v[152:155], v[184:187], v[62:65]
	v_mfma_f32_16x16x32_bf16 v[58:61], v[156:159], v[180:183], v[58:61]
	v_mfma_f32_16x16x32_bf16 v[58:61], v[160:163], v[184:187], v[58:61]
	v_mfma_f32_16x16x32_bf16 v[42:45], v[156:159], v[188:191], v[42:45]
	v_mfma_f32_16x16x32_bf16 v[42:45], v[160:163], v[192:195], v[42:45]
	v_mfma_f32_16x16x32_bf16 v[46:49], v[148:151], v[188:191], v[46:49]
	v_mfma_f32_16x16x32_bf16 v[46:49], v[152:155], v[192:195], v[46:49]
	v_mfma_f32_16x16x32_bf16 v[30:33], v[148:151], v[196:199], v[30:33]
	v_mfma_f32_16x16x32_bf16 v[30:33], v[152:155], v[200:203], v[30:33]
	v_mfma_f32_16x16x32_bf16 v[26:29], v[156:159], v[196:199], v[26:29]
	v_mfma_f32_16x16x32_bf16 v[26:29], v[160:163], v[200:203], v[26:29]
	v_mfma_f32_16x16x32_bf16 v[10:13], v[156:159], v[204:207], v[10:13]
	v_mfma_f32_16x16x32_bf16 v[10:13], v[160:163], v[208:211], v[10:13]
	v_mfma_f32_16x16x32_bf16 v[14:17], v[148:151], v[204:207], v[14:17]
	v_mfma_f32_16x16x32_bf16 v[14:17], v[152:155], v[208:211], v[14:17]
	s_setprio 0
	s_setprio 1
	v_mfma_f32_16x16x32_bf16 v[54:57], v[164:167], v[180:183], v[54:57]
	v_mfma_f32_16x16x32_bf16 v[54:57], v[168:171], v[184:187], v[54:57]
	v_mfma_f32_16x16x32_bf16 v[50:53], v[172:175], v[180:183], v[50:53]
	v_mfma_f32_16x16x32_bf16 v[50:53], v[176:179], v[184:187], v[50:53]
	v_mfma_f32_16x16x32_bf16 v[34:37], v[172:175], v[188:191], v[34:37]
	v_mfma_f32_16x16x32_bf16 v[34:37], v[176:179], v[192:195], v[34:37]
	v_mfma_f32_16x16x32_bf16 v[38:41], v[164:167], v[188:191], v[38:41]
	v_mfma_f32_16x16x32_bf16 v[38:41], v[168:171], v[192:195], v[38:41]
	v_mfma_f32_16x16x32_bf16 v[22:25], v[164:167], v[196:199], v[22:25]
	v_mfma_f32_16x16x32_bf16 v[22:25], v[168:171], v[200:203], v[22:25]
	v_mfma_f32_16x16x32_bf16 v[18:21], v[172:175], v[196:199], v[18:21]
	v_mfma_f32_16x16x32_bf16 v[18:21], v[176:179], v[200:203], v[18:21]
	v_mfma_f32_16x16x32_bf16 v[2:5], v[172:175], v[204:207], v[2:5]
	v_mfma_f32_16x16x32_bf16 v[2:5], v[176:179], v[208:211], v[2:5]
	s_setprio 2
	s_barrier
	v_mfma_f32_16x16x32_bf16 v[6:9], v[164:167], v[204:207], v[6:9]
	v_mfma_f32_16x16x32_bf16 v[6:9], v[168:171], v[208:211], v[6:9]
	s_setprio 0
	s_add_i32 s81, s81, 2
	s_add_u32 s77, s77, 0x100
	s_addc_u32 s78, s78, 0
	s_add_u32 s18, s18, 0x100
	s_addc_u32 s19, s19, 0
	s_add_u32 s79, s79, 0x100
	s_addc_u32 s80, s80, 0
	s_cmp_gt_u32 s81, 29
	s_cbranch_scc0 .LBB0_344
	s_and_b64 vcc, exec, s[6:7]
	s_cbranch_vccz .LBB0_347
	s_barrier

.LBB0_472:
	s_ashr_i32 s13, s12, 31
	s_lshl_b64 s[14:15], s[12:13], 15
	s_add_u32 s14, s28, s14
	s_addc_u32 s15, s29, s15
	s_and_b64 s[16:17], s[2:3], exec
	s_cselect_b32 s13, s15, s23
	s_cselect_b32 s76, s14, s22
	s_ashr_i32 s11, s10, 31
	s_lshl_b64 s[16:17], s[10:11], 15
	s_add_u32 s16, s30, s16
	s_addc_u32 s17, s31, s17
	s_and_b64 s[24:25], s[2:3], exec
	s_cselect_b32 s11, s17, s21
	s_cselect_b32 s77, s16, s20
	s_add_u32 s78, s20, 0x80000
	s_addc_u32 s79, s21, 0
	s_add_u32 s20, s22, 0x204000
	s_addc_u32 s21, s23, 0
	s_add_u32 s80, s22, 0x400000
	s_addc_u32 s81, s23, 0
	s_mov_b32 s82, -2
	s_waitcnt vmcnt(25)
	s_waitcnt vmcnt(24)
	s_waitcnt vmcnt(23)
	s_waitcnt vmcnt(22)
	s_waitcnt vmcnt(21)
	s_waitcnt vmcnt(20)
	s_waitcnt vmcnt(15)
	s_waitcnt vmcnt(14)
	s_waitcnt vmcnt(13)
	s_waitcnt vmcnt(12)
	s_waitcnt vmcnt(7)
	s_waitcnt vmcnt(6)
	s_waitcnt vmcnt(5)
	s_waitcnt vmcnt(4)
	s_waitcnt vmcnt(3)
	s_waitcnt vmcnt(2)
	s_waitcnt vmcnt(1)
	s_waitcnt vmcnt(0)
	ds_read_b128 v[134:137], v161
	ds_read_b128 v[138:141], v161 offset:1024
	ds_read_b128 v[142:145], v161 offset:2048
	ds_read_b128 v[146:149], v161 offset:3072
	ds_read_b128 v[150:153], v162
	ds_read_b128 v[166:169], v162 offset:1024
	ds_read_b128 v[170:173], v162 offset:2048
	ds_read_b128 v[174:177], v162 offset:3072
	s_cmpk_eq_i32 s82, 0x52
	s_cselect_b32 s23, s11, s79
	s_cselect_b32 s22, s77, s78
	s_cselect_b32 s25, s13, s81
	s_cselect_b32 s24, s76, s80
	ds_read_b128 v[178:181], v163
	ds_read_b128 v[182:185], v163 offset:1024
	ds_read_b128 v[186:189], v163 offset:2048
	ds_read_b128 v[190:193], v163 offset:3072
	ds_read_b128 v[194:197], v163 offset:4096
	ds_read_b128 v[198:201], v163 offset:5120
	ds_read_b128 v[202:205], v163 offset:6144
	ds_read_b128 v[206:209], v163 offset:7168
	s_add_u32 s86, s20, 0xffffc000
	s_addc_u32 s87, s21, -1
	s_mov_b32 s83, m0
	s_mov_b32 m0, s65
	s_nop 0
	global_load_lds_dwordx4 v1, s[86:87]
	s_mov_b32 m0, s83
	s_nop 0
	s_mov_b32 s83, m0
	s_mov_b32 m0, s67
	s_nop 0
	global_load_lds_dwordx4 v157, s[86:87]
	s_mov_b32 m0, s83
	s_nop 0
	s_mov_b32 s83, m0
	s_mov_b32 m0, s66
	s_nop 0
	global_load_lds_dwordx4 v1, s[20:21]
	s_mov_b32 m0, s83
	s_nop 0
	s_mov_b32 s83, m0
	s_mov_b32 m0, s73
	s_nop 0
	global_load_lds_dwordx4 v157, s[20:21]
	s_mov_b32 m0, s83
	s_waitcnt vmcnt(8)
	s_waitcnt lgkmcnt(0)
	s_barrier
	s_setprio 1
	.p2align 3
	v_mfma_f32_16x16x32_bf16 v[126:129], v[134:137], v[178:181], 0
	v_mfma_f32_16x16x32_bf16 v[126:129], v[138:141], v[182:185], v[126:129]
	v_mfma_f32_16x16x32_bf16 v[122:125], v[142:145], v[178:181], 0
	v_mfma_f32_16x16x32_bf16 v[122:125], v[146:149], v[182:185], v[122:125]
	v_mfma_f32_16x16x32_bf16 v[114:117], v[142:145], v[186:189], 0
	v_mfma_f32_16x16x32_bf16 v[114:117], v[146:149], v[190:193], v[114:117]
	v_mfma_f32_16x16x32_bf16 v[118:121], v[134:137], v[186:189], 0
	v_mfma_f32_16x16x32_bf16 v[118:121], v[138:141], v[190:193], v[118:121]
	v_mfma_f32_16x16x32_bf16 v[102:105], v[134:137], v[194:197], 0
	v_mfma_f32_16x16x32_bf16 v[102:105], v[138:141], v[198:201], v[102:105]
	v_mfma_f32_16x16x32_bf16 v[94:97], v[142:145], v[194:197], 0
	v_mfma_f32_16x16x32_bf16 v[94:97], v[146:149], v[198:201], v[94:97]
	v_mfma_f32_16x16x32_bf16 v[78:81], v[142:145], v[202:205], 0
	v_mfma_f32_16x16x32_bf16 v[78:81], v[146:149], v[206:209], v[78:81]
	v_mfma_f32_16x16x32_bf16 v[86:89], v[134:137], v[202:205], 0
	v_mfma_f32_16x16x32_bf16 v[86:89], v[138:141], v[206:209], v[86:89]
	s_setprio 0
	s_setprio 1
	v_mfma_f32_16x16x32_bf16 v[110:113], v[150:153], v[178:181], 0
	v_mfma_f32_16x16x32_bf16 v[110:113], v[166:169], v[182:185], v[110:113]
	v_mfma_f32_16x16x32_bf16 v[106:109], v[170:173], v[178:181], 0
	v_mfma_f32_16x16x32_bf16 v[106:109], v[174:177], v[182:185], v[106:109]
	v_mfma_f32_16x16x32_bf16 v[90:93], v[170:173], v[186:189], 0
	v_mfma_f32_16x16x32_bf16 v[90:93], v[174:177], v[190:193], v[90:93]
	v_mfma_f32_16x16x32_bf16 v[98:101], v[150:153], v[186:189], 0
	v_mfma_f32_16x16x32_bf16 v[98:101], v[166:169], v[190:193], v[98:101]
	v_mfma_f32_16x16x32_bf16 v[82:85], v[150:153], v[194:197], 0
	v_mfma_f32_16x16x32_bf16 v[82:85], v[166:169], v[198:201], v[82:85]
	v_mfma_f32_16x16x32_bf16 v[74:77], v[170:173], v[194:197], 0
	v_mfma_f32_16x16x32_bf16 v[74:77], v[174:177], v[198:201], v[74:77]
	v_mfma_f32_16x16x32_bf16 v[66:69], v[170:173], v[202:205], 0
	v_mfma_f32_16x16x32_bf16 v[66:69], v[174:177], v[206:209], v[66:69]
	s_setprio 2
	s_barrier
	v_mfma_f32_16x16x32_bf16 v[70:73], v[150:153], v[202:205], 0
	v_mfma_f32_16x16x32_bf16 v[70:73], v[166:169], v[206:209], v[70:73]
	s_setprio 0
	ds_read_b128 v[178:181], v163 offset:16384
	ds_read_b128 v[182:185], v163 offset:17408
	ds_read_b128 v[186:189], v163 offset:18432
	ds_read_b128 v[190:193], v163 offset:19456
	ds_read_b128 v[194:197], v163 offset:20480
	ds_read_b128 v[198:201], v163 offset:21504
	ds_read_b128 v[202:205], v163 offset:22528
	ds_read_b128 v[206:209], v163 offset:23552
	s_mov_b32 s83, m0
	s_mov_b32 m0, s19
	s_nop 0
	global_load_lds_dwordx4 v156, s[22:23]
	s_mov_b32 m0, s83
	s_add_u32 s86, s22, 0x4000
	s_mov_b32 s83, m0
	s_mov_b32 m0, s35
	s_nop 0
	global_load_lds_dwordx4 v158, s[22:23]
	s_mov_b32 m0, s83
	s_addc_u32 s87, s23, 0
	s_mov_b32 s83, m0
	s_mov_b32 m0, s36
	s_nop 0
	global_load_lds_dwordx4 v156, s[86:87]
	s_mov_b32 m0, s83
	s_nop 0
	s_mov_b32 s83, m0
	s_mov_b32 m0, s37
	s_nop 0
	global_load_lds_dwordx4 v158, s[86:87]
	s_mov_b32 m0, s83
	s_waitcnt vmcnt(4)
	s_waitcnt lgkmcnt(0)
	s_barrier
	s_setprio 1
	.p2align 3
	v_mfma_f32_16x16x32_bf16 v[62:65], v[134:137], v[178:181], 0
	v_mfma_f32_16x16x32_bf16 v[62:65], v[138:141], v[182:185], v[62:65]
	v_mfma_f32_16x16x32_bf16 v[58:61], v[142:145], v[178:181], 0
	v_mfma_f32_16x16x32_bf16 v[58:61], v[146:149], v[182:185], v[58:61]
	v_mfma_f32_16x16x32_bf16 v[46:49], v[142:145], v[186:189], 0
	v_mfma_f32_16x16x32_bf16 v[46:49], v[146:149], v[190:193], v[46:49]
	v_mfma_f32_16x16x32_bf16 v[54:57], v[134:137], v[186:189], 0
	v_mfma_f32_16x16x32_bf16 v[54:57], v[138:141], v[190:193], v[54:57]
	v_mfma_f32_16x16x32_bf16 v[38:41], v[134:137], v[194:197], 0
	v_mfma_f32_16x16x32_bf16 v[38:41], v[138:141], v[198:201], v[38:41]
	v_mfma_f32_16x16x32_bf16 v[30:33], v[142:145], v[194:197], 0
	v_mfma_f32_16x16x32_bf16 v[30:33], v[146:149], v[198:201], v[30:33]
	v_mfma_f32_16x16x32_bf16 v[14:17], v[142:145], v[202:205], 0
	v_mfma_f32_16x16x32_bf16 v[14:17], v[146:149], v[206:209], v[14:17]
	v_mfma_f32_16x16x32_bf16 v[22:25], v[134:137], v[202:205], 0
	v_mfma_f32_16x16x32_bf16 v[22:25], v[138:141], v[206:209], v[22:25]
	s_setprio 0
	s_setprio 1
	v_mfma_f32_16x16x32_bf16 v[50:53], v[150:153], v[178:181], 0
	v_mfma_f32_16x16x32_bf16 v[50:53], v[166:169], v[182:185], v[50:53]
	v_mfma_f32_16x16x32_bf16 v[42:45], v[170:173], v[178:181], 0
	v_mfma_f32_16x16x32_bf16 v[42:45], v[174:177], v[182:185], v[42:45]
	v_mfma_f32_16x16x32_bf16 v[26:29], v[170:173], v[186:189], 0
	v_mfma_f32_16x16x32_bf16 v[26:29], v[174:177], v[190:193], v[26:29]
	v_mfma_f32_16x16x32_bf16 v[34:37], v[150:153], v[186:189], 0
	v_mfma_f32_16x16x32_bf16 v[34:37], v[166:169], v[190:193], v[34:37]
	v_mfma_f32_16x16x32_bf16 v[18:21], v[150:153], v[194:197], 0
	v_mfma_f32_16x16x32_bf16 v[18:21], v[166:169], v[198:201], v[18:21]
	v_mfma_f32_16x16x32_bf16 v[10:13], v[170:173], v[194:197], 0
	v_mfma_f32_16x16x32_bf16 v[10:13], v[174:177], v[198:201], v[10:13]
	v_mfma_f32_16x16x32_bf16 v[2:5], v[170:173], v[202:205], 0
	v_mfma_f32_16x16x32_bf16 v[2:5], v[174:177], v[206:209], v[2:5]
	s_setprio 2
	s_barrier
	v_mfma_f32_16x16x32_bf16 v[6:9], v[150:153], v[202:205], 0
	v_mfma_f32_16x16x32_bf16 v[6:9], v[166:169], v[206:209], v[6:9]
	s_setprio 0
	ds_read_b128 v[134:137], v164
	ds_read_b128 v[138:141], v164 offset:1024
	ds_read_b128 v[142:145], v164 offset:2048
	ds_read_b128 v[146:149], v164 offset:3072
	ds_read_b128 v[150:153], v165
	ds_read_b128 v[166:169], v165 offset:1024
	ds_read_b128 v[170:173], v165 offset:2048
	ds_read_b128 v[174:177], v165 offset:3072
	ds_read_b128 v[178:181], v163 offset:32768
	ds_read_b128 v[182:185], v163 offset:33792
	ds_read_b128 v[186:189], v163 offset:34816
	ds_read_b128 v[190:193], v163 offset:35840
	ds_read_b128 v[194:197], v163 offset:36864
	ds_read_b128 v[198:201], v163 offset:37888
	ds_read_b128 v[202:205], v163 offset:38912
	ds_read_b128 v[206:209], v163 offset:39936
	s_mov_b32 s83, m0
	s_mov_b32 m0, s34
	s_nop 0
	global_load_lds_dwordx4 v1, s[24:25]
	s_mov_b32 m0, s83
	s_nop 0
	s_mov_b32 s83, m0
	s_mov_b32 m0, s42
	s_nop 0
	global_load_lds_dwordx4 v157, s[24:25]
	s_mov_b32 m0, s83
	s_add_u32 s24, s24, 0x4000
	s_addc_u32 s25, s25, 0
	s_mov_b32 s83, m0
	s_mov_b32 m0, s43
	s_nop 0
	global_load_lds_dwordx4 v1, s[24:25]
	s_mov_b32 m0, s83
	s_nop 0
	s_mov_b32 s83, m0
	s_mov_b32 m0, s46
	s_nop 0
	global_load_lds_dwordx4 v157, s[24:25]
	s_mov_b32 m0, s83
	s_waitcnt vmcnt(8)
	s_waitcnt lgkmcnt(0)
	s_barrier
	s_setprio 1
	.p2align 3
	v_mfma_f32_16x16x32_bf16 v[126:129], v[134:137], v[178:181], v[126:129]
	v_mfma_f32_16x16x32_bf16 v[126:129], v[138:141], v[182:185], v[126:129]
	v_mfma_f32_16x16x32_bf16 v[122:125], v[142:145], v[178:181], v[122:125]
	v_mfma_f32_16x16x32_bf16 v[122:125], v[146:149], v[182:185], v[122:125]
	v_mfma_f32_16x16x32_bf16 v[114:117], v[142:145], v[186:189], v[114:117]
	v_mfma_f32_16x16x32_bf16 v[114:117], v[146:149], v[190:193], v[114:117]
	v_mfma_f32_16x16x32_bf16 v[118:121], v[134:137], v[186:189], v[118:121]
	v_mfma_f32_16x16x32_bf16 v[118:121], v[138:141], v[190:193], v[118:121]
	v_mfma_f32_16x16x32_bf16 v[102:105], v[134:137], v[194:197], v[102:105]
	v_mfma_f32_16x16x32_bf16 v[102:105], v[138:141], v[198:201], v[102:105]
	v_mfma_f32_16x16x32_bf16 v[94:97], v[142:145], v[194:197], v[94:97]
	v_mfma_f32_16x16x32_bf16 v[94:97], v[146:149], v[198:201], v[94:97]
	v_mfma_f32_16x16x32_bf16 v[78:81], v[142:145], v[202:205], v[78:81]
	v_mfma_f32_16x16x32_bf16 v[78:81], v[146:149], v[206:209], v[78:81]
	v_mfma_f32_16x16x32_bf16 v[86:89], v[134:137], v[202:205], v[86:89]
	v_mfma_f32_16x16x32_bf16 v[86:89], v[138:141], v[206:209], v[86:89]
	s_setprio 0
	s_setprio 1
	v_mfma_f32_16x16x32_bf16 v[110:113], v[150:153], v[178:181], v[110:113]
	v_mfma_f32_16x16x32_bf16 v[110:113], v[166:169], v[182:185], v[110:113]
	v_mfma_f32_16x16x32_bf16 v[106:109], v[170:173], v[178:181], v[106:109]
	v_mfma_f32_16x16x32_bf16 v[106:109], v[174:177], v[182:185], v[106:109]
	v_mfma_f32_16x16x32_bf16 v[90:93], v[170:173], v[186:189], v[90:93]
	v_mfma_f32_16x16x32_bf16 v[90:93], v[174:177], v[190:193], v[90:93]
	v_mfma_f32_16x16x32_bf16 v[98:101], v[150:153], v[186:189], v[98:101]
	v_mfma_f32_16x16x32_bf16 v[98:101], v[166:169], v[190:193], v[98:101]
	v_mfma_f32_16x16x32_bf16 v[82:85], v[150:153], v[194:197], v[82:85]
	v_mfma_f32_16x16x32_bf16 v[82:85], v[166:169], v[198:201], v[82:85]
	v_mfma_f32_16x16x32_bf16 v[74:77], v[170:173], v[194:197], v[74:77]
	v_mfma_f32_16x16x32_bf16 v[74:77], v[174:177], v[198:201], v[74:77]
	v_mfma_f32_16x16x32_bf16 v[66:69], v[170:173], v[202:205], v[66:69]
	v_mfma_f32_16x16x32_bf16 v[66:69], v[174:177], v[206:209], v[66:69]
	s_setprio 2
	s_barrier
	v_mfma_f32_16x16x32_bf16 v[70:73], v[150:153], v[202:205], v[70:73]
	v_mfma_f32_16x16x32_bf16 v[70:73], v[166:169], v[206:209], v[70:73]
	s_setprio 0
	ds_read_b128 v[178:181], v163 offset:49152
	ds_read_b128 v[182:185], v163 offset:50176
	ds_read_b128 v[186:189], v163 offset:51200
	ds_read_b128 v[190:193], v163 offset:52224
	ds_read_b128 v[194:197], v163 offset:53248
	ds_read_b128 v[198:201], v163 offset:54272
	ds_read_b128 v[202:205], v163 offset:55296
	ds_read_b128 v[206:209], v163 offset:56320
	s_add_u32 s24, s22, 0x40000
	s_addc_u32 s25, s23, 0
	s_mov_b32 s83, m0
	s_mov_b32 m0, s47
	s_nop 0
	global_load_lds_dwordx4 v156, s[24:25]
	s_mov_b32 m0, s83
	s_add_u32 s22, s22, 0x44000
	s_mov_b32 s83, m0
	s_mov_b32 m0, s48
	s_nop 0
	global_load_lds_dwordx4 v158, s[24:25]
	s_mov_b32 m0, s83
	s_addc_u32 s23, s23, 0
	s_mov_b32 s24, m0
	s_mov_b32 m0, s49
	s_nop 0
	global_load_lds_dwordx4 v156, s[22:23]
	s_mov_b32 m0, s24
	s_nop 0
	s_mov_b32 s24, m0
	s_mov_b32 m0, s56
	s_nop 0
	global_load_lds_dwordx4 v158, s[22:23]
	s_mov_b32 m0, s24
	s_waitcnt vmcnt(4)
	s_waitcnt lgkmcnt(0)
	s_barrier
	s_setprio 1
	.p2align 3
	v_mfma_f32_16x16x32_bf16 v[62:65], v[134:137], v[178:181], v[62:65]
	v_mfma_f32_16x16x32_bf16 v[62:65], v[138:141], v[182:185], v[62:65]
	v_mfma_f32_16x16x32_bf16 v[58:61], v[142:145], v[178:181], v[58:61]
	v_mfma_f32_16x16x32_bf16 v[58:61], v[146:149], v[182:185], v[58:61]
	v_mfma_f32_16x16x32_bf16 v[46:49], v[142:145], v[186:189], v[46:49]
	v_mfma_f32_16x16x32_bf16 v[46:49], v[146:149], v[190:193], v[46:49]
	v_mfma_f32_16x16x32_bf16 v[54:57], v[134:137], v[186:189], v[54:57]
	v_mfma_f32_16x16x32_bf16 v[54:57], v[138:141], v[190:193], v[54:57]
	v_mfma_f32_16x16x32_bf16 v[38:41], v[134:137], v[194:197], v[38:41]
	v_mfma_f32_16x16x32_bf16 v[38:41], v[138:141], v[198:201], v[38:41]
	v_mfma_f32_16x16x32_bf16 v[30:33], v[142:145], v[194:197], v[30:33]
	v_mfma_f32_16x16x32_bf16 v[30:33], v[146:149], v[198:201], v[30:33]
	v_mfma_f32_16x16x32_bf16 v[14:17], v[142:145], v[202:205], v[14:17]
	v_mfma_f32_16x16x32_bf16 v[14:17], v[146:149], v[206:209], v[14:17]
	v_mfma_f32_16x16x32_bf16 v[22:25], v[134:137], v[202:205], v[22:25]
	v_mfma_f32_16x16x32_bf16 v[22:25], v[138:141], v[206:209], v[22:25]
	s_setprio 0
	s_setprio 1
	v_mfma_f32_16x16x32_bf16 v[50:53], v[150:153], v[178:181], v[50:53]
	v_mfma_f32_16x16x32_bf16 v[50:53], v[166:169], v[182:185], v[50:53]
	v_mfma_f32_16x16x32_bf16 v[42:45], v[170:173], v[178:181], v[42:45]
	v_mfma_f32_16x16x32_bf16 v[42:45], v[174:177], v[182:185], v[42:45]
	v_mfma_f32_16x16x32_bf16 v[26:29], v[170:173], v[186:189], v[26:29]
	v_mfma_f32_16x16x32_bf16 v[26:29], v[174:177], v[190:193], v[26:29]
	v_mfma_f32_16x16x32_bf16 v[34:37], v[150:153], v[186:189], v[34:37]
	v_mfma_f32_16x16x32_bf16 v[34:37], v[166:169], v[190:193], v[34:37]
	v_mfma_f32_16x16x32_bf16 v[18:21], v[150:153], v[194:197], v[18:21]
	v_mfma_f32_16x16x32_bf16 v[18:21], v[166:169], v[198:201], v[18:21]
	v_mfma_f32_16x16x32_bf16 v[10:13], v[170:173], v[194:197], v[10:13]
	v_mfma_f32_16x16x32_bf16 v[10:13], v[174:177], v[198:201], v[10:13]
	v_mfma_f32_16x16x32_bf16 v[2:5], v[170:173], v[202:205], v[2:5]
	v_mfma_f32_16x16x32_bf16 v[2:5], v[174:177], v[206:209], v[2:5]
	s_setprio 2
	s_barrier
	v_mfma_f32_16x16x32_bf16 v[6:9], v[150:153], v[202:205], v[6:9]
	v_mfma_f32_16x16x32_bf16 v[6:9], v[166:169], v[206:209], v[6:9]
	s_setprio 0
	s_add_i32 s82, s82, 2
	s_add_u32 s78, s78, 0x80000
	s_addc_u32 s79, s79, 0
	s_add_u32 s20, s20, 0x400000
	s_addc_u32 s21, s21, 0
	s_add_u32 s80, s80, 0x400000
	s_addc_u32 s81, s81, 0
	s_cmpk_gt_u32 s82, 0x53
	.p2align 6
.LBB0_473:
	ds_read_b128 v[134:137], v161
	ds_read_b128 v[138:141], v161 offset:1024
	ds_read_b128 v[142:145], v161 offset:2048
	ds_read_b128 v[146:149], v161 offset:3072
	ds_read_b128 v[150:153], v162
	ds_read_b128 v[166:169], v162 offset:1024
	ds_read_b128 v[170:173], v162 offset:2048
	ds_read_b128 v[174:177], v162 offset:3072
	s_cmpk_eq_i32 s82, 0x52
	s_cselect_b32 s23, s11, s79
	s_cselect_b32 s22, s77, s78
	s_cselect_b32 s25, s13, s81
	s_cselect_b32 s24, s76, s80
	ds_read_b128 v[178:181], v163
	ds_read_b128 v[182:185], v163 offset:1024
	ds_read_b128 v[186:189], v163 offset:2048
	ds_read_b128 v[190:193], v163 offset:3072
	ds_read_b128 v[194:197], v163 offset:4096
	ds_read_b128 v[198:201], v163 offset:5120
	ds_read_b128 v[202:205], v163 offset:6144
	ds_read_b128 v[206:209], v163 offset:7168
	s_add_u32 s86, s20, 0xffffc000
	s_addc_u32 s87, s21, -1
	s_mov_b32 s83, m0
	s_mov_b32 m0, s65
	s_nop 0
	global_load_lds_dwordx4 v1, s[86:87]
	s_mov_b32 m0, s83
	s_nop 0
	s_mov_b32 s83, m0
	s_mov_b32 m0, s67
	s_nop 0
	global_load_lds_dwordx4 v157, s[86:87]
	s_mov_b32 m0, s83
	s_nop 0
	s_mov_b32 s83, m0
	s_mov_b32 m0, s66
	s_nop 0
	global_load_lds_dwordx4 v1, s[20:21]
	s_mov_b32 m0, s83
	s_nop 0
	s_mov_b32 s83, m0
	s_mov_b32 m0, s73
	s_nop 0
	global_load_lds_dwordx4 v157, s[20:21]
	s_mov_b32 m0, s83
	s_waitcnt vmcnt(8)
	s_waitcnt lgkmcnt(0)
	s_barrier
	s_setprio 1
	.p2align 3
	v_mfma_f32_16x16x32_bf16 v[126:129], v[134:137], v[178:181], v[126:129]
	v_mfma_f32_16x16x32_bf16 v[126:129], v[138:141], v[182:185], v[126:129]
	v_mfma_f32_16x16x32_bf16 v[122:125], v[142:145], v[178:181], v[122:125]
	v_mfma_f32_16x16x32_bf16 v[122:125], v[146:149], v[182:185], v[122:125]
	v_mfma_f32_16x16x32_bf16 v[114:117], v[142:145], v[186:189], v[114:117]
	v_mfma_f32_16x16x32_bf16 v[114:117], v[146:149], v[190:193], v[114:117]
	v_mfma_f32_16x16x32_bf16 v[118:121], v[134:137], v[186:189], v[118:121]
	v_mfma_f32_16x16x32_bf16 v[118:121], v[138:141], v[190:193], v[118:121]
	v_mfma_f32_16x16x32_bf16 v[102:105], v[134:137], v[194:197], v[102:105]
	v_mfma_f32_16x16x32_bf16 v[102:105], v[138:141], v[198:201], v[102:105]
	v_mfma_f32_16x16x32_bf16 v[94:97], v[142:145], v[194:197], v[94:97]
	v_mfma_f32_16x16x32_bf16 v[94:97], v[146:149], v[198:201], v[94:97]
	v_mfma_f32_16x16x32_bf16 v[78:81], v[142:145], v[202:205], v[78:81]
	v_mfma_f32_16x16x32_bf16 v[78:81], v[146:149], v[206:209], v[78:81]
	v_mfma_f32_16x16x32_bf16 v[86:89], v[134:137], v[202:205], v[86:89]
	v_mfma_f32_16x16x32_bf16 v[86:89], v[138:141], v[206:209], v[86:89]
	s_setprio 0
	s_setprio 1
	v_mfma_f32_16x16x32_bf16 v[110:113], v[150:153], v[178:181], v[110:113]
	v_mfma_f32_16x16x32_bf16 v[110:113], v[166:169], v[182:185], v[110:113]
	v_mfma_f32_16x16x32_bf16 v[106:109], v[170:173], v[178:181], v[106:109]
	v_mfma_f32_16x16x32_bf16 v[106:109], v[174:177], v[182:185], v[106:109]
	v_mfma_f32_16x16x32_bf16 v[90:93], v[170:173], v[186:189], v[90:93]
	v_mfma_f32_16x16x32_bf16 v[90:93], v[174:177], v[190:193], v[90:93]
	v_mfma_f32_16x16x32_bf16 v[98:101], v[150:153], v[186:189], v[98:101]
	v_mfma_f32_16x16x32_bf16 v[98:101], v[166:169], v[190:193], v[98:101]
	v_mfma_f32_16x16x32_bf16 v[82:85], v[150:153], v[194:197], v[82:85]
	v_mfma_f32_16x16x32_bf16 v[82:85], v[166:169], v[198:201], v[82:85]
	v_mfma_f32_16x16x32_bf16 v[74:77], v[170:173], v[194:197], v[74:77]
	v_mfma_f32_16x16x32_bf16 v[74:77], v[174:177], v[198:201], v[74:77]
	v_mfma_f32_16x16x32_bf16 v[66:69], v[170:173], v[202:205], v[66:69]
	v_mfma_f32_16x16x32_bf16 v[66:69], v[174:177], v[206:209], v[66:69]
	s_setprio 2
	s_barrier
	v_mfma_f32_16x16x32_bf16 v[70:73], v[150:153], v[202:205], v[70:73]
	v_mfma_f32_16x16x32_bf16 v[70:73], v[166:169], v[206:209], v[70:73]
	s_setprio 0
	ds_read_b128 v[178:181], v163 offset:16384
	ds_read_b128 v[182:185], v163 offset:17408
	ds_read_b128 v[186:189], v163 offset:18432
	ds_read_b128 v[190:193], v163 offset:19456
	ds_read_b128 v[194:197], v163 offset:20480
	ds_read_b128 v[198:201], v163 offset:21504
	ds_read_b128 v[202:205], v163 offset:22528
	ds_read_b128 v[206:209], v163 offset:23552
	s_mov_b32 s83, m0
	s_mov_b32 m0, s19
	s_nop 0
	global_load_lds_dwordx4 v156, s[22:23]
	s_mov_b32 m0, s83
	s_add_u32 s86, s22, 0x4000
	s_mov_b32 s83, m0
	s_mov_b32 m0, s35
	s_nop 0
	global_load_lds_dwordx4 v158, s[22:23]
	s_mov_b32 m0, s83
	s_addc_u32 s87, s23, 0
	s_mov_b32 s83, m0
	s_mov_b32 m0, s36
	s_nop 0
	global_load_lds_dwordx4 v156, s[86:87]
	s_mov_b32 m0, s83
	s_nop 0
	s_mov_b32 s83, m0
	s_mov_b32 m0, s37
	s_nop 0
	global_load_lds_dwordx4 v158, s[86:87]
	s_mov_b32 m0, s83
	s_waitcnt vmcnt(4)
	s_waitcnt lgkmcnt(0)
	s_barrier
	s_setprio 1
	.p2align 3
	v_mfma_f32_16x16x32_bf16 v[62:65], v[134:137], v[178:181], v[62:65]
	v_mfma_f32_16x16x32_bf16 v[62:65], v[138:141], v[182:185], v[62:65]
	v_mfma_f32_16x16x32_bf16 v[58:61], v[142:145], v[178:181], v[58:61]
	v_mfma_f32_16x16x32_bf16 v[58:61], v[146:149], v[182:185], v[58:61]
	v_mfma_f32_16x16x32_bf16 v[46:49], v[142:145], v[186:189], v[46:49]
	v_mfma_f32_16x16x32_bf16 v[46:49], v[146:149], v[190:193], v[46:49]
	v_mfma_f32_16x16x32_bf16 v[54:57], v[134:137], v[186:189], v[54:57]
	v_mfma_f32_16x16x32_bf16 v[54:57], v[138:141], v[190:193], v[54:57]
	v_mfma_f32_16x16x32_bf16 v[38:41], v[134:137], v[194:197], v[38:41]
	v_mfma_f32_16x16x32_bf16 v[38:41], v[138:141], v[198:201], v[38:41]
	v_mfma_f32_16x16x32_bf16 v[30:33], v[142:145], v[194:197], v[30:33]
	v_mfma_f32_16x16x32_bf16 v[30:33], v[146:149], v[198:201], v[30:33]
	v_mfma_f32_16x16x32_bf16 v[14:17], v[142:145], v[202:205], v[14:17]
	v_mfma_f32_16x16x32_bf16 v[14:17], v[146:149], v[206:209], v[14:17]
	v_mfma_f32_16x16x32_bf16 v[22:25], v[134:137], v[202:205], v[22:25]
	v_mfma_f32_16x16x32_bf16 v[22:25], v[138:141], v[206:209], v[22:25]
	s_setprio 0
	s_setprio 1
	v_mfma_f32_16x16x32_bf16 v[50:53], v[150:153], v[178:181], v[50:53]
	v_mfma_f32_16x16x32_bf16 v[50:53], v[166:169], v[182:185], v[50:53]
	v_mfma_f32_16x16x32_bf16 v[42:45], v[170:173], v[178:181], v[42:45]
	v_mfma_f32_16x16x32_bf16 v[42:45], v[174:177], v[182:185], v[42:45]
	v_mfma_f32_16x16x32_bf16 v[26:29], v[170:173], v[186:189], v[26:29]
	v_mfma_f32_16x16x32_bf16 v[26:29], v[174:177], v[190:193], v[26:29]
	v_mfma_f32_16x16x32_bf16 v[34:37], v[150:153], v[186:189], v[34:37]
	v_mfma_f32_16x16x32_bf16 v[34:37], v[166:169], v[190:193], v[34:37]
	v_mfma_f32_16x16x32_bf16 v[18:21], v[150:153], v[194:197], v[18:21]
	v_mfma_f32_16x16x32_bf16 v[18:21], v[166:169], v[198:201], v[18:21]
	v_mfma_f32_16x16x32_bf16 v[10:13], v[170:173], v[194:197], v[10:13]
	v_mfma_f32_16x16x32_bf16 v[10:13], v[174:177], v[198:201], v[10:13]
	v_mfma_f32_16x16x32_bf16 v[2:5], v[170:173], v[202:205], v[2:5]
	v_mfma_f32_16x16x32_bf16 v[2:5], v[174:177], v[206:209], v[2:5]
	s_setprio 2
	s_barrier
	v_mfma_f32_16x16x32_bf16 v[6:9], v[150:153], v[202:205], v[6:9]
	v_mfma_f32_16x16x32_bf16 v[6:9], v[166:169], v[206:209], v[6:9]
	s_setprio 0
	ds_read_b128 v[134:137], v164
	ds_read_b128 v[138:141], v164 offset:1024
	ds_read_b128 v[142:145], v164 offset:2048
	ds_read_b128 v[146:149], v164 offset:3072
	ds_read_b128 v[150:153], v165
	ds_read_b128 v[166:169], v165 offset:1024
	ds_read_b128 v[170:173], v165 offset:2048
	ds_read_b128 v[174:177], v165 offset:3072
	ds_read_b128 v[178:181], v163 offset:32768
	ds_read_b128 v[182:185], v163 offset:33792
	ds_read_b128 v[186:189], v163 offset:34816
	ds_read_b128 v[190:193], v163 offset:35840
	ds_read_b128 v[194:197], v163 offset:36864
	ds_read_b128 v[198:201], v163 offset:37888
	ds_read_b128 v[202:205], v163 offset:38912
	ds_read_b128 v[206:209], v163 offset:39936
	s_mov_b32 s83, m0
	s_mov_b32 m0, s34
	s_nop 0
	global_load_lds_dwordx4 v1, s[24:25]
	s_mov_b32 m0, s83
	s_nop 0
	s_mov_b32 s83, m0
	s_mov_b32 m0, s42
	s_nop 0
	global_load_lds_dwordx4 v157, s[24:25]
	s_mov_b32 m0, s83
	s_add_u32 s24, s24, 0x4000
	s_addc_u32 s25, s25, 0
	s_mov_b32 s83, m0
	s_mov_b32 m0, s43
	s_nop 0
	global_load_lds_dwordx4 v1, s[24:25]
	s_mov_b32 m0, s83
	s_nop 0
	s_mov_b32 s83, m0
	s_mov_b32 m0, s46
	s_nop 0
	global_load_lds_dwordx4 v157, s[24:25]
	s_mov_b32 m0, s83
	s_waitcnt vmcnt(8)
	s_waitcnt lgkmcnt(0)
	s_barrier
	s_setprio 1
	.p2align 3
	v_mfma_f32_16x16x32_bf16 v[126:129], v[134:137], v[178:181], v[126:129]
	v_mfma_f32_16x16x32_bf16 v[126:129], v[138:141], v[182:185], v[126:129]
	v_mfma_f32_16x16x32_bf16 v[122:125], v[142:145], v[178:181], v[122:125]
	v_mfma_f32_16x16x32_bf16 v[122:125], v[146:149], v[182:185], v[122:125]
	v_mfma_f32_16x16x32_bf16 v[114:117], v[142:145], v[186:189], v[114:117]
	v_mfma_f32_16x16x32_bf16 v[114:117], v[146:149], v[190:193], v[114:117]
	v_mfma_f32_16x16x32_bf16 v[118:121], v[134:137], v[186:189], v[118:121]
	v_mfma_f32_16x16x32_bf16 v[118:121], v[138:141], v[190:193], v[118:121]
	v_mfma_f32_16x16x32_bf16 v[102:105], v[134:137], v[194:197], v[102:105]
	v_mfma_f32_16x16x32_bf16 v[102:105], v[138:141], v[198:201], v[102:105]
	v_mfma_f32_16x16x32_bf16 v[94:97], v[142:145], v[194:197], v[94:97]
	v_mfma_f32_16x16x32_bf16 v[94:97], v[146:149], v[198:201], v[94:97]
	v_mfma_f32_16x16x32_bf16 v[78:81], v[142:145], v[202:205], v[78:81]
	v_mfma_f32_16x16x32_bf16 v[78:81], v[146:149], v[206:209], v[78:81]
	v_mfma_f32_16x16x32_bf16 v[86:89], v[134:137], v[202:205], v[86:89]
	v_mfma_f32_16x16x32_bf16 v[86:89], v[138:141], v[206:209], v[86:89]
	s_setprio 0
	s_setprio 1
	v_mfma_f32_16x16x32_bf16 v[110:113], v[150:153], v[178:181], v[110:113]
	v_mfma_f32_16x16x32_bf16 v[110:113], v[166:169], v[182:185], v[110:113]
	v_mfma_f32_16x16x32_bf16 v[106:109], v[170:173], v[178:181], v[106:109]
	v_mfma_f32_16x16x32_bf16 v[106:109], v[174:177], v[182:185], v[106:109]
	v_mfma_f32_16x16x32_bf16 v[90:93], v[170:173], v[186:189], v[90:93]
	v_mfma_f32_16x16x32_bf16 v[90:93], v[174:177], v[190:193], v[90:93]
	v_mfma_f32_16x16x32_bf16 v[98:101], v[150:153], v[186:189], v[98:101]
	v_mfma_f32_16x16x32_bf16 v[98:101], v[166:169], v[190:193], v[98:101]
	v_mfma_f32_16x16x32_bf16 v[82:85], v[150:153], v[194:197], v[82:85]
	v_mfma_f32_16x16x32_bf16 v[82:85], v[166:169], v[198:201], v[82:85]
	v_mfma_f32_16x16x32_bf16 v[74:77], v[170:173], v[194:197], v[74:77]
	v_mfma_f32_16x16x32_bf16 v[74:77], v[174:177], v[198:201], v[74:77]
	v_mfma_f32_16x16x32_bf16 v[66:69], v[170:173], v[202:205], v[66:69]
	v_mfma_f32_16x16x32_bf16 v[66:69], v[174:177], v[206:209], v[66:69]
	s_setprio 2
	s_barrier
	v_mfma_f32_16x16x32_bf16 v[70:73], v[150:153], v[202:205], v[70:73]
	v_mfma_f32_16x16x32_bf16 v[70:73], v[166:169], v[206:209], v[70:73]
	s_setprio 0
	ds_read_b128 v[178:181], v163 offset:49152
	ds_read_b128 v[182:185], v163 offset:50176
	ds_read_b128 v[186:189], v163 offset:51200
	ds_read_b128 v[190:193], v163 offset:52224
	ds_read_b128 v[194:197], v163 offset:53248
	ds_read_b128 v[198:201], v163 offset:54272
	ds_read_b128 v[202:205], v163 offset:55296
	ds_read_b128 v[206:209], v163 offset:56320
	s_add_u32 s24, s22, 0x40000
	s_addc_u32 s25, s23, 0
	s_mov_b32 s83, m0
	s_mov_b32 m0, s47
	s_nop 0
	global_load_lds_dwordx4 v156, s[24:25]
	s_mov_b32 m0, s83
	s_add_u32 s22, s22, 0x44000
	s_mov_b32 s83, m0
	s_mov_b32 m0, s48
	s_nop 0
	global_load_lds_dwordx4 v158, s[24:25]
	s_mov_b32 m0, s83
	s_addc_u32 s23, s23, 0
	s_mov_b32 s24, m0
	s_mov_b32 m0, s49
	s_nop 0
	global_load_lds_dwordx4 v156, s[22:23]
	s_mov_b32 m0, s24
	s_nop 0
	s_mov_b32 s24, m0
	s_mov_b32 m0, s56
	s_nop 0
	global_load_lds_dwordx4 v158, s[22:23]
	s_mov_b32 m0, s24
	s_waitcnt vmcnt(4)
	s_waitcnt lgkmcnt(0)
	s_barrier
	s_setprio 1
	.p2align 3
	v_mfma_f32_16x16x32_bf16 v[62:65], v[134:137], v[178:181], v[62:65]
	v_mfma_f32_16x16x32_bf16 v[62:65], v[138:141], v[182:185], v[62:65]
	v_mfma_f32_16x16x32_bf16 v[58:61], v[142:145], v[178:181], v[58:61]
	v_mfma_f32_16x16x32_bf16 v[58:61], v[146:149], v[182:185], v[58:61]
	v_mfma_f32_16x16x32_bf16 v[46:49], v[142:145], v[186:189], v[46:49]
	v_mfma_f32_16x16x32_bf16 v[46:49], v[146:149], v[190:193], v[46:49]
	v_mfma_f32_16x16x32_bf16 v[54:57], v[134:137], v[186:189], v[54:57]
	v_mfma_f32_16x16x32_bf16 v[54:57], v[138:141], v[190:193], v[54:57]
	v_mfma_f32_16x16x32_bf16 v[38:41], v[134:137], v[194:197], v[38:41]
	v_mfma_f32_16x16x32_bf16 v[38:41], v[138:141], v[198:201], v[38:41]
	v_mfma_f32_16x16x32_bf16 v[30:33], v[142:145], v[194:197], v[30:33]
	v_mfma_f32_16x16x32_bf16 v[30:33], v[146:149], v[198:201], v[30:33]
	v_mfma_f32_16x16x32_bf16 v[14:17], v[142:145], v[202:205], v[14:17]
	v_mfma_f32_16x16x32_bf16 v[14:17], v[146:149], v[206:209], v[14:17]
	v_mfma_f32_16x16x32_bf16 v[22:25], v[134:137], v[202:205], v[22:25]
	v_mfma_f32_16x16x32_bf16 v[22:25], v[138:141], v[206:209], v[22:25]
	s_setprio 0
	s_setprio 1
	v_mfma_f32_16x16x32_bf16 v[50:53], v[150:153], v[178:181], v[50:53]
	v_mfma_f32_16x16x32_bf16 v[50:53], v[166:169], v[182:185], v[50:53]
	v_mfma_f32_16x16x32_bf16 v[42:45], v[170:173], v[178:181], v[42:45]
	v_mfma_f32_16x16x32_bf16 v[42:45], v[174:177], v[182:185], v[42:45]
	v_mfma_f32_16x16x32_bf16 v[26:29], v[170:173], v[186:189], v[26:29]
	v_mfma_f32_16x16x32_bf16 v[26:29], v[174:177], v[190:193], v[26:29]
	v_mfma_f32_16x16x32_bf16 v[34:37], v[150:153], v[186:189], v[34:37]
	v_mfma_f32_16x16x32_bf16 v[34:37], v[166:169], v[190:193], v[34:37]
	v_mfma_f32_16x16x32_bf16 v[18:21], v[150:153], v[194:197], v[18:21]
	v_mfma_f32_16x16x32_bf16 v[18:21], v[166:169], v[198:201], v[18:21]
	v_mfma_f32_16x16x32_bf16 v[10:13], v[170:173], v[194:197], v[10:13]
	v_mfma_f32_16x16x32_bf16 v[10:13], v[174:177], v[198:201], v[10:13]
	v_mfma_f32_16x16x32_bf16 v[2:5], v[170:173], v[202:205], v[2:5]
	v_mfma_f32_16x16x32_bf16 v[2:5], v[174:177], v[206:209], v[2:5]
	s_setprio 2
	s_barrier
	v_mfma_f32_16x16x32_bf16 v[6:9], v[150:153], v[202:205], v[6:9]
	v_mfma_f32_16x16x32_bf16 v[6:9], v[166:169], v[206:209], v[6:9]
	s_setprio 0
	s_add_i32 s82, s82, 2
	s_add_u32 s78, s78, 0x80000
	s_addc_u32 s79, s79, 0
	s_add_u32 s20, s20, 0x400000
	s_addc_u32 s21, s21, 0
	s_add_u32 s80, s80, 0x400000
	s_addc_u32 s81, s81, 0
	s_cmpk_gt_u32 s82, 0x53
	s_cbranch_scc0 .LBB0_473
	s_and_b64 vcc, exec, s[8:9]
	s_cbranch_vccz .LBB0_476
	s_barrier

.LBB0_653:
	s_ashr_i32 s23, s22, 31
	s_lshl_b64 s[24:25], s[22:23], 20
	s_add_u32 s24, s35, s24
	s_addc_u32 s25, s36, s25
	s_and_b64 s[26:27], s[2:3], exec
	s_cselect_b32 s7, s25, s11
	s_cselect_b32 s9, s24, s10
	s_ashr_i32 s21, s20, 31
	s_lshl_b64 s[26:27], s[20:21], 20
	s_add_u32 s26, s37, s26
	s_addc_u32 s27, s40, s27
	s_and_b64 s[28:29], s[2:3], exec
	s_cselect_b32 s21, s27, s5
	s_cselect_b32 s23, s26, s4
	s_add_u32 s30, s4, 0x100
	s_addc_u32 s31, s5, 0
	s_add_u32 s4, s10, 0x80080
	s_addc_u32 s5, s11, 0
	s_add_u32 s33, s10, 0x100
	s_addc_u32 s73, s11, 0
	s_mov_b32 s74, -2
	s_waitcnt vmcnt(25)
	s_waitcnt vmcnt(24)
	s_waitcnt vmcnt(15)
	s_waitcnt vmcnt(14)
	s_waitcnt vmcnt(13)
	s_waitcnt vmcnt(12)
	s_waitcnt vmcnt(11)
	s_waitcnt vmcnt(10)
	s_waitcnt vmcnt(9)
	s_waitcnt vmcnt(8)
	s_waitcnt vmcnt(7)
	s_waitcnt vmcnt(6)
	s_waitcnt vmcnt(5)
	s_waitcnt vmcnt(4)
	s_waitcnt vmcnt(3)
	s_waitcnt vmcnt(2)
	s_waitcnt vmcnt(1)
	s_waitcnt vmcnt(0)
	ds_read_b128 v[130:133], v161
	ds_read_b128 v[138:141], v161 offset:1024
	ds_read_b128 v[142:145], v161 offset:2048
	ds_read_b128 v[146:149], v161 offset:3072
	ds_read_b128 v[150:153], v162
	ds_read_b128 v[168:171], v162 offset:1024
	ds_read_b128 v[172:175], v162 offset:2048
	ds_read_b128 v[176:179], v162 offset:3072
	s_cmp_eq_u32 s74, 28
	s_cselect_b32 s11, s21, s31
	s_cselect_b32 s10, s23, s30
	s_cselect_b32 s29, s7, s73
	s_cselect_b32 s28, s9, s33
	ds_read_b128 v[180:183], v163
	ds_read_b128 v[184:187], v163 offset:1024
	ds_read_b128 v[188:191], v163 offset:2048
	ds_read_b128 v[192:195], v163 offset:3072
	ds_read_b128 v[196:199], v163 offset:4096
	ds_read_b128 v[200:203], v163 offset:5120
	ds_read_b128 v[204:207], v163 offset:6144
	ds_read_b128 v[208:211], v163 offset:7168
	s_add_u32 s76, s4, 0xfff80000
	s_addc_u32 s77, s5, -1
	s_mov_b32 s75, m0
	s_mov_b32 m0, s80
	s_nop 0
	global_load_lds_dwordx4 v1, s[76:77]
	s_mov_b32 m0, s75
	s_nop 0
	s_mov_b32 s75, m0
	s_mov_b32 m0, s82
	s_nop 0
	global_load_lds_dwordx4 v157, s[76:77]
	s_mov_b32 m0, s75
	s_nop 0
	s_mov_b32 s75, m0
	s_mov_b32 m0, s81
	s_nop 0
	global_load_lds_dwordx4 v1, s[4:5]
	s_mov_b32 m0, s75
	s_nop 0
	s_mov_b32 s75, m0
	s_mov_b32 m0, s83
	s_nop 0
	global_load_lds_dwordx4 v157, s[4:5]
	s_mov_b32 m0, s75
	s_waitcnt vmcnt(8)
	s_waitcnt lgkmcnt(0)
	s_barrier
	s_setprio 1
	.p2align 3
	v_mfma_f32_16x16x32_bf16 v[126:129], v[130:133], v[180:183], 0
	v_mfma_f32_16x16x32_bf16 v[126:129], v[138:141], v[184:187], v[126:129]
	v_mfma_f32_16x16x32_bf16 v[122:125], v[142:145], v[180:183], 0
	v_mfma_f32_16x16x32_bf16 v[122:125], v[146:149], v[184:187], v[122:125]
	v_mfma_f32_16x16x32_bf16 v[106:109], v[142:145], v[188:191], 0
	v_mfma_f32_16x16x32_bf16 v[106:109], v[146:149], v[192:195], v[106:109]
	v_mfma_f32_16x16x32_bf16 v[110:113], v[130:133], v[188:191], 0
	v_mfma_f32_16x16x32_bf16 v[110:113], v[138:141], v[192:195], v[110:113]
	v_mfma_f32_16x16x32_bf16 v[94:97], v[130:133], v[196:199], 0
	v_mfma_f32_16x16x32_bf16 v[94:97], v[138:141], v[200:203], v[94:97]
	v_mfma_f32_16x16x32_bf16 v[90:93], v[142:145], v[196:199], 0
	v_mfma_f32_16x16x32_bf16 v[90:93], v[146:149], v[200:203], v[90:93]
	v_mfma_f32_16x16x32_bf16 v[74:77], v[142:145], v[204:207], 0
	v_mfma_f32_16x16x32_bf16 v[74:77], v[146:149], v[208:211], v[74:77]
	v_mfma_f32_16x16x32_bf16 v[78:81], v[130:133], v[204:207], 0
	v_mfma_f32_16x16x32_bf16 v[78:81], v[138:141], v[208:211], v[78:81]
	s_setprio 0
	s_setprio 1
	v_mfma_f32_16x16x32_bf16 v[118:121], v[150:153], v[180:183], 0
	v_mfma_f32_16x16x32_bf16 v[118:121], v[168:171], v[184:187], v[118:121]
	v_mfma_f32_16x16x32_bf16 v[114:117], v[172:175], v[180:183], 0
	v_mfma_f32_16x16x32_bf16 v[114:117], v[176:179], v[184:187], v[114:117]
	v_mfma_f32_16x16x32_bf16 v[98:101], v[172:175], v[188:191], 0
	v_mfma_f32_16x16x32_bf16 v[98:101], v[176:179], v[192:195], v[98:101]
	v_mfma_f32_16x16x32_bf16 v[102:105], v[150:153], v[188:191], 0
	v_mfma_f32_16x16x32_bf16 v[102:105], v[168:171], v[192:195], v[102:105]
	v_mfma_f32_16x16x32_bf16 v[86:89], v[150:153], v[196:199], 0
	v_mfma_f32_16x16x32_bf16 v[86:89], v[168:171], v[200:203], v[86:89]
	v_mfma_f32_16x16x32_bf16 v[82:85], v[172:175], v[196:199], 0
	v_mfma_f32_16x16x32_bf16 v[82:85], v[176:179], v[200:203], v[82:85]
	v_mfma_f32_16x16x32_bf16 v[66:69], v[172:175], v[204:207], 0
	v_mfma_f32_16x16x32_bf16 v[66:69], v[176:179], v[208:211], v[66:69]
	s_setprio 2
	s_barrier
	v_mfma_f32_16x16x32_bf16 v[70:73], v[150:153], v[204:207], 0
	v_mfma_f32_16x16x32_bf16 v[70:73], v[168:171], v[208:211], v[70:73]
	s_setprio 0
	ds_read_b128 v[180:183], v163 offset:16384
	ds_read_b128 v[184:187], v163 offset:17408
	ds_read_b128 v[188:191], v163 offset:18432
	ds_read_b128 v[192:195], v163 offset:19456
	ds_read_b128 v[196:199], v163 offset:20480
	ds_read_b128 v[200:203], v163 offset:21504
	ds_read_b128 v[204:207], v163 offset:22528
	ds_read_b128 v[208:211], v163 offset:23552
	s_mov_b32 s75, m0
	s_mov_b32 m0, s43
	s_nop 0
	global_load_lds_dwordx4 v156, s[10:11]
	s_mov_b32 m0, s75
	s_add_u32 s76, s10, 0x80000
	s_mov_b32 s75, m0
	s_mov_b32 m0, s46
	s_nop 0
	global_load_lds_dwordx4 v158, s[10:11]
	s_mov_b32 m0, s75
	s_addc_u32 s77, s11, 0
	s_mov_b32 s75, m0
	s_mov_b32 m0, s47
	s_nop 0
	global_load_lds_dwordx4 v156, s[76:77]
	s_mov_b32 m0, s75
	s_nop 0
	s_mov_b32 s75, m0
	s_mov_b32 m0, s48
	s_nop 0
	global_load_lds_dwordx4 v158, s[76:77]
	s_mov_b32 m0, s75
	s_waitcnt vmcnt(4)
	s_waitcnt lgkmcnt(0)
	s_barrier
	s_setprio 1
	.p2align 3
	v_mfma_f32_16x16x32_bf16 v[62:65], v[130:133], v[180:183], 0
	v_mfma_f32_16x16x32_bf16 v[62:65], v[138:141], v[184:187], v[62:65]
	v_mfma_f32_16x16x32_bf16 v[58:61], v[142:145], v[180:183], 0
	v_mfma_f32_16x16x32_bf16 v[58:61], v[146:149], v[184:187], v[58:61]
	v_mfma_f32_16x16x32_bf16 v[42:45], v[142:145], v[188:191], 0
	v_mfma_f32_16x16x32_bf16 v[42:45], v[146:149], v[192:195], v[42:45]
	v_mfma_f32_16x16x32_bf16 v[46:49], v[130:133], v[188:191], 0
	v_mfma_f32_16x16x32_bf16 v[46:49], v[138:141], v[192:195], v[46:49]
	v_mfma_f32_16x16x32_bf16 v[30:33], v[130:133], v[196:199], 0
	v_mfma_f32_16x16x32_bf16 v[30:33], v[138:141], v[200:203], v[30:33]
	v_mfma_f32_16x16x32_bf16 v[26:29], v[142:145], v[196:199], 0
	v_mfma_f32_16x16x32_bf16 v[26:29], v[146:149], v[200:203], v[26:29]
	v_mfma_f32_16x16x32_bf16 v[10:13], v[142:145], v[204:207], 0
	v_mfma_f32_16x16x32_bf16 v[10:13], v[146:149], v[208:211], v[10:13]
	v_mfma_f32_16x16x32_bf16 v[14:17], v[130:133], v[204:207], 0
	v_mfma_f32_16x16x32_bf16 v[14:17], v[138:141], v[208:211], v[14:17]
	s_setprio 0
	s_setprio 1
	v_mfma_f32_16x16x32_bf16 v[54:57], v[150:153], v[180:183], 0
	v_mfma_f32_16x16x32_bf16 v[54:57], v[168:171], v[184:187], v[54:57]
	v_mfma_f32_16x16x32_bf16 v[50:53], v[172:175], v[180:183], 0
	v_mfma_f32_16x16x32_bf16 v[50:53], v[176:179], v[184:187], v[50:53]
	v_mfma_f32_16x16x32_bf16 v[34:37], v[172:175], v[188:191], 0
	v_mfma_f32_16x16x32_bf16 v[34:37], v[176:179], v[192:195], v[34:37]
	v_mfma_f32_16x16x32_bf16 v[38:41], v[150:153], v[188:191], 0
	v_mfma_f32_16x16x32_bf16 v[38:41], v[168:171], v[192:195], v[38:41]
	v_mfma_f32_16x16x32_bf16 v[22:25], v[150:153], v[196:199], 0
	v_mfma_f32_16x16x32_bf16 v[22:25], v[168:171], v[200:203], v[22:25]
	v_mfma_f32_16x16x32_bf16 v[18:21], v[172:175], v[196:199], 0
	v_mfma_f32_16x16x32_bf16 v[18:21], v[176:179], v[200:203], v[18:21]
	v_mfma_f32_16x16x32_bf16 v[2:5], v[172:175], v[204:207], 0
	v_mfma_f32_16x16x32_bf16 v[2:5], v[176:179], v[208:211], v[2:5]
	s_setprio 2
	s_barrier
	v_mfma_f32_16x16x32_bf16 v[6:9], v[150:153], v[204:207], 0
	v_mfma_f32_16x16x32_bf16 v[6:9], v[168:171], v[208:211], v[6:9]
	s_setprio 0
	ds_read_b128 v[130:133], v164
	ds_read_b128 v[138:141], v164 offset:1024
	ds_read_b128 v[142:145], v164 offset:2048
	ds_read_b128 v[146:149], v164 offset:3072
	ds_read_b128 v[150:153], v165
	ds_read_b128 v[168:171], v165 offset:1024
	ds_read_b128 v[172:175], v165 offset:2048
	ds_read_b128 v[176:179], v165 offset:3072
	ds_read_b128 v[180:183], v163 offset:32768
	ds_read_b128 v[184:187], v163 offset:33792
	ds_read_b128 v[188:191], v163 offset:34816
	ds_read_b128 v[192:195], v163 offset:35840
	ds_read_b128 v[196:199], v163 offset:36864
	ds_read_b128 v[200:203], v163 offset:37888
	ds_read_b128 v[204:207], v163 offset:38912
	ds_read_b128 v[208:211], v163 offset:39936
	s_mov_b32 s75, m0
	s_mov_b32 m0, s42
	s_nop 0
	global_load_lds_dwordx4 v1, s[28:29]
	s_mov_b32 m0, s75
	s_nop 0
	s_mov_b32 s75, m0
	s_mov_b32 m0, s49
	s_nop 0
	global_load_lds_dwordx4 v157, s[28:29]
	s_mov_b32 m0, s75
	s_add_u32 s28, s28, 0x80000
	s_addc_u32 s29, s29, 0
	s_mov_b32 s75, m0
	s_mov_b32 m0, s56
	s_nop 0
	global_load_lds_dwordx4 v1, s[28:29]
	s_mov_b32 m0, s75
	s_nop 0
	s_mov_b32 s75, m0
	s_mov_b32 m0, s57
	s_nop 0
	global_load_lds_dwordx4 v157, s[28:29]
	s_mov_b32 m0, s75
	s_waitcnt vmcnt(8)
	s_waitcnt lgkmcnt(0)
	s_barrier
	s_setprio 1
	.p2align 3
	v_mfma_f32_16x16x32_bf16 v[126:129], v[130:133], v[180:183], v[126:129]
	v_mfma_f32_16x16x32_bf16 v[126:129], v[138:141], v[184:187], v[126:129]
	v_mfma_f32_16x16x32_bf16 v[122:125], v[142:145], v[180:183], v[122:125]
	v_mfma_f32_16x16x32_bf16 v[122:125], v[146:149], v[184:187], v[122:125]
	v_mfma_f32_16x16x32_bf16 v[106:109], v[142:145], v[188:191], v[106:109]
	v_mfma_f32_16x16x32_bf16 v[106:109], v[146:149], v[192:195], v[106:109]
	v_mfma_f32_16x16x32_bf16 v[110:113], v[130:133], v[188:191], v[110:113]
	v_mfma_f32_16x16x32_bf16 v[110:113], v[138:141], v[192:195], v[110:113]
	v_mfma_f32_16x16x32_bf16 v[94:97], v[130:133], v[196:199], v[94:97]
	v_mfma_f32_16x16x32_bf16 v[94:97], v[138:141], v[200:203], v[94:97]
	v_mfma_f32_16x16x32_bf16 v[90:93], v[142:145], v[196:199], v[90:93]
	v_mfma_f32_16x16x32_bf16 v[90:93], v[146:149], v[200:203], v[90:93]
	v_mfma_f32_16x16x32_bf16 v[74:77], v[142:145], v[204:207], v[74:77]
	v_mfma_f32_16x16x32_bf16 v[74:77], v[146:149], v[208:211], v[74:77]
	v_mfma_f32_16x16x32_bf16 v[78:81], v[130:133], v[204:207], v[78:81]
	v_mfma_f32_16x16x32_bf16 v[78:81], v[138:141], v[208:211], v[78:81]
	s_setprio 0
	s_setprio 1
	v_mfma_f32_16x16x32_bf16 v[118:121], v[150:153], v[180:183], v[118:121]
	v_mfma_f32_16x16x32_bf16 v[118:121], v[168:171], v[184:187], v[118:121]
	v_mfma_f32_16x16x32_bf16 v[114:117], v[172:175], v[180:183], v[114:117]
	v_mfma_f32_16x16x32_bf16 v[114:117], v[176:179], v[184:187], v[114:117]
	v_mfma_f32_16x16x32_bf16 v[98:101], v[172:175], v[188:191], v[98:101]
	v_mfma_f32_16x16x32_bf16 v[98:101], v[176:179], v[192:195], v[98:101]
	v_mfma_f32_16x16x32_bf16 v[102:105], v[150:153], v[188:191], v[102:105]
	v_mfma_f32_16x16x32_bf16 v[102:105], v[168:171], v[192:195], v[102:105]
	v_mfma_f32_16x16x32_bf16 v[86:89], v[150:153], v[196:199], v[86:89]
	v_mfma_f32_16x16x32_bf16 v[86:89], v[168:171], v[200:203], v[86:89]
	v_mfma_f32_16x16x32_bf16 v[82:85], v[172:175], v[196:199], v[82:85]
	v_mfma_f32_16x16x32_bf16 v[82:85], v[176:179], v[200:203], v[82:85]
	v_mfma_f32_16x16x32_bf16 v[66:69], v[172:175], v[204:207], v[66:69]
	v_mfma_f32_16x16x32_bf16 v[66:69], v[176:179], v[208:211], v[66:69]
	s_setprio 2
	s_barrier
	v_mfma_f32_16x16x32_bf16 v[70:73], v[150:153], v[204:207], v[70:73]
	v_mfma_f32_16x16x32_bf16 v[70:73], v[168:171], v[208:211], v[70:73]
	s_setprio 0
	ds_read_b128 v[180:183], v163 offset:49152
	ds_read_b128 v[184:187], v163 offset:50176
	ds_read_b128 v[188:191], v163 offset:51200
	ds_read_b128 v[192:195], v163 offset:52224
	ds_read_b128 v[196:199], v163 offset:53248
	ds_read_b128 v[200:203], v163 offset:54272
	ds_read_b128 v[204:207], v163 offset:55296
	ds_read_b128 v[208:211], v163 offset:56320
	s_add_u32 s28, s10, 0x80
	s_addc_u32 s29, s11, 0
	s_mov_b32 s75, m0
	s_mov_b32 m0, s64
	s_nop 0
	global_load_lds_dwordx4 v156, s[28:29]
	s_mov_b32 m0, s75
	s_add_u32 s10, s10, 0x80080
	s_mov_b32 s75, m0
	s_mov_b32 m0, s65
	s_nop 0
	global_load_lds_dwordx4 v158, s[28:29]
	s_mov_b32 m0, s75
	s_addc_u32 s11, s11, 0
	s_mov_b32 s28, m0
	s_mov_b32 m0, s66
	s_nop 0
	global_load_lds_dwordx4 v156, s[10:11]
	s_mov_b32 m0, s28
	s_nop 0
	s_mov_b32 s28, m0
	s_mov_b32 m0, s67
	s_nop 0
	global_load_lds_dwordx4 v158, s[10:11]
	s_mov_b32 m0, s28
	s_waitcnt vmcnt(4)
	s_waitcnt lgkmcnt(0)
	s_barrier
	s_setprio 1
	.p2align 3
	v_mfma_f32_16x16x32_bf16 v[62:65], v[130:133], v[180:183], v[62:65]
	v_mfma_f32_16x16x32_bf16 v[62:65], v[138:141], v[184:187], v[62:65]
	v_mfma_f32_16x16x32_bf16 v[58:61], v[142:145], v[180:183], v[58:61]
	v_mfma_f32_16x16x32_bf16 v[58:61], v[146:149], v[184:187], v[58:61]
	v_mfma_f32_16x16x32_bf16 v[42:45], v[142:145], v[188:191], v[42:45]
	v_mfma_f32_16x16x32_bf16 v[42:45], v[146:149], v[192:195], v[42:45]
	v_mfma_f32_16x16x32_bf16 v[46:49], v[130:133], v[188:191], v[46:49]
	v_mfma_f32_16x16x32_bf16 v[46:49], v[138:141], v[192:195], v[46:49]
	v_mfma_f32_16x16x32_bf16 v[30:33], v[130:133], v[196:199], v[30:33]
	v_mfma_f32_16x16x32_bf16 v[30:33], v[138:141], v[200:203], v[30:33]
	v_mfma_f32_16x16x32_bf16 v[26:29], v[142:145], v[196:199], v[26:29]
	v_mfma_f32_16x16x32_bf16 v[26:29], v[146:149], v[200:203], v[26:29]
	v_mfma_f32_16x16x32_bf16 v[10:13], v[142:145], v[204:207], v[10:13]
	v_mfma_f32_16x16x32_bf16 v[10:13], v[146:149], v[208:211], v[10:13]
	v_mfma_f32_16x16x32_bf16 v[14:17], v[130:133], v[204:207], v[14:17]
	v_mfma_f32_16x16x32_bf16 v[14:17], v[138:141], v[208:211], v[14:17]
	s_setprio 0
	s_setprio 1
	v_mfma_f32_16x16x32_bf16 v[54:57], v[150:153], v[180:183], v[54:57]
	v_mfma_f32_16x16x32_bf16 v[54:57], v[168:171], v[184:187], v[54:57]
	v_mfma_f32_16x16x32_bf16 v[50:53], v[172:175], v[180:183], v[50:53]
	v_mfma_f32_16x16x32_bf16 v[50:53], v[176:179], v[184:187], v[50:53]
	v_mfma_f32_16x16x32_bf16 v[34:37], v[172:175], v[188:191], v[34:37]
	v_mfma_f32_16x16x32_bf16 v[34:37], v[176:179], v[192:195], v[34:37]
	v_mfma_f32_16x16x32_bf16 v[38:41], v[150:153], v[188:191], v[38:41]
	v_mfma_f32_16x16x32_bf16 v[38:41], v[168:171], v[192:195], v[38:41]
	v_mfma_f32_16x16x32_bf16 v[22:25], v[150:153], v[196:199], v[22:25]
	v_mfma_f32_16x16x32_bf16 v[22:25], v[168:171], v[200:203], v[22:25]
	v_mfma_f32_16x16x32_bf16 v[18:21], v[172:175], v[196:199], v[18:21]
	v_mfma_f32_16x16x32_bf16 v[18:21], v[176:179], v[200:203], v[18:21]
	v_mfma_f32_16x16x32_bf16 v[2:5], v[172:175], v[204:207], v[2:5]
	v_mfma_f32_16x16x32_bf16 v[2:5], v[176:179], v[208:211], v[2:5]
	s_setprio 2
	s_barrier
	v_mfma_f32_16x16x32_bf16 v[6:9], v[150:153], v[204:207], v[6:9]
	v_mfma_f32_16x16x32_bf16 v[6:9], v[168:171], v[208:211], v[6:9]
	s_setprio 0
	s_add_i32 s74, s74, 2
	s_add_u32 s30, s30, 0x100
	s_addc_u32 s31, s31, 0
	s_add_u32 s4, s4, 0x100
	s_addc_u32 s5, s5, 0
	s_add_u32 s33, s33, 0x100
	s_addc_u32 s73, s73, 0
	s_cmp_gt_u32 s74, 29
	.p2align 6
.LBB0_654:
	ds_read_b128 v[130:133], v161
	ds_read_b128 v[138:141], v161 offset:1024
	ds_read_b128 v[142:145], v161 offset:2048
	ds_read_b128 v[146:149], v161 offset:3072
	ds_read_b128 v[150:153], v162
	ds_read_b128 v[168:171], v162 offset:1024
	ds_read_b128 v[172:175], v162 offset:2048
	ds_read_b128 v[176:179], v162 offset:3072
	s_cmp_eq_u32 s74, 28
	s_cselect_b32 s11, s21, s31
	s_cselect_b32 s10, s23, s30
	s_cselect_b32 s29, s7, s73
	s_cselect_b32 s28, s9, s33
	ds_read_b128 v[180:183], v163
	ds_read_b128 v[184:187], v163 offset:1024
	ds_read_b128 v[188:191], v163 offset:2048
	ds_read_b128 v[192:195], v163 offset:3072
	ds_read_b128 v[196:199], v163 offset:4096
	ds_read_b128 v[200:203], v163 offset:5120
	ds_read_b128 v[204:207], v163 offset:6144
	ds_read_b128 v[208:211], v163 offset:7168
	s_add_u32 s76, s4, 0xfff80000
	s_addc_u32 s77, s5, -1
	s_mov_b32 s75, m0
	s_mov_b32 m0, s80
	s_nop 0
	global_load_lds_dwordx4 v1, s[76:77]
	s_mov_b32 m0, s75
	s_nop 0
	s_mov_b32 s75, m0
	s_mov_b32 m0, s82
	s_nop 0
	global_load_lds_dwordx4 v157, s[76:77]
	s_mov_b32 m0, s75
	s_nop 0
	s_mov_b32 s75, m0
	s_mov_b32 m0, s81
	s_nop 0
	global_load_lds_dwordx4 v1, s[4:5]
	s_mov_b32 m0, s75
	s_nop 0
	s_mov_b32 s75, m0
	s_mov_b32 m0, s83
	s_nop 0
	global_load_lds_dwordx4 v157, s[4:5]
	s_mov_b32 m0, s75
	s_waitcnt vmcnt(8)
	s_waitcnt lgkmcnt(0)
	s_barrier
	s_setprio 1
	.p2align 3
	v_mfma_f32_16x16x32_bf16 v[126:129], v[130:133], v[180:183], v[126:129]
	v_mfma_f32_16x16x32_bf16 v[126:129], v[138:141], v[184:187], v[126:129]
	v_mfma_f32_16x16x32_bf16 v[122:125], v[142:145], v[180:183], v[122:125]
	v_mfma_f32_16x16x32_bf16 v[122:125], v[146:149], v[184:187], v[122:125]
	v_mfma_f32_16x16x32_bf16 v[106:109], v[142:145], v[188:191], v[106:109]
	v_mfma_f32_16x16x32_bf16 v[106:109], v[146:149], v[192:195], v[106:109]
	v_mfma_f32_16x16x32_bf16 v[110:113], v[130:133], v[188:191], v[110:113]
	v_mfma_f32_16x16x32_bf16 v[110:113], v[138:141], v[192:195], v[110:113]
	v_mfma_f32_16x16x32_bf16 v[94:97], v[130:133], v[196:199], v[94:97]
	v_mfma_f32_16x16x32_bf16 v[94:97], v[138:141], v[200:203], v[94:97]
	v_mfma_f32_16x16x32_bf16 v[90:93], v[142:145], v[196:199], v[90:93]
	v_mfma_f32_16x16x32_bf16 v[90:93], v[146:149], v[200:203], v[90:93]
	v_mfma_f32_16x16x32_bf16 v[74:77], v[142:145], v[204:207], v[74:77]
	v_mfma_f32_16x16x32_bf16 v[74:77], v[146:149], v[208:211], v[74:77]
	v_mfma_f32_16x16x32_bf16 v[78:81], v[130:133], v[204:207], v[78:81]
	v_mfma_f32_16x16x32_bf16 v[78:81], v[138:141], v[208:211], v[78:81]
	s_setprio 0
	s_setprio 1
	v_mfma_f32_16x16x32_bf16 v[118:121], v[150:153], v[180:183], v[118:121]
	v_mfma_f32_16x16x32_bf16 v[118:121], v[168:171], v[184:187], v[118:121]
	v_mfma_f32_16x16x32_bf16 v[114:117], v[172:175], v[180:183], v[114:117]
	v_mfma_f32_16x16x32_bf16 v[114:117], v[176:179], v[184:187], v[114:117]
	v_mfma_f32_16x16x32_bf16 v[98:101], v[172:175], v[188:191], v[98:101]
	v_mfma_f32_16x16x32_bf16 v[98:101], v[176:179], v[192:195], v[98:101]
	v_mfma_f32_16x16x32_bf16 v[102:105], v[150:153], v[188:191], v[102:105]
	v_mfma_f32_16x16x32_bf16 v[102:105], v[168:171], v[192:195], v[102:105]
	v_mfma_f32_16x16x32_bf16 v[86:89], v[150:153], v[196:199], v[86:89]
	v_mfma_f32_16x16x32_bf16 v[86:89], v[168:171], v[200:203], v[86:89]
	v_mfma_f32_16x16x32_bf16 v[82:85], v[172:175], v[196:199], v[82:85]
	v_mfma_f32_16x16x32_bf16 v[82:85], v[176:179], v[200:203], v[82:85]
	v_mfma_f32_16x16x32_bf16 v[66:69], v[172:175], v[204:207], v[66:69]
	v_mfma_f32_16x16x32_bf16 v[66:69], v[176:179], v[208:211], v[66:69]
	s_setprio 2
	s_barrier
	v_mfma_f32_16x16x32_bf16 v[70:73], v[150:153], v[204:207], v[70:73]
	v_mfma_f32_16x16x32_bf16 v[70:73], v[168:171], v[208:211], v[70:73]
	s_setprio 0
	ds_read_b128 v[180:183], v163 offset:16384
	ds_read_b128 v[184:187], v163 offset:17408
	ds_read_b128 v[188:191], v163 offset:18432
	ds_read_b128 v[192:195], v163 offset:19456
	ds_read_b128 v[196:199], v163 offset:20480
	ds_read_b128 v[200:203], v163 offset:21504
	ds_read_b128 v[204:207], v163 offset:22528
	ds_read_b128 v[208:211], v163 offset:23552
	s_mov_b32 s75, m0
	s_mov_b32 m0, s43
	s_nop 0
	global_load_lds_dwordx4 v156, s[10:11]
	s_mov_b32 m0, s75
	s_add_u32 s76, s10, 0x80000
	s_mov_b32 s75, m0
	s_mov_b32 m0, s46
	s_nop 0
	global_load_lds_dwordx4 v158, s[10:11]
	s_mov_b32 m0, s75
	s_addc_u32 s77, s11, 0
	s_mov_b32 s75, m0
	s_mov_b32 m0, s47
	s_nop 0
	global_load_lds_dwordx4 v156, s[76:77]
	s_mov_b32 m0, s75
	s_nop 0
	s_mov_b32 s75, m0
	s_mov_b32 m0, s48
	s_nop 0
	global_load_lds_dwordx4 v158, s[76:77]
	s_mov_b32 m0, s75
	s_waitcnt vmcnt(4)
	s_waitcnt lgkmcnt(0)
	s_barrier
	s_setprio 1
	.p2align 3
	v_mfma_f32_16x16x32_bf16 v[62:65], v[130:133], v[180:183], v[62:65]
	v_mfma_f32_16x16x32_bf16 v[62:65], v[138:141], v[184:187], v[62:65]
	v_mfma_f32_16x16x32_bf16 v[58:61], v[142:145], v[180:183], v[58:61]
	v_mfma_f32_16x16x32_bf16 v[58:61], v[146:149], v[184:187], v[58:61]
	v_mfma_f32_16x16x32_bf16 v[42:45], v[142:145], v[188:191], v[42:45]
	v_mfma_f32_16x16x32_bf16 v[42:45], v[146:149], v[192:195], v[42:45]
	v_mfma_f32_16x16x32_bf16 v[46:49], v[130:133], v[188:191], v[46:49]
	v_mfma_f32_16x16x32_bf16 v[46:49], v[138:141], v[192:195], v[46:49]
	v_mfma_f32_16x16x32_bf16 v[30:33], v[130:133], v[196:199], v[30:33]
	v_mfma_f32_16x16x32_bf16 v[30:33], v[138:141], v[200:203], v[30:33]
	v_mfma_f32_16x16x32_bf16 v[26:29], v[142:145], v[196:199], v[26:29]
	v_mfma_f32_16x16x32_bf16 v[26:29], v[146:149], v[200:203], v[26:29]
	v_mfma_f32_16x16x32_bf16 v[10:13], v[142:145], v[204:207], v[10:13]
	v_mfma_f32_16x16x32_bf16 v[10:13], v[146:149], v[208:211], v[10:13]
	v_mfma_f32_16x16x32_bf16 v[14:17], v[130:133], v[204:207], v[14:17]
	v_mfma_f32_16x16x32_bf16 v[14:17], v[138:141], v[208:211], v[14:17]
	s_setprio 0
	s_setprio 1
	v_mfma_f32_16x16x32_bf16 v[54:57], v[150:153], v[180:183], v[54:57]
	v_mfma_f32_16x16x32_bf16 v[54:57], v[168:171], v[184:187], v[54:57]
	v_mfma_f32_16x16x32_bf16 v[50:53], v[172:175], v[180:183], v[50:53]
	v_mfma_f32_16x16x32_bf16 v[50:53], v[176:179], v[184:187], v[50:53]
	v_mfma_f32_16x16x32_bf16 v[34:37], v[172:175], v[188:191], v[34:37]
	v_mfma_f32_16x16x32_bf16 v[34:37], v[176:179], v[192:195], v[34:37]
	v_mfma_f32_16x16x32_bf16 v[38:41], v[150:153], v[188:191], v[38:41]
	v_mfma_f32_16x16x32_bf16 v[38:41], v[168:171], v[192:195], v[38:41]
	v_mfma_f32_16x16x32_bf16 v[22:25], v[150:153], v[196:199], v[22:25]
	v_mfma_f32_16x16x32_bf16 v[22:25], v[168:171], v[200:203], v[22:25]
	v_mfma_f32_16x16x32_bf16 v[18:21], v[172:175], v[196:199], v[18:21]
	v_mfma_f32_16x16x32_bf16 v[18:21], v[176:179], v[200:203], v[18:21]
	v_mfma_f32_16x16x32_bf16 v[2:5], v[172:175], v[204:207], v[2:5]
	v_mfma_f32_16x16x32_bf16 v[2:5], v[176:179], v[208:211], v[2:5]
	s_setprio 2
	s_barrier
	v_mfma_f32_16x16x32_bf16 v[6:9], v[150:153], v[204:207], v[6:9]
	v_mfma_f32_16x16x32_bf16 v[6:9], v[168:171], v[208:211], v[6:9]
	s_setprio 0
	ds_read_b128 v[130:133], v164
	ds_read_b128 v[138:141], v164 offset:1024
	ds_read_b128 v[142:145], v164 offset:2048
	ds_read_b128 v[146:149], v164 offset:3072
	ds_read_b128 v[150:153], v165
	ds_read_b128 v[168:171], v165 offset:1024
	ds_read_b128 v[172:175], v165 offset:2048
	ds_read_b128 v[176:179], v165 offset:3072
	ds_read_b128 v[180:183], v163 offset:32768
	ds_read_b128 v[184:187], v163 offset:33792
	ds_read_b128 v[188:191], v163 offset:34816
	ds_read_b128 v[192:195], v163 offset:35840
	ds_read_b128 v[196:199], v163 offset:36864
	ds_read_b128 v[200:203], v163 offset:37888
	ds_read_b128 v[204:207], v163 offset:38912
	ds_read_b128 v[208:211], v163 offset:39936
	s_mov_b32 s75, m0
	s_mov_b32 m0, s42
	s_nop 0
	global_load_lds_dwordx4 v1, s[28:29]
	s_mov_b32 m0, s75
	s_nop 0
	s_mov_b32 s75, m0
	s_mov_b32 m0, s49
	s_nop 0
	global_load_lds_dwordx4 v157, s[28:29]
	s_mov_b32 m0, s75
	s_add_u32 s28, s28, 0x80000
	s_addc_u32 s29, s29, 0
	s_mov_b32 s75, m0
	s_mov_b32 m0, s56
	s_nop 0
	global_load_lds_dwordx4 v1, s[28:29]
	s_mov_b32 m0, s75
	s_nop 0
	s_mov_b32 s75, m0
	s_mov_b32 m0, s57
	s_nop 0
	global_load_lds_dwordx4 v157, s[28:29]
	s_mov_b32 m0, s75
	s_waitcnt vmcnt(8)
	s_waitcnt lgkmcnt(0)
	s_barrier
	s_setprio 1
	.p2align 3
	v_mfma_f32_16x16x32_bf16 v[126:129], v[130:133], v[180:183], v[126:129]
	v_mfma_f32_16x16x32_bf16 v[126:129], v[138:141], v[184:187], v[126:129]
	v_mfma_f32_16x16x32_bf16 v[122:125], v[142:145], v[180:183], v[122:125]
	v_mfma_f32_16x16x32_bf16 v[122:125], v[146:149], v[184:187], v[122:125]
	v_mfma_f32_16x16x32_bf16 v[106:109], v[142:145], v[188:191], v[106:109]
	v_mfma_f32_16x16x32_bf16 v[106:109], v[146:149], v[192:195], v[106:109]
	v_mfma_f32_16x16x32_bf16 v[110:113], v[130:133], v[188:191], v[110:113]
	v_mfma_f32_16x16x32_bf16 v[110:113], v[138:141], v[192:195], v[110:113]
	v_mfma_f32_16x16x32_bf16 v[94:97], v[130:133], v[196:199], v[94:97]
	v_mfma_f32_16x16x32_bf16 v[94:97], v[138:141], v[200:203], v[94:97]
	v_mfma_f32_16x16x32_bf16 v[90:93], v[142:145], v[196:199], v[90:93]
	v_mfma_f32_16x16x32_bf16 v[90:93], v[146:149], v[200:203], v[90:93]
	v_mfma_f32_16x16x32_bf16 v[74:77], v[142:145], v[204:207], v[74:77]
	v_mfma_f32_16x16x32_bf16 v[74:77], v[146:149], v[208:211], v[74:77]
	v_mfma_f32_16x16x32_bf16 v[78:81], v[130:133], v[204:207], v[78:81]
	v_mfma_f32_16x16x32_bf16 v[78:81], v[138:141], v[208:211], v[78:81]
	s_setprio 0
	s_setprio 1
	v_mfma_f32_16x16x32_bf16 v[118:121], v[150:153], v[180:183], v[118:121]
	v_mfma_f32_16x16x32_bf16 v[118:121], v[168:171], v[184:187], v[118:121]
	v_mfma_f32_16x16x32_bf16 v[114:117], v[172:175], v[180:183], v[114:117]
	v_mfma_f32_16x16x32_bf16 v[114:117], v[176:179], v[184:187], v[114:117]
	v_mfma_f32_16x16x32_bf16 v[98:101], v[172:175], v[188:191], v[98:101]
	v_mfma_f32_16x16x32_bf16 v[98:101], v[176:179], v[192:195], v[98:101]
	v_mfma_f32_16x16x32_bf16 v[102:105], v[150:153], v[188:191], v[102:105]
	v_mfma_f32_16x16x32_bf16 v[102:105], v[168:171], v[192:195], v[102:105]
	v_mfma_f32_16x16x32_bf16 v[86:89], v[150:153], v[196:199], v[86:89]
	v_mfma_f32_16x16x32_bf16 v[86:89], v[168:171], v[200:203], v[86:89]
	v_mfma_f32_16x16x32_bf16 v[82:85], v[172:175], v[196:199], v[82:85]
	v_mfma_f32_16x16x32_bf16 v[82:85], v[176:179], v[200:203], v[82:85]
	v_mfma_f32_16x16x32_bf16 v[66:69], v[172:175], v[204:207], v[66:69]
	v_mfma_f32_16x16x32_bf16 v[66:69], v[176:179], v[208:211], v[66:69]
	s_setprio 2
	s_barrier
	v_mfma_f32_16x16x32_bf16 v[70:73], v[150:153], v[204:207], v[70:73]
	v_mfma_f32_16x16x32_bf16 v[70:73], v[168:171], v[208:211], v[70:73]
	s_setprio 0
	ds_read_b128 v[180:183], v163 offset:49152
	ds_read_b128 v[184:187], v163 offset:50176
	ds_read_b128 v[188:191], v163 offset:51200
	ds_read_b128 v[192:195], v163 offset:52224
	ds_read_b128 v[196:199], v163 offset:53248
	ds_read_b128 v[200:203], v163 offset:54272
	ds_read_b128 v[204:207], v163 offset:55296
	ds_read_b128 v[208:211], v163 offset:56320
	s_add_u32 s28, s10, 0x80
	s_addc_u32 s29, s11, 0
	s_mov_b32 s75, m0
	s_mov_b32 m0, s64
	s_nop 0
	global_load_lds_dwordx4 v156, s[28:29]
	s_mov_b32 m0, s75
	s_add_u32 s10, s10, 0x80080
	s_mov_b32 s75, m0
	s_mov_b32 m0, s65
	s_nop 0
	global_load_lds_dwordx4 v158, s[28:29]
	s_mov_b32 m0, s75
	s_addc_u32 s11, s11, 0
	s_mov_b32 s28, m0
	s_mov_b32 m0, s66
	s_nop 0
	global_load_lds_dwordx4 v156, s[10:11]
	s_mov_b32 m0, s28
	s_nop 0
	s_mov_b32 s28, m0
	s_mov_b32 m0, s67
	s_nop 0
	global_load_lds_dwordx4 v158, s[10:11]
	s_mov_b32 m0, s28
	s_waitcnt vmcnt(4)
	s_waitcnt lgkmcnt(0)
	s_barrier
	s_setprio 1
	.p2align 3
	v_mfma_f32_16x16x32_bf16 v[62:65], v[130:133], v[180:183], v[62:65]
	v_mfma_f32_16x16x32_bf16 v[62:65], v[138:141], v[184:187], v[62:65]
	v_mfma_f32_16x16x32_bf16 v[58:61], v[142:145], v[180:183], v[58:61]
	v_mfma_f32_16x16x32_bf16 v[58:61], v[146:149], v[184:187], v[58:61]
	v_mfma_f32_16x16x32_bf16 v[42:45], v[142:145], v[188:191], v[42:45]
	v_mfma_f32_16x16x32_bf16 v[42:45], v[146:149], v[192:195], v[42:45]
	v_mfma_f32_16x16x32_bf16 v[46:49], v[130:133], v[188:191], v[46:49]
	v_mfma_f32_16x16x32_bf16 v[46:49], v[138:141], v[192:195], v[46:49]
	v_mfma_f32_16x16x32_bf16 v[30:33], v[130:133], v[196:199], v[30:33]
	v_mfma_f32_16x16x32_bf16 v[30:33], v[138:141], v[200:203], v[30:33]
	v_mfma_f32_16x16x32_bf16 v[26:29], v[142:145], v[196:199], v[26:29]
	v_mfma_f32_16x16x32_bf16 v[26:29], v[146:149], v[200:203], v[26:29]
	v_mfma_f32_16x16x32_bf16 v[10:13], v[142:145], v[204:207], v[10:13]
	v_mfma_f32_16x16x32_bf16 v[10:13], v[146:149], v[208:211], v[10:13]
	v_mfma_f32_16x16x32_bf16 v[14:17], v[130:133], v[204:207], v[14:17]
	v_mfma_f32_16x16x32_bf16 v[14:17], v[138:141], v[208:211], v[14:17]
	s_setprio 0
	s_setprio 1
	v_mfma_f32_16x16x32_bf16 v[54:57], v[150:153], v[180:183], v[54:57]
	v_mfma_f32_16x16x32_bf16 v[54:57], v[168:171], v[184:187], v[54:57]
	v_mfma_f32_16x16x32_bf16 v[50:53], v[172:175], v[180:183], v[50:53]
	v_mfma_f32_16x16x32_bf16 v[50:53], v[176:179], v[184:187], v[50:53]
	v_mfma_f32_16x16x32_bf16 v[34:37], v[172:175], v[188:191], v[34:37]
	v_mfma_f32_16x16x32_bf16 v[34:37], v[176:179], v[192:195], v[34:37]
	v_mfma_f32_16x16x32_bf16 v[38:41], v[150:153], v[188:191], v[38:41]
	v_mfma_f32_16x16x32_bf16 v[38:41], v[168:171], v[192:195], v[38:41]
	v_mfma_f32_16x16x32_bf16 v[22:25], v[150:153], v[196:199], v[22:25]
	v_mfma_f32_16x16x32_bf16 v[22:25], v[168:171], v[200:203], v[22:25]
	v_mfma_f32_16x16x32_bf16 v[18:21], v[172:175], v[196:199], v[18:21]
	v_mfma_f32_16x16x32_bf16 v[18:21], v[176:179], v[200:203], v[18:21]
	v_mfma_f32_16x16x32_bf16 v[2:5], v[172:175], v[204:207], v[2:5]
	v_mfma_f32_16x16x32_bf16 v[2:5], v[176:179], v[208:211], v[2:5]
	s_setprio 2
	s_barrier
	v_mfma_f32_16x16x32_bf16 v[6:9], v[150:153], v[204:207], v[6:9]
	v_mfma_f32_16x16x32_bf16 v[6:9], v[168:171], v[208:211], v[6:9]
	s_setprio 0
	s_add_i32 s74, s74, 2
	s_add_u32 s30, s30, 0x100
	s_addc_u32 s31, s31, 0
	s_add_u32 s4, s4, 0x100
	s_addc_u32 s5, s5, 0
	s_add_u32 s33, s33, 0x100
	s_addc_u32 s73, s73, 0
	s_cmp_gt_u32 s74, 29
	s_cbranch_scc0 .LBB0_654
	s_and_b64 vcc, exec, s[18:19]
	s_cbranch_vccz .LBB0_657
	s_barrier

.LBB0_1052:
	s_ashr_i32 s13, s12, 31
	s_lshl_b64 s[14:15], s[12:13], 20
	s_add_u32 s14, s28, s14
	s_addc_u32 s15, s29, s15
	s_and_b64 s[16:17], s[2:3], exec
	s_cselect_b32 s13, s15, s23
	s_cselect_b32 s67, s14, s22
	s_ashr_i32 s11, s10, 31
	s_lshl_b64 s[16:17], s[10:11], 20
	s_add_u32 s16, s30, s16
	s_addc_u32 s17, s31, s17
	s_and_b64 s[24:25], s[2:3], exec
	s_cselect_b32 s11, s17, s21
	s_cselect_b32 s73, s16, s20
	s_add_u32 s74, s20, 0x100
	s_addc_u32 s75, s21, 0
	s_add_u32 s20, s22, 0x80080
	s_addc_u32 s21, s23, 0
	s_add_u32 s76, s22, 0x100
	s_addc_u32 s77, s23, 0
	s_mov_b32 s78, -2
	s_waitcnt vmcnt(25)
	s_waitcnt vmcnt(24)
	s_waitcnt vmcnt(15)
	s_waitcnt vmcnt(14)
	s_waitcnt vmcnt(13)
	s_waitcnt vmcnt(12)
	s_waitcnt vmcnt(11)
	s_waitcnt vmcnt(10)
	s_waitcnt vmcnt(9)
	s_waitcnt vmcnt(8)
	s_waitcnt vmcnt(7)
	s_waitcnt vmcnt(6)
	s_waitcnt vmcnt(5)
	s_waitcnt vmcnt(4)
	s_waitcnt vmcnt(3)
	s_waitcnt vmcnt(2)
	s_waitcnt vmcnt(1)
	s_waitcnt vmcnt(0)
	ds_read_b128 v[130:133], v181
	ds_read_b128 v[134:137], v181 offset:1024
	ds_read_b128 v[138:141], v181 offset:2048
	ds_read_b128 v[142:145], v181 offset:3072
	ds_read_b128 v[146:149], v182
	ds_read_b128 v[150:153], v182 offset:1024
	ds_read_b128 v[154:157], v182 offset:2048
	ds_read_b128 v[158:161], v182 offset:3072
	s_cmp_eq_u32 s78, 28
	s_cselect_b32 s23, s11, s75
	s_cselect_b32 s22, s73, s74
	s_cselect_b32 s25, s13, s77
	s_cselect_b32 s24, s67, s76
	ds_read_b128 v[166:169], v183
	ds_read_b128 v[170:173], v183 offset:1024
	ds_read_b128 v[186:189], v183 offset:2048
	ds_read_b128 v[190:193], v183 offset:3072
	ds_read_b128 v[194:197], v183 offset:4096
	ds_read_b128 v[198:201], v183 offset:5120
	ds_read_b128 v[202:205], v183 offset:6144
	ds_read_b128 v[206:209], v183 offset:7168
	s_add_u32 s80, s20, 0xfff80000
	s_addc_u32 s81, s21, -1
	s_mov_b32 s79, m0
	s_mov_b32 m0, s58
	s_nop 0
	global_load_lds_dwordx4 v1, s[80:81]
	s_mov_b32 m0, s79
	s_nop 0
	s_mov_b32 s79, m0
	s_mov_b32 m0, s64
	s_nop 0
	global_load_lds_dwordx4 v177, s[80:81]
	s_mov_b32 m0, s79
	s_nop 0
	s_mov_b32 s79, m0
	s_mov_b32 m0, s59
	s_nop 0
	global_load_lds_dwordx4 v1, s[20:21]
	s_mov_b32 m0, s79
	s_nop 0
	s_mov_b32 s79, m0
	s_mov_b32 m0, s65
	s_nop 0
	global_load_lds_dwordx4 v177, s[20:21]
	s_mov_b32 m0, s79
	s_waitcnt vmcnt(8)
	s_waitcnt lgkmcnt(0)
	s_barrier
	s_setprio 1
	.p2align 3
	v_mfma_f32_16x16x32_bf16 v[126:129], v[130:133], v[166:169], 0
	v_mfma_f32_16x16x32_bf16 v[126:129], v[134:137], v[170:173], v[126:129]
	v_mfma_f32_16x16x32_bf16 v[122:125], v[138:141], v[166:169], 0
	v_mfma_f32_16x16x32_bf16 v[122:125], v[142:145], v[170:173], v[122:125]
	v_mfma_f32_16x16x32_bf16 v[114:117], v[138:141], v[186:189], 0
	v_mfma_f32_16x16x32_bf16 v[114:117], v[142:145], v[190:193], v[114:117]
	v_mfma_f32_16x16x32_bf16 v[118:121], v[130:133], v[186:189], 0
	v_mfma_f32_16x16x32_bf16 v[118:121], v[134:137], v[190:193], v[118:121]
	v_mfma_f32_16x16x32_bf16 v[94:97], v[130:133], v[194:197], 0
	v_mfma_f32_16x16x32_bf16 v[94:97], v[134:137], v[198:201], v[94:97]
	v_mfma_f32_16x16x32_bf16 v[90:93], v[138:141], v[194:197], 0
	v_mfma_f32_16x16x32_bf16 v[90:93], v[142:145], v[198:201], v[90:93]
	v_mfma_f32_16x16x32_bf16 v[78:81], v[138:141], v[202:205], 0
	v_mfma_f32_16x16x32_bf16 v[78:81], v[142:145], v[206:209], v[78:81]
	v_mfma_f32_16x16x32_bf16 v[86:89], v[130:133], v[202:205], 0
	v_mfma_f32_16x16x32_bf16 v[86:89], v[134:137], v[206:209], v[86:89]
	s_setprio 0
	s_setprio 1
	v_mfma_f32_16x16x32_bf16 v[110:113], v[146:149], v[166:169], 0
	v_mfma_f32_16x16x32_bf16 v[110:113], v[150:153], v[170:173], v[110:113]
	v_mfma_f32_16x16x32_bf16 v[106:109], v[154:157], v[166:169], 0
	v_mfma_f32_16x16x32_bf16 v[106:109], v[158:161], v[170:173], v[106:109]
	v_mfma_f32_16x16x32_bf16 v[98:101], v[154:157], v[186:189], 0
	v_mfma_f32_16x16x32_bf16 v[98:101], v[158:161], v[190:193], v[98:101]
	v_mfma_f32_16x16x32_bf16 v[102:105], v[146:149], v[186:189], 0
	v_mfma_f32_16x16x32_bf16 v[102:105], v[150:153], v[190:193], v[102:105]
	v_mfma_f32_16x16x32_bf16 v[82:85], v[146:149], v[194:197], 0
	v_mfma_f32_16x16x32_bf16 v[82:85], v[150:153], v[198:201], v[82:85]
	v_mfma_f32_16x16x32_bf16 v[74:77], v[154:157], v[194:197], 0
	v_mfma_f32_16x16x32_bf16 v[74:77], v[158:161], v[198:201], v[74:77]
	v_mfma_f32_16x16x32_bf16 v[66:69], v[154:157], v[202:205], 0
	v_mfma_f32_16x16x32_bf16 v[66:69], v[158:161], v[206:209], v[66:69]
	s_setprio 2
	s_barrier
	v_mfma_f32_16x16x32_bf16 v[70:73], v[146:149], v[202:205], 0
	v_mfma_f32_16x16x32_bf16 v[70:73], v[150:153], v[206:209], v[70:73]
	s_setprio 0
	ds_read_b128 v[166:169], v183 offset:16384
	ds_read_b128 v[170:173], v183 offset:17408
	ds_read_b128 v[186:189], v183 offset:18432
	ds_read_b128 v[190:193], v183 offset:19456
	ds_read_b128 v[194:197], v183 offset:20480
	ds_read_b128 v[198:201], v183 offset:21504
	ds_read_b128 v[202:205], v183 offset:22528
	ds_read_b128 v[206:209], v183 offset:23552
	s_mov_b32 s79, m0
	s_mov_b32 m0, s35
	s_nop 0
	global_load_lds_dwordx4 v176, s[22:23]
	s_mov_b32 m0, s79
	s_add_u32 s80, s22, 0x80000
	s_mov_b32 s79, m0
	s_mov_b32 m0, s36
	s_nop 0
	global_load_lds_dwordx4 v178, s[22:23]
	s_mov_b32 m0, s79
	s_addc_u32 s81, s23, 0
	s_mov_b32 s79, m0
	s_mov_b32 m0, s37
	s_nop 0
	global_load_lds_dwordx4 v176, s[80:81]
	s_mov_b32 m0, s79
	s_nop 0
	s_mov_b32 s79, m0
	s_mov_b32 m0, s40
	s_nop 0
	global_load_lds_dwordx4 v178, s[80:81]
	s_mov_b32 m0, s79
	s_waitcnt vmcnt(4)
	s_waitcnt lgkmcnt(0)
	s_barrier
	s_setprio 1
	.p2align 3
	v_mfma_f32_16x16x32_bf16 v[62:65], v[130:133], v[166:169], 0
	v_mfma_f32_16x16x32_bf16 v[62:65], v[134:137], v[170:173], v[62:65]
	v_mfma_f32_16x16x32_bf16 v[58:61], v[138:141], v[166:169], 0
	v_mfma_f32_16x16x32_bf16 v[58:61], v[142:145], v[170:173], v[58:61]
	v_mfma_f32_16x16x32_bf16 v[42:45], v[138:141], v[186:189], 0
	v_mfma_f32_16x16x32_bf16 v[42:45], v[142:145], v[190:193], v[42:45]
	v_mfma_f32_16x16x32_bf16 v[46:49], v[130:133], v[186:189], 0
	v_mfma_f32_16x16x32_bf16 v[46:49], v[134:137], v[190:193], v[46:49]
	v_mfma_f32_16x16x32_bf16 v[30:33], v[130:133], v[194:197], 0
	v_mfma_f32_16x16x32_bf16 v[30:33], v[134:137], v[198:201], v[30:33]
	v_mfma_f32_16x16x32_bf16 v[26:29], v[138:141], v[194:197], 0
	v_mfma_f32_16x16x32_bf16 v[26:29], v[142:145], v[198:201], v[26:29]
	v_mfma_f32_16x16x32_bf16 v[10:13], v[138:141], v[202:205], 0
	v_mfma_f32_16x16x32_bf16 v[10:13], v[142:145], v[206:209], v[10:13]
	v_mfma_f32_16x16x32_bf16 v[14:17], v[130:133], v[202:205], 0
	v_mfma_f32_16x16x32_bf16 v[14:17], v[134:137], v[206:209], v[14:17]
	s_setprio 0
	s_setprio 1
	v_mfma_f32_16x16x32_bf16 v[54:57], v[146:149], v[166:169], 0
	v_mfma_f32_16x16x32_bf16 v[54:57], v[150:153], v[170:173], v[54:57]
	v_mfma_f32_16x16x32_bf16 v[50:53], v[154:157], v[166:169], 0
	v_mfma_f32_16x16x32_bf16 v[50:53], v[158:161], v[170:173], v[50:53]
	v_mfma_f32_16x16x32_bf16 v[34:37], v[154:157], v[186:189], 0
	v_mfma_f32_16x16x32_bf16 v[34:37], v[158:161], v[190:193], v[34:37]
	v_mfma_f32_16x16x32_bf16 v[38:41], v[146:149], v[186:189], 0
	v_mfma_f32_16x16x32_bf16 v[38:41], v[150:153], v[190:193], v[38:41]
	v_mfma_f32_16x16x32_bf16 v[22:25], v[146:149], v[194:197], 0
	v_mfma_f32_16x16x32_bf16 v[22:25], v[150:153], v[198:201], v[22:25]
	v_mfma_f32_16x16x32_bf16 v[18:21], v[154:157], v[194:197], 0
	v_mfma_f32_16x16x32_bf16 v[18:21], v[158:161], v[198:201], v[18:21]
	v_mfma_f32_16x16x32_bf16 v[2:5], v[154:157], v[202:205], 0
	v_mfma_f32_16x16x32_bf16 v[2:5], v[158:161], v[206:209], v[2:5]
	s_setprio 2
	s_barrier
	v_mfma_f32_16x16x32_bf16 v[6:9], v[146:149], v[202:205], 0
	v_mfma_f32_16x16x32_bf16 v[6:9], v[150:153], v[206:209], v[6:9]
	s_setprio 0
	ds_read_b128 v[130:133], v184
	ds_read_b128 v[134:137], v184 offset:1024
	ds_read_b128 v[138:141], v184 offset:2048
	ds_read_b128 v[142:145], v184 offset:3072
	ds_read_b128 v[146:149], v185
	ds_read_b128 v[150:153], v185 offset:1024
	ds_read_b128 v[154:157], v185 offset:2048
	ds_read_b128 v[158:161], v185 offset:3072
	ds_read_b128 v[166:169], v183 offset:32768
	ds_read_b128 v[170:173], v183 offset:33792
	ds_read_b128 v[186:189], v183 offset:34816
	ds_read_b128 v[190:193], v183 offset:35840
	ds_read_b128 v[194:197], v183 offset:36864
	ds_read_b128 v[198:201], v183 offset:37888
	ds_read_b128 v[202:205], v183 offset:38912
	ds_read_b128 v[206:209], v183 offset:39936
	s_mov_b32 s79, m0
	s_mov_b32 m0, s34
	s_nop 0
	global_load_lds_dwordx4 v1, s[24:25]
	s_mov_b32 m0, s79
	s_nop 0
	s_mov_b32 s79, m0
	s_mov_b32 m0, s41
	s_nop 0
	global_load_lds_dwordx4 v177, s[24:25]
	s_mov_b32 m0, s79
	s_add_u32 s24, s24, 0x80000
	s_addc_u32 s25, s25, 0
	s_mov_b32 s79, m0
	s_mov_b32 m0, s42
	s_nop 0
	global_load_lds_dwordx4 v1, s[24:25]
	s_mov_b32 m0, s79
	s_nop 0
	s_mov_b32 s79, m0
	s_mov_b32 m0, s43
	s_nop 0
	global_load_lds_dwordx4 v177, s[24:25]
	s_mov_b32 m0, s79
	s_waitcnt vmcnt(8)
	s_waitcnt lgkmcnt(0)
	s_barrier
	s_setprio 1
	.p2align 3
	v_mfma_f32_16x16x32_bf16 v[126:129], v[130:133], v[166:169], v[126:129]
	v_mfma_f32_16x16x32_bf16 v[126:129], v[134:137], v[170:173], v[126:129]
	v_mfma_f32_16x16x32_bf16 v[122:125], v[138:141], v[166:169], v[122:125]
	v_mfma_f32_16x16x32_bf16 v[122:125], v[142:145], v[170:173], v[122:125]
	v_mfma_f32_16x16x32_bf16 v[114:117], v[138:141], v[186:189], v[114:117]
	v_mfma_f32_16x16x32_bf16 v[114:117], v[142:145], v[190:193], v[114:117]
	v_mfma_f32_16x16x32_bf16 v[118:121], v[130:133], v[186:189], v[118:121]
	v_mfma_f32_16x16x32_bf16 v[118:121], v[134:137], v[190:193], v[118:121]
	v_mfma_f32_16x16x32_bf16 v[94:97], v[130:133], v[194:197], v[94:97]
	v_mfma_f32_16x16x32_bf16 v[94:97], v[134:137], v[198:201], v[94:97]
	v_mfma_f32_16x16x32_bf16 v[90:93], v[138:141], v[194:197], v[90:93]
	v_mfma_f32_16x16x32_bf16 v[90:93], v[142:145], v[198:201], v[90:93]
	v_mfma_f32_16x16x32_bf16 v[78:81], v[138:141], v[202:205], v[78:81]
	v_mfma_f32_16x16x32_bf16 v[78:81], v[142:145], v[206:209], v[78:81]
	v_mfma_f32_16x16x32_bf16 v[86:89], v[130:133], v[202:205], v[86:89]
	v_mfma_f32_16x16x32_bf16 v[86:89], v[134:137], v[206:209], v[86:89]
	s_setprio 0
	s_setprio 1
	v_mfma_f32_16x16x32_bf16 v[110:113], v[146:149], v[166:169], v[110:113]
	v_mfma_f32_16x16x32_bf16 v[110:113], v[150:153], v[170:173], v[110:113]
	v_mfma_f32_16x16x32_bf16 v[106:109], v[154:157], v[166:169], v[106:109]
	v_mfma_f32_16x16x32_bf16 v[106:109], v[158:161], v[170:173], v[106:109]
	v_mfma_f32_16x16x32_bf16 v[98:101], v[154:157], v[186:189], v[98:101]
	v_mfma_f32_16x16x32_bf16 v[98:101], v[158:161], v[190:193], v[98:101]
	v_mfma_f32_16x16x32_bf16 v[102:105], v[146:149], v[186:189], v[102:105]
	v_mfma_f32_16x16x32_bf16 v[102:105], v[150:153], v[190:193], v[102:105]
	v_mfma_f32_16x16x32_bf16 v[82:85], v[146:149], v[194:197], v[82:85]
	v_mfma_f32_16x16x32_bf16 v[82:85], v[150:153], v[198:201], v[82:85]
	v_mfma_f32_16x16x32_bf16 v[74:77], v[154:157], v[194:197], v[74:77]
	v_mfma_f32_16x16x32_bf16 v[74:77], v[158:161], v[198:201], v[74:77]
	v_mfma_f32_16x16x32_bf16 v[66:69], v[154:157], v[202:205], v[66:69]
	v_mfma_f32_16x16x32_bf16 v[66:69], v[158:161], v[206:209], v[66:69]
	s_setprio 2
	s_barrier
	v_mfma_f32_16x16x32_bf16 v[70:73], v[146:149], v[202:205], v[70:73]
	v_mfma_f32_16x16x32_bf16 v[70:73], v[150:153], v[206:209], v[70:73]
	s_setprio 0
	ds_read_b128 v[166:169], v183 offset:49152
	ds_read_b128 v[170:173], v183 offset:50176
	ds_read_b128 v[186:189], v183 offset:51200
	ds_read_b128 v[190:193], v183 offset:52224
	ds_read_b128 v[194:197], v183 offset:53248
	ds_read_b128 v[198:201], v183 offset:54272
	ds_read_b128 v[202:205], v183 offset:55296
	ds_read_b128 v[206:209], v183 offset:56320
	s_add_u32 s24, s22, 0x80
	s_addc_u32 s25, s23, 0
	s_mov_b32 s79, m0
	s_mov_b32 m0, s46
	s_nop 0
	global_load_lds_dwordx4 v176, s[24:25]
	s_mov_b32 m0, s79
	s_add_u32 s22, s22, 0x80080
	s_mov_b32 s79, m0
	s_mov_b32 m0, s47
	s_nop 0
	global_load_lds_dwordx4 v178, s[24:25]
	s_mov_b32 m0, s79
	s_addc_u32 s23, s23, 0
	s_mov_b32 s24, m0
	s_mov_b32 m0, s48
	s_nop 0
	global_load_lds_dwordx4 v176, s[22:23]
	s_mov_b32 m0, s24
	s_nop 0
	s_mov_b32 s24, m0
	s_mov_b32 m0, s49
	s_nop 0
	global_load_lds_dwordx4 v178, s[22:23]
	s_mov_b32 m0, s24
	s_waitcnt vmcnt(4)
	s_waitcnt lgkmcnt(0)
	s_barrier
	s_setprio 1
	.p2align 3
	v_mfma_f32_16x16x32_bf16 v[62:65], v[130:133], v[166:169], v[62:65]
	v_mfma_f32_16x16x32_bf16 v[62:65], v[134:137], v[170:173], v[62:65]
	v_mfma_f32_16x16x32_bf16 v[58:61], v[138:141], v[166:169], v[58:61]
	v_mfma_f32_16x16x32_bf16 v[58:61], v[142:145], v[170:173], v[58:61]
	v_mfma_f32_16x16x32_bf16 v[42:45], v[138:141], v[186:189], v[42:45]
	v_mfma_f32_16x16x32_bf16 v[42:45], v[142:145], v[190:193], v[42:45]
	v_mfma_f32_16x16x32_bf16 v[46:49], v[130:133], v[186:189], v[46:49]
	v_mfma_f32_16x16x32_bf16 v[46:49], v[134:137], v[190:193], v[46:49]
	v_mfma_f32_16x16x32_bf16 v[30:33], v[130:133], v[194:197], v[30:33]
	v_mfma_f32_16x16x32_bf16 v[30:33], v[134:137], v[198:201], v[30:33]
	v_mfma_f32_16x16x32_bf16 v[26:29], v[138:141], v[194:197], v[26:29]
	v_mfma_f32_16x16x32_bf16 v[26:29], v[142:145], v[198:201], v[26:29]
	v_mfma_f32_16x16x32_bf16 v[10:13], v[138:141], v[202:205], v[10:13]
	v_mfma_f32_16x16x32_bf16 v[10:13], v[142:145], v[206:209], v[10:13]
	v_mfma_f32_16x16x32_bf16 v[14:17], v[130:133], v[202:205], v[14:17]
	v_mfma_f32_16x16x32_bf16 v[14:17], v[134:137], v[206:209], v[14:17]
	s_setprio 0
	s_setprio 1
	v_mfma_f32_16x16x32_bf16 v[54:57], v[146:149], v[166:169], v[54:57]
	v_mfma_f32_16x16x32_bf16 v[54:57], v[150:153], v[170:173], v[54:57]
	v_mfma_f32_16x16x32_bf16 v[50:53], v[154:157], v[166:169], v[50:53]
	v_mfma_f32_16x16x32_bf16 v[50:53], v[158:161], v[170:173], v[50:53]
	v_mfma_f32_16x16x32_bf16 v[34:37], v[154:157], v[186:189], v[34:37]
	v_mfma_f32_16x16x32_bf16 v[34:37], v[158:161], v[190:193], v[34:37]
	v_mfma_f32_16x16x32_bf16 v[38:41], v[146:149], v[186:189], v[38:41]
	v_mfma_f32_16x16x32_bf16 v[38:41], v[150:153], v[190:193], v[38:41]
	v_mfma_f32_16x16x32_bf16 v[22:25], v[146:149], v[194:197], v[22:25]
	v_mfma_f32_16x16x32_bf16 v[22:25], v[150:153], v[198:201], v[22:25]
	v_mfma_f32_16x16x32_bf16 v[18:21], v[154:157], v[194:197], v[18:21]
	v_mfma_f32_16x16x32_bf16 v[18:21], v[158:161], v[198:201], v[18:21]
	v_mfma_f32_16x16x32_bf16 v[2:5], v[154:157], v[202:205], v[2:5]
	v_mfma_f32_16x16x32_bf16 v[2:5], v[158:161], v[206:209], v[2:5]
	s_setprio 2
	s_barrier
	v_mfma_f32_16x16x32_bf16 v[6:9], v[146:149], v[202:205], v[6:9]
	v_mfma_f32_16x16x32_bf16 v[6:9], v[150:153], v[206:209], v[6:9]
	s_setprio 0
	s_add_i32 s78, s78, 2
	s_add_u32 s74, s74, 0x100
	s_addc_u32 s75, s75, 0
	s_add_u32 s20, s20, 0x100
	s_addc_u32 s21, s21, 0
	s_add_u32 s76, s76, 0x100
	s_addc_u32 s77, s77, 0
	s_cmp_gt_u32 s78, 29
	.p2align 6
.LBB0_1053:
	ds_read_b128 v[130:133], v181
	ds_read_b128 v[134:137], v181 offset:1024
	ds_read_b128 v[138:141], v181 offset:2048
	ds_read_b128 v[142:145], v181 offset:3072
	ds_read_b128 v[146:149], v182
	ds_read_b128 v[150:153], v182 offset:1024
	ds_read_b128 v[154:157], v182 offset:2048
	ds_read_b128 v[158:161], v182 offset:3072
	s_cmp_eq_u32 s78, 28
	s_cselect_b32 s23, s11, s75
	s_cselect_b32 s22, s73, s74
	s_cselect_b32 s25, s13, s77
	s_cselect_b32 s24, s67, s76
	ds_read_b128 v[166:169], v183
	ds_read_b128 v[170:173], v183 offset:1024
	ds_read_b128 v[186:189], v183 offset:2048
	ds_read_b128 v[190:193], v183 offset:3072
	ds_read_b128 v[194:197], v183 offset:4096
	ds_read_b128 v[198:201], v183 offset:5120
	ds_read_b128 v[202:205], v183 offset:6144
	ds_read_b128 v[206:209], v183 offset:7168
	s_add_u32 s80, s20, 0xfff80000
	s_addc_u32 s81, s21, -1
	s_mov_b32 s79, m0
	s_mov_b32 m0, s58
	s_nop 0
	global_load_lds_dwordx4 v1, s[80:81]
	s_mov_b32 m0, s79
	s_nop 0
	s_mov_b32 s79, m0
	s_mov_b32 m0, s64
	s_nop 0
	global_load_lds_dwordx4 v177, s[80:81]
	s_mov_b32 m0, s79
	s_nop 0
	s_mov_b32 s79, m0
	s_mov_b32 m0, s59
	s_nop 0
	global_load_lds_dwordx4 v1, s[20:21]
	s_mov_b32 m0, s79
	s_nop 0
	s_mov_b32 s79, m0
	s_mov_b32 m0, s65
	s_nop 0
	global_load_lds_dwordx4 v177, s[20:21]
	s_mov_b32 m0, s79
	s_waitcnt vmcnt(8)
	s_waitcnt lgkmcnt(0)
	s_barrier
	s_setprio 1
	.p2align 3
	v_mfma_f32_16x16x32_bf16 v[126:129], v[130:133], v[166:169], v[126:129]
	v_mfma_f32_16x16x32_bf16 v[126:129], v[134:137], v[170:173], v[126:129]
	v_mfma_f32_16x16x32_bf16 v[122:125], v[138:141], v[166:169], v[122:125]
	v_mfma_f32_16x16x32_bf16 v[122:125], v[142:145], v[170:173], v[122:125]
	v_mfma_f32_16x16x32_bf16 v[114:117], v[138:141], v[186:189], v[114:117]
	v_mfma_f32_16x16x32_bf16 v[114:117], v[142:145], v[190:193], v[114:117]
	v_mfma_f32_16x16x32_bf16 v[118:121], v[130:133], v[186:189], v[118:121]
	v_mfma_f32_16x16x32_bf16 v[118:121], v[134:137], v[190:193], v[118:121]
	v_mfma_f32_16x16x32_bf16 v[94:97], v[130:133], v[194:197], v[94:97]
	v_mfma_f32_16x16x32_bf16 v[94:97], v[134:137], v[198:201], v[94:97]
	v_mfma_f32_16x16x32_bf16 v[90:93], v[138:141], v[194:197], v[90:93]
	v_mfma_f32_16x16x32_bf16 v[90:93], v[142:145], v[198:201], v[90:93]
	v_mfma_f32_16x16x32_bf16 v[78:81], v[138:141], v[202:205], v[78:81]
	v_mfma_f32_16x16x32_bf16 v[78:81], v[142:145], v[206:209], v[78:81]
	v_mfma_f32_16x16x32_bf16 v[86:89], v[130:133], v[202:205], v[86:89]
	v_mfma_f32_16x16x32_bf16 v[86:89], v[134:137], v[206:209], v[86:89]
	s_setprio 0
	s_setprio 1
	v_mfma_f32_16x16x32_bf16 v[110:113], v[146:149], v[166:169], v[110:113]
	v_mfma_f32_16x16x32_bf16 v[110:113], v[150:153], v[170:173], v[110:113]
	v_mfma_f32_16x16x32_bf16 v[106:109], v[154:157], v[166:169], v[106:109]
	v_mfma_f32_16x16x32_bf16 v[106:109], v[158:161], v[170:173], v[106:109]
	v_mfma_f32_16x16x32_bf16 v[98:101], v[154:157], v[186:189], v[98:101]
	v_mfma_f32_16x16x32_bf16 v[98:101], v[158:161], v[190:193], v[98:101]
	v_mfma_f32_16x16x32_bf16 v[102:105], v[146:149], v[186:189], v[102:105]
	v_mfma_f32_16x16x32_bf16 v[102:105], v[150:153], v[190:193], v[102:105]
	v_mfma_f32_16x16x32_bf16 v[82:85], v[146:149], v[194:197], v[82:85]
	v_mfma_f32_16x16x32_bf16 v[82:85], v[150:153], v[198:201], v[82:85]
	v_mfma_f32_16x16x32_bf16 v[74:77], v[154:157], v[194:197], v[74:77]
	v_mfma_f32_16x16x32_bf16 v[74:77], v[158:161], v[198:201], v[74:77]
	v_mfma_f32_16x16x32_bf16 v[66:69], v[154:157], v[202:205], v[66:69]
	v_mfma_f32_16x16x32_bf16 v[66:69], v[158:161], v[206:209], v[66:69]
	s_setprio 2
	s_barrier
	v_mfma_f32_16x16x32_bf16 v[70:73], v[146:149], v[202:205], v[70:73]
	v_mfma_f32_16x16x32_bf16 v[70:73], v[150:153], v[206:209], v[70:73]
	s_setprio 0
	ds_read_b128 v[166:169], v183 offset:16384
	ds_read_b128 v[170:173], v183 offset:17408
	ds_read_b128 v[186:189], v183 offset:18432
	ds_read_b128 v[190:193], v183 offset:19456
	ds_read_b128 v[194:197], v183 offset:20480
	ds_read_b128 v[198:201], v183 offset:21504
	ds_read_b128 v[202:205], v183 offset:22528
	ds_read_b128 v[206:209], v183 offset:23552
	s_mov_b32 s79, m0
	s_mov_b32 m0, s35
	s_nop 0
	global_load_lds_dwordx4 v176, s[22:23]
	s_mov_b32 m0, s79
	s_add_u32 s80, s22, 0x80000
	s_mov_b32 s79, m0
	s_mov_b32 m0, s36
	s_nop 0
	global_load_lds_dwordx4 v178, s[22:23]
	s_mov_b32 m0, s79
	s_addc_u32 s81, s23, 0
	s_mov_b32 s79, m0
	s_mov_b32 m0, s37
	s_nop 0
	global_load_lds_dwordx4 v176, s[80:81]
	s_mov_b32 m0, s79
	s_nop 0
	s_mov_b32 s79, m0
	s_mov_b32 m0, s40
	s_nop 0
	global_load_lds_dwordx4 v178, s[80:81]
	s_mov_b32 m0, s79
	s_waitcnt vmcnt(4)
	s_waitcnt lgkmcnt(0)
	s_barrier
	s_setprio 1
	.p2align 3
	v_mfma_f32_16x16x32_bf16 v[62:65], v[130:133], v[166:169], v[62:65]
	v_mfma_f32_16x16x32_bf16 v[62:65], v[134:137], v[170:173], v[62:65]
	v_mfma_f32_16x16x32_bf16 v[58:61], v[138:141], v[166:169], v[58:61]
	v_mfma_f32_16x16x32_bf16 v[58:61], v[142:145], v[170:173], v[58:61]
	v_mfma_f32_16x16x32_bf16 v[42:45], v[138:141], v[186:189], v[42:45]
	v_mfma_f32_16x16x32_bf16 v[42:45], v[142:145], v[190:193], v[42:45]
	v_mfma_f32_16x16x32_bf16 v[46:49], v[130:133], v[186:189], v[46:49]
	v_mfma_f32_16x16x32_bf16 v[46:49], v[134:137], v[190:193], v[46:49]
	v_mfma_f32_16x16x32_bf16 v[30:33], v[130:133], v[194:197], v[30:33]
	v_mfma_f32_16x16x32_bf16 v[30:33], v[134:137], v[198:201], v[30:33]
	v_mfma_f32_16x16x32_bf16 v[26:29], v[138:141], v[194:197], v[26:29]
	v_mfma_f32_16x16x32_bf16 v[26:29], v[142:145], v[198:201], v[26:29]
	v_mfma_f32_16x16x32_bf16 v[10:13], v[138:141], v[202:205], v[10:13]
	v_mfma_f32_16x16x32_bf16 v[10:13], v[142:145], v[206:209], v[10:13]
	v_mfma_f32_16x16x32_bf16 v[14:17], v[130:133], v[202:205], v[14:17]
	v_mfma_f32_16x16x32_bf16 v[14:17], v[134:137], v[206:209], v[14:17]
	s_setprio 0
	s_setprio 1
	v_mfma_f32_16x16x32_bf16 v[54:57], v[146:149], v[166:169], v[54:57]
	v_mfma_f32_16x16x32_bf16 v[54:57], v[150:153], v[170:173], v[54:57]
	v_mfma_f32_16x16x32_bf16 v[50:53], v[154:157], v[166:169], v[50:53]
	v_mfma_f32_16x16x32_bf16 v[50:53], v[158:161], v[170:173], v[50:53]
	v_mfma_f32_16x16x32_bf16 v[34:37], v[154:157], v[186:189], v[34:37]
	v_mfma_f32_16x16x32_bf16 v[34:37], v[158:161], v[190:193], v[34:37]
	v_mfma_f32_16x16x32_bf16 v[38:41], v[146:149], v[186:189], v[38:41]
	v_mfma_f32_16x16x32_bf16 v[38:41], v[150:153], v[190:193], v[38:41]
	v_mfma_f32_16x16x32_bf16 v[22:25], v[146:149], v[194:197], v[22:25]
	v_mfma_f32_16x16x32_bf16 v[22:25], v[150:153], v[198:201], v[22:25]
	v_mfma_f32_16x16x32_bf16 v[18:21], v[154:157], v[194:197], v[18:21]
	v_mfma_f32_16x16x32_bf16 v[18:21], v[158:161], v[198:201], v[18:21]
	v_mfma_f32_16x16x32_bf16 v[2:5], v[154:157], v[202:205], v[2:5]
	v_mfma_f32_16x16x32_bf16 v[2:5], v[158:161], v[206:209], v[2:5]
	s_setprio 2
	s_barrier
	v_mfma_f32_16x16x32_bf16 v[6:9], v[146:149], v[202:205], v[6:9]
	v_mfma_f32_16x16x32_bf16 v[6:9], v[150:153], v[206:209], v[6:9]
	s_setprio 0
	ds_read_b128 v[130:133], v184
	ds_read_b128 v[134:137], v184 offset:1024
	ds_read_b128 v[138:141], v184 offset:2048
	ds_read_b128 v[142:145], v184 offset:3072
	ds_read_b128 v[146:149], v185
	ds_read_b128 v[150:153], v185 offset:1024
	ds_read_b128 v[154:157], v185 offset:2048
	ds_read_b128 v[158:161], v185 offset:3072
	ds_read_b128 v[166:169], v183 offset:32768
	ds_read_b128 v[170:173], v183 offset:33792
	ds_read_b128 v[186:189], v183 offset:34816
	ds_read_b128 v[190:193], v183 offset:35840
	ds_read_b128 v[194:197], v183 offset:36864
	ds_read_b128 v[198:201], v183 offset:37888
	ds_read_b128 v[202:205], v183 offset:38912
	ds_read_b128 v[206:209], v183 offset:39936
	s_mov_b32 s79, m0
	s_mov_b32 m0, s34
	s_nop 0
	global_load_lds_dwordx4 v1, s[24:25]
	s_mov_b32 m0, s79
	s_nop 0
	s_mov_b32 s79, m0
	s_mov_b32 m0, s41
	s_nop 0
	global_load_lds_dwordx4 v177, s[24:25]
	s_mov_b32 m0, s79
	s_add_u32 s24, s24, 0x80000
	s_addc_u32 s25, s25, 0
	s_mov_b32 s79, m0
	s_mov_b32 m0, s42
	s_nop 0
	global_load_lds_dwordx4 v1, s[24:25]
	s_mov_b32 m0, s79
	s_nop 0
	s_mov_b32 s79, m0
	s_mov_b32 m0, s43
	s_nop 0
	global_load_lds_dwordx4 v177, s[24:25]
	s_mov_b32 m0, s79
	s_waitcnt vmcnt(8)
	s_waitcnt lgkmcnt(0)
	s_barrier
	s_setprio 1
	.p2align 3
	v_mfma_f32_16x16x32_bf16 v[126:129], v[130:133], v[166:169], v[126:129]
	v_mfma_f32_16x16x32_bf16 v[126:129], v[134:137], v[170:173], v[126:129]
	v_mfma_f32_16x16x32_bf16 v[122:125], v[138:141], v[166:169], v[122:125]
	v_mfma_f32_16x16x32_bf16 v[122:125], v[142:145], v[170:173], v[122:125]
	v_mfma_f32_16x16x32_bf16 v[114:117], v[138:141], v[186:189], v[114:117]
	v_mfma_f32_16x16x32_bf16 v[114:117], v[142:145], v[190:193], v[114:117]
	v_mfma_f32_16x16x32_bf16 v[118:121], v[130:133], v[186:189], v[118:121]
	v_mfma_f32_16x16x32_bf16 v[118:121], v[134:137], v[190:193], v[118:121]
	v_mfma_f32_16x16x32_bf16 v[94:97], v[130:133], v[194:197], v[94:97]
	v_mfma_f32_16x16x32_bf16 v[94:97], v[134:137], v[198:201], v[94:97]
	v_mfma_f32_16x16x32_bf16 v[90:93], v[138:141], v[194:197], v[90:93]
	v_mfma_f32_16x16x32_bf16 v[90:93], v[142:145], v[198:201], v[90:93]
	v_mfma_f32_16x16x32_bf16 v[78:81], v[138:141], v[202:205], v[78:81]
	v_mfma_f32_16x16x32_bf16 v[78:81], v[142:145], v[206:209], v[78:81]
	v_mfma_f32_16x16x32_bf16 v[86:89], v[130:133], v[202:205], v[86:89]
	v_mfma_f32_16x16x32_bf16 v[86:89], v[134:137], v[206:209], v[86:89]
	s_setprio 0
	s_setprio 1
	v_mfma_f32_16x16x32_bf16 v[110:113], v[146:149], v[166:169], v[110:113]
	v_mfma_f32_16x16x32_bf16 v[110:113], v[150:153], v[170:173], v[110:113]
	v_mfma_f32_16x16x32_bf16 v[106:109], v[154:157], v[166:169], v[106:109]
	v_mfma_f32_16x16x32_bf16 v[106:109], v[158:161], v[170:173], v[106:109]
	v_mfma_f32_16x16x32_bf16 v[98:101], v[154:157], v[186:189], v[98:101]
	v_mfma_f32_16x16x32_bf16 v[98:101], v[158:161], v[190:193], v[98:101]
	v_mfma_f32_16x16x32_bf16 v[102:105], v[146:149], v[186:189], v[102:105]
	v_mfma_f32_16x16x32_bf16 v[102:105], v[150:153], v[190:193], v[102:105]
	v_mfma_f32_16x16x32_bf16 v[82:85], v[146:149], v[194:197], v[82:85]
	v_mfma_f32_16x16x32_bf16 v[82:85], v[150:153], v[198:201], v[82:85]
	v_mfma_f32_16x16x32_bf16 v[74:77], v[154:157], v[194:197], v[74:77]
	v_mfma_f32_16x16x32_bf16 v[74:77], v[158:161], v[198:201], v[74:77]
	v_mfma_f32_16x16x32_bf16 v[66:69], v[154:157], v[202:205], v[66:69]
	v_mfma_f32_16x16x32_bf16 v[66:69], v[158:161], v[206:209], v[66:69]
	s_setprio 2
	s_barrier
	v_mfma_f32_16x16x32_bf16 v[70:73], v[146:149], v[202:205], v[70:73]
	v_mfma_f32_16x16x32_bf16 v[70:73], v[150:153], v[206:209], v[70:73]
	s_setprio 0
	ds_read_b128 v[166:169], v183 offset:49152
	ds_read_b128 v[170:173], v183 offset:50176
	ds_read_b128 v[186:189], v183 offset:51200
	ds_read_b128 v[190:193], v183 offset:52224
	ds_read_b128 v[194:197], v183 offset:53248
	ds_read_b128 v[198:201], v183 offset:54272
	ds_read_b128 v[202:205], v183 offset:55296
	ds_read_b128 v[206:209], v183 offset:56320
	s_add_u32 s24, s22, 0x80
	s_addc_u32 s25, s23, 0
	s_mov_b32 s79, m0
	s_mov_b32 m0, s46
	s_nop 0
	global_load_lds_dwordx4 v176, s[24:25]
	s_mov_b32 m0, s79
	s_add_u32 s22, s22, 0x80080
	s_mov_b32 s79, m0
	s_mov_b32 m0, s47
	s_nop 0
	global_load_lds_dwordx4 v178, s[24:25]
	s_mov_b32 m0, s79
	s_addc_u32 s23, s23, 0
	s_mov_b32 s24, m0
	s_mov_b32 m0, s48
	s_nop 0
	global_load_lds_dwordx4 v176, s[22:23]
	s_mov_b32 m0, s24
	s_nop 0
	s_mov_b32 s24, m0
	s_mov_b32 m0, s49
	s_nop 0
	global_load_lds_dwordx4 v178, s[22:23]
	s_mov_b32 m0, s24
	s_waitcnt vmcnt(4)
	s_waitcnt lgkmcnt(0)
	s_barrier
	s_setprio 1
	.p2align 3
	v_mfma_f32_16x16x32_bf16 v[62:65], v[130:133], v[166:169], v[62:65]
	v_mfma_f32_16x16x32_bf16 v[62:65], v[134:137], v[170:173], v[62:65]
	v_mfma_f32_16x16x32_bf16 v[58:61], v[138:141], v[166:169], v[58:61]
	v_mfma_f32_16x16x32_bf16 v[58:61], v[142:145], v[170:173], v[58:61]
	v_mfma_f32_16x16x32_bf16 v[42:45], v[138:141], v[186:189], v[42:45]
	v_mfma_f32_16x16x32_bf16 v[42:45], v[142:145], v[190:193], v[42:45]
	v_mfma_f32_16x16x32_bf16 v[46:49], v[130:133], v[186:189], v[46:49]
	v_mfma_f32_16x16x32_bf16 v[46:49], v[134:137], v[190:193], v[46:49]
	v_mfma_f32_16x16x32_bf16 v[30:33], v[130:133], v[194:197], v[30:33]
	v_mfma_f32_16x16x32_bf16 v[30:33], v[134:137], v[198:201], v[30:33]
	v_mfma_f32_16x16x32_bf16 v[26:29], v[138:141], v[194:197], v[26:29]
	v_mfma_f32_16x16x32_bf16 v[26:29], v[142:145], v[198:201], v[26:29]
	v_mfma_f32_16x16x32_bf16 v[10:13], v[138:141], v[202:205], v[10:13]
	v_mfma_f32_16x16x32_bf16 v[10:13], v[142:145], v[206:209], v[10:13]
	v_mfma_f32_16x16x32_bf16 v[14:17], v[130:133], v[202:205], v[14:17]
	v_mfma_f32_16x16x32_bf16 v[14:17], v[134:137], v[206:209], v[14:17]
	s_setprio 0
	s_setprio 1
	v_mfma_f32_16x16x32_bf16 v[54:57], v[146:149], v[166:169], v[54:57]
	v_mfma_f32_16x16x32_bf16 v[54:57], v[150:153], v[170:173], v[54:57]
	v_mfma_f32_16x16x32_bf16 v[50:53], v[154:157], v[166:169], v[50:53]
	v_mfma_f32_16x16x32_bf16 v[50:53], v[158:161], v[170:173], v[50:53]
	v_mfma_f32_16x16x32_bf16 v[34:37], v[154:157], v[186:189], v[34:37]
	v_mfma_f32_16x16x32_bf16 v[34:37], v[158:161], v[190:193], v[34:37]
	v_mfma_f32_16x16x32_bf16 v[38:41], v[146:149], v[186:189], v[38:41]
	v_mfma_f32_16x16x32_bf16 v[38:41], v[150:153], v[190:193], v[38:41]
	v_mfma_f32_16x16x32_bf16 v[22:25], v[146:149], v[194:197], v[22:25]
	v_mfma_f32_16x16x32_bf16 v[22:25], v[150:153], v[198:201], v[22:25]
	v_mfma_f32_16x16x32_bf16 v[18:21], v[154:157], v[194:197], v[18:21]
	v_mfma_f32_16x16x32_bf16 v[18:21], v[158:161], v[198:201], v[18:21]
	v_mfma_f32_16x16x32_bf16 v[2:5], v[154:157], v[202:205], v[2:5]
	v_mfma_f32_16x16x32_bf16 v[2:5], v[158:161], v[206:209], v[2:5]
	s_setprio 2
	s_barrier
	v_mfma_f32_16x16x32_bf16 v[6:9], v[146:149], v[202:205], v[6:9]
	v_mfma_f32_16x16x32_bf16 v[6:9], v[150:153], v[206:209], v[6:9]
	s_setprio 0
	s_add_i32 s78, s78, 2
	s_add_u32 s74, s74, 0x100
	s_addc_u32 s75, s75, 0
	s_add_u32 s20, s20, 0x100
	s_addc_u32 s21, s21, 0
	s_add_u32 s76, s76, 0x100
	s_addc_u32 s77, s77, 0
	s_cmp_gt_u32 s78, 29
	s_cbranch_scc0 .LBB0_1053
	s_and_b64 vcc, exec, s[8:9]
	s_cbranch_vccz .LBB0_1056
	s_barrier

.LBB0_1223:
	s_ashr_i32 s11, s10, 31
	s_lshl_b64 s[12:13], s[10:11], 20
	s_add_u32 s12, s26, s12
	s_addc_u32 s13, s27, s13
	s_and_b64 s[14:15], s[2:3], exec
	s_cselect_b32 s11, s13, s21
	s_cselect_b32 s66, s12, s20
	s_ashr_i32 s9, s8, 31
	s_lshl_b64 s[14:15], s[8:9], 20
	s_add_u32 s14, s28, s14
	s_addc_u32 s15, s29, s15
	s_and_b64 s[22:23], s[2:3], exec
	s_cselect_b32 s9, s15, s19
	s_cselect_b32 s67, s14, s18
	s_add_u32 s73, s18, 0x100
	s_addc_u32 s74, s19, 0
	s_add_u32 s18, s20, 0x80080
	s_addc_u32 s19, s21, 0
	s_add_u32 s75, s20, 0x100
	s_addc_u32 s76, s21, 0
	s_mov_b32 s77, -2
	ds_read_b128 v[148:151], v143
	ds_read_b128 v[152:155], v143 offset:1024
	ds_read_b128 v[156:159], v143 offset:2048
	ds_read_b128 v[160:163], v143 offset:3072
	ds_read_b128 v[164:167], v144
	ds_read_b128 v[168:171], v144 offset:1024
	ds_read_b128 v[172:175], v144 offset:2048
	ds_read_b128 v[176:179], v144 offset:3072
	s_cmp_eq_u32 s77, 28
	s_cselect_b32 s21, s9, s74
	s_cselect_b32 s20, s67, s73
	s_cselect_b32 s23, s11, s76
	s_cselect_b32 s22, s66, s75
	ds_read_b128 v[180:183], v145
	ds_read_b128 v[184:187], v145 offset:1024
	ds_read_b128 v[188:191], v145 offset:2048
	ds_read_b128 v[192:195], v145 offset:3072
	ds_read_b128 v[196:199], v145 offset:4096
	ds_read_b128 v[200:203], v145 offset:5120
	ds_read_b128 v[204:207], v145 offset:6144
	ds_read_b128 v[208:211], v145 offset:7168
	s_add_u32 s78, s18, 0xfff80000
	s_addc_u32 s79, s19, -1
	s_mov_b32 s80, m0
	s_mov_b32 m0, s56
	s_nop 0
	global_load_lds_dwordx4 v138, s[78:79]
	s_mov_b32 m0, s80
	s_nop 0
	s_mov_b32 s80, m0
	s_mov_b32 m0, s59
	s_nop 0
	global_load_lds_dwordx4 v140, s[78:79]
	s_mov_b32 m0, s80
	s_mov_b32 s78, m0
	s_mov_b32 m0, s57
	s_nop 0
	global_load_lds_dwordx4 v138, s[18:19]
	s_mov_b32 m0, s78
	s_nop 0
	s_mov_b32 s78, m0
	s_mov_b32 m0, s64
	s_nop 0
	global_load_lds_dwordx4 v140, s[18:19]
	s_mov_b32 m0, s78
	s_waitcnt vmcnt(8)
	s_waitcnt lgkmcnt(0)
	s_barrier
	s_setprio 1
	.p2align 3
	v_mfma_f32_16x16x32_bf16 v[126:129], v[148:151], v[180:183], 0
	v_mfma_f32_16x16x32_bf16 v[126:129], v[152:155], v[184:187], v[126:129]
	v_mfma_f32_16x16x32_bf16 v[122:125], v[156:159], v[180:183], 0
	v_mfma_f32_16x16x32_bf16 v[122:125], v[160:163], v[184:187], v[122:125]
	v_mfma_f32_16x16x32_bf16 v[106:109], v[156:159], v[188:191], 0
	v_mfma_f32_16x16x32_bf16 v[106:109], v[160:163], v[192:195], v[106:109]
	v_mfma_f32_16x16x32_bf16 v[110:113], v[148:151], v[188:191], 0
	v_mfma_f32_16x16x32_bf16 v[110:113], v[152:155], v[192:195], v[110:113]
	v_mfma_f32_16x16x32_bf16 v[94:97], v[148:151], v[196:199], 0
	v_mfma_f32_16x16x32_bf16 v[94:97], v[152:155], v[200:203], v[94:97]
	v_mfma_f32_16x16x32_bf16 v[90:93], v[156:159], v[196:199], 0
	v_mfma_f32_16x16x32_bf16 v[90:93], v[160:163], v[200:203], v[90:93]
	v_mfma_f32_16x16x32_bf16 v[74:77], v[156:159], v[204:207], 0
	v_mfma_f32_16x16x32_bf16 v[74:77], v[160:163], v[208:211], v[74:77]
	v_mfma_f32_16x16x32_bf16 v[78:81], v[148:151], v[204:207], 0
	v_mfma_f32_16x16x32_bf16 v[78:81], v[152:155], v[208:211], v[78:81]
	s_setprio 0
	s_setprio 1
	v_mfma_f32_16x16x32_bf16 v[118:121], v[164:167], v[180:183], 0
	v_mfma_f32_16x16x32_bf16 v[118:121], v[168:171], v[184:187], v[118:121]
	v_mfma_f32_16x16x32_bf16 v[114:117], v[172:175], v[180:183], 0
	v_mfma_f32_16x16x32_bf16 v[114:117], v[176:179], v[184:187], v[114:117]
	v_mfma_f32_16x16x32_bf16 v[98:101], v[172:175], v[188:191], 0
	v_mfma_f32_16x16x32_bf16 v[98:101], v[176:179], v[192:195], v[98:101]
	v_mfma_f32_16x16x32_bf16 v[102:105], v[164:167], v[188:191], 0
	v_mfma_f32_16x16x32_bf16 v[102:105], v[168:171], v[192:195], v[102:105]
	v_mfma_f32_16x16x32_bf16 v[86:89], v[164:167], v[196:199], 0
	v_mfma_f32_16x16x32_bf16 v[86:89], v[168:171], v[200:203], v[86:89]
	v_mfma_f32_16x16x32_bf16 v[82:85], v[172:175], v[196:199], 0
	v_mfma_f32_16x16x32_bf16 v[82:85], v[176:179], v[200:203], v[82:85]
	v_mfma_f32_16x16x32_bf16 v[66:69], v[172:175], v[204:207], 0
	v_mfma_f32_16x16x32_bf16 v[66:69], v[176:179], v[208:211], v[66:69]
	s_setprio 2
	s_barrier
	v_mfma_f32_16x16x32_bf16 v[70:73], v[164:167], v[204:207], 0
	v_mfma_f32_16x16x32_bf16 v[70:73], v[168:171], v[208:211], v[70:73]
	s_setprio 0
	ds_read_b128 v[180:183], v145 offset:16384
	ds_read_b128 v[184:187], v145 offset:17408
	ds_read_b128 v[188:191], v145 offset:18432
	ds_read_b128 v[192:195], v145 offset:19456
	ds_read_b128 v[196:199], v145 offset:20480
	ds_read_b128 v[200:203], v145 offset:21504
	ds_read_b128 v[204:207], v145 offset:22528
	ds_read_b128 v[208:211], v145 offset:23552
	s_mov_b32 s78, m0
	s_mov_b32 m0, s35
	s_nop 0
	global_load_lds_dwordx4 v139, s[20:21]
	s_mov_b32 m0, s78
	s_nop 0
	s_mov_b32 s78, m0
	s_mov_b32 m0, s36
	s_nop 0
	global_load_lds_dwordx4 v141, s[20:21]
	s_mov_b32 m0, s78
	s_add_u32 s78, s20, 0x80000
	s_addc_u32 s79, s21, 0
	s_mov_b32 s80, m0
	s_mov_b32 m0, s37
	s_nop 0
	global_load_lds_dwordx4 v139, s[78:79]
	s_mov_b32 m0, s80
	s_nop 0
	s_mov_b32 s80, m0
	s_mov_b32 m0, s40
	s_nop 0
	global_load_lds_dwordx4 v141, s[78:79]
	s_mov_b32 m0, s80
	s_waitcnt vmcnt(4)
	s_waitcnt lgkmcnt(0)
	s_barrier
	s_setprio 1
	.p2align 3
	v_mfma_f32_16x16x32_bf16 v[62:65], v[148:151], v[180:183], 0
	v_mfma_f32_16x16x32_bf16 v[62:65], v[152:155], v[184:187], v[62:65]
	v_mfma_f32_16x16x32_bf16 v[58:61], v[156:159], v[180:183], 0
	v_mfma_f32_16x16x32_bf16 v[58:61], v[160:163], v[184:187], v[58:61]
	v_mfma_f32_16x16x32_bf16 v[42:45], v[156:159], v[188:191], 0
	v_mfma_f32_16x16x32_bf16 v[42:45], v[160:163], v[192:195], v[42:45]
	v_mfma_f32_16x16x32_bf16 v[46:49], v[148:151], v[188:191], 0
	v_mfma_f32_16x16x32_bf16 v[46:49], v[152:155], v[192:195], v[46:49]
	v_mfma_f32_16x16x32_bf16 v[30:33], v[148:151], v[196:199], 0
	v_mfma_f32_16x16x32_bf16 v[30:33], v[152:155], v[200:203], v[30:33]
	v_mfma_f32_16x16x32_bf16 v[26:29], v[156:159], v[196:199], 0
	v_mfma_f32_16x16x32_bf16 v[26:29], v[160:163], v[200:203], v[26:29]
	v_mfma_f32_16x16x32_bf16 v[10:13], v[156:159], v[204:207], 0
	v_mfma_f32_16x16x32_bf16 v[10:13], v[160:163], v[208:211], v[10:13]
	v_mfma_f32_16x16x32_bf16 v[14:17], v[148:151], v[204:207], 0
	v_mfma_f32_16x16x32_bf16 v[14:17], v[152:155], v[208:211], v[14:17]
	s_setprio 0
	s_setprio 1
	v_mfma_f32_16x16x32_bf16 v[54:57], v[164:167], v[180:183], 0
	v_mfma_f32_16x16x32_bf16 v[54:57], v[168:171], v[184:187], v[54:57]
	v_mfma_f32_16x16x32_bf16 v[50:53], v[172:175], v[180:183], 0
	v_mfma_f32_16x16x32_bf16 v[50:53], v[176:179], v[184:187], v[50:53]
	v_mfma_f32_16x16x32_bf16 v[34:37], v[172:175], v[188:191], 0
	v_mfma_f32_16x16x32_bf16 v[34:37], v[176:179], v[192:195], v[34:37]
	v_mfma_f32_16x16x32_bf16 v[38:41], v[164:167], v[188:191], 0
	v_mfma_f32_16x16x32_bf16 v[38:41], v[168:171], v[192:195], v[38:41]
	v_mfma_f32_16x16x32_bf16 v[22:25], v[164:167], v[196:199], 0
	v_mfma_f32_16x16x32_bf16 v[22:25], v[168:171], v[200:203], v[22:25]
	v_mfma_f32_16x16x32_bf16 v[18:21], v[172:175], v[196:199], 0
	v_mfma_f32_16x16x32_bf16 v[18:21], v[176:179], v[200:203], v[18:21]
	v_mfma_f32_16x16x32_bf16 v[2:5], v[172:175], v[204:207], 0
	v_mfma_f32_16x16x32_bf16 v[2:5], v[176:179], v[208:211], v[2:5]
	s_setprio 2
	s_barrier
	v_mfma_f32_16x16x32_bf16 v[6:9], v[164:167], v[204:207], 0
	v_mfma_f32_16x16x32_bf16 v[6:9], v[168:171], v[208:211], v[6:9]
	s_setprio 0
	ds_read_b128 v[148:151], v146
	ds_read_b128 v[152:155], v146 offset:1024
	ds_read_b128 v[156:159], v146 offset:2048
	ds_read_b128 v[160:163], v146 offset:3072
	ds_read_b128 v[164:167], v147
	ds_read_b128 v[168:171], v147 offset:1024
	ds_read_b128 v[172:175], v147 offset:2048
	ds_read_b128 v[176:179], v147 offset:3072
	ds_read_b128 v[180:183], v145 offset:32768
	ds_read_b128 v[184:187], v145 offset:33792
	ds_read_b128 v[188:191], v145 offset:34816
	ds_read_b128 v[192:195], v145 offset:35840
	ds_read_b128 v[196:199], v145 offset:36864
	ds_read_b128 v[200:203], v145 offset:37888
	ds_read_b128 v[204:207], v145 offset:38912
	ds_read_b128 v[208:211], v145 offset:39936
	s_mov_b32 s78, m0
	s_mov_b32 m0, s31
	s_nop 0
	global_load_lds_dwordx4 v138, s[22:23]
	s_mov_b32 m0, s78
	s_nop 0
	s_mov_b32 s78, m0
	s_mov_b32 m0, s41
	s_nop 0
	global_load_lds_dwordx4 v140, s[22:23]
	s_mov_b32 m0, s78
	s_add_u32 s22, s22, 0x80000
	s_addc_u32 s23, s23, 0
	s_mov_b32 s78, m0
	s_mov_b32 m0, s42
	s_nop 0
	global_load_lds_dwordx4 v138, s[22:23]
	s_mov_b32 m0, s78
	s_nop 0
	s_mov_b32 s78, m0
	s_mov_b32 m0, s43
	s_nop 0
	global_load_lds_dwordx4 v140, s[22:23]
	s_mov_b32 m0, s78
	s_waitcnt vmcnt(8)
	s_waitcnt lgkmcnt(0)
	s_barrier
	s_setprio 1
	.p2align 3
	v_mfma_f32_16x16x32_bf16 v[126:129], v[148:151], v[180:183], v[126:129]
	v_mfma_f32_16x16x32_bf16 v[126:129], v[152:155], v[184:187], v[126:129]
	v_mfma_f32_16x16x32_bf16 v[122:125], v[156:159], v[180:183], v[122:125]
	v_mfma_f32_16x16x32_bf16 v[122:125], v[160:163], v[184:187], v[122:125]
	v_mfma_f32_16x16x32_bf16 v[106:109], v[156:159], v[188:191], v[106:109]
	v_mfma_f32_16x16x32_bf16 v[106:109], v[160:163], v[192:195], v[106:109]
	v_mfma_f32_16x16x32_bf16 v[110:113], v[148:151], v[188:191], v[110:113]
	v_mfma_f32_16x16x32_bf16 v[110:113], v[152:155], v[192:195], v[110:113]
	v_mfma_f32_16x16x32_bf16 v[94:97], v[148:151], v[196:199], v[94:97]
	v_mfma_f32_16x16x32_bf16 v[94:97], v[152:155], v[200:203], v[94:97]
	v_mfma_f32_16x16x32_bf16 v[90:93], v[156:159], v[196:199], v[90:93]
	v_mfma_f32_16x16x32_bf16 v[90:93], v[160:163], v[200:203], v[90:93]
	v_mfma_f32_16x16x32_bf16 v[74:77], v[156:159], v[204:207], v[74:77]
	v_mfma_f32_16x16x32_bf16 v[74:77], v[160:163], v[208:211], v[74:77]
	v_mfma_f32_16x16x32_bf16 v[78:81], v[148:151], v[204:207], v[78:81]
	v_mfma_f32_16x16x32_bf16 v[78:81], v[152:155], v[208:211], v[78:81]
	s_setprio 0
	s_setprio 1
	v_mfma_f32_16x16x32_bf16 v[118:121], v[164:167], v[180:183], v[118:121]
	v_mfma_f32_16x16x32_bf16 v[118:121], v[168:171], v[184:187], v[118:121]
	v_mfma_f32_16x16x32_bf16 v[114:117], v[172:175], v[180:183], v[114:117]
	v_mfma_f32_16x16x32_bf16 v[114:117], v[176:179], v[184:187], v[114:117]
	v_mfma_f32_16x16x32_bf16 v[98:101], v[172:175], v[188:191], v[98:101]
	v_mfma_f32_16x16x32_bf16 v[98:101], v[176:179], v[192:195], v[98:101]
	v_mfma_f32_16x16x32_bf16 v[102:105], v[164:167], v[188:191], v[102:105]
	v_mfma_f32_16x16x32_bf16 v[102:105], v[168:171], v[192:195], v[102:105]
	v_mfma_f32_16x16x32_bf16 v[86:89], v[164:167], v[196:199], v[86:89]
	v_mfma_f32_16x16x32_bf16 v[86:89], v[168:171], v[200:203], v[86:89]
	v_mfma_f32_16x16x32_bf16 v[82:85], v[172:175], v[196:199], v[82:85]
	v_mfma_f32_16x16x32_bf16 v[82:85], v[176:179], v[200:203], v[82:85]
	v_mfma_f32_16x16x32_bf16 v[66:69], v[172:175], v[204:207], v[66:69]
	v_mfma_f32_16x16x32_bf16 v[66:69], v[176:179], v[208:211], v[66:69]
	s_setprio 2
	s_barrier
	v_mfma_f32_16x16x32_bf16 v[70:73], v[164:167], v[204:207], v[70:73]
	v_mfma_f32_16x16x32_bf16 v[70:73], v[168:171], v[208:211], v[70:73]
	s_setprio 0
	ds_read_b128 v[180:183], v145 offset:49152
	ds_read_b128 v[184:187], v145 offset:50176
	ds_read_b128 v[188:191], v145 offset:51200
	ds_read_b128 v[192:195], v145 offset:52224
	ds_read_b128 v[196:199], v145 offset:53248
	ds_read_b128 v[200:203], v145 offset:54272
	ds_read_b128 v[204:207], v145 offset:55296
	ds_read_b128 v[208:211], v145 offset:56320
	s_add_u32 s22, s20, 0x80
	s_addc_u32 s23, s21, 0
	s_mov_b32 s78, m0
	s_mov_b32 m0, s46
	s_nop 0
	global_load_lds_dwordx4 v139, s[22:23]
	s_mov_b32 m0, s78
	s_add_u32 s20, s20, 0x80080
	s_mov_b32 s78, m0
	s_mov_b32 m0, s47
	s_nop 0
	global_load_lds_dwordx4 v141, s[22:23]
	s_mov_b32 m0, s78
	s_addc_u32 s21, s21, 0
	s_mov_b32 s22, m0
	s_mov_b32 m0, s48
	s_nop 0
	global_load_lds_dwordx4 v139, s[20:21]
	s_mov_b32 m0, s22
	s_nop 0
	s_mov_b32 s22, m0
	s_mov_b32 m0, s49
	s_nop 0
	global_load_lds_dwordx4 v141, s[20:21]
	s_mov_b32 m0, s22
	s_waitcnt vmcnt(4)
	s_waitcnt lgkmcnt(0)
	s_barrier
	s_setprio 1
	.p2align 3
	v_mfma_f32_16x16x32_bf16 v[62:65], v[148:151], v[180:183], v[62:65]
	v_mfma_f32_16x16x32_bf16 v[62:65], v[152:155], v[184:187], v[62:65]
	v_mfma_f32_16x16x32_bf16 v[58:61], v[156:159], v[180:183], v[58:61]
	v_mfma_f32_16x16x32_bf16 v[58:61], v[160:163], v[184:187], v[58:61]
	v_mfma_f32_16x16x32_bf16 v[42:45], v[156:159], v[188:191], v[42:45]
	v_mfma_f32_16x16x32_bf16 v[42:45], v[160:163], v[192:195], v[42:45]
	v_mfma_f32_16x16x32_bf16 v[46:49], v[148:151], v[188:191], v[46:49]
	v_mfma_f32_16x16x32_bf16 v[46:49], v[152:155], v[192:195], v[46:49]
	v_mfma_f32_16x16x32_bf16 v[30:33], v[148:151], v[196:199], v[30:33]
	v_mfma_f32_16x16x32_bf16 v[30:33], v[152:155], v[200:203], v[30:33]
	v_mfma_f32_16x16x32_bf16 v[26:29], v[156:159], v[196:199], v[26:29]
	v_mfma_f32_16x16x32_bf16 v[26:29], v[160:163], v[200:203], v[26:29]
	v_mfma_f32_16x16x32_bf16 v[10:13], v[156:159], v[204:207], v[10:13]
	v_mfma_f32_16x16x32_bf16 v[10:13], v[160:163], v[208:211], v[10:13]
	v_mfma_f32_16x16x32_bf16 v[14:17], v[148:151], v[204:207], v[14:17]
	v_mfma_f32_16x16x32_bf16 v[14:17], v[152:155], v[208:211], v[14:17]
	s_setprio 0
	s_setprio 1
	v_mfma_f32_16x16x32_bf16 v[54:57], v[164:167], v[180:183], v[54:57]
	v_mfma_f32_16x16x32_bf16 v[54:57], v[168:171], v[184:187], v[54:57]
	v_mfma_f32_16x16x32_bf16 v[50:53], v[172:175], v[180:183], v[50:53]
	v_mfma_f32_16x16x32_bf16 v[50:53], v[176:179], v[184:187], v[50:53]
	v_mfma_f32_16x16x32_bf16 v[34:37], v[172:175], v[188:191], v[34:37]
	v_mfma_f32_16x16x32_bf16 v[34:37], v[176:179], v[192:195], v[34:37]
	v_mfma_f32_16x16x32_bf16 v[38:41], v[164:167], v[188:191], v[38:41]
	v_mfma_f32_16x16x32_bf16 v[38:41], v[168:171], v[192:195], v[38:41]
	v_mfma_f32_16x16x32_bf16 v[22:25], v[164:167], v[196:199], v[22:25]
	v_mfma_f32_16x16x32_bf16 v[22:25], v[168:171], v[200:203], v[22:25]
	v_mfma_f32_16x16x32_bf16 v[18:21], v[172:175], v[196:199], v[18:21]
	v_mfma_f32_16x16x32_bf16 v[18:21], v[176:179], v[200:203], v[18:21]
	v_mfma_f32_16x16x32_bf16 v[2:5], v[172:175], v[204:207], v[2:5]
	v_mfma_f32_16x16x32_bf16 v[2:5], v[176:179], v[208:211], v[2:5]
	s_setprio 2
	s_barrier
	v_mfma_f32_16x16x32_bf16 v[6:9], v[164:167], v[204:207], v[6:9]
	v_mfma_f32_16x16x32_bf16 v[6:9], v[168:171], v[208:211], v[6:9]
	s_setprio 0
	s_add_i32 s77, s77, 2
	s_add_u32 s73, s73, 0x100
	s_addc_u32 s74, s74, 0
	s_add_u32 s18, s18, 0x100
	s_addc_u32 s19, s19, 0
	s_add_u32 s75, s75, 0x100
	s_addc_u32 s76, s76, 0
	s_cmp_gt_u32 s77, 29
	.p2align 6
.LBB0_1224:
	ds_read_b128 v[148:151], v143
	ds_read_b128 v[152:155], v143 offset:1024
	ds_read_b128 v[156:159], v143 offset:2048
	ds_read_b128 v[160:163], v143 offset:3072
	ds_read_b128 v[164:167], v144
	ds_read_b128 v[168:171], v144 offset:1024
	ds_read_b128 v[172:175], v144 offset:2048
	ds_read_b128 v[176:179], v144 offset:3072
	s_cmp_eq_u32 s77, 28
	s_cselect_b32 s21, s9, s74
	s_cselect_b32 s20, s67, s73
	s_cselect_b32 s23, s11, s76
	s_cselect_b32 s22, s66, s75
	ds_read_b128 v[180:183], v145
	ds_read_b128 v[184:187], v145 offset:1024
	ds_read_b128 v[188:191], v145 offset:2048
	ds_read_b128 v[192:195], v145 offset:3072
	ds_read_b128 v[196:199], v145 offset:4096
	ds_read_b128 v[200:203], v145 offset:5120
	ds_read_b128 v[204:207], v145 offset:6144
	ds_read_b128 v[208:211], v145 offset:7168
	s_add_u32 s78, s18, 0xfff80000
	s_addc_u32 s79, s19, -1
	s_mov_b32 s80, m0
	s_mov_b32 m0, s56
	s_nop 0
	global_load_lds_dwordx4 v138, s[78:79]
	s_mov_b32 m0, s80
	s_nop 0
	s_mov_b32 s80, m0
	s_mov_b32 m0, s59
	s_nop 0
	global_load_lds_dwordx4 v140, s[78:79]
	s_mov_b32 m0, s80
	s_mov_b32 s78, m0
	s_mov_b32 m0, s57
	s_nop 0
	global_load_lds_dwordx4 v138, s[18:19]
	s_mov_b32 m0, s78
	s_nop 0
	s_mov_b32 s78, m0
	s_mov_b32 m0, s64
	s_nop 0
	global_load_lds_dwordx4 v140, s[18:19]
	s_mov_b32 m0, s78
	s_waitcnt vmcnt(8)
	s_waitcnt lgkmcnt(0)
	s_barrier
	s_setprio 1
	.p2align 3
	v_mfma_f32_16x16x32_bf16 v[126:129], v[148:151], v[180:183], v[126:129]
	v_mfma_f32_16x16x32_bf16 v[126:129], v[152:155], v[184:187], v[126:129]
	v_mfma_f32_16x16x32_bf16 v[122:125], v[156:159], v[180:183], v[122:125]
	v_mfma_f32_16x16x32_bf16 v[122:125], v[160:163], v[184:187], v[122:125]
	v_mfma_f32_16x16x32_bf16 v[106:109], v[156:159], v[188:191], v[106:109]
	v_mfma_f32_16x16x32_bf16 v[106:109], v[160:163], v[192:195], v[106:109]
	v_mfma_f32_16x16x32_bf16 v[110:113], v[148:151], v[188:191], v[110:113]
	v_mfma_f32_16x16x32_bf16 v[110:113], v[152:155], v[192:195], v[110:113]
	v_mfma_f32_16x16x32_bf16 v[94:97], v[148:151], v[196:199], v[94:97]
	v_mfma_f32_16x16x32_bf16 v[94:97], v[152:155], v[200:203], v[94:97]
	v_mfma_f32_16x16x32_bf16 v[90:93], v[156:159], v[196:199], v[90:93]
	v_mfma_f32_16x16x32_bf16 v[90:93], v[160:163], v[200:203], v[90:93]
	v_mfma_f32_16x16x32_bf16 v[74:77], v[156:159], v[204:207], v[74:77]
	v_mfma_f32_16x16x32_bf16 v[74:77], v[160:163], v[208:211], v[74:77]
	v_mfma_f32_16x16x32_bf16 v[78:81], v[148:151], v[204:207], v[78:81]
	v_mfma_f32_16x16x32_bf16 v[78:81], v[152:155], v[208:211], v[78:81]
	s_setprio 0
	s_setprio 1
	v_mfma_f32_16x16x32_bf16 v[118:121], v[164:167], v[180:183], v[118:121]
	v_mfma_f32_16x16x32_bf16 v[118:121], v[168:171], v[184:187], v[118:121]
	v_mfma_f32_16x16x32_bf16 v[114:117], v[172:175], v[180:183], v[114:117]
	v_mfma_f32_16x16x32_bf16 v[114:117], v[176:179], v[184:187], v[114:117]
	v_mfma_f32_16x16x32_bf16 v[98:101], v[172:175], v[188:191], v[98:101]
	v_mfma_f32_16x16x32_bf16 v[98:101], v[176:179], v[192:195], v[98:101]
	v_mfma_f32_16x16x32_bf16 v[102:105], v[164:167], v[188:191], v[102:105]
	v_mfma_f32_16x16x32_bf16 v[102:105], v[168:171], v[192:195], v[102:105]
	v_mfma_f32_16x16x32_bf16 v[86:89], v[164:167], v[196:199], v[86:89]
	v_mfma_f32_16x16x32_bf16 v[86:89], v[168:171], v[200:203], v[86:89]
	v_mfma_f32_16x16x32_bf16 v[82:85], v[172:175], v[196:199], v[82:85]
	v_mfma_f32_16x16x32_bf16 v[82:85], v[176:179], v[200:203], v[82:85]
	v_mfma_f32_16x16x32_bf16 v[66:69], v[172:175], v[204:207], v[66:69]
	v_mfma_f32_16x16x32_bf16 v[66:69], v[176:179], v[208:211], v[66:69]
	s_setprio 2
	s_barrier
	v_mfma_f32_16x16x32_bf16 v[70:73], v[164:167], v[204:207], v[70:73]
	v_mfma_f32_16x16x32_bf16 v[70:73], v[168:171], v[208:211], v[70:73]
	s_setprio 0
	ds_read_b128 v[180:183], v145 offset:16384
	ds_read_b128 v[184:187], v145 offset:17408
	ds_read_b128 v[188:191], v145 offset:18432
	ds_read_b128 v[192:195], v145 offset:19456
	ds_read_b128 v[196:199], v145 offset:20480
	ds_read_b128 v[200:203], v145 offset:21504
	ds_read_b128 v[204:207], v145 offset:22528
	ds_read_b128 v[208:211], v145 offset:23552
	s_mov_b32 s78, m0
	s_mov_b32 m0, s35
	s_nop 0
	global_load_lds_dwordx4 v139, s[20:21]
	s_mov_b32 m0, s78
	s_nop 0
	s_mov_b32 s78, m0
	s_mov_b32 m0, s36
	s_nop 0
	global_load_lds_dwordx4 v141, s[20:21]
	s_mov_b32 m0, s78
	s_add_u32 s78, s20, 0x80000
	s_addc_u32 s79, s21, 0
	s_mov_b32 s80, m0
	s_mov_b32 m0, s37
	s_nop 0
	global_load_lds_dwordx4 v139, s[78:79]
	s_mov_b32 m0, s80
	s_nop 0
	s_mov_b32 s80, m0
	s_mov_b32 m0, s40
	s_nop 0
	global_load_lds_dwordx4 v141, s[78:79]
	s_mov_b32 m0, s80
	s_waitcnt vmcnt(4)
	s_waitcnt lgkmcnt(0)
	s_barrier
	s_setprio 1
	.p2align 3
	v_mfma_f32_16x16x32_bf16 v[62:65], v[148:151], v[180:183], v[62:65]
	v_mfma_f32_16x16x32_bf16 v[62:65], v[152:155], v[184:187], v[62:65]
	v_mfma_f32_16x16x32_bf16 v[58:61], v[156:159], v[180:183], v[58:61]
	v_mfma_f32_16x16x32_bf16 v[58:61], v[160:163], v[184:187], v[58:61]
	v_mfma_f32_16x16x32_bf16 v[42:45], v[156:159], v[188:191], v[42:45]
	v_mfma_f32_16x16x32_bf16 v[42:45], v[160:163], v[192:195], v[42:45]
	v_mfma_f32_16x16x32_bf16 v[46:49], v[148:151], v[188:191], v[46:49]
	v_mfma_f32_16x16x32_bf16 v[46:49], v[152:155], v[192:195], v[46:49]
	v_mfma_f32_16x16x32_bf16 v[30:33], v[148:151], v[196:199], v[30:33]
	v_mfma_f32_16x16x32_bf16 v[30:33], v[152:155], v[200:203], v[30:33]
	v_mfma_f32_16x16x32_bf16 v[26:29], v[156:159], v[196:199], v[26:29]
	v_mfma_f32_16x16x32_bf16 v[26:29], v[160:163], v[200:203], v[26:29]
	v_mfma_f32_16x16x32_bf16 v[10:13], v[156:159], v[204:207], v[10:13]
	v_mfma_f32_16x16x32_bf16 v[10:13], v[160:163], v[208:211], v[10:13]
	v_mfma_f32_16x16x32_bf16 v[14:17], v[148:151], v[204:207], v[14:17]
	v_mfma_f32_16x16x32_bf16 v[14:17], v[152:155], v[208:211], v[14:17]
	s_setprio 0
	s_setprio 1
	v_mfma_f32_16x16x32_bf16 v[54:57], v[164:167], v[180:183], v[54:57]
	v_mfma_f32_16x16x32_bf16 v[54:57], v[168:171], v[184:187], v[54:57]
	v_mfma_f32_16x16x32_bf16 v[50:53], v[172:175], v[180:183], v[50:53]
	v_mfma_f32_16x16x32_bf16 v[50:53], v[176:179], v[184:187], v[50:53]
	v_mfma_f32_16x16x32_bf16 v[34:37], v[172:175], v[188:191], v[34:37]
	v_mfma_f32_16x16x32_bf16 v[34:37], v[176:179], v[192:195], v[34:37]
	v_mfma_f32_16x16x32_bf16 v[38:41], v[164:167], v[188:191], v[38:41]
	v_mfma_f32_16x16x32_bf16 v[38:41], v[168:171], v[192:195], v[38:41]
	v_mfma_f32_16x16x32_bf16 v[22:25], v[164:167], v[196:199], v[22:25]
	v_mfma_f32_16x16x32_bf16 v[22:25], v[168:171], v[200:203], v[22:25]
	v_mfma_f32_16x16x32_bf16 v[18:21], v[172:175], v[196:199], v[18:21]
	v_mfma_f32_16x16x32_bf16 v[18:21], v[176:179], v[200:203], v[18:21]
	v_mfma_f32_16x16x32_bf16 v[2:5], v[172:175], v[204:207], v[2:5]
	v_mfma_f32_16x16x32_bf16 v[2:5], v[176:179], v[208:211], v[2:5]
	s_setprio 2
	s_barrier
	v_mfma_f32_16x16x32_bf16 v[6:9], v[164:167], v[204:207], v[6:9]
	v_mfma_f32_16x16x32_bf16 v[6:9], v[168:171], v[208:211], v[6:9]
	s_setprio 0
	ds_read_b128 v[148:151], v146
	ds_read_b128 v[152:155], v146 offset:1024
	ds_read_b128 v[156:159], v146 offset:2048
	ds_read_b128 v[160:163], v146 offset:3072
	ds_read_b128 v[164:167], v147
	ds_read_b128 v[168:171], v147 offset:1024
	ds_read_b128 v[172:175], v147 offset:2048
	ds_read_b128 v[176:179], v147 offset:3072
	ds_read_b128 v[180:183], v145 offset:32768
	ds_read_b128 v[184:187], v145 offset:33792
	ds_read_b128 v[188:191], v145 offset:34816
	ds_read_b128 v[192:195], v145 offset:35840
	ds_read_b128 v[196:199], v145 offset:36864
	ds_read_b128 v[200:203], v145 offset:37888
	ds_read_b128 v[204:207], v145 offset:38912
	ds_read_b128 v[208:211], v145 offset:39936
	s_mov_b32 s78, m0
	s_mov_b32 m0, s31
	s_nop 0
	global_load_lds_dwordx4 v138, s[22:23]
	s_mov_b32 m0, s78
	s_nop 0
	s_mov_b32 s78, m0
	s_mov_b32 m0, s41
	s_nop 0
	global_load_lds_dwordx4 v140, s[22:23]
	s_mov_b32 m0, s78
	s_add_u32 s22, s22, 0x80000
	s_addc_u32 s23, s23, 0
	s_mov_b32 s78, m0
	s_mov_b32 m0, s42
	s_nop 0
	global_load_lds_dwordx4 v138, s[22:23]
	s_mov_b32 m0, s78
	s_nop 0
	s_mov_b32 s78, m0
	s_mov_b32 m0, s43
	s_nop 0
	global_load_lds_dwordx4 v140, s[22:23]
	s_mov_b32 m0, s78
	s_waitcnt vmcnt(8)
	s_waitcnt lgkmcnt(0)
	s_barrier
	s_setprio 1
	.p2align 3
	v_mfma_f32_16x16x32_bf16 v[126:129], v[148:151], v[180:183], v[126:129]
	v_mfma_f32_16x16x32_bf16 v[126:129], v[152:155], v[184:187], v[126:129]
	v_mfma_f32_16x16x32_bf16 v[122:125], v[156:159], v[180:183], v[122:125]
	v_mfma_f32_16x16x32_bf16 v[122:125], v[160:163], v[184:187], v[122:125]
	v_mfma_f32_16x16x32_bf16 v[106:109], v[156:159], v[188:191], v[106:109]
	v_mfma_f32_16x16x32_bf16 v[106:109], v[160:163], v[192:195], v[106:109]
	v_mfma_f32_16x16x32_bf16 v[110:113], v[148:151], v[188:191], v[110:113]
	v_mfma_f32_16x16x32_bf16 v[110:113], v[152:155], v[192:195], v[110:113]
	v_mfma_f32_16x16x32_bf16 v[94:97], v[148:151], v[196:199], v[94:97]
	v_mfma_f32_16x16x32_bf16 v[94:97], v[152:155], v[200:203], v[94:97]
	v_mfma_f32_16x16x32_bf16 v[90:93], v[156:159], v[196:199], v[90:93]
	v_mfma_f32_16x16x32_bf16 v[90:93], v[160:163], v[200:203], v[90:93]
	v_mfma_f32_16x16x32_bf16 v[74:77], v[156:159], v[204:207], v[74:77]
	v_mfma_f32_16x16x32_bf16 v[74:77], v[160:163], v[208:211], v[74:77]
	v_mfma_f32_16x16x32_bf16 v[78:81], v[148:151], v[204:207], v[78:81]
	v_mfma_f32_16x16x32_bf16 v[78:81], v[152:155], v[208:211], v[78:81]
	s_setprio 0
	s_setprio 1
	v_mfma_f32_16x16x32_bf16 v[118:121], v[164:167], v[180:183], v[118:121]
	v_mfma_f32_16x16x32_bf16 v[118:121], v[168:171], v[184:187], v[118:121]
	v_mfma_f32_16x16x32_bf16 v[114:117], v[172:175], v[180:183], v[114:117]
	v_mfma_f32_16x16x32_bf16 v[114:117], v[176:179], v[184:187], v[114:117]
	v_mfma_f32_16x16x32_bf16 v[98:101], v[172:175], v[188:191], v[98:101]
	v_mfma_f32_16x16x32_bf16 v[98:101], v[176:179], v[192:195], v[98:101]
	v_mfma_f32_16x16x32_bf16 v[102:105], v[164:167], v[188:191], v[102:105]
	v_mfma_f32_16x16x32_bf16 v[102:105], v[168:171], v[192:195], v[102:105]
	v_mfma_f32_16x16x32_bf16 v[86:89], v[164:167], v[196:199], v[86:89]
	v_mfma_f32_16x16x32_bf16 v[86:89], v[168:171], v[200:203], v[86:89]
	v_mfma_f32_16x16x32_bf16 v[82:85], v[172:175], v[196:199], v[82:85]
	v_mfma_f32_16x16x32_bf16 v[82:85], v[176:179], v[200:203], v[82:85]
	v_mfma_f32_16x16x32_bf16 v[66:69], v[172:175], v[204:207], v[66:69]
	v_mfma_f32_16x16x32_bf16 v[66:69], v[176:179], v[208:211], v[66:69]
	s_setprio 2
	s_barrier
	v_mfma_f32_16x16x32_bf16 v[70:73], v[164:167], v[204:207], v[70:73]
	v_mfma_f32_16x16x32_bf16 v[70:73], v[168:171], v[208:211], v[70:73]
	s_setprio 0
	ds_read_b128 v[180:183], v145 offset:49152
	ds_read_b128 v[184:187], v145 offset:50176
	ds_read_b128 v[188:191], v145 offset:51200
	ds_read_b128 v[192:195], v145 offset:52224
	ds_read_b128 v[196:199], v145 offset:53248
	ds_read_b128 v[200:203], v145 offset:54272
	ds_read_b128 v[204:207], v145 offset:55296
	ds_read_b128 v[208:211], v145 offset:56320
	s_add_u32 s22, s20, 0x80
	s_addc_u32 s23, s21, 0
	s_mov_b32 s78, m0
	s_mov_b32 m0, s46
	s_nop 0
	global_load_lds_dwordx4 v139, s[22:23]
	s_mov_b32 m0, s78
	s_add_u32 s20, s20, 0x80080
	s_mov_b32 s78, m0
	s_mov_b32 m0, s47
	s_nop 0
	global_load_lds_dwordx4 v141, s[22:23]
	s_mov_b32 m0, s78
	s_addc_u32 s21, s21, 0
	s_mov_b32 s22, m0
	s_mov_b32 m0, s48
	s_nop 0
	global_load_lds_dwordx4 v139, s[20:21]
	s_mov_b32 m0, s22
	s_nop 0
	s_mov_b32 s22, m0
	s_mov_b32 m0, s49
	s_nop 0
	global_load_lds_dwordx4 v141, s[20:21]
	s_mov_b32 m0, s22
	s_waitcnt vmcnt(4)
	s_waitcnt lgkmcnt(0)
	s_barrier
	s_setprio 1
	.p2align 3
	v_mfma_f32_16x16x32_bf16 v[62:65], v[148:151], v[180:183], v[62:65]
	v_mfma_f32_16x16x32_bf16 v[62:65], v[152:155], v[184:187], v[62:65]
	v_mfma_f32_16x16x32_bf16 v[58:61], v[156:159], v[180:183], v[58:61]
	v_mfma_f32_16x16x32_bf16 v[58:61], v[160:163], v[184:187], v[58:61]
	v_mfma_f32_16x16x32_bf16 v[42:45], v[156:159], v[188:191], v[42:45]
	v_mfma_f32_16x16x32_bf16 v[42:45], v[160:163], v[192:195], v[42:45]
	v_mfma_f32_16x16x32_bf16 v[46:49], v[148:151], v[188:191], v[46:49]
	v_mfma_f32_16x16x32_bf16 v[46:49], v[152:155], v[192:195], v[46:49]
	v_mfma_f32_16x16x32_bf16 v[30:33], v[148:151], v[196:199], v[30:33]
	v_mfma_f32_16x16x32_bf16 v[30:33], v[152:155], v[200:203], v[30:33]
	v_mfma_f32_16x16x32_bf16 v[26:29], v[156:159], v[196:199], v[26:29]
	v_mfma_f32_16x16x32_bf16 v[26:29], v[160:163], v[200:203], v[26:29]
	v_mfma_f32_16x16x32_bf16 v[10:13], v[156:159], v[204:207], v[10:13]
	v_mfma_f32_16x16x32_bf16 v[10:13], v[160:163], v[208:211], v[10:13]
	v_mfma_f32_16x16x32_bf16 v[14:17], v[148:151], v[204:207], v[14:17]
	v_mfma_f32_16x16x32_bf16 v[14:17], v[152:155], v[208:211], v[14:17]
	s_setprio 0
	s_setprio 1
	v_mfma_f32_16x16x32_bf16 v[54:57], v[164:167], v[180:183], v[54:57]
	v_mfma_f32_16x16x32_bf16 v[54:57], v[168:171], v[184:187], v[54:57]
	v_mfma_f32_16x16x32_bf16 v[50:53], v[172:175], v[180:183], v[50:53]
	v_mfma_f32_16x16x32_bf16 v[50:53], v[176:179], v[184:187], v[50:53]
	v_mfma_f32_16x16x32_bf16 v[34:37], v[172:175], v[188:191], v[34:37]
	v_mfma_f32_16x16x32_bf16 v[34:37], v[176:179], v[192:195], v[34:37]
	v_mfma_f32_16x16x32_bf16 v[38:41], v[164:167], v[188:191], v[38:41]
	v_mfma_f32_16x16x32_bf16 v[38:41], v[168:171], v[192:195], v[38:41]
	v_mfma_f32_16x16x32_bf16 v[22:25], v[164:167], v[196:199], v[22:25]
	v_mfma_f32_16x16x32_bf16 v[22:25], v[168:171], v[200:203], v[22:25]
	v_mfma_f32_16x16x32_bf16 v[18:21], v[172:175], v[196:199], v[18:21]
	v_mfma_f32_16x16x32_bf16 v[18:21], v[176:179], v[200:203], v[18:21]
	v_mfma_f32_16x16x32_bf16 v[2:5], v[172:175], v[204:207], v[2:5]
	v_mfma_f32_16x16x32_bf16 v[2:5], v[176:179], v[208:211], v[2:5]
	s_setprio 2
	s_barrier
	v_mfma_f32_16x16x32_bf16 v[6:9], v[164:167], v[204:207], v[6:9]
	v_mfma_f32_16x16x32_bf16 v[6:9], v[168:171], v[208:211], v[6:9]
	s_setprio 0
	s_add_i32 s77, s77, 2
	s_add_u32 s73, s73, 0x100
	s_addc_u32 s74, s74, 0
	s_add_u32 s18, s18, 0x100
	s_addc_u32 s19, s19, 0
	s_add_u32 s75, s75, 0x100
	s_addc_u32 s76, s76, 0
	s_cmp_gt_u32 s77, 29
	s_cbranch_scc0 .LBB0_1224
	s_and_b64 vcc, exec, s[6:7]
	s_cbranch_vccz .LBB0_1227
	s_barrier

.LBB0_1356:
	s_ashr_i32 s13, s12, 31
	s_lshl_b64 s[14:15], s[12:13], 15
	s_add_u32 s14, s28, s14
	s_addc_u32 s15, s29, s15
	s_and_b64 s[16:17], s[2:3], exec
	s_cselect_b32 s13, s15, s23
	s_cselect_b32 s67, s14, s22
	s_ashr_i32 s11, s10, 31
	s_lshl_b64 s[16:17], s[10:11], 15
	s_add_u32 s16, s30, s16
	s_addc_u32 s17, s31, s17
	s_and_b64 s[24:25], s[2:3], exec
	s_cselect_b32 s11, s17, s21
	s_cselect_b32 s73, s16, s20
	s_add_u32 s74, s20, 0x80000
	s_addc_u32 s75, s21, 0
	s_add_u32 s20, s22, 0x204000
	s_addc_u32 s21, s23, 0
	s_add_u32 s76, s22, 0x400000
	s_addc_u32 s77, s23, 0
	s_mov_b32 s78, -2
	s_waitcnt vmcnt(25)
	s_waitcnt vmcnt(24)
	s_waitcnt vmcnt(15)
	s_waitcnt vmcnt(14)
	s_waitcnt vmcnt(13)
	s_waitcnt vmcnt(12)
	s_waitcnt vmcnt(11)
	s_waitcnt vmcnt(10)
	s_waitcnt vmcnt(9)
	s_waitcnt vmcnt(8)
	s_waitcnt vmcnt(7)
	s_waitcnt vmcnt(6)
	s_waitcnt vmcnt(5)
	s_waitcnt vmcnt(4)
	s_waitcnt vmcnt(3)
	s_waitcnt vmcnt(2)
	s_waitcnt vmcnt(1)
	s_waitcnt vmcnt(0)
	ds_read_b128 v[130:133], v181
	ds_read_b128 v[134:137], v181 offset:1024
	ds_read_b128 v[138:141], v181 offset:2048
	ds_read_b128 v[142:145], v181 offset:3072
	ds_read_b128 v[150:153], v182
	ds_read_b128 v[154:157], v182 offset:1024
	ds_read_b128 v[158:161], v182 offset:2048
	ds_read_b128 v[162:165], v182 offset:3072
	s_cmpk_eq_i32 s78, 0x52
	s_cselect_b32 s23, s11, s75
	s_cselect_b32 s22, s73, s74
	s_cselect_b32 s25, s13, s77
	s_cselect_b32 s24, s67, s76
	ds_read_b128 v[166:169], v183
	ds_read_b128 v[170:173], v183 offset:1024
	ds_read_b128 v[186:189], v183 offset:2048
	ds_read_b128 v[190:193], v183 offset:3072
	ds_read_b128 v[194:197], v183 offset:4096
	ds_read_b128 v[198:201], v183 offset:5120
	ds_read_b128 v[202:205], v183 offset:6144
	ds_read_b128 v[206:209], v183 offset:7168
	s_add_u32 s80, s20, 0xffffc000
	s_addc_u32 s81, s21, -1
	s_mov_b32 s79, m0
	s_mov_b32 m0, s58
	s_nop 0
	global_load_lds_dwordx4 v1, s[80:81]
	s_mov_b32 m0, s79
	s_nop 0
	s_mov_b32 s79, m0
	s_mov_b32 m0, s64
	s_nop 0
	global_load_lds_dwordx4 v177, s[80:81]
	s_mov_b32 m0, s79
	s_nop 0
	s_mov_b32 s79, m0
	s_mov_b32 m0, s59
	s_nop 0
	global_load_lds_dwordx4 v1, s[20:21]
	s_mov_b32 m0, s79
	s_nop 0
	s_mov_b32 s79, m0
	s_mov_b32 m0, s65
	s_nop 0
	global_load_lds_dwordx4 v177, s[20:21]
	s_mov_b32 m0, s79
	s_waitcnt vmcnt(8)
	s_waitcnt lgkmcnt(0)
	s_barrier
	s_setprio 1
	.p2align 3
	v_mfma_f32_16x16x32_bf16 v[126:129], v[130:133], v[166:169], 0
	v_mfma_f32_16x16x32_bf16 v[126:129], v[134:137], v[170:173], v[126:129]
	v_mfma_f32_16x16x32_bf16 v[122:125], v[138:141], v[166:169], 0
	v_mfma_f32_16x16x32_bf16 v[122:125], v[142:145], v[170:173], v[122:125]
	v_mfma_f32_16x16x32_bf16 v[110:113], v[138:141], v[186:189], 0
	v_mfma_f32_16x16x32_bf16 v[110:113], v[142:145], v[190:193], v[110:113]
	v_mfma_f32_16x16x32_bf16 v[118:121], v[130:133], v[186:189], 0
	v_mfma_f32_16x16x32_bf16 v[118:121], v[134:137], v[190:193], v[118:121]
	v_mfma_f32_16x16x32_bf16 v[94:97], v[130:133], v[194:197], 0
	v_mfma_f32_16x16x32_bf16 v[94:97], v[134:137], v[198:201], v[94:97]
	v_mfma_f32_16x16x32_bf16 v[90:93], v[138:141], v[194:197], 0
	v_mfma_f32_16x16x32_bf16 v[90:93], v[142:145], v[198:201], v[90:93]
	v_mfma_f32_16x16x32_bf16 v[78:81], v[138:141], v[202:205], 0
	v_mfma_f32_16x16x32_bf16 v[78:81], v[142:145], v[206:209], v[78:81]
	v_mfma_f32_16x16x32_bf16 v[86:89], v[130:133], v[202:205], 0
	v_mfma_f32_16x16x32_bf16 v[86:89], v[134:137], v[206:209], v[86:89]
	s_setprio 0
	s_setprio 1
	v_mfma_f32_16x16x32_bf16 v[114:117], v[150:153], v[166:169], 0
	v_mfma_f32_16x16x32_bf16 v[114:117], v[154:157], v[170:173], v[114:117]
	v_mfma_f32_16x16x32_bf16 v[106:109], v[158:161], v[166:169], 0
	v_mfma_f32_16x16x32_bf16 v[106:109], v[162:165], v[170:173], v[106:109]
	v_mfma_f32_16x16x32_bf16 v[98:101], v[158:161], v[186:189], 0
	v_mfma_f32_16x16x32_bf16 v[98:101], v[162:165], v[190:193], v[98:101]
	v_mfma_f32_16x16x32_bf16 v[102:105], v[150:153], v[186:189], 0
	v_mfma_f32_16x16x32_bf16 v[102:105], v[154:157], v[190:193], v[102:105]
	v_mfma_f32_16x16x32_bf16 v[82:85], v[150:153], v[194:197], 0
	v_mfma_f32_16x16x32_bf16 v[82:85], v[154:157], v[198:201], v[82:85]
	v_mfma_f32_16x16x32_bf16 v[74:77], v[158:161], v[194:197], 0
	v_mfma_f32_16x16x32_bf16 v[74:77], v[162:165], v[198:201], v[74:77]
	v_mfma_f32_16x16x32_bf16 v[66:69], v[158:161], v[202:205], 0
	v_mfma_f32_16x16x32_bf16 v[66:69], v[162:165], v[206:209], v[66:69]
	s_setprio 2
	s_barrier
	v_mfma_f32_16x16x32_bf16 v[70:73], v[150:153], v[202:205], 0
	v_mfma_f32_16x16x32_bf16 v[70:73], v[154:157], v[206:209], v[70:73]
	s_setprio 0
	ds_read_b128 v[166:169], v183 offset:16384
	ds_read_b128 v[170:173], v183 offset:17408
	ds_read_b128 v[186:189], v183 offset:18432
	ds_read_b128 v[190:193], v183 offset:19456
	ds_read_b128 v[194:197], v183 offset:20480
	ds_read_b128 v[198:201], v183 offset:21504
	ds_read_b128 v[202:205], v183 offset:22528
	ds_read_b128 v[206:209], v183 offset:23552
	s_mov_b32 s79, m0
	s_mov_b32 m0, s35
	s_nop 0
	global_load_lds_dwordx4 v176, s[22:23]
	s_mov_b32 m0, s79
	s_add_u32 s80, s22, 0x4000
	s_mov_b32 s79, m0
	s_mov_b32 m0, s36
	s_nop 0
	global_load_lds_dwordx4 v178, s[22:23]
	s_mov_b32 m0, s79
	s_addc_u32 s81, s23, 0
	s_mov_b32 s79, m0
	s_mov_b32 m0, s37
	s_nop 0
	global_load_lds_dwordx4 v176, s[80:81]
	s_mov_b32 m0, s79
	s_nop 0
	s_mov_b32 s79, m0
	s_mov_b32 m0, s40
	s_nop 0
	global_load_lds_dwordx4 v178, s[80:81]
	s_mov_b32 m0, s79
	s_waitcnt vmcnt(4)
	s_waitcnt lgkmcnt(0)
	s_barrier
	s_setprio 1
	.p2align 3
	v_mfma_f32_16x16x32_bf16 v[62:65], v[130:133], v[166:169], 0
	v_mfma_f32_16x16x32_bf16 v[62:65], v[134:137], v[170:173], v[62:65]
	v_mfma_f32_16x16x32_bf16 v[58:61], v[138:141], v[166:169], 0
	v_mfma_f32_16x16x32_bf16 v[58:61], v[142:145], v[170:173], v[58:61]
	v_mfma_f32_16x16x32_bf16 v[42:45], v[138:141], v[186:189], 0
	v_mfma_f32_16x16x32_bf16 v[42:45], v[142:145], v[190:193], v[42:45]
	v_mfma_f32_16x16x32_bf16 v[46:49], v[130:133], v[186:189], 0
	v_mfma_f32_16x16x32_bf16 v[46:49], v[134:137], v[190:193], v[46:49]
	v_mfma_f32_16x16x32_bf16 v[30:33], v[130:133], v[194:197], 0
	v_mfma_f32_16x16x32_bf16 v[30:33], v[134:137], v[198:201], v[30:33]
	v_mfma_f32_16x16x32_bf16 v[26:29], v[138:141], v[194:197], 0
	v_mfma_f32_16x16x32_bf16 v[26:29], v[142:145], v[198:201], v[26:29]
	v_mfma_f32_16x16x32_bf16 v[10:13], v[138:141], v[202:205], 0
	v_mfma_f32_16x16x32_bf16 v[10:13], v[142:145], v[206:209], v[10:13]
	v_mfma_f32_16x16x32_bf16 v[14:17], v[130:133], v[202:205], 0
	v_mfma_f32_16x16x32_bf16 v[14:17], v[134:137], v[206:209], v[14:17]
	s_setprio 0
	s_setprio 1
	v_mfma_f32_16x16x32_bf16 v[54:57], v[150:153], v[166:169], 0
	v_mfma_f32_16x16x32_bf16 v[54:57], v[154:157], v[170:173], v[54:57]
	v_mfma_f32_16x16x32_bf16 v[50:53], v[158:161], v[166:169], 0
	v_mfma_f32_16x16x32_bf16 v[50:53], v[162:165], v[170:173], v[50:53]
	v_mfma_f32_16x16x32_bf16 v[34:37], v[158:161], v[186:189], 0
	v_mfma_f32_16x16x32_bf16 v[34:37], v[162:165], v[190:193], v[34:37]
	v_mfma_f32_16x16x32_bf16 v[38:41], v[150:153], v[186:189], 0
	v_mfma_f32_16x16x32_bf16 v[38:41], v[154:157], v[190:193], v[38:41]
	v_mfma_f32_16x16x32_bf16 v[22:25], v[150:153], v[194:197], 0
	v_mfma_f32_16x16x32_bf16 v[22:25], v[154:157], v[198:201], v[22:25]
	v_mfma_f32_16x16x32_bf16 v[18:21], v[158:161], v[194:197], 0
	v_mfma_f32_16x16x32_bf16 v[18:21], v[162:165], v[198:201], v[18:21]
	v_mfma_f32_16x16x32_bf16 v[2:5], v[158:161], v[202:205], 0
	v_mfma_f32_16x16x32_bf16 v[2:5], v[162:165], v[206:209], v[2:5]
	s_setprio 2
	s_barrier
	v_mfma_f32_16x16x32_bf16 v[6:9], v[150:153], v[202:205], 0
	v_mfma_f32_16x16x32_bf16 v[6:9], v[154:157], v[206:209], v[6:9]
	s_setprio 0
	ds_read_b128 v[130:133], v184
	ds_read_b128 v[134:137], v184 offset:1024
	ds_read_b128 v[138:141], v184 offset:2048
	ds_read_b128 v[142:145], v184 offset:3072
	ds_read_b128 v[150:153], v185
	ds_read_b128 v[154:157], v185 offset:1024
	ds_read_b128 v[158:161], v185 offset:2048
	ds_read_b128 v[162:165], v185 offset:3072
	ds_read_b128 v[166:169], v183 offset:32768
	ds_read_b128 v[170:173], v183 offset:33792
	ds_read_b128 v[186:189], v183 offset:34816
	ds_read_b128 v[190:193], v183 offset:35840
	ds_read_b128 v[194:197], v183 offset:36864
	ds_read_b128 v[198:201], v183 offset:37888
	ds_read_b128 v[202:205], v183 offset:38912
	ds_read_b128 v[206:209], v183 offset:39936
	s_mov_b32 s79, m0
	s_mov_b32 m0, s34
	s_nop 0
	global_load_lds_dwordx4 v1, s[24:25]
	s_mov_b32 m0, s79
	s_nop 0
	s_mov_b32 s79, m0
	s_mov_b32 m0, s41
	s_nop 0
	global_load_lds_dwordx4 v177, s[24:25]
	s_mov_b32 m0, s79
	s_add_u32 s24, s24, 0x4000
	s_addc_u32 s25, s25, 0
	s_mov_b32 s79, m0
	s_mov_b32 m0, s42
	s_nop 0
	global_load_lds_dwordx4 v1, s[24:25]
	s_mov_b32 m0, s79
	s_nop 0
	s_mov_b32 s79, m0
	s_mov_b32 m0, s43
	s_nop 0
	global_load_lds_dwordx4 v177, s[24:25]
	s_mov_b32 m0, s79
	s_waitcnt vmcnt(8)
	s_waitcnt lgkmcnt(0)
	s_barrier
	s_setprio 1
	.p2align 3
	v_mfma_f32_16x16x32_bf16 v[126:129], v[130:133], v[166:169], v[126:129]
	v_mfma_f32_16x16x32_bf16 v[126:129], v[134:137], v[170:173], v[126:129]
	v_mfma_f32_16x16x32_bf16 v[122:125], v[138:141], v[166:169], v[122:125]
	v_mfma_f32_16x16x32_bf16 v[122:125], v[142:145], v[170:173], v[122:125]
	v_mfma_f32_16x16x32_bf16 v[110:113], v[138:141], v[186:189], v[110:113]
	v_mfma_f32_16x16x32_bf16 v[110:113], v[142:145], v[190:193], v[110:113]
	v_mfma_f32_16x16x32_bf16 v[118:121], v[130:133], v[186:189], v[118:121]
	v_mfma_f32_16x16x32_bf16 v[118:121], v[134:137], v[190:193], v[118:121]
	v_mfma_f32_16x16x32_bf16 v[94:97], v[130:133], v[194:197], v[94:97]
	v_mfma_f32_16x16x32_bf16 v[94:97], v[134:137], v[198:201], v[94:97]
	v_mfma_f32_16x16x32_bf16 v[90:93], v[138:141], v[194:197], v[90:93]
	v_mfma_f32_16x16x32_bf16 v[90:93], v[142:145], v[198:201], v[90:93]
	v_mfma_f32_16x16x32_bf16 v[78:81], v[138:141], v[202:205], v[78:81]
	v_mfma_f32_16x16x32_bf16 v[78:81], v[142:145], v[206:209], v[78:81]
	v_mfma_f32_16x16x32_bf16 v[86:89], v[130:133], v[202:205], v[86:89]
	v_mfma_f32_16x16x32_bf16 v[86:89], v[134:137], v[206:209], v[86:89]
	s_setprio 0
	s_setprio 1
	v_mfma_f32_16x16x32_bf16 v[114:117], v[150:153], v[166:169], v[114:117]
	v_mfma_f32_16x16x32_bf16 v[114:117], v[154:157], v[170:173], v[114:117]
	v_mfma_f32_16x16x32_bf16 v[106:109], v[158:161], v[166:169], v[106:109]
	v_mfma_f32_16x16x32_bf16 v[106:109], v[162:165], v[170:173], v[106:109]
	v_mfma_f32_16x16x32_bf16 v[98:101], v[158:161], v[186:189], v[98:101]
	v_mfma_f32_16x16x32_bf16 v[98:101], v[162:165], v[190:193], v[98:101]
	v_mfma_f32_16x16x32_bf16 v[102:105], v[150:153], v[186:189], v[102:105]
	v_mfma_f32_16x16x32_bf16 v[102:105], v[154:157], v[190:193], v[102:105]
	v_mfma_f32_16x16x32_bf16 v[82:85], v[150:153], v[194:197], v[82:85]
	v_mfma_f32_16x16x32_bf16 v[82:85], v[154:157], v[198:201], v[82:85]
	v_mfma_f32_16x16x32_bf16 v[74:77], v[158:161], v[194:197], v[74:77]
	v_mfma_f32_16x16x32_bf16 v[74:77], v[162:165], v[198:201], v[74:77]
	v_mfma_f32_16x16x32_bf16 v[66:69], v[158:161], v[202:205], v[66:69]
	v_mfma_f32_16x16x32_bf16 v[66:69], v[162:165], v[206:209], v[66:69]
	s_setprio 2
	s_barrier
	v_mfma_f32_16x16x32_bf16 v[70:73], v[150:153], v[202:205], v[70:73]
	v_mfma_f32_16x16x32_bf16 v[70:73], v[154:157], v[206:209], v[70:73]
	s_setprio 0
	ds_read_b128 v[166:169], v183 offset:49152
	ds_read_b128 v[170:173], v183 offset:50176
	ds_read_b128 v[186:189], v183 offset:51200
	ds_read_b128 v[190:193], v183 offset:52224
	ds_read_b128 v[194:197], v183 offset:53248
	ds_read_b128 v[198:201], v183 offset:54272
	ds_read_b128 v[202:205], v183 offset:55296
	ds_read_b128 v[206:209], v183 offset:56320
	s_add_u32 s24, s22, 0x40000
	s_addc_u32 s25, s23, 0
	s_mov_b32 s79, m0
	s_mov_b32 m0, s46
	s_nop 0
	global_load_lds_dwordx4 v176, s[24:25]
	s_mov_b32 m0, s79
	s_add_u32 s22, s22, 0x44000
	s_mov_b32 s79, m0
	s_mov_b32 m0, s47
	s_nop 0
	global_load_lds_dwordx4 v178, s[24:25]
	s_mov_b32 m0, s79
	s_addc_u32 s23, s23, 0
	s_mov_b32 s24, m0
	s_mov_b32 m0, s48
	s_nop 0
	global_load_lds_dwordx4 v176, s[22:23]
	s_mov_b32 m0, s24
	s_nop 0
	s_mov_b32 s24, m0
	s_mov_b32 m0, s49
	s_nop 0
	global_load_lds_dwordx4 v178, s[22:23]
	s_mov_b32 m0, s24
	s_waitcnt vmcnt(4)
	s_waitcnt lgkmcnt(0)
	s_barrier
	s_setprio 1
	.p2align 3
	v_mfma_f32_16x16x32_bf16 v[62:65], v[130:133], v[166:169], v[62:65]
	v_mfma_f32_16x16x32_bf16 v[62:65], v[134:137], v[170:173], v[62:65]
	v_mfma_f32_16x16x32_bf16 v[58:61], v[138:141], v[166:169], v[58:61]
	v_mfma_f32_16x16x32_bf16 v[58:61], v[142:145], v[170:173], v[58:61]
	v_mfma_f32_16x16x32_bf16 v[42:45], v[138:141], v[186:189], v[42:45]
	v_mfma_f32_16x16x32_bf16 v[42:45], v[142:145], v[190:193], v[42:45]
	v_mfma_f32_16x16x32_bf16 v[46:49], v[130:133], v[186:189], v[46:49]
	v_mfma_f32_16x16x32_bf16 v[46:49], v[134:137], v[190:193], v[46:49]
	v_mfma_f32_16x16x32_bf16 v[30:33], v[130:133], v[194:197], v[30:33]
	v_mfma_f32_16x16x32_bf16 v[30:33], v[134:137], v[198:201], v[30:33]
	v_mfma_f32_16x16x32_bf16 v[26:29], v[138:141], v[194:197], v[26:29]
	v_mfma_f32_16x16x32_bf16 v[26:29], v[142:145], v[198:201], v[26:29]
	v_mfma_f32_16x16x32_bf16 v[10:13], v[138:141], v[202:205], v[10:13]
	v_mfma_f32_16x16x32_bf16 v[10:13], v[142:145], v[206:209], v[10:13]
	v_mfma_f32_16x16x32_bf16 v[14:17], v[130:133], v[202:205], v[14:17]
	v_mfma_f32_16x16x32_bf16 v[14:17], v[134:137], v[206:209], v[14:17]
	s_setprio 0
	s_setprio 1
	v_mfma_f32_16x16x32_bf16 v[54:57], v[150:153], v[166:169], v[54:57]
	v_mfma_f32_16x16x32_bf16 v[54:57], v[154:157], v[170:173], v[54:57]
	v_mfma_f32_16x16x32_bf16 v[50:53], v[158:161], v[166:169], v[50:53]
	v_mfma_f32_16x16x32_bf16 v[50:53], v[162:165], v[170:173], v[50:53]
	v_mfma_f32_16x16x32_bf16 v[34:37], v[158:161], v[186:189], v[34:37]
	v_mfma_f32_16x16x32_bf16 v[34:37], v[162:165], v[190:193], v[34:37]
	v_mfma_f32_16x16x32_bf16 v[38:41], v[150:153], v[186:189], v[38:41]
	v_mfma_f32_16x16x32_bf16 v[38:41], v[154:157], v[190:193], v[38:41]
	v_mfma_f32_16x16x32_bf16 v[22:25], v[150:153], v[194:197], v[22:25]
	v_mfma_f32_16x16x32_bf16 v[22:25], v[154:157], v[198:201], v[22:25]
	v_mfma_f32_16x16x32_bf16 v[18:21], v[158:161], v[194:197], v[18:21]
	v_mfma_f32_16x16x32_bf16 v[18:21], v[162:165], v[198:201], v[18:21]
	v_mfma_f32_16x16x32_bf16 v[2:5], v[158:161], v[202:205], v[2:5]
	v_mfma_f32_16x16x32_bf16 v[2:5], v[162:165], v[206:209], v[2:5]
	s_setprio 2
	s_barrier
	v_mfma_f32_16x16x32_bf16 v[6:9], v[150:153], v[202:205], v[6:9]
	v_mfma_f32_16x16x32_bf16 v[6:9], v[154:157], v[206:209], v[6:9]
	s_setprio 0
	s_add_i32 s78, s78, 2
	s_add_u32 s74, s74, 0x80000
	s_addc_u32 s75, s75, 0
	s_add_u32 s20, s20, 0x400000
	s_addc_u32 s21, s21, 0
	s_add_u32 s76, s76, 0x400000
	s_addc_u32 s77, s77, 0
	s_cmpk_gt_u32 s78, 0x53
	.p2align 6
.LBB0_1357:
	ds_read_b128 v[130:133], v181
	ds_read_b128 v[134:137], v181 offset:1024
	ds_read_b128 v[138:141], v181 offset:2048
	ds_read_b128 v[142:145], v181 offset:3072
	ds_read_b128 v[150:153], v182
	ds_read_b128 v[154:157], v182 offset:1024
	ds_read_b128 v[158:161], v182 offset:2048
	ds_read_b128 v[162:165], v182 offset:3072
	s_cmpk_eq_i32 s78, 0x52
	s_cselect_b32 s23, s11, s75
	s_cselect_b32 s22, s73, s74
	s_cselect_b32 s25, s13, s77
	s_cselect_b32 s24, s67, s76
	ds_read_b128 v[166:169], v183
	ds_read_b128 v[170:173], v183 offset:1024
	ds_read_b128 v[186:189], v183 offset:2048
	ds_read_b128 v[190:193], v183 offset:3072
	ds_read_b128 v[194:197], v183 offset:4096
	ds_read_b128 v[198:201], v183 offset:5120
	ds_read_b128 v[202:205], v183 offset:6144
	ds_read_b128 v[206:209], v183 offset:7168
	s_add_u32 s80, s20, 0xffffc000
	s_addc_u32 s81, s21, -1
	s_mov_b32 s79, m0
	s_mov_b32 m0, s58
	s_nop 0
	global_load_lds_dwordx4 v1, s[80:81]
	s_mov_b32 m0, s79
	s_nop 0
	s_mov_b32 s79, m0
	s_mov_b32 m0, s64
	s_nop 0
	global_load_lds_dwordx4 v177, s[80:81]
	s_mov_b32 m0, s79
	s_nop 0
	s_mov_b32 s79, m0
	s_mov_b32 m0, s59
	s_nop 0
	global_load_lds_dwordx4 v1, s[20:21]
	s_mov_b32 m0, s79
	s_nop 0
	s_mov_b32 s79, m0
	s_mov_b32 m0, s65
	s_nop 0
	global_load_lds_dwordx4 v177, s[20:21]
	s_mov_b32 m0, s79
	s_waitcnt vmcnt(8)
	s_waitcnt lgkmcnt(0)
	s_barrier
	s_setprio 1
	.p2align 3
	v_mfma_f32_16x16x32_bf16 v[126:129], v[130:133], v[166:169], v[126:129]
	v_mfma_f32_16x16x32_bf16 v[126:129], v[134:137], v[170:173], v[126:129]
	v_mfma_f32_16x16x32_bf16 v[122:125], v[138:141], v[166:169], v[122:125]
	v_mfma_f32_16x16x32_bf16 v[122:125], v[142:145], v[170:173], v[122:125]
	v_mfma_f32_16x16x32_bf16 v[110:113], v[138:141], v[186:189], v[110:113]
	v_mfma_f32_16x16x32_bf16 v[110:113], v[142:145], v[190:193], v[110:113]
	v_mfma_f32_16x16x32_bf16 v[118:121], v[130:133], v[186:189], v[118:121]
	v_mfma_f32_16x16x32_bf16 v[118:121], v[134:137], v[190:193], v[118:121]
	v_mfma_f32_16x16x32_bf16 v[94:97], v[130:133], v[194:197], v[94:97]
	v_mfma_f32_16x16x32_bf16 v[94:97], v[134:137], v[198:201], v[94:97]
	v_mfma_f32_16x16x32_bf16 v[90:93], v[138:141], v[194:197], v[90:93]
	v_mfma_f32_16x16x32_bf16 v[90:93], v[142:145], v[198:201], v[90:93]
	v_mfma_f32_16x16x32_bf16 v[78:81], v[138:141], v[202:205], v[78:81]
	v_mfma_f32_16x16x32_bf16 v[78:81], v[142:145], v[206:209], v[78:81]
	v_mfma_f32_16x16x32_bf16 v[86:89], v[130:133], v[202:205], v[86:89]
	v_mfma_f32_16x16x32_bf16 v[86:89], v[134:137], v[206:209], v[86:89]
	s_setprio 0
	s_setprio 1
	v_mfma_f32_16x16x32_bf16 v[114:117], v[150:153], v[166:169], v[114:117]
	v_mfma_f32_16x16x32_bf16 v[114:117], v[154:157], v[170:173], v[114:117]
	v_mfma_f32_16x16x32_bf16 v[106:109], v[158:161], v[166:169], v[106:109]
	v_mfma_f32_16x16x32_bf16 v[106:109], v[162:165], v[170:173], v[106:109]
	v_mfma_f32_16x16x32_bf16 v[98:101], v[158:161], v[186:189], v[98:101]
	v_mfma_f32_16x16x32_bf16 v[98:101], v[162:165], v[190:193], v[98:101]
	v_mfma_f32_16x16x32_bf16 v[102:105], v[150:153], v[186:189], v[102:105]
	v_mfma_f32_16x16x32_bf16 v[102:105], v[154:157], v[190:193], v[102:105]
	v_mfma_f32_16x16x32_bf16 v[82:85], v[150:153], v[194:197], v[82:85]
	v_mfma_f32_16x16x32_bf16 v[82:85], v[154:157], v[198:201], v[82:85]
	v_mfma_f32_16x16x32_bf16 v[74:77], v[158:161], v[194:197], v[74:77]
	v_mfma_f32_16x16x32_bf16 v[74:77], v[162:165], v[198:201], v[74:77]
	v_mfma_f32_16x16x32_bf16 v[66:69], v[158:161], v[202:205], v[66:69]
	v_mfma_f32_16x16x32_bf16 v[66:69], v[162:165], v[206:209], v[66:69]
	s_setprio 2
	s_barrier
	v_mfma_f32_16x16x32_bf16 v[70:73], v[150:153], v[202:205], v[70:73]
	v_mfma_f32_16x16x32_bf16 v[70:73], v[154:157], v[206:209], v[70:73]
	s_setprio 0
	ds_read_b128 v[166:169], v183 offset:16384
	ds_read_b128 v[170:173], v183 offset:17408
	ds_read_b128 v[186:189], v183 offset:18432
	ds_read_b128 v[190:193], v183 offset:19456
	ds_read_b128 v[194:197], v183 offset:20480
	ds_read_b128 v[198:201], v183 offset:21504
	ds_read_b128 v[202:205], v183 offset:22528
	ds_read_b128 v[206:209], v183 offset:23552
	s_mov_b32 s79, m0
	s_mov_b32 m0, s35
	s_nop 0
	global_load_lds_dwordx4 v176, s[22:23]
	s_mov_b32 m0, s79
	s_add_u32 s80, s22, 0x4000
	s_mov_b32 s79, m0
	s_mov_b32 m0, s36
	s_nop 0
	global_load_lds_dwordx4 v178, s[22:23]
	s_mov_b32 m0, s79
	s_addc_u32 s81, s23, 0
	s_mov_b32 s79, m0
	s_mov_b32 m0, s37
	s_nop 0
	global_load_lds_dwordx4 v176, s[80:81]
	s_mov_b32 m0, s79
	s_nop 0
	s_mov_b32 s79, m0
	s_mov_b32 m0, s40
	s_nop 0
	global_load_lds_dwordx4 v178, s[80:81]
	s_mov_b32 m0, s79
	s_waitcnt vmcnt(4)
	s_waitcnt lgkmcnt(0)
	s_barrier
	s_setprio 1
	.p2align 3
	v_mfma_f32_16x16x32_bf16 v[62:65], v[130:133], v[166:169], v[62:65]
	v_mfma_f32_16x16x32_bf16 v[62:65], v[134:137], v[170:173], v[62:65]
	v_mfma_f32_16x16x32_bf16 v[58:61], v[138:141], v[166:169], v[58:61]
	v_mfma_f32_16x16x32_bf16 v[58:61], v[142:145], v[170:173], v[58:61]
	v_mfma_f32_16x16x32_bf16 v[42:45], v[138:141], v[186:189], v[42:45]
	v_mfma_f32_16x16x32_bf16 v[42:45], v[142:145], v[190:193], v[42:45]
	v_mfma_f32_16x16x32_bf16 v[46:49], v[130:133], v[186:189], v[46:49]
	v_mfma_f32_16x16x32_bf16 v[46:49], v[134:137], v[190:193], v[46:49]
	v_mfma_f32_16x16x32_bf16 v[30:33], v[130:133], v[194:197], v[30:33]
	v_mfma_f32_16x16x32_bf16 v[30:33], v[134:137], v[198:201], v[30:33]
	v_mfma_f32_16x16x32_bf16 v[26:29], v[138:141], v[194:197], v[26:29]
	v_mfma_f32_16x16x32_bf16 v[26:29], v[142:145], v[198:201], v[26:29]
	v_mfma_f32_16x16x32_bf16 v[10:13], v[138:141], v[202:205], v[10:13]
	v_mfma_f32_16x16x32_bf16 v[10:13], v[142:145], v[206:209], v[10:13]
	v_mfma_f32_16x16x32_bf16 v[14:17], v[130:133], v[202:205], v[14:17]
	v_mfma_f32_16x16x32_bf16 v[14:17], v[134:137], v[206:209], v[14:17]
	s_setprio 0
	s_setprio 1
	v_mfma_f32_16x16x32_bf16 v[54:57], v[150:153], v[166:169], v[54:57]
	v_mfma_f32_16x16x32_bf16 v[54:57], v[154:157], v[170:173], v[54:57]
	v_mfma_f32_16x16x32_bf16 v[50:53], v[158:161], v[166:169], v[50:53]
	v_mfma_f32_16x16x32_bf16 v[50:53], v[162:165], v[170:173], v[50:53]
	v_mfma_f32_16x16x32_bf16 v[34:37], v[158:161], v[186:189], v[34:37]
	v_mfma_f32_16x16x32_bf16 v[34:37], v[162:165], v[190:193], v[34:37]
	v_mfma_f32_16x16x32_bf16 v[38:41], v[150:153], v[186:189], v[38:41]
	v_mfma_f32_16x16x32_bf16 v[38:41], v[154:157], v[190:193], v[38:41]
	v_mfma_f32_16x16x32_bf16 v[22:25], v[150:153], v[194:197], v[22:25]
	v_mfma_f32_16x16x32_bf16 v[22:25], v[154:157], v[198:201], v[22:25]
	v_mfma_f32_16x16x32_bf16 v[18:21], v[158:161], v[194:197], v[18:21]
	v_mfma_f32_16x16x32_bf16 v[18:21], v[162:165], v[198:201], v[18:21]
	v_mfma_f32_16x16x32_bf16 v[2:5], v[158:161], v[202:205], v[2:5]
	v_mfma_f32_16x16x32_bf16 v[2:5], v[162:165], v[206:209], v[2:5]
	s_setprio 2
	s_barrier
	v_mfma_f32_16x16x32_bf16 v[6:9], v[150:153], v[202:205], v[6:9]
	v_mfma_f32_16x16x32_bf16 v[6:9], v[154:157], v[206:209], v[6:9]
	s_setprio 0
	ds_read_b128 v[130:133], v184
	ds_read_b128 v[134:137], v184 offset:1024
	ds_read_b128 v[138:141], v184 offset:2048
	ds_read_b128 v[142:145], v184 offset:3072
	ds_read_b128 v[150:153], v185
	ds_read_b128 v[154:157], v185 offset:1024
	ds_read_b128 v[158:161], v185 offset:2048
	ds_read_b128 v[162:165], v185 offset:3072
	ds_read_b128 v[166:169], v183 offset:32768
	ds_read_b128 v[170:173], v183 offset:33792
	ds_read_b128 v[186:189], v183 offset:34816
	ds_read_b128 v[190:193], v183 offset:35840
	ds_read_b128 v[194:197], v183 offset:36864
	ds_read_b128 v[198:201], v183 offset:37888
	ds_read_b128 v[202:205], v183 offset:38912
	ds_read_b128 v[206:209], v183 offset:39936
	s_mov_b32 s79, m0
	s_mov_b32 m0, s34
	s_nop 0
	global_load_lds_dwordx4 v1, s[24:25]
	s_mov_b32 m0, s79
	s_nop 0
	s_mov_b32 s79, m0
	s_mov_b32 m0, s41
	s_nop 0
	global_load_lds_dwordx4 v177, s[24:25]
	s_mov_b32 m0, s79
	s_add_u32 s24, s24, 0x4000
	s_addc_u32 s25, s25, 0
	s_mov_b32 s79, m0
	s_mov_b32 m0, s42
	s_nop 0
	global_load_lds_dwordx4 v1, s[24:25]
	s_mov_b32 m0, s79
	s_nop 0
	s_mov_b32 s79, m0
	s_mov_b32 m0, s43
	s_nop 0
	global_load_lds_dwordx4 v177, s[24:25]
	s_mov_b32 m0, s79
	s_waitcnt vmcnt(8)
	s_waitcnt lgkmcnt(0)
	s_barrier
	s_setprio 1
	.p2align 3
	v_mfma_f32_16x16x32_bf16 v[126:129], v[130:133], v[166:169], v[126:129]
	v_mfma_f32_16x16x32_bf16 v[126:129], v[134:137], v[170:173], v[126:129]
	v_mfma_f32_16x16x32_bf16 v[122:125], v[138:141], v[166:169], v[122:125]
	v_mfma_f32_16x16x32_bf16 v[122:125], v[142:145], v[170:173], v[122:125]
	v_mfma_f32_16x16x32_bf16 v[110:113], v[138:141], v[186:189], v[110:113]
	v_mfma_f32_16x16x32_bf16 v[110:113], v[142:145], v[190:193], v[110:113]
	v_mfma_f32_16x16x32_bf16 v[118:121], v[130:133], v[186:189], v[118:121]
	v_mfma_f32_16x16x32_bf16 v[118:121], v[134:137], v[190:193], v[118:121]
	v_mfma_f32_16x16x32_bf16 v[94:97], v[130:133], v[194:197], v[94:97]
	v_mfma_f32_16x16x32_bf16 v[94:97], v[134:137], v[198:201], v[94:97]
	v_mfma_f32_16x16x32_bf16 v[90:93], v[138:141], v[194:197], v[90:93]
	v_mfma_f32_16x16x32_bf16 v[90:93], v[142:145], v[198:201], v[90:93]
	v_mfma_f32_16x16x32_bf16 v[78:81], v[138:141], v[202:205], v[78:81]
	v_mfma_f32_16x16x32_bf16 v[78:81], v[142:145], v[206:209], v[78:81]
	v_mfma_f32_16x16x32_bf16 v[86:89], v[130:133], v[202:205], v[86:89]
	v_mfma_f32_16x16x32_bf16 v[86:89], v[134:137], v[206:209], v[86:89]
	s_setprio 0
	s_setprio 1
	v_mfma_f32_16x16x32_bf16 v[114:117], v[150:153], v[166:169], v[114:117]
	v_mfma_f32_16x16x32_bf16 v[114:117], v[154:157], v[170:173], v[114:117]
	v_mfma_f32_16x16x32_bf16 v[106:109], v[158:161], v[166:169], v[106:109]
	v_mfma_f32_16x16x32_bf16 v[106:109], v[162:165], v[170:173], v[106:109]
	v_mfma_f32_16x16x32_bf16 v[98:101], v[158:161], v[186:189], v[98:101]
	v_mfma_f32_16x16x32_bf16 v[98:101], v[162:165], v[190:193], v[98:101]
	v_mfma_f32_16x16x32_bf16 v[102:105], v[150:153], v[186:189], v[102:105]
	v_mfma_f32_16x16x32_bf16 v[102:105], v[154:157], v[190:193], v[102:105]
	v_mfma_f32_16x16x32_bf16 v[82:85], v[150:153], v[194:197], v[82:85]
	v_mfma_f32_16x16x32_bf16 v[82:85], v[154:157], v[198:201], v[82:85]
	v_mfma_f32_16x16x32_bf16 v[74:77], v[158:161], v[194:197], v[74:77]
	v_mfma_f32_16x16x32_bf16 v[74:77], v[162:165], v[198:201], v[74:77]
	v_mfma_f32_16x16x32_bf16 v[66:69], v[158:161], v[202:205], v[66:69]
	v_mfma_f32_16x16x32_bf16 v[66:69], v[162:165], v[206:209], v[66:69]
	s_setprio 2
	s_barrier
	v_mfma_f32_16x16x32_bf16 v[70:73], v[150:153], v[202:205], v[70:73]
	v_mfma_f32_16x16x32_bf16 v[70:73], v[154:157], v[206:209], v[70:73]
	s_setprio 0
	ds_read_b128 v[166:169], v183 offset:49152
	ds_read_b128 v[170:173], v183 offset:50176
	ds_read_b128 v[186:189], v183 offset:51200
	ds_read_b128 v[190:193], v183 offset:52224
	ds_read_b128 v[194:197], v183 offset:53248
	ds_read_b128 v[198:201], v183 offset:54272
	ds_read_b128 v[202:205], v183 offset:55296
	ds_read_b128 v[206:209], v183 offset:56320
	s_add_u32 s24, s22, 0x40000
	s_addc_u32 s25, s23, 0
	s_mov_b32 s79, m0
	s_mov_b32 m0, s46
	s_nop 0
	global_load_lds_dwordx4 v176, s[24:25]
	s_mov_b32 m0, s79
	s_add_u32 s22, s22, 0x44000
	s_mov_b32 s79, m0
	s_mov_b32 m0, s47
	s_nop 0
	global_load_lds_dwordx4 v178, s[24:25]
	s_mov_b32 m0, s79
	s_addc_u32 s23, s23, 0
	s_mov_b32 s24, m0
	s_mov_b32 m0, s48
	s_nop 0
	global_load_lds_dwordx4 v176, s[22:23]
	s_mov_b32 m0, s24
	s_nop 0
	s_mov_b32 s24, m0
	s_mov_b32 m0, s49
	s_nop 0
	global_load_lds_dwordx4 v178, s[22:23]
	s_mov_b32 m0, s24
	s_waitcnt vmcnt(4)
	s_waitcnt lgkmcnt(0)
	s_barrier
	s_setprio 1
	.p2align 3
	v_mfma_f32_16x16x32_bf16 v[62:65], v[130:133], v[166:169], v[62:65]
	v_mfma_f32_16x16x32_bf16 v[62:65], v[134:137], v[170:173], v[62:65]
	v_mfma_f32_16x16x32_bf16 v[58:61], v[138:141], v[166:169], v[58:61]
	v_mfma_f32_16x16x32_bf16 v[58:61], v[142:145], v[170:173], v[58:61]
	v_mfma_f32_16x16x32_bf16 v[42:45], v[138:141], v[186:189], v[42:45]
	v_mfma_f32_16x16x32_bf16 v[42:45], v[142:145], v[190:193], v[42:45]
	v_mfma_f32_16x16x32_bf16 v[46:49], v[130:133], v[186:189], v[46:49]
	v_mfma_f32_16x16x32_bf16 v[46:49], v[134:137], v[190:193], v[46:49]
	v_mfma_f32_16x16x32_bf16 v[30:33], v[130:133], v[194:197], v[30:33]
	v_mfma_f32_16x16x32_bf16 v[30:33], v[134:137], v[198:201], v[30:33]
	v_mfma_f32_16x16x32_bf16 v[26:29], v[138:141], v[194:197], v[26:29]
	v_mfma_f32_16x16x32_bf16 v[26:29], v[142:145], v[198:201], v[26:29]
	v_mfma_f32_16x16x32_bf16 v[10:13], v[138:141], v[202:205], v[10:13]
	v_mfma_f32_16x16x32_bf16 v[10:13], v[142:145], v[206:209], v[10:13]
	v_mfma_f32_16x16x32_bf16 v[14:17], v[130:133], v[202:205], v[14:17]
	v_mfma_f32_16x16x32_bf16 v[14:17], v[134:137], v[206:209], v[14:17]
	s_setprio 0
	s_setprio 1
	v_mfma_f32_16x16x32_bf16 v[54:57], v[150:153], v[166:169], v[54:57]
	v_mfma_f32_16x16x32_bf16 v[54:57], v[154:157], v[170:173], v[54:57]
	v_mfma_f32_16x16x32_bf16 v[50:53], v[158:161], v[166:169], v[50:53]
	v_mfma_f32_16x16x32_bf16 v[50:53], v[162:165], v[170:173], v[50:53]
	v_mfma_f32_16x16x32_bf16 v[34:37], v[158:161], v[186:189], v[34:37]
	v_mfma_f32_16x16x32_bf16 v[34:37], v[162:165], v[190:193], v[34:37]
	v_mfma_f32_16x16x32_bf16 v[38:41], v[150:153], v[186:189], v[38:41]
	v_mfma_f32_16x16x32_bf16 v[38:41], v[154:157], v[190:193], v[38:41]
	v_mfma_f32_16x16x32_bf16 v[22:25], v[150:153], v[194:197], v[22:25]
	v_mfma_f32_16x16x32_bf16 v[22:25], v[154:157], v[198:201], v[22:25]
	v_mfma_f32_16x16x32_bf16 v[18:21], v[158:161], v[194:197], v[18:21]
	v_mfma_f32_16x16x32_bf16 v[18:21], v[162:165], v[198:201], v[18:21]
	v_mfma_f32_16x16x32_bf16 v[2:5], v[158:161], v[202:205], v[2:5]
	v_mfma_f32_16x16x32_bf16 v[2:5], v[162:165], v[206:209], v[2:5]
	s_setprio 2
	s_barrier
	v_mfma_f32_16x16x32_bf16 v[6:9], v[150:153], v[202:205], v[6:9]
	v_mfma_f32_16x16x32_bf16 v[6:9], v[154:157], v[206:209], v[6:9]
	s_setprio 0
	s_add_i32 s78, s78, 2
	s_add_u32 s74, s74, 0x80000
	s_addc_u32 s75, s75, 0
	s_add_u32 s20, s20, 0x400000
	s_addc_u32 s21, s21, 0
	s_add_u32 s76, s76, 0x400000
	s_addc_u32 s77, s77, 0
	s_cmpk_gt_u32 s78, 0x53
	s_cbranch_scc0 .LBB0_1357
	s_and_b64 vcc, exec, s[8:9]
	s_cbranch_vccz .LBB0_1360
	s_barrier

.LBB0_1537:
	s_ashr_i32 s23, s22, 31
	s_lshl_b64 s[24:25], s[22:23], 20
	s_add_u32 s24, s41, s24
	s_addc_u32 s25, s42, s25
	s_and_b64 s[26:27], s[4:5], exec
	s_cselect_b32 s7, s25, s35
	s_cselect_b32 s23, s24, s34
	s_ashr_i32 s21, s20, 31
	s_lshl_b64 s[26:27], s[20:21], 20
	s_add_u32 s26, s43, s26
	s_addc_u32 s27, s46, s27
	s_and_b64 s[36:37], s[4:5], exec
	s_cselect_b32 s21, s27, s31
	s_cselect_b32 s29, s26, s30
	s_add_u32 s79, s30, 0x100
	s_addc_u32 s80, s31, 0
	s_add_u32 s30, s34, 0x80080
	s_addc_u32 s31, s35, 0
	s_add_u32 s81, s34, 0x100
	s_addc_u32 s82, s35, 0
	s_mov_b32 s83, -2
	s_waitcnt vmcnt(25)
	s_waitcnt vmcnt(24)
	s_waitcnt vmcnt(4)
	s_waitcnt vmcnt(14)
	s_waitcnt vmcnt(13)
	s_waitcnt vmcnt(12)
	s_waitcnt vmcnt(2)
	s_waitcnt vmcnt(10)
	s_waitcnt vmcnt(9)
	s_waitcnt vmcnt(8)
	s_waitcnt vmcnt(7)
	s_waitcnt vmcnt(6)
	s_waitcnt vmcnt(5)
	s_waitcnt vmcnt(4)
	s_waitcnt vmcnt(3)
	s_waitcnt vmcnt(2)
	s_waitcnt vmcnt(1)
	s_waitcnt vmcnt(0)
	ds_read_b128 v[46:49], v182
	ds_read_b128 v[54:57], v182 offset:1024
	ds_read_b128 v[58:61], v182 offset:2048
	ds_read_b128 v[62:65], v182 offset:3072
	ds_read_b128 v[146:149], v183
	ds_read_b128 v[150:153], v183 offset:1024
	ds_read_b128 v[154:157], v183 offset:2048
	ds_read_b128 v[158:161], v183 offset:3072
	s_cmp_eq_u32 s83, 28
	s_cselect_b32 s35, s21, s80
	s_cselect_b32 s34, s29, s79
	s_cselect_b32 s37, s7, s82
	s_cselect_b32 s36, s23, s81
	ds_read_b128 v[170:173], v184
	ds_read_b128 v[188:191], v184 offset:1024
	ds_read_b128 v[192:195], v184 offset:2048
	ds_read_b128 v[196:199], v184 offset:3072
	ds_read_b128 v[200:203], v184 offset:4096
	ds_read_b128 v[204:207], v184 offset:5120
	ds_read_b128 v[208:211], v184 offset:6144
	ds_read_b128 v[212:215], v184 offset:7168
	s_add_u32 s86, s30, 0xfff80000
	s_addc_u32 s87, s31, -1
	s_mov_b32 s92, m0
	s_mov_b32 m0, s73
	s_nop 0
	global_load_lds_dwordx4 v176, s[86:87]
	s_mov_b32 m0, s92
	s_nop 0
	s_mov_b32 s92, m0
	s_mov_b32 m0, s75
	s_nop 0
	global_load_lds_dwordx4 v178, s[86:87]
	s_mov_b32 m0, s92
	s_mov_b32 s86, m0
	s_mov_b32 m0, s74
	s_nop 0
	global_load_lds_dwordx4 v176, s[30:31]
	s_mov_b32 m0, s86
	s_nop 0
	s_mov_b32 s86, m0
	s_mov_b32 m0, s76
	s_nop 0
	global_load_lds_dwordx4 v178, s[30:31]
	s_mov_b32 m0, s86
	s_waitcnt vmcnt(8)
	s_waitcnt lgkmcnt(0)
	s_barrier
	s_setprio 1
	.p2align 3
	v_mfma_f32_16x16x32_bf16 v[142:145], v[46:49], v[170:173], 0
	v_mfma_f32_16x16x32_bf16 v[142:145], v[54:57], v[188:191], v[142:145]
	v_mfma_f32_16x16x32_bf16 v[138:141], v[58:61], v[170:173], 0
	v_mfma_f32_16x16x32_bf16 v[138:141], v[62:65], v[188:191], v[138:141]
	v_mfma_f32_16x16x32_bf16 v[126:129], v[46:49], v[192:195], 0
	v_mfma_f32_16x16x32_bf16 v[126:129], v[54:57], v[196:199], v[126:129]
	v_mfma_f32_16x16x32_bf16 v[122:125], v[58:61], v[192:195], 0
	v_mfma_f32_16x16x32_bf16 v[122:125], v[62:65], v[196:199], v[122:125]
	v_mfma_f32_16x16x32_bf16 v[110:113], v[46:49], v[200:203], 0
	v_mfma_f32_16x16x32_bf16 v[110:113], v[54:57], v[204:207], v[110:113]
	v_mfma_f32_16x16x32_bf16 v[106:109], v[58:61], v[200:203], 0
	v_mfma_f32_16x16x32_bf16 v[106:109], v[62:65], v[204:207], v[106:109]
	v_mfma_f32_16x16x32_bf16 v[94:97], v[46:49], v[208:211], 0
	v_mfma_f32_16x16x32_bf16 v[94:97], v[54:57], v[212:215], v[94:97]
	v_mfma_f32_16x16x32_bf16 v[90:93], v[58:61], v[208:211], 0
	v_mfma_f32_16x16x32_bf16 v[90:93], v[62:65], v[212:215], v[90:93]
	s_setprio 0
	s_setprio 1
	v_mfma_f32_16x16x32_bf16 v[134:137], v[146:149], v[170:173], 0
	v_mfma_f32_16x16x32_bf16 v[134:137], v[150:153], v[188:191], v[134:137]
	v_mfma_f32_16x16x32_bf16 v[130:133], v[154:157], v[170:173], 0
	v_mfma_f32_16x16x32_bf16 v[130:133], v[158:161], v[188:191], v[130:133]
	v_mfma_f32_16x16x32_bf16 v[118:121], v[146:149], v[192:195], 0
	v_mfma_f32_16x16x32_bf16 v[118:121], v[150:153], v[196:199], v[118:121]
	v_mfma_f32_16x16x32_bf16 v[114:117], v[154:157], v[192:195], 0
	v_mfma_f32_16x16x32_bf16 v[114:117], v[158:161], v[196:199], v[114:117]
	v_mfma_f32_16x16x32_bf16 v[102:105], v[146:149], v[200:203], 0
	v_mfma_f32_16x16x32_bf16 v[102:105], v[150:153], v[204:207], v[102:105]
	v_mfma_f32_16x16x32_bf16 v[98:101], v[154:157], v[200:203], 0
	v_mfma_f32_16x16x32_bf16 v[98:101], v[158:161], v[204:207], v[98:101]
	v_mfma_f32_16x16x32_bf16 v[86:89], v[146:149], v[208:211], 0
	v_mfma_f32_16x16x32_bf16 v[86:89], v[150:153], v[212:215], v[86:89]
	s_setprio 2
	s_barrier
	v_mfma_f32_16x16x32_bf16 v[82:85], v[154:157], v[208:211], 0
	v_mfma_f32_16x16x32_bf16 v[82:85], v[158:161], v[212:215], v[82:85]
	s_setprio 0
	ds_read_b128 v[170:173], v184 offset:16384
	ds_read_b128 v[188:191], v184 offset:17408
	ds_read_b128 v[192:195], v184 offset:18432
	ds_read_b128 v[196:199], v184 offset:19456
	ds_read_b128 v[200:203], v184 offset:20480
	ds_read_b128 v[204:207], v184 offset:21504
	ds_read_b128 v[208:211], v184 offset:22528
	ds_read_b128 v[212:215], v184 offset:23552
	s_mov_b32 s86, m0
	s_mov_b32 m0, s49
	s_nop 0
	global_load_lds_dwordx4 v177, s[34:35]
	s_mov_b32 m0, s86
	s_nop 0
	s_mov_b32 s86, m0
	s_mov_b32 m0, s56
	s_nop 0
	global_load_lds_dwordx4 v179, s[34:35]
	s_mov_b32 m0, s86
	s_add_u32 s86, s34, 0x80000
	s_addc_u32 s87, s35, 0
	s_mov_b32 s92, m0
	s_mov_b32 m0, s57
	s_nop 0
	global_load_lds_dwordx4 v177, s[86:87]
	s_mov_b32 m0, s92
	s_nop 0
	s_mov_b32 s92, m0
	s_mov_b32 m0, s58
	s_nop 0
	global_load_lds_dwordx4 v179, s[86:87]
	s_mov_b32 m0, s92
	s_waitcnt vmcnt(4)
	s_waitcnt lgkmcnt(0)
	s_barrier
	s_setprio 1
	.p2align 3
	v_mfma_f32_16x16x32_bf16 v[78:81], v[46:49], v[170:173], 0
	v_mfma_f32_16x16x32_bf16 v[78:81], v[54:57], v[188:191], v[78:81]
	v_mfma_f32_16x16x32_bf16 v[74:77], v[58:61], v[170:173], 0
	v_mfma_f32_16x16x32_bf16 v[74:77], v[62:65], v[188:191], v[74:77]
	v_mfma_f32_16x16x32_bf16 v[50:53], v[46:49], v[192:195], 0
	v_mfma_f32_16x16x32_bf16 v[50:53], v[54:57], v[196:199], v[50:53]
	v_mfma_f32_16x16x32_bf16 v[42:45], v[58:61], v[192:195], 0
	v_mfma_f32_16x16x32_bf16 v[42:45], v[62:65], v[196:199], v[42:45]
	v_mfma_f32_16x16x32_bf16 v[30:33], v[46:49], v[200:203], 0
	v_mfma_f32_16x16x32_bf16 v[30:33], v[54:57], v[204:207], v[30:33]
	v_mfma_f32_16x16x32_bf16 v[26:29], v[58:61], v[200:203], 0
	v_mfma_f32_16x16x32_bf16 v[26:29], v[62:65], v[204:207], v[26:29]
	v_mfma_f32_16x16x32_bf16 v[14:17], v[46:49], v[208:211], 0
	v_mfma_f32_16x16x32_bf16 v[14:17], v[54:57], v[212:215], v[14:17]
	v_mfma_f32_16x16x32_bf16 v[10:13], v[58:61], v[208:211], 0
	v_mfma_f32_16x16x32_bf16 v[10:13], v[62:65], v[212:215], v[10:13]
	s_setprio 0
	s_setprio 1
	v_mfma_f32_16x16x32_bf16 v[38:41], v[146:149], v[192:195], 0
	v_mfma_f32_16x16x32_bf16 v[38:41], v[150:153], v[196:199], v[38:41]
	v_mfma_f32_16x16x32_bf16 v[34:37], v[154:157], v[192:195], 0
	v_mfma_f32_16x16x32_bf16 v[34:37], v[158:161], v[196:199], v[34:37]
	v_mfma_f32_16x16x32_bf16 v[22:25], v[146:149], v[200:203], 0
	v_mfma_f32_16x16x32_bf16 v[22:25], v[150:153], v[204:207], v[22:25]
	v_mfma_f32_16x16x32_bf16 v[18:21], v[154:157], v[200:203], 0
	v_mfma_f32_16x16x32_bf16 v[18:21], v[158:161], v[204:207], v[18:21]
	v_mfma_f32_16x16x32_bf16 v[6:9], v[146:149], v[208:211], 0
	v_mfma_f32_16x16x32_bf16 v[6:9], v[150:153], v[212:215], v[6:9]
	v_mfma_f32_16x16x32_bf16 v[2:5], v[154:157], v[208:211], 0
	v_mfma_f32_16x16x32_bf16 v[2:5], v[158:161], v[212:215], v[2:5]
	v_mfma_f32_16x16x32_bf16 v[46:49], v[146:149], v[170:173], 0
	v_mfma_f32_16x16x32_bf16 v[46:49], v[150:153], v[188:191], v[46:49]
	s_setprio 2
	s_barrier
	v_mfma_f32_16x16x32_bf16 v[54:57], v[154:157], v[170:173], 0
	v_mfma_f32_16x16x32_bf16 v[54:57], v[158:161], v[188:191], v[54:57]
	s_setprio 0
	ds_read_b128 v[58:61], v185
	ds_read_b128 v[62:65], v185 offset:1024
	ds_read_b128 v[66:69], v185 offset:2048
	ds_read_b128 v[70:73], v185 offset:3072
	ds_read_b128 v[146:149], v186
	ds_read_b128 v[150:153], v186 offset:1024
	ds_read_b128 v[154:157], v186 offset:2048
	ds_read_b128 v[158:161], v186 offset:3072
	ds_read_b128 v[170:173], v184 offset:32768
	ds_read_b128 v[188:191], v184 offset:33792
	ds_read_b128 v[192:195], v184 offset:34816
	ds_read_b128 v[196:199], v184 offset:35840
	ds_read_b128 v[200:203], v184 offset:36864
	ds_read_b128 v[204:207], v184 offset:37888
	ds_read_b128 v[208:211], v184 offset:38912
	ds_read_b128 v[212:215], v184 offset:39936
	s_mov_b32 s86, m0
	s_mov_b32 m0, s48
	s_nop 0
	global_load_lds_dwordx4 v176, s[36:37]
	s_mov_b32 m0, s86
	s_nop 0
	s_mov_b32 s86, m0
	s_mov_b32 m0, s59
	s_nop 0
	global_load_lds_dwordx4 v178, s[36:37]
	s_mov_b32 m0, s86
	s_add_u32 s36, s36, 0x80000
	s_addc_u32 s37, s37, 0
	s_mov_b32 s86, m0
	s_mov_b32 m0, s62
	s_nop 0
	global_load_lds_dwordx4 v176, s[36:37]
	s_mov_b32 m0, s86
	s_nop 0
	s_mov_b32 s86, m0
	s_mov_b32 m0, s63
	s_nop 0
	global_load_lds_dwordx4 v178, s[36:37]
	s_mov_b32 m0, s86
	s_waitcnt vmcnt(8)
	s_waitcnt lgkmcnt(0)
	s_barrier
	s_setprio 1
	.p2align 3
	v_mfma_f32_16x16x32_bf16 v[142:145], v[58:61], v[170:173], v[142:145]
	v_mfma_f32_16x16x32_bf16 v[142:145], v[62:65], v[188:191], v[142:145]
	v_mfma_f32_16x16x32_bf16 v[138:141], v[66:69], v[170:173], v[138:141]
	v_mfma_f32_16x16x32_bf16 v[138:141], v[70:73], v[188:191], v[138:141]
	v_mfma_f32_16x16x32_bf16 v[126:129], v[58:61], v[192:195], v[126:129]
	v_mfma_f32_16x16x32_bf16 v[126:129], v[62:65], v[196:199], v[126:129]
	v_mfma_f32_16x16x32_bf16 v[122:125], v[66:69], v[192:195], v[122:125]
	v_mfma_f32_16x16x32_bf16 v[122:125], v[70:73], v[196:199], v[122:125]
	v_mfma_f32_16x16x32_bf16 v[110:113], v[58:61], v[200:203], v[110:113]
	v_mfma_f32_16x16x32_bf16 v[110:113], v[62:65], v[204:207], v[110:113]
	v_mfma_f32_16x16x32_bf16 v[106:109], v[66:69], v[200:203], v[106:109]
	v_mfma_f32_16x16x32_bf16 v[106:109], v[70:73], v[204:207], v[106:109]
	v_mfma_f32_16x16x32_bf16 v[94:97], v[58:61], v[208:211], v[94:97]
	v_mfma_f32_16x16x32_bf16 v[94:97], v[62:65], v[212:215], v[94:97]
	v_mfma_f32_16x16x32_bf16 v[90:93], v[66:69], v[208:211], v[90:93]
	v_mfma_f32_16x16x32_bf16 v[90:93], v[70:73], v[212:215], v[90:93]
	s_setprio 0
	s_setprio 1
	v_mfma_f32_16x16x32_bf16 v[134:137], v[146:149], v[170:173], v[134:137]
	v_mfma_f32_16x16x32_bf16 v[134:137], v[150:153], v[188:191], v[134:137]
	v_mfma_f32_16x16x32_bf16 v[130:133], v[154:157], v[170:173], v[130:133]
	v_mfma_f32_16x16x32_bf16 v[130:133], v[158:161], v[188:191], v[130:133]
	v_mfma_f32_16x16x32_bf16 v[118:121], v[146:149], v[192:195], v[118:121]
	v_mfma_f32_16x16x32_bf16 v[118:121], v[150:153], v[196:199], v[118:121]
	v_mfma_f32_16x16x32_bf16 v[114:117], v[154:157], v[192:195], v[114:117]
	v_mfma_f32_16x16x32_bf16 v[114:117], v[158:161], v[196:199], v[114:117]
	v_mfma_f32_16x16x32_bf16 v[102:105], v[146:149], v[200:203], v[102:105]
	v_mfma_f32_16x16x32_bf16 v[102:105], v[150:153], v[204:207], v[102:105]
	v_mfma_f32_16x16x32_bf16 v[98:101], v[154:157], v[200:203], v[98:101]
	v_mfma_f32_16x16x32_bf16 v[98:101], v[158:161], v[204:207], v[98:101]
	v_mfma_f32_16x16x32_bf16 v[86:89], v[146:149], v[208:211], v[86:89]
	v_mfma_f32_16x16x32_bf16 v[86:89], v[150:153], v[212:215], v[86:89]
	s_setprio 2
	s_barrier
	v_mfma_f32_16x16x32_bf16 v[82:85], v[154:157], v[208:211], v[82:85]
	v_mfma_f32_16x16x32_bf16 v[82:85], v[158:161], v[212:215], v[82:85]
	s_setprio 0
	ds_read_b128 v[170:173], v184 offset:49152
	ds_read_b128 v[188:191], v184 offset:50176
	ds_read_b128 v[192:195], v184 offset:51200
	ds_read_b128 v[196:199], v184 offset:52224
	ds_read_b128 v[200:203], v184 offset:53248
	ds_read_b128 v[204:207], v184 offset:54272
	ds_read_b128 v[208:211], v184 offset:55296
	ds_read_b128 v[212:215], v184 offset:56320
	s_add_u32 s36, s34, 0x80
	s_addc_u32 s37, s35, 0
	s_mov_b32 s86, m0
	s_mov_b32 m0, s64
	s_nop 0
	global_load_lds_dwordx4 v177, s[36:37]
	s_mov_b32 m0, s86
	s_add_u32 s34, s34, 0x80080
	s_mov_b32 s86, m0
	s_mov_b32 m0, s65
	s_nop 0
	global_load_lds_dwordx4 v179, s[36:37]
	s_mov_b32 m0, s86
	s_addc_u32 s35, s35, 0
	s_mov_b32 s36, m0
	s_mov_b32 m0, s66
	s_nop 0
	global_load_lds_dwordx4 v177, s[34:35]
	s_mov_b32 m0, s36
	s_nop 0
	s_mov_b32 s36, m0
	s_mov_b32 m0, s67
	s_nop 0
	global_load_lds_dwordx4 v179, s[34:35]
	s_mov_b32 m0, s36
	s_waitcnt vmcnt(4)
	s_waitcnt lgkmcnt(0)
	s_barrier
	s_setprio 1
	.p2align 3
	v_mfma_f32_16x16x32_bf16 v[78:81], v[58:61], v[170:173], v[78:81]
	v_mfma_f32_16x16x32_bf16 v[78:81], v[62:65], v[188:191], v[78:81]
	v_mfma_f32_16x16x32_bf16 v[74:77], v[66:69], v[170:173], v[74:77]
	v_mfma_f32_16x16x32_bf16 v[74:77], v[70:73], v[188:191], v[74:77]
	v_mfma_f32_16x16x32_bf16 v[50:53], v[58:61], v[192:195], v[50:53]
	v_mfma_f32_16x16x32_bf16 v[50:53], v[62:65], v[196:199], v[50:53]
	v_mfma_f32_16x16x32_bf16 v[42:45], v[66:69], v[192:195], v[42:45]
	v_mfma_f32_16x16x32_bf16 v[42:45], v[70:73], v[196:199], v[42:45]
	v_mfma_f32_16x16x32_bf16 v[30:33], v[58:61], v[200:203], v[30:33]
	v_mfma_f32_16x16x32_bf16 v[30:33], v[62:65], v[204:207], v[30:33]
	v_mfma_f32_16x16x32_bf16 v[26:29], v[66:69], v[200:203], v[26:29]
	v_mfma_f32_16x16x32_bf16 v[26:29], v[70:73], v[204:207], v[26:29]
	v_mfma_f32_16x16x32_bf16 v[14:17], v[58:61], v[208:211], v[14:17]
	v_mfma_f32_16x16x32_bf16 v[14:17], v[62:65], v[212:215], v[14:17]
	v_mfma_f32_16x16x32_bf16 v[10:13], v[66:69], v[208:211], v[10:13]
	v_mfma_f32_16x16x32_bf16 v[10:13], v[70:73], v[212:215], v[10:13]
	s_setprio 0
	s_setprio 1
	v_mfma_f32_16x16x32_bf16 v[46:49], v[146:149], v[170:173], v[46:49]
	v_mfma_f32_16x16x32_bf16 v[70:73], v[150:153], v[188:191], v[46:49]
	v_mfma_f32_16x16x32_bf16 v[46:49], v[154:157], v[170:173], v[54:57]
	v_mfma_f32_16x16x32_bf16 v[66:69], v[158:161], v[188:191], v[46:49]
	v_mfma_f32_16x16x32_bf16 v[38:41], v[146:149], v[192:195], v[38:41]
	v_mfma_f32_16x16x32_bf16 v[38:41], v[150:153], v[196:199], v[38:41]
	v_mfma_f32_16x16x32_bf16 v[34:37], v[154:157], v[192:195], v[34:37]
	v_mfma_f32_16x16x32_bf16 v[34:37], v[158:161], v[196:199], v[34:37]
	v_mfma_f32_16x16x32_bf16 v[22:25], v[146:149], v[200:203], v[22:25]
	v_mfma_f32_16x16x32_bf16 v[22:25], v[150:153], v[204:207], v[22:25]
	v_mfma_f32_16x16x32_bf16 v[18:21], v[154:157], v[200:203], v[18:21]
	v_mfma_f32_16x16x32_bf16 v[18:21], v[158:161], v[204:207], v[18:21]
	v_mfma_f32_16x16x32_bf16 v[6:9], v[146:149], v[208:211], v[6:9]
	v_mfma_f32_16x16x32_bf16 v[6:9], v[150:153], v[212:215], v[6:9]
	s_setprio 2
	s_barrier
	v_mfma_f32_16x16x32_bf16 v[2:5], v[154:157], v[208:211], v[2:5]
	v_mfma_f32_16x16x32_bf16 v[2:5], v[158:161], v[212:215], v[2:5]
	s_setprio 0
	s_add_i32 s83, s83, 2
	s_add_u32 s79, s79, 0x100
	s_addc_u32 s80, s80, 0
	s_add_u32 s30, s30, 0x100
	s_addc_u32 s31, s31, 0
	s_add_u32 s81, s81, 0x100
	s_addc_u32 s82, s82, 0
	s_cmp_gt_u32 s83, 29
	.p2align 6
.LBB0_1538:
	ds_read_b128 v[46:49], v182
	ds_read_b128 v[54:57], v182 offset:1024
	ds_read_b128 v[58:61], v182 offset:2048
	ds_read_b128 v[62:65], v182 offset:3072
	ds_read_b128 v[146:149], v183
	ds_read_b128 v[150:153], v183 offset:1024
	ds_read_b128 v[154:157], v183 offset:2048
	ds_read_b128 v[158:161], v183 offset:3072
	s_cmp_eq_u32 s83, 28
	s_cselect_b32 s35, s21, s80
	s_cselect_b32 s34, s29, s79
	s_cselect_b32 s37, s7, s82
	s_cselect_b32 s36, s23, s81
	ds_read_b128 v[170:173], v184
	ds_read_b128 v[188:191], v184 offset:1024
	ds_read_b128 v[192:195], v184 offset:2048
	ds_read_b128 v[196:199], v184 offset:3072
	ds_read_b128 v[200:203], v184 offset:4096
	ds_read_b128 v[204:207], v184 offset:5120
	ds_read_b128 v[208:211], v184 offset:6144
	ds_read_b128 v[212:215], v184 offset:7168
	s_add_u32 s86, s30, 0xfff80000
	s_addc_u32 s87, s31, -1
	s_mov_b32 s92, m0
	s_mov_b32 m0, s73
	s_nop 0
	global_load_lds_dwordx4 v176, s[86:87]
	s_mov_b32 m0, s92
	s_nop 0
	s_mov_b32 s92, m0
	s_mov_b32 m0, s75
	s_nop 0
	global_load_lds_dwordx4 v178, s[86:87]
	s_mov_b32 m0, s92
	s_mov_b32 s86, m0
	s_mov_b32 m0, s74
	s_nop 0
	global_load_lds_dwordx4 v176, s[30:31]
	s_mov_b32 m0, s86
	s_nop 0
	s_mov_b32 s86, m0
	s_mov_b32 m0, s76
	s_nop 0
	global_load_lds_dwordx4 v178, s[30:31]
	s_mov_b32 m0, s86
	s_waitcnt vmcnt(8)
	s_waitcnt lgkmcnt(0)
	s_barrier
	s_setprio 1
	.p2align 3
	v_mfma_f32_16x16x32_bf16 v[142:145], v[46:49], v[170:173], v[142:145]
	v_mfma_f32_16x16x32_bf16 v[142:145], v[54:57], v[188:191], v[142:145]
	v_mfma_f32_16x16x32_bf16 v[138:141], v[58:61], v[170:173], v[138:141]
	v_mfma_f32_16x16x32_bf16 v[138:141], v[62:65], v[188:191], v[138:141]
	v_mfma_f32_16x16x32_bf16 v[126:129], v[46:49], v[192:195], v[126:129]
	v_mfma_f32_16x16x32_bf16 v[126:129], v[54:57], v[196:199], v[126:129]
	v_mfma_f32_16x16x32_bf16 v[122:125], v[58:61], v[192:195], v[122:125]
	v_mfma_f32_16x16x32_bf16 v[122:125], v[62:65], v[196:199], v[122:125]
	v_mfma_f32_16x16x32_bf16 v[110:113], v[46:49], v[200:203], v[110:113]
	v_mfma_f32_16x16x32_bf16 v[110:113], v[54:57], v[204:207], v[110:113]
	v_mfma_f32_16x16x32_bf16 v[106:109], v[58:61], v[200:203], v[106:109]
	v_mfma_f32_16x16x32_bf16 v[106:109], v[62:65], v[204:207], v[106:109]
	v_mfma_f32_16x16x32_bf16 v[94:97], v[46:49], v[208:211], v[94:97]
	v_mfma_f32_16x16x32_bf16 v[94:97], v[54:57], v[212:215], v[94:97]
	v_mfma_f32_16x16x32_bf16 v[90:93], v[58:61], v[208:211], v[90:93]
	v_mfma_f32_16x16x32_bf16 v[90:93], v[62:65], v[212:215], v[90:93]
	s_setprio 0
	s_setprio 1
	v_mfma_f32_16x16x32_bf16 v[134:137], v[146:149], v[170:173], v[134:137]
	v_mfma_f32_16x16x32_bf16 v[134:137], v[150:153], v[188:191], v[134:137]
	v_mfma_f32_16x16x32_bf16 v[130:133], v[154:157], v[170:173], v[130:133]
	v_mfma_f32_16x16x32_bf16 v[130:133], v[158:161], v[188:191], v[130:133]
	v_mfma_f32_16x16x32_bf16 v[118:121], v[146:149], v[192:195], v[118:121]
	v_mfma_f32_16x16x32_bf16 v[118:121], v[150:153], v[196:199], v[118:121]
	v_mfma_f32_16x16x32_bf16 v[114:117], v[154:157], v[192:195], v[114:117]
	v_mfma_f32_16x16x32_bf16 v[114:117], v[158:161], v[196:199], v[114:117]
	v_mfma_f32_16x16x32_bf16 v[102:105], v[146:149], v[200:203], v[102:105]
	v_mfma_f32_16x16x32_bf16 v[102:105], v[150:153], v[204:207], v[102:105]
	v_mfma_f32_16x16x32_bf16 v[98:101], v[154:157], v[200:203], v[98:101]
	v_mfma_f32_16x16x32_bf16 v[98:101], v[158:161], v[204:207], v[98:101]
	v_mfma_f32_16x16x32_bf16 v[86:89], v[146:149], v[208:211], v[86:89]
	v_mfma_f32_16x16x32_bf16 v[86:89], v[150:153], v[212:215], v[86:89]
	s_setprio 2
	s_barrier
	v_mfma_f32_16x16x32_bf16 v[82:85], v[154:157], v[208:211], v[82:85]
	v_mfma_f32_16x16x32_bf16 v[82:85], v[158:161], v[212:215], v[82:85]
	s_setprio 0
	ds_read_b128 v[170:173], v184 offset:16384
	ds_read_b128 v[188:191], v184 offset:17408
	ds_read_b128 v[192:195], v184 offset:18432
	ds_read_b128 v[196:199], v184 offset:19456
	ds_read_b128 v[200:203], v184 offset:20480
	ds_read_b128 v[204:207], v184 offset:21504
	ds_read_b128 v[208:211], v184 offset:22528
	ds_read_b128 v[212:215], v184 offset:23552
	s_mov_b32 s86, m0
	s_mov_b32 m0, s49
	s_nop 0
	global_load_lds_dwordx4 v177, s[34:35]
	s_mov_b32 m0, s86
	s_nop 0
	s_mov_b32 s86, m0
	s_mov_b32 m0, s56
	s_nop 0
	global_load_lds_dwordx4 v179, s[34:35]
	s_mov_b32 m0, s86
	s_add_u32 s86, s34, 0x80000
	s_addc_u32 s87, s35, 0
	s_mov_b32 s92, m0
	s_mov_b32 m0, s57
	s_nop 0
	global_load_lds_dwordx4 v177, s[86:87]
	s_mov_b32 m0, s92
	s_nop 0
	s_mov_b32 s92, m0
	s_mov_b32 m0, s58
	s_nop 0
	global_load_lds_dwordx4 v179, s[86:87]
	s_mov_b32 m0, s92
	s_waitcnt vmcnt(4)
	s_waitcnt lgkmcnt(0)
	s_barrier
	s_setprio 1
	.p2align 3
	v_mfma_f32_16x16x32_bf16 v[78:81], v[46:49], v[170:173], v[78:81]
	v_mfma_f32_16x16x32_bf16 v[78:81], v[54:57], v[188:191], v[78:81]
	v_mfma_f32_16x16x32_bf16 v[74:77], v[58:61], v[170:173], v[74:77]
	v_mfma_f32_16x16x32_bf16 v[74:77], v[62:65], v[188:191], v[74:77]
	v_mfma_f32_16x16x32_bf16 v[50:53], v[46:49], v[192:195], v[50:53]
	v_mfma_f32_16x16x32_bf16 v[50:53], v[54:57], v[196:199], v[50:53]
	v_mfma_f32_16x16x32_bf16 v[42:45], v[58:61], v[192:195], v[42:45]
	v_mfma_f32_16x16x32_bf16 v[42:45], v[62:65], v[196:199], v[42:45]
	v_mfma_f32_16x16x32_bf16 v[30:33], v[46:49], v[200:203], v[30:33]
	v_mfma_f32_16x16x32_bf16 v[30:33], v[54:57], v[204:207], v[30:33]
	v_mfma_f32_16x16x32_bf16 v[26:29], v[58:61], v[200:203], v[26:29]
	v_mfma_f32_16x16x32_bf16 v[26:29], v[62:65], v[204:207], v[26:29]
	v_mfma_f32_16x16x32_bf16 v[14:17], v[46:49], v[208:211], v[14:17]
	v_mfma_f32_16x16x32_bf16 v[14:17], v[54:57], v[212:215], v[14:17]
	v_mfma_f32_16x16x32_bf16 v[10:13], v[58:61], v[208:211], v[10:13]
	v_mfma_f32_16x16x32_bf16 v[10:13], v[62:65], v[212:215], v[10:13]
	s_setprio 0
	s_setprio 1
	v_mfma_f32_16x16x32_bf16 v[38:41], v[146:149], v[192:195], v[38:41]
	v_mfma_f32_16x16x32_bf16 v[38:41], v[150:153], v[196:199], v[38:41]
	v_mfma_f32_16x16x32_bf16 v[34:37], v[154:157], v[192:195], v[34:37]
	v_mfma_f32_16x16x32_bf16 v[34:37], v[158:161], v[196:199], v[34:37]
	v_mfma_f32_16x16x32_bf16 v[22:25], v[146:149], v[200:203], v[22:25]
	v_mfma_f32_16x16x32_bf16 v[22:25], v[150:153], v[204:207], v[22:25]
	v_mfma_f32_16x16x32_bf16 v[18:21], v[154:157], v[200:203], v[18:21]
	v_mfma_f32_16x16x32_bf16 v[18:21], v[158:161], v[204:207], v[18:21]
	v_mfma_f32_16x16x32_bf16 v[6:9], v[146:149], v[208:211], v[6:9]
	v_mfma_f32_16x16x32_bf16 v[6:9], v[150:153], v[212:215], v[6:9]
	v_mfma_f32_16x16x32_bf16 v[2:5], v[154:157], v[208:211], v[2:5]
	v_mfma_f32_16x16x32_bf16 v[2:5], v[158:161], v[212:215], v[2:5]
	v_mfma_f32_16x16x32_bf16 v[46:49], v[146:149], v[170:173], v[70:73]
	v_mfma_f32_16x16x32_bf16 v[46:49], v[150:153], v[188:191], v[46:49]
	s_setprio 2
	s_barrier
	v_mfma_f32_16x16x32_bf16 v[54:57], v[154:157], v[170:173], v[66:69]
	v_mfma_f32_16x16x32_bf16 v[54:57], v[158:161], v[188:191], v[54:57]
	s_setprio 0
	ds_read_b128 v[58:61], v185
	ds_read_b128 v[62:65], v185 offset:1024
	ds_read_b128 v[66:69], v185 offset:2048
	ds_read_b128 v[70:73], v185 offset:3072
	ds_read_b128 v[146:149], v186
	ds_read_b128 v[150:153], v186 offset:1024
	ds_read_b128 v[154:157], v186 offset:2048
	ds_read_b128 v[158:161], v186 offset:3072
	ds_read_b128 v[170:173], v184 offset:32768
	ds_read_b128 v[188:191], v184 offset:33792
	ds_read_b128 v[192:195], v184 offset:34816
	ds_read_b128 v[196:199], v184 offset:35840
	ds_read_b128 v[200:203], v184 offset:36864
	ds_read_b128 v[204:207], v184 offset:37888
	ds_read_b128 v[208:211], v184 offset:38912
	ds_read_b128 v[212:215], v184 offset:39936
	s_mov_b32 s86, m0
	s_mov_b32 m0, s48
	s_nop 0
	global_load_lds_dwordx4 v176, s[36:37]
	s_mov_b32 m0, s86
	s_nop 0
	s_mov_b32 s86, m0
	s_mov_b32 m0, s59
	s_nop 0
	global_load_lds_dwordx4 v178, s[36:37]
	s_mov_b32 m0, s86
	s_add_u32 s36, s36, 0x80000
	s_addc_u32 s37, s37, 0
	s_mov_b32 s86, m0
	s_mov_b32 m0, s62
	s_nop 0
	global_load_lds_dwordx4 v176, s[36:37]
	s_mov_b32 m0, s86
	s_nop 0
	s_mov_b32 s86, m0
	s_mov_b32 m0, s63
	s_nop 0
	global_load_lds_dwordx4 v178, s[36:37]
	s_mov_b32 m0, s86
	s_waitcnt vmcnt(8)
	s_waitcnt lgkmcnt(0)
	s_barrier
	s_setprio 1
	.p2align 3
	v_mfma_f32_16x16x32_bf16 v[142:145], v[58:61], v[170:173], v[142:145]
	v_mfma_f32_16x16x32_bf16 v[142:145], v[62:65], v[188:191], v[142:145]
	v_mfma_f32_16x16x32_bf16 v[138:141], v[66:69], v[170:173], v[138:141]
	v_mfma_f32_16x16x32_bf16 v[138:141], v[70:73], v[188:191], v[138:141]
	v_mfma_f32_16x16x32_bf16 v[126:129], v[58:61], v[192:195], v[126:129]
	v_mfma_f32_16x16x32_bf16 v[126:129], v[62:65], v[196:199], v[126:129]
	v_mfma_f32_16x16x32_bf16 v[122:125], v[66:69], v[192:195], v[122:125]
	v_mfma_f32_16x16x32_bf16 v[122:125], v[70:73], v[196:199], v[122:125]
	v_mfma_f32_16x16x32_bf16 v[110:113], v[58:61], v[200:203], v[110:113]
	v_mfma_f32_16x16x32_bf16 v[110:113], v[62:65], v[204:207], v[110:113]
	v_mfma_f32_16x16x32_bf16 v[106:109], v[66:69], v[200:203], v[106:109]
	v_mfma_f32_16x16x32_bf16 v[106:109], v[70:73], v[204:207], v[106:109]
	v_mfma_f32_16x16x32_bf16 v[94:97], v[58:61], v[208:211], v[94:97]
	v_mfma_f32_16x16x32_bf16 v[94:97], v[62:65], v[212:215], v[94:97]
	v_mfma_f32_16x16x32_bf16 v[90:93], v[66:69], v[208:211], v[90:93]
	v_mfma_f32_16x16x32_bf16 v[90:93], v[70:73], v[212:215], v[90:93]
	s_setprio 0
	s_setprio 1
	v_mfma_f32_16x16x32_bf16 v[134:137], v[146:149], v[170:173], v[134:137]
	v_mfma_f32_16x16x32_bf16 v[134:137], v[150:153], v[188:191], v[134:137]
	v_mfma_f32_16x16x32_bf16 v[130:133], v[154:157], v[170:173], v[130:133]
	v_mfma_f32_16x16x32_bf16 v[130:133], v[158:161], v[188:191], v[130:133]
	v_mfma_f32_16x16x32_bf16 v[118:121], v[146:149], v[192:195], v[118:121]
	v_mfma_f32_16x16x32_bf16 v[118:121], v[150:153], v[196:199], v[118:121]
	v_mfma_f32_16x16x32_bf16 v[114:117], v[154:157], v[192:195], v[114:117]
	v_mfma_f32_16x16x32_bf16 v[114:117], v[158:161], v[196:199], v[114:117]
	v_mfma_f32_16x16x32_bf16 v[102:105], v[146:149], v[200:203], v[102:105]
	v_mfma_f32_16x16x32_bf16 v[102:105], v[150:153], v[204:207], v[102:105]
	v_mfma_f32_16x16x32_bf16 v[98:101], v[154:157], v[200:203], v[98:101]
	v_mfma_f32_16x16x32_bf16 v[98:101], v[158:161], v[204:207], v[98:101]
	v_mfma_f32_16x16x32_bf16 v[86:89], v[146:149], v[208:211], v[86:89]
	v_mfma_f32_16x16x32_bf16 v[86:89], v[150:153], v[212:215], v[86:89]
	s_setprio 2
	s_barrier
	v_mfma_f32_16x16x32_bf16 v[82:85], v[154:157], v[208:211], v[82:85]
	v_mfma_f32_16x16x32_bf16 v[82:85], v[158:161], v[212:215], v[82:85]
	s_setprio 0
	ds_read_b128 v[170:173], v184 offset:49152
	ds_read_b128 v[188:191], v184 offset:50176
	ds_read_b128 v[192:195], v184 offset:51200
	ds_read_b128 v[196:199], v184 offset:52224
	ds_read_b128 v[200:203], v184 offset:53248
	ds_read_b128 v[204:207], v184 offset:54272
	ds_read_b128 v[208:211], v184 offset:55296
	ds_read_b128 v[212:215], v184 offset:56320
	s_add_u32 s36, s34, 0x80
	s_addc_u32 s37, s35, 0
	s_mov_b32 s86, m0
	s_mov_b32 m0, s64
	s_nop 0
	global_load_lds_dwordx4 v177, s[36:37]
	s_mov_b32 m0, s86
	s_add_u32 s34, s34, 0x80080
	s_mov_b32 s86, m0
	s_mov_b32 m0, s65
	s_nop 0
	global_load_lds_dwordx4 v179, s[36:37]
	s_mov_b32 m0, s86
	s_addc_u32 s35, s35, 0
	s_mov_b32 s36, m0
	s_mov_b32 m0, s66
	s_nop 0
	global_load_lds_dwordx4 v177, s[34:35]
	s_mov_b32 m0, s36
	s_nop 0
	s_mov_b32 s36, m0
	s_mov_b32 m0, s67
	s_nop 0
	global_load_lds_dwordx4 v179, s[34:35]
	s_mov_b32 m0, s36
	s_waitcnt vmcnt(4)
	s_waitcnt lgkmcnt(0)
	s_barrier
	s_setprio 1
	.p2align 3
	v_mfma_f32_16x16x32_bf16 v[78:81], v[58:61], v[170:173], v[78:81]
	v_mfma_f32_16x16x32_bf16 v[78:81], v[62:65], v[188:191], v[78:81]
	v_mfma_f32_16x16x32_bf16 v[74:77], v[66:69], v[170:173], v[74:77]
	v_mfma_f32_16x16x32_bf16 v[74:77], v[70:73], v[188:191], v[74:77]
	v_mfma_f32_16x16x32_bf16 v[50:53], v[58:61], v[192:195], v[50:53]
	v_mfma_f32_16x16x32_bf16 v[50:53], v[62:65], v[196:199], v[50:53]
	v_mfma_f32_16x16x32_bf16 v[42:45], v[66:69], v[192:195], v[42:45]
	v_mfma_f32_16x16x32_bf16 v[42:45], v[70:73], v[196:199], v[42:45]
	v_mfma_f32_16x16x32_bf16 v[30:33], v[58:61], v[200:203], v[30:33]
	v_mfma_f32_16x16x32_bf16 v[30:33], v[62:65], v[204:207], v[30:33]
	v_mfma_f32_16x16x32_bf16 v[26:29], v[66:69], v[200:203], v[26:29]
	v_mfma_f32_16x16x32_bf16 v[26:29], v[70:73], v[204:207], v[26:29]
	v_mfma_f32_16x16x32_bf16 v[14:17], v[58:61], v[208:211], v[14:17]
	v_mfma_f32_16x16x32_bf16 v[14:17], v[62:65], v[212:215], v[14:17]
	v_mfma_f32_16x16x32_bf16 v[10:13], v[66:69], v[208:211], v[10:13]
	v_mfma_f32_16x16x32_bf16 v[10:13], v[70:73], v[212:215], v[10:13]
	s_setprio 0
	s_setprio 1
	v_mfma_f32_16x16x32_bf16 v[46:49], v[146:149], v[170:173], v[46:49]
	v_mfma_f32_16x16x32_bf16 v[70:73], v[150:153], v[188:191], v[46:49]
	v_mfma_f32_16x16x32_bf16 v[46:49], v[154:157], v[170:173], v[54:57]
	v_mfma_f32_16x16x32_bf16 v[66:69], v[158:161], v[188:191], v[46:49]
	v_mfma_f32_16x16x32_bf16 v[38:41], v[146:149], v[192:195], v[38:41]
	v_mfma_f32_16x16x32_bf16 v[38:41], v[150:153], v[196:199], v[38:41]
	v_mfma_f32_16x16x32_bf16 v[34:37], v[154:157], v[192:195], v[34:37]
	v_mfma_f32_16x16x32_bf16 v[34:37], v[158:161], v[196:199], v[34:37]
	v_mfma_f32_16x16x32_bf16 v[22:25], v[146:149], v[200:203], v[22:25]
	v_mfma_f32_16x16x32_bf16 v[22:25], v[150:153], v[204:207], v[22:25]
	v_mfma_f32_16x16x32_bf16 v[18:21], v[154:157], v[200:203], v[18:21]
	v_mfma_f32_16x16x32_bf16 v[18:21], v[158:161], v[204:207], v[18:21]
	v_mfma_f32_16x16x32_bf16 v[6:9], v[146:149], v[208:211], v[6:9]
	v_mfma_f32_16x16x32_bf16 v[6:9], v[150:153], v[212:215], v[6:9]
	s_setprio 2
	s_barrier
	v_mfma_f32_16x16x32_bf16 v[2:5], v[154:157], v[208:211], v[2:5]
	v_mfma_f32_16x16x32_bf16 v[2:5], v[158:161], v[212:215], v[2:5]
	s_setprio 0
	s_add_i32 s83, s83, 2
	s_add_u32 s79, s79, 0x100
	s_addc_u32 s80, s80, 0
	s_add_u32 s30, s30, 0x100
	s_addc_u32 s31, s31, 0
	s_add_u32 s81, s81, 0x100
	s_addc_u32 s82, s82, 0
	s_cmp_gt_u32 s83, 29
	s_cbranch_scc0 .LBB0_1538
	s_and_b64 vcc, exec, s[16:17]
	s_cbranch_vccz .LBB0_1541
	s_barrier

.LBB0_1784:
	s_ashr_i32 s11, s10, 31
	s_lshl_b64 s[12:13], s[10:11], 20
	s_add_u32 s12, s26, s12
	s_addc_u32 s13, s27, s13
	s_and_b64 s[14:15], s[2:3], exec
	s_cselect_b32 s11, s13, s21
	s_cselect_b32 s64, s12, s20
	s_ashr_i32 s9, s8, 31
	s_lshl_b64 s[14:15], s[8:9], 20
	s_add_u32 s14, s28, s14
	s_addc_u32 s15, s29, s15
	s_and_b64 s[22:23], s[2:3], exec
	s_cselect_b32 s9, s15, s19
	s_cselect_b32 s65, s14, s18
	s_add_u32 s66, s18, 0x100
	s_addc_u32 s67, s19, 0
	s_add_u32 s18, s20, 0x80080
	s_addc_u32 s19, s21, 0
	s_add_u32 s70, s20, 0x100
	s_addc_u32 s71, s21, 0
	s_mov_b32 s73, -2
	ds_read_b128 v[148:151], v143
	ds_read_b128 v[152:155], v143 offset:1024
	ds_read_b128 v[156:159], v143 offset:2048
	ds_read_b128 v[160:163], v143 offset:3072
	ds_read_b128 v[164:167], v144
	ds_read_b128 v[168:171], v144 offset:1024
	ds_read_b128 v[172:175], v144 offset:2048
	ds_read_b128 v[176:179], v144 offset:3072
	s_cmp_eq_u32 s73, 28
	s_cselect_b32 s21, s9, s67
	s_cselect_b32 s20, s65, s66
	s_cselect_b32 s23, s11, s71
	s_cselect_b32 s22, s64, s70
	ds_read_b128 v[180:183], v145
	ds_read_b128 v[184:187], v145 offset:1024
	ds_read_b128 v[188:191], v145 offset:2048
	ds_read_b128 v[192:195], v145 offset:3072
	ds_read_b128 v[196:199], v145 offset:4096
	ds_read_b128 v[200:203], v145 offset:5120
	ds_read_b128 v[204:207], v145 offset:6144
	ds_read_b128 v[208:211], v145 offset:7168
	s_add_u32 s74, s18, 0xfff80000
	s_addc_u32 s75, s19, -1
	s_mov_b32 s76, m0
	s_mov_b32 m0, s56
	s_nop 0
	global_load_lds_dwordx4 v138, s[74:75]
	s_mov_b32 m0, s76
	s_nop 0
	s_mov_b32 s76, m0
	s_mov_b32 m0, s59
	s_nop 0
	global_load_lds_dwordx4 v140, s[74:75]
	s_mov_b32 m0, s76
	s_mov_b32 s74, m0
	s_mov_b32 m0, s57
	s_nop 0
	global_load_lds_dwordx4 v138, s[18:19]
	s_mov_b32 m0, s74
	s_nop 0
	s_mov_b32 s74, m0
	s_mov_b32 m0, s62
	s_nop 0
	global_load_lds_dwordx4 v140, s[18:19]
	s_mov_b32 m0, s74
	s_waitcnt vmcnt(8)
	s_waitcnt lgkmcnt(0)
	s_barrier
	s_setprio 1
	.p2align 3
	v_mfma_f32_16x16x32_bf16 v[126:129], v[148:151], v[180:183], 0
	v_mfma_f32_16x16x32_bf16 v[126:129], v[152:155], v[184:187], v[126:129]
	v_mfma_f32_16x16x32_bf16 v[122:125], v[156:159], v[180:183], 0
	v_mfma_f32_16x16x32_bf16 v[122:125], v[160:163], v[184:187], v[122:125]
	v_mfma_f32_16x16x32_bf16 v[106:109], v[156:159], v[188:191], 0
	v_mfma_f32_16x16x32_bf16 v[106:109], v[160:163], v[192:195], v[106:109]
	v_mfma_f32_16x16x32_bf16 v[110:113], v[148:151], v[188:191], 0
	v_mfma_f32_16x16x32_bf16 v[110:113], v[152:155], v[192:195], v[110:113]
	v_mfma_f32_16x16x32_bf16 v[94:97], v[148:151], v[196:199], 0
	v_mfma_f32_16x16x32_bf16 v[94:97], v[152:155], v[200:203], v[94:97]
	v_mfma_f32_16x16x32_bf16 v[90:93], v[156:159], v[196:199], 0
	v_mfma_f32_16x16x32_bf16 v[90:93], v[160:163], v[200:203], v[90:93]
	v_mfma_f32_16x16x32_bf16 v[74:77], v[156:159], v[204:207], 0
	v_mfma_f32_16x16x32_bf16 v[74:77], v[160:163], v[208:211], v[74:77]
	v_mfma_f32_16x16x32_bf16 v[78:81], v[148:151], v[204:207], 0
	v_mfma_f32_16x16x32_bf16 v[78:81], v[152:155], v[208:211], v[78:81]
	s_setprio 0
	s_setprio 1
	v_mfma_f32_16x16x32_bf16 v[118:121], v[164:167], v[180:183], 0
	v_mfma_f32_16x16x32_bf16 v[118:121], v[168:171], v[184:187], v[118:121]
	v_mfma_f32_16x16x32_bf16 v[114:117], v[172:175], v[180:183], 0
	v_mfma_f32_16x16x32_bf16 v[114:117], v[176:179], v[184:187], v[114:117]
	v_mfma_f32_16x16x32_bf16 v[98:101], v[172:175], v[188:191], 0
	v_mfma_f32_16x16x32_bf16 v[98:101], v[176:179], v[192:195], v[98:101]
	v_mfma_f32_16x16x32_bf16 v[102:105], v[164:167], v[188:191], 0
	v_mfma_f32_16x16x32_bf16 v[102:105], v[168:171], v[192:195], v[102:105]
	v_mfma_f32_16x16x32_bf16 v[86:89], v[164:167], v[196:199], 0
	v_mfma_f32_16x16x32_bf16 v[86:89], v[168:171], v[200:203], v[86:89]
	v_mfma_f32_16x16x32_bf16 v[82:85], v[172:175], v[196:199], 0
	v_mfma_f32_16x16x32_bf16 v[82:85], v[176:179], v[200:203], v[82:85]
	v_mfma_f32_16x16x32_bf16 v[66:69], v[172:175], v[204:207], 0
	v_mfma_f32_16x16x32_bf16 v[66:69], v[176:179], v[208:211], v[66:69]
	s_setprio 2
	s_barrier
	v_mfma_f32_16x16x32_bf16 v[70:73], v[164:167], v[204:207], 0
	v_mfma_f32_16x16x32_bf16 v[70:73], v[168:171], v[208:211], v[70:73]
	s_setprio 0
	ds_read_b128 v[180:183], v145 offset:16384
	ds_read_b128 v[184:187], v145 offset:17408
	ds_read_b128 v[188:191], v145 offset:18432
	ds_read_b128 v[192:195], v145 offset:19456
	ds_read_b128 v[196:199], v145 offset:20480
	ds_read_b128 v[200:203], v145 offset:21504
	ds_read_b128 v[204:207], v145 offset:22528
	ds_read_b128 v[208:211], v145 offset:23552
	s_mov_b32 s74, m0
	s_mov_b32 m0, s35
	s_nop 0
	global_load_lds_dwordx4 v139, s[20:21]
	s_mov_b32 m0, s74
	s_nop 0
	s_mov_b32 s74, m0
	s_mov_b32 m0, s36
	s_nop 0
	global_load_lds_dwordx4 v141, s[20:21]
	s_mov_b32 m0, s74
	s_add_u32 s74, s20, 0x80000
	s_addc_u32 s75, s21, 0
	s_mov_b32 s76, m0
	s_mov_b32 m0, s37
	s_nop 0
	global_load_lds_dwordx4 v139, s[74:75]
	s_mov_b32 m0, s76
	s_nop 0
	s_mov_b32 s76, m0
	s_mov_b32 m0, s40
	s_nop 0
	global_load_lds_dwordx4 v141, s[74:75]
	s_mov_b32 m0, s76
	s_waitcnt vmcnt(4)
	s_waitcnt lgkmcnt(0)
	s_barrier
	s_setprio 1
	.p2align 3
	v_mfma_f32_16x16x32_bf16 v[62:65], v[148:151], v[180:183], 0
	v_mfma_f32_16x16x32_bf16 v[62:65], v[152:155], v[184:187], v[62:65]
	v_mfma_f32_16x16x32_bf16 v[58:61], v[156:159], v[180:183], 0
	v_mfma_f32_16x16x32_bf16 v[58:61], v[160:163], v[184:187], v[58:61]
	v_mfma_f32_16x16x32_bf16 v[42:45], v[156:159], v[188:191], 0
	v_mfma_f32_16x16x32_bf16 v[42:45], v[160:163], v[192:195], v[42:45]
	v_mfma_f32_16x16x32_bf16 v[46:49], v[148:151], v[188:191], 0
	v_mfma_f32_16x16x32_bf16 v[46:49], v[152:155], v[192:195], v[46:49]
	v_mfma_f32_16x16x32_bf16 v[30:33], v[148:151], v[196:199], 0
	v_mfma_f32_16x16x32_bf16 v[30:33], v[152:155], v[200:203], v[30:33]
	v_mfma_f32_16x16x32_bf16 v[26:29], v[156:159], v[196:199], 0
	v_mfma_f32_16x16x32_bf16 v[26:29], v[160:163], v[200:203], v[26:29]
	v_mfma_f32_16x16x32_bf16 v[10:13], v[156:159], v[204:207], 0
	v_mfma_f32_16x16x32_bf16 v[10:13], v[160:163], v[208:211], v[10:13]
	v_mfma_f32_16x16x32_bf16 v[14:17], v[148:151], v[204:207], 0
	v_mfma_f32_16x16x32_bf16 v[14:17], v[152:155], v[208:211], v[14:17]
	s_setprio 0
	s_setprio 1
	v_mfma_f32_16x16x32_bf16 v[54:57], v[164:167], v[180:183], 0
	v_mfma_f32_16x16x32_bf16 v[54:57], v[168:171], v[184:187], v[54:57]
	v_mfma_f32_16x16x32_bf16 v[50:53], v[172:175], v[180:183], 0
	v_mfma_f32_16x16x32_bf16 v[50:53], v[176:179], v[184:187], v[50:53]
	v_mfma_f32_16x16x32_bf16 v[34:37], v[172:175], v[188:191], 0
	v_mfma_f32_16x16x32_bf16 v[34:37], v[176:179], v[192:195], v[34:37]
	v_mfma_f32_16x16x32_bf16 v[38:41], v[164:167], v[188:191], 0
	v_mfma_f32_16x16x32_bf16 v[38:41], v[168:171], v[192:195], v[38:41]
	v_mfma_f32_16x16x32_bf16 v[22:25], v[164:167], v[196:199], 0
	v_mfma_f32_16x16x32_bf16 v[22:25], v[168:171], v[200:203], v[22:25]
	v_mfma_f32_16x16x32_bf16 v[18:21], v[172:175], v[196:199], 0
	v_mfma_f32_16x16x32_bf16 v[18:21], v[176:179], v[200:203], v[18:21]
	v_mfma_f32_16x16x32_bf16 v[2:5], v[172:175], v[204:207], 0
	v_mfma_f32_16x16x32_bf16 v[2:5], v[176:179], v[208:211], v[2:5]
	s_setprio 2
	s_barrier
	v_mfma_f32_16x16x32_bf16 v[6:9], v[164:167], v[204:207], 0
	v_mfma_f32_16x16x32_bf16 v[6:9], v[168:171], v[208:211], v[6:9]
	s_setprio 0
	ds_read_b128 v[148:151], v146
	ds_read_b128 v[152:155], v146 offset:1024
	ds_read_b128 v[156:159], v146 offset:2048
	ds_read_b128 v[160:163], v146 offset:3072
	ds_read_b128 v[164:167], v147
	ds_read_b128 v[168:171], v147 offset:1024
	ds_read_b128 v[172:175], v147 offset:2048
	ds_read_b128 v[176:179], v147 offset:3072
	ds_read_b128 v[180:183], v145 offset:32768
	ds_read_b128 v[184:187], v145 offset:33792
	ds_read_b128 v[188:191], v145 offset:34816
	ds_read_b128 v[192:195], v145 offset:35840
	ds_read_b128 v[196:199], v145 offset:36864
	ds_read_b128 v[200:203], v145 offset:37888
	ds_read_b128 v[204:207], v145 offset:38912
	ds_read_b128 v[208:211], v145 offset:39936
	s_mov_b32 s74, m0
	s_mov_b32 m0, s31
	s_nop 0
	global_load_lds_dwordx4 v138, s[22:23]
	s_mov_b32 m0, s74
	s_nop 0
	s_mov_b32 s74, m0
	s_mov_b32 m0, s41
	s_nop 0
	global_load_lds_dwordx4 v140, s[22:23]
	s_mov_b32 m0, s74
	s_add_u32 s22, s22, 0x80000
	s_addc_u32 s23, s23, 0
	s_mov_b32 s74, m0
	s_mov_b32 m0, s42
	s_nop 0
	global_load_lds_dwordx4 v138, s[22:23]
	s_mov_b32 m0, s74
	s_nop 0
	s_mov_b32 s74, m0
	s_mov_b32 m0, s43
	s_nop 0
	global_load_lds_dwordx4 v140, s[22:23]
	s_mov_b32 m0, s74
	s_waitcnt vmcnt(8)
	s_waitcnt lgkmcnt(0)
	s_barrier
	s_setprio 1
	.p2align 3
	v_mfma_f32_16x16x32_bf16 v[126:129], v[148:151], v[180:183], v[126:129]
	v_mfma_f32_16x16x32_bf16 v[126:129], v[152:155], v[184:187], v[126:129]
	v_mfma_f32_16x16x32_bf16 v[122:125], v[156:159], v[180:183], v[122:125]
	v_mfma_f32_16x16x32_bf16 v[122:125], v[160:163], v[184:187], v[122:125]
	v_mfma_f32_16x16x32_bf16 v[106:109], v[156:159], v[188:191], v[106:109]
	v_mfma_f32_16x16x32_bf16 v[106:109], v[160:163], v[192:195], v[106:109]
	v_mfma_f32_16x16x32_bf16 v[110:113], v[148:151], v[188:191], v[110:113]
	v_mfma_f32_16x16x32_bf16 v[110:113], v[152:155], v[192:195], v[110:113]
	v_mfma_f32_16x16x32_bf16 v[94:97], v[148:151], v[196:199], v[94:97]
	v_mfma_f32_16x16x32_bf16 v[94:97], v[152:155], v[200:203], v[94:97]
	v_mfma_f32_16x16x32_bf16 v[90:93], v[156:159], v[196:199], v[90:93]
	v_mfma_f32_16x16x32_bf16 v[90:93], v[160:163], v[200:203], v[90:93]
	v_mfma_f32_16x16x32_bf16 v[74:77], v[156:159], v[204:207], v[74:77]
	v_mfma_f32_16x16x32_bf16 v[74:77], v[160:163], v[208:211], v[74:77]
	v_mfma_f32_16x16x32_bf16 v[78:81], v[148:151], v[204:207], v[78:81]
	v_mfma_f32_16x16x32_bf16 v[78:81], v[152:155], v[208:211], v[78:81]
	s_setprio 0
	s_setprio 1
	v_mfma_f32_16x16x32_bf16 v[118:121], v[164:167], v[180:183], v[118:121]
	v_mfma_f32_16x16x32_bf16 v[118:121], v[168:171], v[184:187], v[118:121]
	v_mfma_f32_16x16x32_bf16 v[114:117], v[172:175], v[180:183], v[114:117]
	v_mfma_f32_16x16x32_bf16 v[114:117], v[176:179], v[184:187], v[114:117]
	v_mfma_f32_16x16x32_bf16 v[98:101], v[172:175], v[188:191], v[98:101]
	v_mfma_f32_16x16x32_bf16 v[98:101], v[176:179], v[192:195], v[98:101]
	v_mfma_f32_16x16x32_bf16 v[102:105], v[164:167], v[188:191], v[102:105]
	v_mfma_f32_16x16x32_bf16 v[102:105], v[168:171], v[192:195], v[102:105]
	v_mfma_f32_16x16x32_bf16 v[86:89], v[164:167], v[196:199], v[86:89]
	v_mfma_f32_16x16x32_bf16 v[86:89], v[168:171], v[200:203], v[86:89]
	v_mfma_f32_16x16x32_bf16 v[82:85], v[172:175], v[196:199], v[82:85]
	v_mfma_f32_16x16x32_bf16 v[82:85], v[176:179], v[200:203], v[82:85]
	v_mfma_f32_16x16x32_bf16 v[66:69], v[172:175], v[204:207], v[66:69]
	v_mfma_f32_16x16x32_bf16 v[66:69], v[176:179], v[208:211], v[66:69]
	s_setprio 2
	s_barrier
	v_mfma_f32_16x16x32_bf16 v[70:73], v[164:167], v[204:207], v[70:73]
	v_mfma_f32_16x16x32_bf16 v[70:73], v[168:171], v[208:211], v[70:73]
	s_setprio 0
	ds_read_b128 v[180:183], v145 offset:49152
	ds_read_b128 v[184:187], v145 offset:50176
	ds_read_b128 v[188:191], v145 offset:51200
	ds_read_b128 v[192:195], v145 offset:52224
	ds_read_b128 v[196:199], v145 offset:53248
	ds_read_b128 v[200:203], v145 offset:54272
	ds_read_b128 v[204:207], v145 offset:55296
	ds_read_b128 v[208:211], v145 offset:56320
	s_add_u32 s22, s20, 0x80
	s_addc_u32 s23, s21, 0
	s_mov_b32 s74, m0
	s_mov_b32 m0, s46
	s_nop 0
	global_load_lds_dwordx4 v139, s[22:23]
	s_mov_b32 m0, s74
	s_add_u32 s20, s20, 0x80080
	s_mov_b32 s74, m0
	s_mov_b32 m0, s47
	s_nop 0
	global_load_lds_dwordx4 v141, s[22:23]
	s_mov_b32 m0, s74
	s_addc_u32 s21, s21, 0
	s_mov_b32 s22, m0
	s_mov_b32 m0, s48
	s_nop 0
	global_load_lds_dwordx4 v139, s[20:21]
	s_mov_b32 m0, s22
	s_nop 0
	s_mov_b32 s22, m0
	s_mov_b32 m0, s49
	s_nop 0
	global_load_lds_dwordx4 v141, s[20:21]
	s_mov_b32 m0, s22
	s_waitcnt vmcnt(4)
	s_waitcnt lgkmcnt(0)
	s_barrier
	s_setprio 1
	.p2align 3
	v_mfma_f32_16x16x32_bf16 v[62:65], v[148:151], v[180:183], v[62:65]
	v_mfma_f32_16x16x32_bf16 v[62:65], v[152:155], v[184:187], v[62:65]
	v_mfma_f32_16x16x32_bf16 v[58:61], v[156:159], v[180:183], v[58:61]
	v_mfma_f32_16x16x32_bf16 v[58:61], v[160:163], v[184:187], v[58:61]
	v_mfma_f32_16x16x32_bf16 v[42:45], v[156:159], v[188:191], v[42:45]
	v_mfma_f32_16x16x32_bf16 v[42:45], v[160:163], v[192:195], v[42:45]
	v_mfma_f32_16x16x32_bf16 v[46:49], v[148:151], v[188:191], v[46:49]
	v_mfma_f32_16x16x32_bf16 v[46:49], v[152:155], v[192:195], v[46:49]
	v_mfma_f32_16x16x32_bf16 v[30:33], v[148:151], v[196:199], v[30:33]
	v_mfma_f32_16x16x32_bf16 v[30:33], v[152:155], v[200:203], v[30:33]
	v_mfma_f32_16x16x32_bf16 v[26:29], v[156:159], v[196:199], v[26:29]
	v_mfma_f32_16x16x32_bf16 v[26:29], v[160:163], v[200:203], v[26:29]
	v_mfma_f32_16x16x32_bf16 v[10:13], v[156:159], v[204:207], v[10:13]
	v_mfma_f32_16x16x32_bf16 v[10:13], v[160:163], v[208:211], v[10:13]
	v_mfma_f32_16x16x32_bf16 v[14:17], v[148:151], v[204:207], v[14:17]
	v_mfma_f32_16x16x32_bf16 v[14:17], v[152:155], v[208:211], v[14:17]
	s_setprio 0
	s_setprio 1
	v_mfma_f32_16x16x32_bf16 v[54:57], v[164:167], v[180:183], v[54:57]
	v_mfma_f32_16x16x32_bf16 v[54:57], v[168:171], v[184:187], v[54:57]
	v_mfma_f32_16x16x32_bf16 v[50:53], v[172:175], v[180:183], v[50:53]
	v_mfma_f32_16x16x32_bf16 v[50:53], v[176:179], v[184:187], v[50:53]
	v_mfma_f32_16x16x32_bf16 v[34:37], v[172:175], v[188:191], v[34:37]
	v_mfma_f32_16x16x32_bf16 v[34:37], v[176:179], v[192:195], v[34:37]
	v_mfma_f32_16x16x32_bf16 v[38:41], v[164:167], v[188:191], v[38:41]
	v_mfma_f32_16x16x32_bf16 v[38:41], v[168:171], v[192:195], v[38:41]
	v_mfma_f32_16x16x32_bf16 v[22:25], v[164:167], v[196:199], v[22:25]
	v_mfma_f32_16x16x32_bf16 v[22:25], v[168:171], v[200:203], v[22:25]
	v_mfma_f32_16x16x32_bf16 v[18:21], v[172:175], v[196:199], v[18:21]
	v_mfma_f32_16x16x32_bf16 v[18:21], v[176:179], v[200:203], v[18:21]
	v_mfma_f32_16x16x32_bf16 v[2:5], v[172:175], v[204:207], v[2:5]
	v_mfma_f32_16x16x32_bf16 v[2:5], v[176:179], v[208:211], v[2:5]
	s_setprio 2
	s_barrier
	v_mfma_f32_16x16x32_bf16 v[6:9], v[164:167], v[204:207], v[6:9]
	v_mfma_f32_16x16x32_bf16 v[6:9], v[168:171], v[208:211], v[6:9]
	s_setprio 0
	s_add_i32 s73, s73, 2
	s_add_u32 s66, s66, 0x100
	s_addc_u32 s67, s67, 0
	s_add_u32 s18, s18, 0x100
	s_addc_u32 s19, s19, 0
	s_add_u32 s70, s70, 0x100
	s_addc_u32 s71, s71, 0
	s_cmp_gt_u32 s73, 29
	.p2align 6
.LBB0_1785:
	ds_read_b128 v[148:151], v143
	ds_read_b128 v[152:155], v143 offset:1024
	ds_read_b128 v[156:159], v143 offset:2048
	ds_read_b128 v[160:163], v143 offset:3072
	ds_read_b128 v[164:167], v144
	ds_read_b128 v[168:171], v144 offset:1024
	ds_read_b128 v[172:175], v144 offset:2048
	ds_read_b128 v[176:179], v144 offset:3072
	s_cmp_eq_u32 s73, 28
	s_cselect_b32 s21, s9, s67
	s_cselect_b32 s20, s65, s66
	s_cselect_b32 s23, s11, s71
	s_cselect_b32 s22, s64, s70
	ds_read_b128 v[180:183], v145
	ds_read_b128 v[184:187], v145 offset:1024
	ds_read_b128 v[188:191], v145 offset:2048
	ds_read_b128 v[192:195], v145 offset:3072
	ds_read_b128 v[196:199], v145 offset:4096
	ds_read_b128 v[200:203], v145 offset:5120
	ds_read_b128 v[204:207], v145 offset:6144
	ds_read_b128 v[208:211], v145 offset:7168
	s_add_u32 s74, s18, 0xfff80000
	s_addc_u32 s75, s19, -1
	s_mov_b32 s76, m0
	s_mov_b32 m0, s56
	s_nop 0
	global_load_lds_dwordx4 v138, s[74:75]
	s_mov_b32 m0, s76
	s_nop 0
	s_mov_b32 s76, m0
	s_mov_b32 m0, s59
	s_nop 0
	global_load_lds_dwordx4 v140, s[74:75]
	s_mov_b32 m0, s76
	s_mov_b32 s74, m0
	s_mov_b32 m0, s57
	s_nop 0
	global_load_lds_dwordx4 v138, s[18:19]
	s_mov_b32 m0, s74
	s_nop 0
	s_mov_b32 s74, m0
	s_mov_b32 m0, s62
	s_nop 0
	global_load_lds_dwordx4 v140, s[18:19]
	s_mov_b32 m0, s74
	s_waitcnt vmcnt(8)
	s_waitcnt lgkmcnt(0)
	s_barrier
	s_setprio 1
	.p2align 3
	v_mfma_f32_16x16x32_bf16 v[126:129], v[148:151], v[180:183], v[126:129]
	v_mfma_f32_16x16x32_bf16 v[126:129], v[152:155], v[184:187], v[126:129]
	v_mfma_f32_16x16x32_bf16 v[122:125], v[156:159], v[180:183], v[122:125]
	v_mfma_f32_16x16x32_bf16 v[122:125], v[160:163], v[184:187], v[122:125]
	v_mfma_f32_16x16x32_bf16 v[106:109], v[156:159], v[188:191], v[106:109]
	v_mfma_f32_16x16x32_bf16 v[106:109], v[160:163], v[192:195], v[106:109]
	v_mfma_f32_16x16x32_bf16 v[110:113], v[148:151], v[188:191], v[110:113]
	v_mfma_f32_16x16x32_bf16 v[110:113], v[152:155], v[192:195], v[110:113]
	v_mfma_f32_16x16x32_bf16 v[94:97], v[148:151], v[196:199], v[94:97]
	v_mfma_f32_16x16x32_bf16 v[94:97], v[152:155], v[200:203], v[94:97]
	v_mfma_f32_16x16x32_bf16 v[90:93], v[156:159], v[196:199], v[90:93]
	v_mfma_f32_16x16x32_bf16 v[90:93], v[160:163], v[200:203], v[90:93]
	v_mfma_f32_16x16x32_bf16 v[74:77], v[156:159], v[204:207], v[74:77]
	v_mfma_f32_16x16x32_bf16 v[74:77], v[160:163], v[208:211], v[74:77]
	v_mfma_f32_16x16x32_bf16 v[78:81], v[148:151], v[204:207], v[78:81]
	v_mfma_f32_16x16x32_bf16 v[78:81], v[152:155], v[208:211], v[78:81]
	s_setprio 0
	s_setprio 1
	v_mfma_f32_16x16x32_bf16 v[118:121], v[164:167], v[180:183], v[118:121]
	v_mfma_f32_16x16x32_bf16 v[118:121], v[168:171], v[184:187], v[118:121]
	v_mfma_f32_16x16x32_bf16 v[114:117], v[172:175], v[180:183], v[114:117]
	v_mfma_f32_16x16x32_bf16 v[114:117], v[176:179], v[184:187], v[114:117]
	v_mfma_f32_16x16x32_bf16 v[98:101], v[172:175], v[188:191], v[98:101]
	v_mfma_f32_16x16x32_bf16 v[98:101], v[176:179], v[192:195], v[98:101]
	v_mfma_f32_16x16x32_bf16 v[102:105], v[164:167], v[188:191], v[102:105]
	v_mfma_f32_16x16x32_bf16 v[102:105], v[168:171], v[192:195], v[102:105]
	v_mfma_f32_16x16x32_bf16 v[86:89], v[164:167], v[196:199], v[86:89]
	v_mfma_f32_16x16x32_bf16 v[86:89], v[168:171], v[200:203], v[86:89]
	v_mfma_f32_16x16x32_bf16 v[82:85], v[172:175], v[196:199], v[82:85]
	v_mfma_f32_16x16x32_bf16 v[82:85], v[176:179], v[200:203], v[82:85]
	v_mfma_f32_16x16x32_bf16 v[66:69], v[172:175], v[204:207], v[66:69]
	v_mfma_f32_16x16x32_bf16 v[66:69], v[176:179], v[208:211], v[66:69]
	s_setprio 2
	s_barrier
	v_mfma_f32_16x16x32_bf16 v[70:73], v[164:167], v[204:207], v[70:73]
	v_mfma_f32_16x16x32_bf16 v[70:73], v[168:171], v[208:211], v[70:73]
	s_setprio 0
	ds_read_b128 v[180:183], v145 offset:16384
	ds_read_b128 v[184:187], v145 offset:17408
	ds_read_b128 v[188:191], v145 offset:18432
	ds_read_b128 v[192:195], v145 offset:19456
	ds_read_b128 v[196:199], v145 offset:20480
	ds_read_b128 v[200:203], v145 offset:21504
	ds_read_b128 v[204:207], v145 offset:22528
	ds_read_b128 v[208:211], v145 offset:23552
	s_mov_b32 s74, m0
	s_mov_b32 m0, s35
	s_nop 0
	global_load_lds_dwordx4 v139, s[20:21]
	s_mov_b32 m0, s74
	s_nop 0
	s_mov_b32 s74, m0
	s_mov_b32 m0, s36
	s_nop 0
	global_load_lds_dwordx4 v141, s[20:21]
	s_mov_b32 m0, s74
	s_add_u32 s74, s20, 0x80000
	s_addc_u32 s75, s21, 0
	s_mov_b32 s76, m0
	s_mov_b32 m0, s37
	s_nop 0
	global_load_lds_dwordx4 v139, s[74:75]
	s_mov_b32 m0, s76
	s_nop 0
	s_mov_b32 s76, m0
	s_mov_b32 m0, s40
	s_nop 0
	global_load_lds_dwordx4 v141, s[74:75]
	s_mov_b32 m0, s76
	s_waitcnt vmcnt(4)
	s_waitcnt lgkmcnt(0)
	s_barrier
	s_setprio 1
	.p2align 3
	v_mfma_f32_16x16x32_bf16 v[62:65], v[148:151], v[180:183], v[62:65]
	v_mfma_f32_16x16x32_bf16 v[62:65], v[152:155], v[184:187], v[62:65]
	v_mfma_f32_16x16x32_bf16 v[58:61], v[156:159], v[180:183], v[58:61]
	v_mfma_f32_16x16x32_bf16 v[58:61], v[160:163], v[184:187], v[58:61]
	v_mfma_f32_16x16x32_bf16 v[42:45], v[156:159], v[188:191], v[42:45]
	v_mfma_f32_16x16x32_bf16 v[42:45], v[160:163], v[192:195], v[42:45]
	v_mfma_f32_16x16x32_bf16 v[46:49], v[148:151], v[188:191], v[46:49]
	v_mfma_f32_16x16x32_bf16 v[46:49], v[152:155], v[192:195], v[46:49]
	v_mfma_f32_16x16x32_bf16 v[30:33], v[148:151], v[196:199], v[30:33]
	v_mfma_f32_16x16x32_bf16 v[30:33], v[152:155], v[200:203], v[30:33]
	v_mfma_f32_16x16x32_bf16 v[26:29], v[156:159], v[196:199], v[26:29]
	v_mfma_f32_16x16x32_bf16 v[26:29], v[160:163], v[200:203], v[26:29]
	v_mfma_f32_16x16x32_bf16 v[10:13], v[156:159], v[204:207], v[10:13]
	v_mfma_f32_16x16x32_bf16 v[10:13], v[160:163], v[208:211], v[10:13]
	v_mfma_f32_16x16x32_bf16 v[14:17], v[148:151], v[204:207], v[14:17]
	v_mfma_f32_16x16x32_bf16 v[14:17], v[152:155], v[208:211], v[14:17]
	s_setprio 0
	s_setprio 1
	v_mfma_f32_16x16x32_bf16 v[54:57], v[164:167], v[180:183], v[54:57]
	v_mfma_f32_16x16x32_bf16 v[54:57], v[168:171], v[184:187], v[54:57]
	v_mfma_f32_16x16x32_bf16 v[50:53], v[172:175], v[180:183], v[50:53]
	v_mfma_f32_16x16x32_bf16 v[50:53], v[176:179], v[184:187], v[50:53]
	v_mfma_f32_16x16x32_bf16 v[34:37], v[172:175], v[188:191], v[34:37]
	v_mfma_f32_16x16x32_bf16 v[34:37], v[176:179], v[192:195], v[34:37]
	v_mfma_f32_16x16x32_bf16 v[38:41], v[164:167], v[188:191], v[38:41]
	v_mfma_f32_16x16x32_bf16 v[38:41], v[168:171], v[192:195], v[38:41]
	v_mfma_f32_16x16x32_bf16 v[22:25], v[164:167], v[196:199], v[22:25]
	v_mfma_f32_16x16x32_bf16 v[22:25], v[168:171], v[200:203], v[22:25]
	v_mfma_f32_16x16x32_bf16 v[18:21], v[172:175], v[196:199], v[18:21]
	v_mfma_f32_16x16x32_bf16 v[18:21], v[176:179], v[200:203], v[18:21]
	v_mfma_f32_16x16x32_bf16 v[2:5], v[172:175], v[204:207], v[2:5]
	v_mfma_f32_16x16x32_bf16 v[2:5], v[176:179], v[208:211], v[2:5]
	s_setprio 2
	s_barrier
	v_mfma_f32_16x16x32_bf16 v[6:9], v[164:167], v[204:207], v[6:9]
	v_mfma_f32_16x16x32_bf16 v[6:9], v[168:171], v[208:211], v[6:9]
	s_setprio 0
	ds_read_b128 v[148:151], v146
	ds_read_b128 v[152:155], v146 offset:1024
	ds_read_b128 v[156:159], v146 offset:2048
	ds_read_b128 v[160:163], v146 offset:3072
	ds_read_b128 v[164:167], v147
	ds_read_b128 v[168:171], v147 offset:1024
	ds_read_b128 v[172:175], v147 offset:2048
	ds_read_b128 v[176:179], v147 offset:3072
	ds_read_b128 v[180:183], v145 offset:32768
	ds_read_b128 v[184:187], v145 offset:33792
	ds_read_b128 v[188:191], v145 offset:34816
	ds_read_b128 v[192:195], v145 offset:35840
	ds_read_b128 v[196:199], v145 offset:36864
	ds_read_b128 v[200:203], v145 offset:37888
	ds_read_b128 v[204:207], v145 offset:38912
	ds_read_b128 v[208:211], v145 offset:39936
	s_mov_b32 s74, m0
	s_mov_b32 m0, s31
	s_nop 0
	global_load_lds_dwordx4 v138, s[22:23]
	s_mov_b32 m0, s74
	s_nop 0
	s_mov_b32 s74, m0
	s_mov_b32 m0, s41
	s_nop 0
	global_load_lds_dwordx4 v140, s[22:23]
	s_mov_b32 m0, s74
	s_add_u32 s22, s22, 0x80000
	s_addc_u32 s23, s23, 0
	s_mov_b32 s74, m0
	s_mov_b32 m0, s42
	s_nop 0
	global_load_lds_dwordx4 v138, s[22:23]
	s_mov_b32 m0, s74
	s_nop 0
	s_mov_b32 s74, m0
	s_mov_b32 m0, s43
	s_nop 0
	global_load_lds_dwordx4 v140, s[22:23]
	s_mov_b32 m0, s74
	s_waitcnt vmcnt(8)
	s_waitcnt lgkmcnt(0)
	s_barrier
	s_setprio 1
	.p2align 3
	v_mfma_f32_16x16x32_bf16 v[126:129], v[148:151], v[180:183], v[126:129]
	v_mfma_f32_16x16x32_bf16 v[126:129], v[152:155], v[184:187], v[126:129]
	v_mfma_f32_16x16x32_bf16 v[122:125], v[156:159], v[180:183], v[122:125]
	v_mfma_f32_16x16x32_bf16 v[122:125], v[160:163], v[184:187], v[122:125]
	v_mfma_f32_16x16x32_bf16 v[106:109], v[156:159], v[188:191], v[106:109]
	v_mfma_f32_16x16x32_bf16 v[106:109], v[160:163], v[192:195], v[106:109]
	v_mfma_f32_16x16x32_bf16 v[110:113], v[148:151], v[188:191], v[110:113]
	v_mfma_f32_16x16x32_bf16 v[110:113], v[152:155], v[192:195], v[110:113]
	v_mfma_f32_16x16x32_bf16 v[94:97], v[148:151], v[196:199], v[94:97]
	v_mfma_f32_16x16x32_bf16 v[94:97], v[152:155], v[200:203], v[94:97]
	v_mfma_f32_16x16x32_bf16 v[90:93], v[156:159], v[196:199], v[90:93]
	v_mfma_f32_16x16x32_bf16 v[90:93], v[160:163], v[200:203], v[90:93]
	v_mfma_f32_16x16x32_bf16 v[74:77], v[156:159], v[204:207], v[74:77]
	v_mfma_f32_16x16x32_bf16 v[74:77], v[160:163], v[208:211], v[74:77]
	v_mfma_f32_16x16x32_bf16 v[78:81], v[148:151], v[204:207], v[78:81]
	v_mfma_f32_16x16x32_bf16 v[78:81], v[152:155], v[208:211], v[78:81]
	s_setprio 0
	s_setprio 1
	v_mfma_f32_16x16x32_bf16 v[118:121], v[164:167], v[180:183], v[118:121]
	v_mfma_f32_16x16x32_bf16 v[118:121], v[168:171], v[184:187], v[118:121]
	v_mfma_f32_16x16x32_bf16 v[114:117], v[172:175], v[180:183], v[114:117]
	v_mfma_f32_16x16x32_bf16 v[114:117], v[176:179], v[184:187], v[114:117]
	v_mfma_f32_16x16x32_bf16 v[98:101], v[172:175], v[188:191], v[98:101]
	v_mfma_f32_16x16x32_bf16 v[98:101], v[176:179], v[192:195], v[98:101]
	v_mfma_f32_16x16x32_bf16 v[102:105], v[164:167], v[188:191], v[102:105]
	v_mfma_f32_16x16x32_bf16 v[102:105], v[168:171], v[192:195], v[102:105]
	v_mfma_f32_16x16x32_bf16 v[86:89], v[164:167], v[196:199], v[86:89]
	v_mfma_f32_16x16x32_bf16 v[86:89], v[168:171], v[200:203], v[86:89]
	v_mfma_f32_16x16x32_bf16 v[82:85], v[172:175], v[196:199], v[82:85]
	v_mfma_f32_16x16x32_bf16 v[82:85], v[176:179], v[200:203], v[82:85]
	v_mfma_f32_16x16x32_bf16 v[66:69], v[172:175], v[204:207], v[66:69]
	v_mfma_f32_16x16x32_bf16 v[66:69], v[176:179], v[208:211], v[66:69]
	s_setprio 2
	s_barrier
	v_mfma_f32_16x16x32_bf16 v[70:73], v[164:167], v[204:207], v[70:73]
	v_mfma_f32_16x16x32_bf16 v[70:73], v[168:171], v[208:211], v[70:73]
	s_setprio 0
	ds_read_b128 v[180:183], v145 offset:49152
	ds_read_b128 v[184:187], v145 offset:50176
	ds_read_b128 v[188:191], v145 offset:51200
	ds_read_b128 v[192:195], v145 offset:52224
	ds_read_b128 v[196:199], v145 offset:53248
	ds_read_b128 v[200:203], v145 offset:54272
	ds_read_b128 v[204:207], v145 offset:55296
	ds_read_b128 v[208:211], v145 offset:56320
	s_add_u32 s22, s20, 0x80
	s_addc_u32 s23, s21, 0
	s_mov_b32 s74, m0
	s_mov_b32 m0, s46
	s_nop 0
	global_load_lds_dwordx4 v139, s[22:23]
	s_mov_b32 m0, s74
	s_add_u32 s20, s20, 0x80080
	s_mov_b32 s74, m0
	s_mov_b32 m0, s47
	s_nop 0
	global_load_lds_dwordx4 v141, s[22:23]
	s_mov_b32 m0, s74
	s_addc_u32 s21, s21, 0
	s_mov_b32 s22, m0
	s_mov_b32 m0, s48
	s_nop 0
	global_load_lds_dwordx4 v139, s[20:21]
	s_mov_b32 m0, s22
	s_nop 0
	s_mov_b32 s22, m0
	s_mov_b32 m0, s49
	s_nop 0
	global_load_lds_dwordx4 v141, s[20:21]
	s_mov_b32 m0, s22
	s_waitcnt vmcnt(4)
	s_waitcnt lgkmcnt(0)
	s_barrier
	s_setprio 1
	.p2align 3
	v_mfma_f32_16x16x32_bf16 v[62:65], v[148:151], v[180:183], v[62:65]
	v_mfma_f32_16x16x32_bf16 v[62:65], v[152:155], v[184:187], v[62:65]
	v_mfma_f32_16x16x32_bf16 v[58:61], v[156:159], v[180:183], v[58:61]
	v_mfma_f32_16x16x32_bf16 v[58:61], v[160:163], v[184:187], v[58:61]
	v_mfma_f32_16x16x32_bf16 v[42:45], v[156:159], v[188:191], v[42:45]
	v_mfma_f32_16x16x32_bf16 v[42:45], v[160:163], v[192:195], v[42:45]
	v_mfma_f32_16x16x32_bf16 v[46:49], v[148:151], v[188:191], v[46:49]
	v_mfma_f32_16x16x32_bf16 v[46:49], v[152:155], v[192:195], v[46:49]
	v_mfma_f32_16x16x32_bf16 v[30:33], v[148:151], v[196:199], v[30:33]
	v_mfma_f32_16x16x32_bf16 v[30:33], v[152:155], v[200:203], v[30:33]
	v_mfma_f32_16x16x32_bf16 v[26:29], v[156:159], v[196:199], v[26:29]
	v_mfma_f32_16x16x32_bf16 v[26:29], v[160:163], v[200:203], v[26:29]
	v_mfma_f32_16x16x32_bf16 v[10:13], v[156:159], v[204:207], v[10:13]
	v_mfma_f32_16x16x32_bf16 v[10:13], v[160:163], v[208:211], v[10:13]
	v_mfma_f32_16x16x32_bf16 v[14:17], v[148:151], v[204:207], v[14:17]
	v_mfma_f32_16x16x32_bf16 v[14:17], v[152:155], v[208:211], v[14:17]
	s_setprio 0
	s_setprio 1
	v_mfma_f32_16x16x32_bf16 v[54:57], v[164:167], v[180:183], v[54:57]
	v_mfma_f32_16x16x32_bf16 v[54:57], v[168:171], v[184:187], v[54:57]
	v_mfma_f32_16x16x32_bf16 v[50:53], v[172:175], v[180:183], v[50:53]
	v_mfma_f32_16x16x32_bf16 v[50:53], v[176:179], v[184:187], v[50:53]
	v_mfma_f32_16x16x32_bf16 v[34:37], v[172:175], v[188:191], v[34:37]
	v_mfma_f32_16x16x32_bf16 v[34:37], v[176:179], v[192:195], v[34:37]
	v_mfma_f32_16x16x32_bf16 v[38:41], v[164:167], v[188:191], v[38:41]
	v_mfma_f32_16x16x32_bf16 v[38:41], v[168:171], v[192:195], v[38:41]
	v_mfma_f32_16x16x32_bf16 v[22:25], v[164:167], v[196:199], v[22:25]
	v_mfma_f32_16x16x32_bf16 v[22:25], v[168:171], v[200:203], v[22:25]
	v_mfma_f32_16x16x32_bf16 v[18:21], v[172:175], v[196:199], v[18:21]
	v_mfma_f32_16x16x32_bf16 v[18:21], v[176:179], v[200:203], v[18:21]
	v_mfma_f32_16x16x32_bf16 v[2:5], v[172:175], v[204:207], v[2:5]
	v_mfma_f32_16x16x32_bf16 v[2:5], v[176:179], v[208:211], v[2:5]
	s_setprio 2
	s_barrier
	v_mfma_f32_16x16x32_bf16 v[6:9], v[164:167], v[204:207], v[6:9]
	v_mfma_f32_16x16x32_bf16 v[6:9], v[168:171], v[208:211], v[6:9]
	s_setprio 0
	s_add_i32 s73, s73, 2
	s_add_u32 s66, s66, 0x100
	s_addc_u32 s67, s67, 0
	s_add_u32 s18, s18, 0x100
	s_addc_u32 s19, s19, 0
	s_add_u32 s70, s70, 0x100
	s_addc_u32 s71, s71, 0
	s_cmp_gt_u32 s73, 29
	s_cbranch_scc0 .LBB0_1785
	s_and_b64 vcc, exec, s[6:7]
	s_cbranch_vccz .LBB0_1788
	s_barrier

.LBB0_1951:
	s_ashr_i32 s13, s12, 31
	s_lshl_b64 s[14:15], s[12:13], 15
	s_add_u32 s14, s28, s14
	s_addc_u32 s15, s29, s15
	s_and_b64 s[16:17], s[2:3], exec
	s_cselect_b32 s13, s15, s23
	s_cselect_b32 s65, s14, s22
	s_ashr_i32 s11, s10, 31
	s_lshl_b64 s[16:17], s[10:11], 15
	s_add_u32 s16, s30, s16
	s_addc_u32 s17, s31, s17
	s_and_b64 s[24:25], s[2:3], exec
	s_cselect_b32 s11, s17, s21
	s_cselect_b32 s66, s16, s20
	s_add_u32 s67, s20, 0x80000
	s_addc_u32 s70, s21, 0
	s_add_u32 s20, s22, 0x204000
	s_addc_u32 s21, s23, 0
	s_add_u32 s71, s22, 0x400000
	s_addc_u32 s73, s23, 0
	s_mov_b32 s74, -2
	s_waitcnt vmcnt(25)
	s_waitcnt vmcnt(24)
	s_waitcnt vmcnt(4)
	s_waitcnt vmcnt(2)
	s_waitcnt vmcnt(1)
	s_waitcnt vmcnt(0)
	ds_read_b128 v[130:133], v181
	ds_read_b128 v[134:137], v181 offset:1024
	ds_read_b128 v[138:141], v181 offset:2048
	ds_read_b128 v[142:145], v181 offset:3072
	ds_read_b128 v[150:153], v182
	ds_read_b128 v[154:157], v182 offset:1024
	ds_read_b128 v[158:161], v182 offset:2048
	ds_read_b128 v[162:165], v182 offset:3072
	s_cmpk_eq_i32 s74, 0x52
	s_cselect_b32 s23, s11, s70
	s_cselect_b32 s22, s66, s67
	s_cselect_b32 s25, s13, s73
	s_cselect_b32 s24, s65, s71
	ds_read_b128 v[166:169], v183
	ds_read_b128 v[170:173], v183 offset:1024
	ds_read_b128 v[186:189], v183 offset:2048
	ds_read_b128 v[190:193], v183 offset:3072
	ds_read_b128 v[194:197], v183 offset:4096
	ds_read_b128 v[198:201], v183 offset:5120
	ds_read_b128 v[202:205], v183 offset:6144
	ds_read_b128 v[206:209], v183 offset:7168
	s_add_u32 s76, s20, 0xffffc000
	s_addc_u32 s77, s21, -1
	s_mov_b32 s75, m0
	s_mov_b32 m0, s58
	s_nop 0
	global_load_lds_dwordx4 v1, s[76:77]
	s_mov_b32 m0, s75
	s_nop 0
	s_mov_b32 s75, m0
	s_mov_b32 m0, s62
	s_nop 0
	global_load_lds_dwordx4 v177, s[76:77]
	s_mov_b32 m0, s75
	s_nop 0
	s_mov_b32 s75, m0
	s_mov_b32 m0, s59
	s_nop 0
	global_load_lds_dwordx4 v1, s[20:21]
	s_mov_b32 m0, s75
	s_nop 0
	s_mov_b32 s75, m0
	s_mov_b32 m0, s63
	s_nop 0
	global_load_lds_dwordx4 v177, s[20:21]
	s_mov_b32 m0, s75
	s_waitcnt vmcnt(8)
	s_waitcnt lgkmcnt(0)
	s_barrier
	s_setprio 1
	.p2align 3
	v_mfma_f32_16x16x32_bf16 v[126:129], v[130:133], v[166:169], 0
	v_mfma_f32_16x16x32_bf16 v[126:129], v[134:137], v[170:173], v[126:129]
	v_mfma_f32_16x16x32_bf16 v[122:125], v[138:141], v[166:169], 0
	v_mfma_f32_16x16x32_bf16 v[122:125], v[142:145], v[170:173], v[122:125]
	v_mfma_f32_16x16x32_bf16 v[110:113], v[138:141], v[186:189], 0
	v_mfma_f32_16x16x32_bf16 v[110:113], v[142:145], v[190:193], v[110:113]
	v_mfma_f32_16x16x32_bf16 v[118:121], v[130:133], v[186:189], 0
	v_mfma_f32_16x16x32_bf16 v[118:121], v[134:137], v[190:193], v[118:121]
	v_mfma_f32_16x16x32_bf16 v[94:97], v[130:133], v[194:197], 0
	v_mfma_f32_16x16x32_bf16 v[94:97], v[134:137], v[198:201], v[94:97]
	v_mfma_f32_16x16x32_bf16 v[90:93], v[138:141], v[194:197], 0
	v_mfma_f32_16x16x32_bf16 v[90:93], v[142:145], v[198:201], v[90:93]
	v_mfma_f32_16x16x32_bf16 v[78:81], v[138:141], v[202:205], 0
	v_mfma_f32_16x16x32_bf16 v[78:81], v[142:145], v[206:209], v[78:81]
	v_mfma_f32_16x16x32_bf16 v[86:89], v[130:133], v[202:205], 0
	v_mfma_f32_16x16x32_bf16 v[86:89], v[134:137], v[206:209], v[86:89]
	s_setprio 0
	s_setprio 1
	v_mfma_f32_16x16x32_bf16 v[114:117], v[150:153], v[166:169], 0
	v_mfma_f32_16x16x32_bf16 v[114:117], v[154:157], v[170:173], v[114:117]
	v_mfma_f32_16x16x32_bf16 v[106:109], v[158:161], v[166:169], 0
	v_mfma_f32_16x16x32_bf16 v[106:109], v[162:165], v[170:173], v[106:109]
	v_mfma_f32_16x16x32_bf16 v[98:101], v[158:161], v[186:189], 0
	v_mfma_f32_16x16x32_bf16 v[98:101], v[162:165], v[190:193], v[98:101]
	v_mfma_f32_16x16x32_bf16 v[102:105], v[150:153], v[186:189], 0
	v_mfma_f32_16x16x32_bf16 v[102:105], v[154:157], v[190:193], v[102:105]
	v_mfma_f32_16x16x32_bf16 v[82:85], v[150:153], v[194:197], 0
	v_mfma_f32_16x16x32_bf16 v[82:85], v[154:157], v[198:201], v[82:85]
	v_mfma_f32_16x16x32_bf16 v[74:77], v[158:161], v[194:197], 0
	v_mfma_f32_16x16x32_bf16 v[74:77], v[162:165], v[198:201], v[74:77]
	v_mfma_f32_16x16x32_bf16 v[66:69], v[158:161], v[202:205], 0
	v_mfma_f32_16x16x32_bf16 v[66:69], v[162:165], v[206:209], v[66:69]
	s_setprio 2
	s_barrier
	v_mfma_f32_16x16x32_bf16 v[70:73], v[150:153], v[202:205], 0
	v_mfma_f32_16x16x32_bf16 v[70:73], v[154:157], v[206:209], v[70:73]
	s_setprio 0
	ds_read_b128 v[166:169], v183 offset:16384
	ds_read_b128 v[170:173], v183 offset:17408
	ds_read_b128 v[186:189], v183 offset:18432
	ds_read_b128 v[190:193], v183 offset:19456
	ds_read_b128 v[194:197], v183 offset:20480
	ds_read_b128 v[198:201], v183 offset:21504
	ds_read_b128 v[202:205], v183 offset:22528
	ds_read_b128 v[206:209], v183 offset:23552
	s_mov_b32 s75, m0
	s_mov_b32 m0, s35
	s_nop 0
	global_load_lds_dwordx4 v176, s[22:23]
	s_mov_b32 m0, s75
	s_add_u32 s76, s22, 0x4000
	s_mov_b32 s75, m0
	s_mov_b32 m0, s36
	s_nop 0
	global_load_lds_dwordx4 v178, s[22:23]
	s_mov_b32 m0, s75
	s_addc_u32 s77, s23, 0
	s_mov_b32 s75, m0
	s_mov_b32 m0, s37
	s_nop 0
	global_load_lds_dwordx4 v176, s[76:77]
	s_mov_b32 m0, s75
	s_nop 0
	s_mov_b32 s75, m0
	s_mov_b32 m0, s40
	s_nop 0
	global_load_lds_dwordx4 v178, s[76:77]
	s_mov_b32 m0, s75
	s_waitcnt vmcnt(4)
	s_waitcnt lgkmcnt(0)
	s_barrier
	s_setprio 1
	.p2align 3
	v_mfma_f32_16x16x32_bf16 v[62:65], v[130:133], v[166:169], 0
	v_mfma_f32_16x16x32_bf16 v[62:65], v[134:137], v[170:173], v[62:65]
	v_mfma_f32_16x16x32_bf16 v[58:61], v[138:141], v[166:169], 0
	v_mfma_f32_16x16x32_bf16 v[58:61], v[142:145], v[170:173], v[58:61]
	v_mfma_f32_16x16x32_bf16 v[42:45], v[138:141], v[186:189], 0
	v_mfma_f32_16x16x32_bf16 v[42:45], v[142:145], v[190:193], v[42:45]
	v_mfma_f32_16x16x32_bf16 v[46:49], v[130:133], v[186:189], 0
	v_mfma_f32_16x16x32_bf16 v[46:49], v[134:137], v[190:193], v[46:49]
	v_mfma_f32_16x16x32_bf16 v[30:33], v[130:133], v[194:197], 0
	v_mfma_f32_16x16x32_bf16 v[30:33], v[134:137], v[198:201], v[30:33]
	v_mfma_f32_16x16x32_bf16 v[26:29], v[138:141], v[194:197], 0
	v_mfma_f32_16x16x32_bf16 v[26:29], v[142:145], v[198:201], v[26:29]
	v_mfma_f32_16x16x32_bf16 v[10:13], v[138:141], v[202:205], 0
	v_mfma_f32_16x16x32_bf16 v[10:13], v[142:145], v[206:209], v[10:13]
	v_mfma_f32_16x16x32_bf16 v[14:17], v[130:133], v[202:205], 0
	v_mfma_f32_16x16x32_bf16 v[14:17], v[134:137], v[206:209], v[14:17]
	s_setprio 0
	s_setprio 1
	v_mfma_f32_16x16x32_bf16 v[54:57], v[150:153], v[166:169], 0
	v_mfma_f32_16x16x32_bf16 v[54:57], v[154:157], v[170:173], v[54:57]
	v_mfma_f32_16x16x32_bf16 v[50:53], v[158:161], v[166:169], 0
	v_mfma_f32_16x16x32_bf16 v[50:53], v[162:165], v[170:173], v[50:53]
	v_mfma_f32_16x16x32_bf16 v[34:37], v[158:161], v[186:189], 0
	v_mfma_f32_16x16x32_bf16 v[34:37], v[162:165], v[190:193], v[34:37]
	v_mfma_f32_16x16x32_bf16 v[38:41], v[150:153], v[186:189], 0
	v_mfma_f32_16x16x32_bf16 v[38:41], v[154:157], v[190:193], v[38:41]
	v_mfma_f32_16x16x32_bf16 v[22:25], v[150:153], v[194:197], 0
	v_mfma_f32_16x16x32_bf16 v[22:25], v[154:157], v[198:201], v[22:25]
	v_mfma_f32_16x16x32_bf16 v[18:21], v[158:161], v[194:197], 0
	v_mfma_f32_16x16x32_bf16 v[18:21], v[162:165], v[198:201], v[18:21]
	v_mfma_f32_16x16x32_bf16 v[2:5], v[158:161], v[202:205], 0
	v_mfma_f32_16x16x32_bf16 v[2:5], v[162:165], v[206:209], v[2:5]
	s_setprio 2
	s_barrier
	v_mfma_f32_16x16x32_bf16 v[6:9], v[150:153], v[202:205], 0
	v_mfma_f32_16x16x32_bf16 v[6:9], v[154:157], v[206:209], v[6:9]
	s_setprio 0
	ds_read_b128 v[130:133], v184
	ds_read_b128 v[134:137], v184 offset:1024
	ds_read_b128 v[138:141], v184 offset:2048
	ds_read_b128 v[142:145], v184 offset:3072
	ds_read_b128 v[150:153], v185
	ds_read_b128 v[154:157], v185 offset:1024
	ds_read_b128 v[158:161], v185 offset:2048
	ds_read_b128 v[162:165], v185 offset:3072
	ds_read_b128 v[166:169], v183 offset:32768
	ds_read_b128 v[170:173], v183 offset:33792
	ds_read_b128 v[186:189], v183 offset:34816
	ds_read_b128 v[190:193], v183 offset:35840
	ds_read_b128 v[194:197], v183 offset:36864
	ds_read_b128 v[198:201], v183 offset:37888
	ds_read_b128 v[202:205], v183 offset:38912
	ds_read_b128 v[206:209], v183 offset:39936
	s_mov_b32 s75, m0
	s_mov_b32 m0, s34
	s_nop 0
	global_load_lds_dwordx4 v1, s[24:25]
	s_mov_b32 m0, s75
	s_nop 0
	s_mov_b32 s75, m0
	s_mov_b32 m0, s41
	s_nop 0
	global_load_lds_dwordx4 v177, s[24:25]
	s_mov_b32 m0, s75
	s_add_u32 s24, s24, 0x4000
	s_addc_u32 s25, s25, 0
	s_mov_b32 s75, m0
	s_mov_b32 m0, s42
	s_nop 0
	global_load_lds_dwordx4 v1, s[24:25]
	s_mov_b32 m0, s75
	s_nop 0
	s_mov_b32 s75, m0
	s_mov_b32 m0, s43
	s_nop 0
	global_load_lds_dwordx4 v177, s[24:25]
	s_mov_b32 m0, s75
	s_waitcnt vmcnt(8)
	s_waitcnt lgkmcnt(0)
	s_barrier
	s_setprio 1
	.p2align 3
	v_mfma_f32_16x16x32_bf16 v[126:129], v[130:133], v[166:169], v[126:129]
	v_mfma_f32_16x16x32_bf16 v[126:129], v[134:137], v[170:173], v[126:129]
	v_mfma_f32_16x16x32_bf16 v[122:125], v[138:141], v[166:169], v[122:125]
	v_mfma_f32_16x16x32_bf16 v[122:125], v[142:145], v[170:173], v[122:125]
	v_mfma_f32_16x16x32_bf16 v[110:113], v[138:141], v[186:189], v[110:113]
	v_mfma_f32_16x16x32_bf16 v[110:113], v[142:145], v[190:193], v[110:113]
	v_mfma_f32_16x16x32_bf16 v[118:121], v[130:133], v[186:189], v[118:121]
	v_mfma_f32_16x16x32_bf16 v[118:121], v[134:137], v[190:193], v[118:121]
	v_mfma_f32_16x16x32_bf16 v[94:97], v[130:133], v[194:197], v[94:97]
	v_mfma_f32_16x16x32_bf16 v[94:97], v[134:137], v[198:201], v[94:97]
	v_mfma_f32_16x16x32_bf16 v[90:93], v[138:141], v[194:197], v[90:93]
	v_mfma_f32_16x16x32_bf16 v[90:93], v[142:145], v[198:201], v[90:93]
	v_mfma_f32_16x16x32_bf16 v[78:81], v[138:141], v[202:205], v[78:81]
	v_mfma_f32_16x16x32_bf16 v[78:81], v[142:145], v[206:209], v[78:81]
	v_mfma_f32_16x16x32_bf16 v[86:89], v[130:133], v[202:205], v[86:89]
	v_mfma_f32_16x16x32_bf16 v[86:89], v[134:137], v[206:209], v[86:89]
	s_setprio 0
	s_setprio 1
	v_mfma_f32_16x16x32_bf16 v[114:117], v[150:153], v[166:169], v[114:117]
	v_mfma_f32_16x16x32_bf16 v[114:117], v[154:157], v[170:173], v[114:117]
	v_mfma_f32_16x16x32_bf16 v[106:109], v[158:161], v[166:169], v[106:109]
	v_mfma_f32_16x16x32_bf16 v[106:109], v[162:165], v[170:173], v[106:109]
	v_mfma_f32_16x16x32_bf16 v[98:101], v[158:161], v[186:189], v[98:101]
	v_mfma_f32_16x16x32_bf16 v[98:101], v[162:165], v[190:193], v[98:101]
	v_mfma_f32_16x16x32_bf16 v[102:105], v[150:153], v[186:189], v[102:105]
	v_mfma_f32_16x16x32_bf16 v[102:105], v[154:157], v[190:193], v[102:105]
	v_mfma_f32_16x16x32_bf16 v[82:85], v[150:153], v[194:197], v[82:85]
	v_mfma_f32_16x16x32_bf16 v[82:85], v[154:157], v[198:201], v[82:85]
	v_mfma_f32_16x16x32_bf16 v[74:77], v[158:161], v[194:197], v[74:77]
	v_mfma_f32_16x16x32_bf16 v[74:77], v[162:165], v[198:201], v[74:77]
	v_mfma_f32_16x16x32_bf16 v[66:69], v[158:161], v[202:205], v[66:69]
	v_mfma_f32_16x16x32_bf16 v[66:69], v[162:165], v[206:209], v[66:69]
	s_setprio 2
	s_barrier
	v_mfma_f32_16x16x32_bf16 v[70:73], v[150:153], v[202:205], v[70:73]
	v_mfma_f32_16x16x32_bf16 v[70:73], v[154:157], v[206:209], v[70:73]
	s_setprio 0
	ds_read_b128 v[166:169], v183 offset:49152
	ds_read_b128 v[170:173], v183 offset:50176
	ds_read_b128 v[186:189], v183 offset:51200
	ds_read_b128 v[190:193], v183 offset:52224
	ds_read_b128 v[194:197], v183 offset:53248
	ds_read_b128 v[198:201], v183 offset:54272
	ds_read_b128 v[202:205], v183 offset:55296
	ds_read_b128 v[206:209], v183 offset:56320
	s_add_u32 s24, s22, 0x40000
	s_addc_u32 s25, s23, 0
	s_mov_b32 s75, m0
	s_mov_b32 m0, s46
	s_nop 0
	global_load_lds_dwordx4 v176, s[24:25]
	s_mov_b32 m0, s75
	s_add_u32 s22, s22, 0x44000
	s_mov_b32 s75, m0
	s_mov_b32 m0, s47
	s_nop 0
	global_load_lds_dwordx4 v178, s[24:25]
	s_mov_b32 m0, s75
	s_addc_u32 s23, s23, 0
	s_mov_b32 s24, m0
	s_mov_b32 m0, s48
	s_nop 0
	global_load_lds_dwordx4 v176, s[22:23]
	s_mov_b32 m0, s24
	s_nop 0
	s_mov_b32 s24, m0
	s_mov_b32 m0, s49
	s_nop 0
	global_load_lds_dwordx4 v178, s[22:23]
	s_mov_b32 m0, s24
	s_waitcnt vmcnt(4)
	s_waitcnt lgkmcnt(0)
	s_barrier
	s_setprio 1
	.p2align 3
	v_mfma_f32_16x16x32_bf16 v[62:65], v[130:133], v[166:169], v[62:65]
	v_mfma_f32_16x16x32_bf16 v[62:65], v[134:137], v[170:173], v[62:65]
	v_mfma_f32_16x16x32_bf16 v[58:61], v[138:141], v[166:169], v[58:61]
	v_mfma_f32_16x16x32_bf16 v[58:61], v[142:145], v[170:173], v[58:61]
	v_mfma_f32_16x16x32_bf16 v[42:45], v[138:141], v[186:189], v[42:45]
	v_mfma_f32_16x16x32_bf16 v[42:45], v[142:145], v[190:193], v[42:45]
	v_mfma_f32_16x16x32_bf16 v[46:49], v[130:133], v[186:189], v[46:49]
	v_mfma_f32_16x16x32_bf16 v[46:49], v[134:137], v[190:193], v[46:49]
	v_mfma_f32_16x16x32_bf16 v[30:33], v[130:133], v[194:197], v[30:33]
	v_mfma_f32_16x16x32_bf16 v[30:33], v[134:137], v[198:201], v[30:33]
	v_mfma_f32_16x16x32_bf16 v[26:29], v[138:141], v[194:197], v[26:29]
	v_mfma_f32_16x16x32_bf16 v[26:29], v[142:145], v[198:201], v[26:29]
	v_mfma_f32_16x16x32_bf16 v[10:13], v[138:141], v[202:205], v[10:13]
	v_mfma_f32_16x16x32_bf16 v[10:13], v[142:145], v[206:209], v[10:13]
	v_mfma_f32_16x16x32_bf16 v[14:17], v[130:133], v[202:205], v[14:17]
	v_mfma_f32_16x16x32_bf16 v[14:17], v[134:137], v[206:209], v[14:17]
	s_setprio 0
	s_setprio 1
	v_mfma_f32_16x16x32_bf16 v[54:57], v[150:153], v[166:169], v[54:57]
	v_mfma_f32_16x16x32_bf16 v[54:57], v[154:157], v[170:173], v[54:57]
	v_mfma_f32_16x16x32_bf16 v[50:53], v[158:161], v[166:169], v[50:53]
	v_mfma_f32_16x16x32_bf16 v[50:53], v[162:165], v[170:173], v[50:53]
	v_mfma_f32_16x16x32_bf16 v[34:37], v[158:161], v[186:189], v[34:37]
	v_mfma_f32_16x16x32_bf16 v[34:37], v[162:165], v[190:193], v[34:37]
	v_mfma_f32_16x16x32_bf16 v[38:41], v[150:153], v[186:189], v[38:41]
	v_mfma_f32_16x16x32_bf16 v[38:41], v[154:157], v[190:193], v[38:41]
	v_mfma_f32_16x16x32_bf16 v[22:25], v[150:153], v[194:197], v[22:25]
	v_mfma_f32_16x16x32_bf16 v[22:25], v[154:157], v[198:201], v[22:25]
	v_mfma_f32_16x16x32_bf16 v[18:21], v[158:161], v[194:197], v[18:21]
	v_mfma_f32_16x16x32_bf16 v[18:21], v[162:165], v[198:201], v[18:21]
	v_mfma_f32_16x16x32_bf16 v[2:5], v[158:161], v[202:205], v[2:5]
	v_mfma_f32_16x16x32_bf16 v[2:5], v[162:165], v[206:209], v[2:5]
	s_setprio 2
	s_barrier
	v_mfma_f32_16x16x32_bf16 v[6:9], v[150:153], v[202:205], v[6:9]
	v_mfma_f32_16x16x32_bf16 v[6:9], v[154:157], v[206:209], v[6:9]
	s_setprio 0
	s_add_i32 s74, s74, 2
	s_add_u32 s67, s67, 0x80000
	s_addc_u32 s70, s70, 0
	s_add_u32 s20, s20, 0x400000
	s_addc_u32 s21, s21, 0
	s_add_u32 s71, s71, 0x400000
	s_addc_u32 s73, s73, 0
	s_cmpk_gt_u32 s74, 0x53
	.p2align 6
.LBB0_1952:
	ds_read_b128 v[130:133], v181
	ds_read_b128 v[134:137], v181 offset:1024
	ds_read_b128 v[138:141], v181 offset:2048
	ds_read_b128 v[142:145], v181 offset:3072
	ds_read_b128 v[150:153], v182
	ds_read_b128 v[154:157], v182 offset:1024
	ds_read_b128 v[158:161], v182 offset:2048
	ds_read_b128 v[162:165], v182 offset:3072
	s_cmpk_eq_i32 s74, 0x52
	s_cselect_b32 s23, s11, s70
	s_cselect_b32 s22, s66, s67
	s_cselect_b32 s25, s13, s73
	s_cselect_b32 s24, s65, s71
	ds_read_b128 v[166:169], v183
	ds_read_b128 v[170:173], v183 offset:1024
	ds_read_b128 v[186:189], v183 offset:2048
	ds_read_b128 v[190:193], v183 offset:3072
	ds_read_b128 v[194:197], v183 offset:4096
	ds_read_b128 v[198:201], v183 offset:5120
	ds_read_b128 v[202:205], v183 offset:6144
	ds_read_b128 v[206:209], v183 offset:7168
	s_add_u32 s76, s20, 0xffffc000
	s_addc_u32 s77, s21, -1
	s_mov_b32 s75, m0
	s_mov_b32 m0, s58
	s_nop 0
	global_load_lds_dwordx4 v1, s[76:77]
	s_mov_b32 m0, s75
	s_nop 0
	s_mov_b32 s75, m0
	s_mov_b32 m0, s62
	s_nop 0
	global_load_lds_dwordx4 v177, s[76:77]
	s_mov_b32 m0, s75
	s_nop 0
	s_mov_b32 s75, m0
	s_mov_b32 m0, s59
	s_nop 0
	global_load_lds_dwordx4 v1, s[20:21]
	s_mov_b32 m0, s75
	s_nop 0
	s_mov_b32 s75, m0
	s_mov_b32 m0, s63
	s_nop 0
	global_load_lds_dwordx4 v177, s[20:21]
	s_mov_b32 m0, s75
	s_waitcnt vmcnt(8)
	s_waitcnt lgkmcnt(0)
	s_barrier
	s_setprio 1
	.p2align 3
	v_mfma_f32_16x16x32_bf16 v[126:129], v[130:133], v[166:169], v[126:129]
	v_mfma_f32_16x16x32_bf16 v[126:129], v[134:137], v[170:173], v[126:129]
	v_mfma_f32_16x16x32_bf16 v[122:125], v[138:141], v[166:169], v[122:125]
	v_mfma_f32_16x16x32_bf16 v[122:125], v[142:145], v[170:173], v[122:125]
	v_mfma_f32_16x16x32_bf16 v[110:113], v[138:141], v[186:189], v[110:113]
	v_mfma_f32_16x16x32_bf16 v[110:113], v[142:145], v[190:193], v[110:113]
	v_mfma_f32_16x16x32_bf16 v[118:121], v[130:133], v[186:189], v[118:121]
	v_mfma_f32_16x16x32_bf16 v[118:121], v[134:137], v[190:193], v[118:121]
	v_mfma_f32_16x16x32_bf16 v[94:97], v[130:133], v[194:197], v[94:97]
	v_mfma_f32_16x16x32_bf16 v[94:97], v[134:137], v[198:201], v[94:97]
	v_mfma_f32_16x16x32_bf16 v[90:93], v[138:141], v[194:197], v[90:93]
	v_mfma_f32_16x16x32_bf16 v[90:93], v[142:145], v[198:201], v[90:93]
	v_mfma_f32_16x16x32_bf16 v[78:81], v[138:141], v[202:205], v[78:81]
	v_mfma_f32_16x16x32_bf16 v[78:81], v[142:145], v[206:209], v[78:81]
	v_mfma_f32_16x16x32_bf16 v[86:89], v[130:133], v[202:205], v[86:89]
	v_mfma_f32_16x16x32_bf16 v[86:89], v[134:137], v[206:209], v[86:89]
	s_setprio 0
	s_setprio 1
	v_mfma_f32_16x16x32_bf16 v[114:117], v[150:153], v[166:169], v[114:117]
	v_mfma_f32_16x16x32_bf16 v[114:117], v[154:157], v[170:173], v[114:117]
	v_mfma_f32_16x16x32_bf16 v[106:109], v[158:161], v[166:169], v[106:109]
	v_mfma_f32_16x16x32_bf16 v[106:109], v[162:165], v[170:173], v[106:109]
	v_mfma_f32_16x16x32_bf16 v[98:101], v[158:161], v[186:189], v[98:101]
	v_mfma_f32_16x16x32_bf16 v[98:101], v[162:165], v[190:193], v[98:101]
	v_mfma_f32_16x16x32_bf16 v[102:105], v[150:153], v[186:189], v[102:105]
	v_mfma_f32_16x16x32_bf16 v[102:105], v[154:157], v[190:193], v[102:105]
	v_mfma_f32_16x16x32_bf16 v[82:85], v[150:153], v[194:197], v[82:85]
	v_mfma_f32_16x16x32_bf16 v[82:85], v[154:157], v[198:201], v[82:85]
	v_mfma_f32_16x16x32_bf16 v[74:77], v[158:161], v[194:197], v[74:77]
	v_mfma_f32_16x16x32_bf16 v[74:77], v[162:165], v[198:201], v[74:77]
	v_mfma_f32_16x16x32_bf16 v[66:69], v[158:161], v[202:205], v[66:69]
	v_mfma_f32_16x16x32_bf16 v[66:69], v[162:165], v[206:209], v[66:69]
	s_setprio 2
	s_barrier
	v_mfma_f32_16x16x32_bf16 v[70:73], v[150:153], v[202:205], v[70:73]
	v_mfma_f32_16x16x32_bf16 v[70:73], v[154:157], v[206:209], v[70:73]
	s_setprio 0
	ds_read_b128 v[166:169], v183 offset:16384
	ds_read_b128 v[170:173], v183 offset:17408
	ds_read_b128 v[186:189], v183 offset:18432
	ds_read_b128 v[190:193], v183 offset:19456
	ds_read_b128 v[194:197], v183 offset:20480
	ds_read_b128 v[198:201], v183 offset:21504
	ds_read_b128 v[202:205], v183 offset:22528
	ds_read_b128 v[206:209], v183 offset:23552
	s_mov_b32 s75, m0
	s_mov_b32 m0, s35
	s_nop 0
	global_load_lds_dwordx4 v176, s[22:23]
	s_mov_b32 m0, s75
	s_add_u32 s76, s22, 0x4000
	s_mov_b32 s75, m0
	s_mov_b32 m0, s36
	s_nop 0
	global_load_lds_dwordx4 v178, s[22:23]
	s_mov_b32 m0, s75
	s_addc_u32 s77, s23, 0
	s_mov_b32 s75, m0
	s_mov_b32 m0, s37
	s_nop 0
	global_load_lds_dwordx4 v176, s[76:77]
	s_mov_b32 m0, s75
	s_nop 0
	s_mov_b32 s75, m0
	s_mov_b32 m0, s40
	s_nop 0
	global_load_lds_dwordx4 v178, s[76:77]
	s_mov_b32 m0, s75
	s_waitcnt vmcnt(4)
	s_waitcnt lgkmcnt(0)
	s_barrier
	s_setprio 1
	.p2align 3
	v_mfma_f32_16x16x32_bf16 v[62:65], v[130:133], v[166:169], v[62:65]
	v_mfma_f32_16x16x32_bf16 v[62:65], v[134:137], v[170:173], v[62:65]
	v_mfma_f32_16x16x32_bf16 v[58:61], v[138:141], v[166:169], v[58:61]
	v_mfma_f32_16x16x32_bf16 v[58:61], v[142:145], v[170:173], v[58:61]
	v_mfma_f32_16x16x32_bf16 v[42:45], v[138:141], v[186:189], v[42:45]
	v_mfma_f32_16x16x32_bf16 v[42:45], v[142:145], v[190:193], v[42:45]
	v_mfma_f32_16x16x32_bf16 v[46:49], v[130:133], v[186:189], v[46:49]
	v_mfma_f32_16x16x32_bf16 v[46:49], v[134:137], v[190:193], v[46:49]
	v_mfma_f32_16x16x32_bf16 v[30:33], v[130:133], v[194:197], v[30:33]
	v_mfma_f32_16x16x32_bf16 v[30:33], v[134:137], v[198:201], v[30:33]
	v_mfma_f32_16x16x32_bf16 v[26:29], v[138:141], v[194:197], v[26:29]
	v_mfma_f32_16x16x32_bf16 v[26:29], v[142:145], v[198:201], v[26:29]
	v_mfma_f32_16x16x32_bf16 v[10:13], v[138:141], v[202:205], v[10:13]
	v_mfma_f32_16x16x32_bf16 v[10:13], v[142:145], v[206:209], v[10:13]
	v_mfma_f32_16x16x32_bf16 v[14:17], v[130:133], v[202:205], v[14:17]
	v_mfma_f32_16x16x32_bf16 v[14:17], v[134:137], v[206:209], v[14:17]
	s_setprio 0
	s_setprio 1
	v_mfma_f32_16x16x32_bf16 v[54:57], v[150:153], v[166:169], v[54:57]
	v_mfma_f32_16x16x32_bf16 v[54:57], v[154:157], v[170:173], v[54:57]
	v_mfma_f32_16x16x32_bf16 v[50:53], v[158:161], v[166:169], v[50:53]
	v_mfma_f32_16x16x32_bf16 v[50:53], v[162:165], v[170:173], v[50:53]
	v_mfma_f32_16x16x32_bf16 v[34:37], v[158:161], v[186:189], v[34:37]
	v_mfma_f32_16x16x32_bf16 v[34:37], v[162:165], v[190:193], v[34:37]
	v_mfma_f32_16x16x32_bf16 v[38:41], v[150:153], v[186:189], v[38:41]
	v_mfma_f32_16x16x32_bf16 v[38:41], v[154:157], v[190:193], v[38:41]
	v_mfma_f32_16x16x32_bf16 v[22:25], v[150:153], v[194:197], v[22:25]
	v_mfma_f32_16x16x32_bf16 v[22:25], v[154:157], v[198:201], v[22:25]
	v_mfma_f32_16x16x32_bf16 v[18:21], v[158:161], v[194:197], v[18:21]
	v_mfma_f32_16x16x32_bf16 v[18:21], v[162:165], v[198:201], v[18:21]
	v_mfma_f32_16x16x32_bf16 v[2:5], v[158:161], v[202:205], v[2:5]
	v_mfma_f32_16x16x32_bf16 v[2:5], v[162:165], v[206:209], v[2:5]
	s_setprio 2
	s_barrier
	v_mfma_f32_16x16x32_bf16 v[6:9], v[150:153], v[202:205], v[6:9]
	v_mfma_f32_16x16x32_bf16 v[6:9], v[154:157], v[206:209], v[6:9]
	s_setprio 0
	ds_read_b128 v[130:133], v184
	ds_read_b128 v[134:137], v184 offset:1024
	ds_read_b128 v[138:141], v184 offset:2048
	ds_read_b128 v[142:145], v184 offset:3072
	ds_read_b128 v[150:153], v185
	ds_read_b128 v[154:157], v185 offset:1024
	ds_read_b128 v[158:161], v185 offset:2048
	ds_read_b128 v[162:165], v185 offset:3072
	ds_read_b128 v[166:169], v183 offset:32768
	ds_read_b128 v[170:173], v183 offset:33792
	ds_read_b128 v[186:189], v183 offset:34816
	ds_read_b128 v[190:193], v183 offset:35840
	ds_read_b128 v[194:197], v183 offset:36864
	ds_read_b128 v[198:201], v183 offset:37888
	ds_read_b128 v[202:205], v183 offset:38912
	ds_read_b128 v[206:209], v183 offset:39936
	s_mov_b32 s75, m0
	s_mov_b32 m0, s34
	s_nop 0
	global_load_lds_dwordx4 v1, s[24:25]
	s_mov_b32 m0, s75
	s_nop 0
	s_mov_b32 s75, m0
	s_mov_b32 m0, s41
	s_nop 0
	global_load_lds_dwordx4 v177, s[24:25]
	s_mov_b32 m0, s75
	s_add_u32 s24, s24, 0x4000
	s_addc_u32 s25, s25, 0
	s_mov_b32 s75, m0
	s_mov_b32 m0, s42
	s_nop 0
	global_load_lds_dwordx4 v1, s[24:25]
	s_mov_b32 m0, s75
	s_nop 0
	s_mov_b32 s75, m0
	s_mov_b32 m0, s43
	s_nop 0
	global_load_lds_dwordx4 v177, s[24:25]
	s_mov_b32 m0, s75
	s_waitcnt vmcnt(8)
	s_waitcnt lgkmcnt(0)
	s_barrier
	s_setprio 1
	.p2align 3
	v_mfma_f32_16x16x32_bf16 v[126:129], v[130:133], v[166:169], v[126:129]
	v_mfma_f32_16x16x32_bf16 v[126:129], v[134:137], v[170:173], v[126:129]
	v_mfma_f32_16x16x32_bf16 v[122:125], v[138:141], v[166:169], v[122:125]
	v_mfma_f32_16x16x32_bf16 v[122:125], v[142:145], v[170:173], v[122:125]
	v_mfma_f32_16x16x32_bf16 v[110:113], v[138:141], v[186:189], v[110:113]
	v_mfma_f32_16x16x32_bf16 v[110:113], v[142:145], v[190:193], v[110:113]
	v_mfma_f32_16x16x32_bf16 v[118:121], v[130:133], v[186:189], v[118:121]
	v_mfma_f32_16x16x32_bf16 v[118:121], v[134:137], v[190:193], v[118:121]
	v_mfma_f32_16x16x32_bf16 v[94:97], v[130:133], v[194:197], v[94:97]
	v_mfma_f32_16x16x32_bf16 v[94:97], v[134:137], v[198:201], v[94:97]
	v_mfma_f32_16x16x32_bf16 v[90:93], v[138:141], v[194:197], v[90:93]
	v_mfma_f32_16x16x32_bf16 v[90:93], v[142:145], v[198:201], v[90:93]
	v_mfma_f32_16x16x32_bf16 v[78:81], v[138:141], v[202:205], v[78:81]
	v_mfma_f32_16x16x32_bf16 v[78:81], v[142:145], v[206:209], v[78:81]
	v_mfma_f32_16x16x32_bf16 v[86:89], v[130:133], v[202:205], v[86:89]
	v_mfma_f32_16x16x32_bf16 v[86:89], v[134:137], v[206:209], v[86:89]
	s_setprio 0
	s_setprio 1
	v_mfma_f32_16x16x32_bf16 v[114:117], v[150:153], v[166:169], v[114:117]
	v_mfma_f32_16x16x32_bf16 v[114:117], v[154:157], v[170:173], v[114:117]
	v_mfma_f32_16x16x32_bf16 v[106:109], v[158:161], v[166:169], v[106:109]
	v_mfma_f32_16x16x32_bf16 v[106:109], v[162:165], v[170:173], v[106:109]
	v_mfma_f32_16x16x32_bf16 v[98:101], v[158:161], v[186:189], v[98:101]
	v_mfma_f32_16x16x32_bf16 v[98:101], v[162:165], v[190:193], v[98:101]
	v_mfma_f32_16x16x32_bf16 v[102:105], v[150:153], v[186:189], v[102:105]
	v_mfma_f32_16x16x32_bf16 v[102:105], v[154:157], v[190:193], v[102:105]
	v_mfma_f32_16x16x32_bf16 v[82:85], v[150:153], v[194:197], v[82:85]
	v_mfma_f32_16x16x32_bf16 v[82:85], v[154:157], v[198:201], v[82:85]
	v_mfma_f32_16x16x32_bf16 v[74:77], v[158:161], v[194:197], v[74:77]
	v_mfma_f32_16x16x32_bf16 v[74:77], v[162:165], v[198:201], v[74:77]
	v_mfma_f32_16x16x32_bf16 v[66:69], v[158:161], v[202:205], v[66:69]
	v_mfma_f32_16x16x32_bf16 v[66:69], v[162:165], v[206:209], v[66:69]
	s_setprio 2
	s_barrier
	v_mfma_f32_16x16x32_bf16 v[70:73], v[150:153], v[202:205], v[70:73]
	v_mfma_f32_16x16x32_bf16 v[70:73], v[154:157], v[206:209], v[70:73]
	s_setprio 0
	ds_read_b128 v[166:169], v183 offset:49152
	ds_read_b128 v[170:173], v183 offset:50176
	ds_read_b128 v[186:189], v183 offset:51200
	ds_read_b128 v[190:193], v183 offset:52224
	ds_read_b128 v[194:197], v183 offset:53248
	ds_read_b128 v[198:201], v183 offset:54272
	ds_read_b128 v[202:205], v183 offset:55296
	ds_read_b128 v[206:209], v183 offset:56320
	s_add_u32 s24, s22, 0x40000
	s_addc_u32 s25, s23, 0
	s_mov_b32 s75, m0
	s_mov_b32 m0, s46
	s_nop 0
	global_load_lds_dwordx4 v176, s[24:25]
	s_mov_b32 m0, s75
	s_add_u32 s22, s22, 0x44000
	s_mov_b32 s75, m0
	s_mov_b32 m0, s47
	s_nop 0
	global_load_lds_dwordx4 v178, s[24:25]
	s_mov_b32 m0, s75
	s_addc_u32 s23, s23, 0
	s_mov_b32 s24, m0
	s_mov_b32 m0, s48
	s_nop 0
	global_load_lds_dwordx4 v176, s[22:23]
	s_mov_b32 m0, s24
	s_nop 0
	s_mov_b32 s24, m0
	s_mov_b32 m0, s49
	s_nop 0
	global_load_lds_dwordx4 v178, s[22:23]
	s_mov_b32 m0, s24
	s_waitcnt vmcnt(4)
	s_waitcnt lgkmcnt(0)
	s_barrier
	s_setprio 1
	.p2align 3
	v_mfma_f32_16x16x32_bf16 v[62:65], v[130:133], v[166:169], v[62:65]
	v_mfma_f32_16x16x32_bf16 v[62:65], v[134:137], v[170:173], v[62:65]
	v_mfma_f32_16x16x32_bf16 v[58:61], v[138:141], v[166:169], v[58:61]
	v_mfma_f32_16x16x32_bf16 v[58:61], v[142:145], v[170:173], v[58:61]
	v_mfma_f32_16x16x32_bf16 v[42:45], v[138:141], v[186:189], v[42:45]
	v_mfma_f32_16x16x32_bf16 v[42:45], v[142:145], v[190:193], v[42:45]
	v_mfma_f32_16x16x32_bf16 v[46:49], v[130:133], v[186:189], v[46:49]
	v_mfma_f32_16x16x32_bf16 v[46:49], v[134:137], v[190:193], v[46:49]
	v_mfma_f32_16x16x32_bf16 v[30:33], v[130:133], v[194:197], v[30:33]
	v_mfma_f32_16x16x32_bf16 v[30:33], v[134:137], v[198:201], v[30:33]
	v_mfma_f32_16x16x32_bf16 v[26:29], v[138:141], v[194:197], v[26:29]
	v_mfma_f32_16x16x32_bf16 v[26:29], v[142:145], v[198:201], v[26:29]
	v_mfma_f32_16x16x32_bf16 v[10:13], v[138:141], v[202:205], v[10:13]
	v_mfma_f32_16x16x32_bf16 v[10:13], v[142:145], v[206:209], v[10:13]
	v_mfma_f32_16x16x32_bf16 v[14:17], v[130:133], v[202:205], v[14:17]
	v_mfma_f32_16x16x32_bf16 v[14:17], v[134:137], v[206:209], v[14:17]
	s_setprio 0
	s_setprio 1
	v_mfma_f32_16x16x32_bf16 v[54:57], v[150:153], v[166:169], v[54:57]
	v_mfma_f32_16x16x32_bf16 v[54:57], v[154:157], v[170:173], v[54:57]
	v_mfma_f32_16x16x32_bf16 v[50:53], v[158:161], v[166:169], v[50:53]
	v_mfma_f32_16x16x32_bf16 v[50:53], v[162:165], v[170:173], v[50:53]
	v_mfma_f32_16x16x32_bf16 v[34:37], v[158:161], v[186:189], v[34:37]
	v_mfma_f32_16x16x32_bf16 v[34:37], v[162:165], v[190:193], v[34:37]
	v_mfma_f32_16x16x32_bf16 v[38:41], v[150:153], v[186:189], v[38:41]
	v_mfma_f32_16x16x32_bf16 v[38:41], v[154:157], v[190:193], v[38:41]
	v_mfma_f32_16x16x32_bf16 v[22:25], v[150:153], v[194:197], v[22:25]
	v_mfma_f32_16x16x32_bf16 v[22:25], v[154:157], v[198:201], v[22:25]
	v_mfma_f32_16x16x32_bf16 v[18:21], v[158:161], v[194:197], v[18:21]
	v_mfma_f32_16x16x32_bf16 v[18:21], v[162:165], v[198:201], v[18:21]
	v_mfma_f32_16x16x32_bf16 v[2:5], v[158:161], v[202:205], v[2:5]
	v_mfma_f32_16x16x32_bf16 v[2:5], v[162:165], v[206:209], v[2:5]
	s_setprio 2
	s_barrier
	v_mfma_f32_16x16x32_bf16 v[6:9], v[150:153], v[202:205], v[6:9]
	v_mfma_f32_16x16x32_bf16 v[6:9], v[154:157], v[206:209], v[6:9]
	s_setprio 0
	s_add_i32 s74, s74, 2
	s_add_u32 s67, s67, 0x80000
	s_addc_u32 s70, s70, 0
	s_add_u32 s20, s20, 0x400000
	s_addc_u32 s21, s21, 0
	s_add_u32 s71, s71, 0x400000
	s_addc_u32 s73, s73, 0
	s_cmpk_gt_u32 s74, 0x53
	s_cbranch_scc0 .LBB0_1952
	s_and_b64 vcc, exec, s[8:9]
	s_cbranch_vccz .LBB0_1955
	s_barrier

.LBB0_2145:
	s_ashr_i32 s25, s24, 31
	s_lshl_b64 s[26:27], s[24:25], 20
	s_add_u32 s26, s33, s26
	s_addc_u32 s27, s42, s27
	s_and_b64 s[28:29], s[2:3], exec
	s_cselect_b32 s5, s27, s37
	s_cselect_b32 s25, s26, s36
	s_ashr_i32 s23, s22, 31
	s_lshl_b64 s[28:29], s[22:23], 20
	s_add_u32 s28, s43, s28
	s_addc_u32 s29, s46, s29
	s_and_b64 s[40:41], s[2:3], exec
	s_cselect_b32 s23, s29, s35
	s_cselect_b32 s31, s28, s34
	s_add_u32 s77, s34, 0x100
	s_addc_u32 s78, s35, 0
	s_add_u32 s34, s36, 0x80080
	s_addc_u32 s35, s37, 0
	s_add_u32 s79, s36, 0x100
	s_addc_u32 s80, s37, 0
	s_mov_b32 s81, -2
	s_waitcnt vmcnt(25)
	s_waitcnt vmcnt(24)
	s_waitcnt vmcnt(4)
	s_waitcnt vmcnt(2)
	s_waitcnt vmcnt(1)
	s_waitcnt vmcnt(0)
	ds_read_b128 v[42:45], v181
	ds_read_b128 v[46:49], v181 offset:1024
	ds_read_b128 v[58:61], v181 offset:2048
	ds_read_b128 v[62:65], v181 offset:3072
	ds_read_b128 v[146:149], v182
	ds_read_b128 v[150:153], v182 offset:1024
	ds_read_b128 v[154:157], v182 offset:2048
	ds_read_b128 v[158:161], v182 offset:3072
	s_cmp_eq_u32 s81, 28
	s_cselect_b32 s37, s23, s78
	s_cselect_b32 s36, s31, s77
	s_cselect_b32 s41, s5, s80
	s_cselect_b32 s40, s25, s79
	ds_read_b128 v[170:173], v183
	ds_read_b128 v[188:191], v183 offset:1024
	ds_read_b128 v[192:195], v183 offset:2048
	ds_read_b128 v[196:199], v183 offset:3072
	ds_read_b128 v[200:203], v183 offset:4096
	ds_read_b128 v[204:207], v183 offset:5120
	ds_read_b128 v[208:211], v183 offset:6144
	ds_read_b128 v[212:215], v183 offset:7168
	s_add_u32 s82, s34, 0xfff80000
	s_addc_u32 s83, s35, -1
	s_mov_b32 s86, m0
	s_mov_b32 m0, s70
	s_nop 0
	global_load_lds_dwordx4 v1, s[82:83]
	s_mov_b32 m0, s86
	s_nop 0
	s_mov_b32 s86, m0
	s_mov_b32 m0, s73
	s_nop 0
	global_load_lds_dwordx4 v177, s[82:83]
	s_mov_b32 m0, s86
	s_mov_b32 s82, m0
	s_mov_b32 m0, s71
	s_nop 0
	global_load_lds_dwordx4 v1, s[34:35]
	s_mov_b32 m0, s82
	s_nop 0
	s_mov_b32 s82, m0
	s_mov_b32 m0, s74
	s_nop 0
	global_load_lds_dwordx4 v177, s[34:35]
	s_mov_b32 m0, s82
	s_waitcnt vmcnt(8)
	s_waitcnt lgkmcnt(0)
	s_barrier
	s_setprio 1
	.p2align 3
	v_mfma_f32_16x16x32_bf16 v[142:145], v[42:45], v[170:173], 0
	v_mfma_f32_16x16x32_bf16 v[142:145], v[46:49], v[188:191], v[142:145]
	v_mfma_f32_16x16x32_bf16 v[138:141], v[58:61], v[170:173], 0
	v_mfma_f32_16x16x32_bf16 v[138:141], v[62:65], v[188:191], v[138:141]
	v_mfma_f32_16x16x32_bf16 v[126:129], v[42:45], v[192:195], 0
	v_mfma_f32_16x16x32_bf16 v[126:129], v[46:49], v[196:199], v[126:129]
	v_mfma_f32_16x16x32_bf16 v[122:125], v[58:61], v[192:195], 0
	v_mfma_f32_16x16x32_bf16 v[122:125], v[62:65], v[196:199], v[122:125]
	v_mfma_f32_16x16x32_bf16 v[110:113], v[42:45], v[200:203], 0
	v_mfma_f32_16x16x32_bf16 v[110:113], v[46:49], v[204:207], v[110:113]
	v_mfma_f32_16x16x32_bf16 v[106:109], v[58:61], v[200:203], 0
	v_mfma_f32_16x16x32_bf16 v[106:109], v[62:65], v[204:207], v[106:109]
	v_mfma_f32_16x16x32_bf16 v[94:97], v[42:45], v[208:211], 0
	v_mfma_f32_16x16x32_bf16 v[94:97], v[46:49], v[212:215], v[94:97]
	v_mfma_f32_16x16x32_bf16 v[90:93], v[58:61], v[208:211], 0
	v_mfma_f32_16x16x32_bf16 v[90:93], v[62:65], v[212:215], v[90:93]
	s_setprio 0
	s_setprio 1
	v_mfma_f32_16x16x32_bf16 v[134:137], v[146:149], v[170:173], 0
	v_mfma_f32_16x16x32_bf16 v[134:137], v[150:153], v[188:191], v[134:137]
	v_mfma_f32_16x16x32_bf16 v[130:133], v[154:157], v[170:173], 0
	v_mfma_f32_16x16x32_bf16 v[130:133], v[158:161], v[188:191], v[130:133]
	v_mfma_f32_16x16x32_bf16 v[118:121], v[146:149], v[192:195], 0
	v_mfma_f32_16x16x32_bf16 v[118:121], v[150:153], v[196:199], v[118:121]
	v_mfma_f32_16x16x32_bf16 v[114:117], v[154:157], v[192:195], 0
	v_mfma_f32_16x16x32_bf16 v[114:117], v[158:161], v[196:199], v[114:117]
	v_mfma_f32_16x16x32_bf16 v[102:105], v[146:149], v[200:203], 0
	v_mfma_f32_16x16x32_bf16 v[102:105], v[150:153], v[204:207], v[102:105]
	v_mfma_f32_16x16x32_bf16 v[98:101], v[154:157], v[200:203], 0
	v_mfma_f32_16x16x32_bf16 v[98:101], v[158:161], v[204:207], v[98:101]
	v_mfma_f32_16x16x32_bf16 v[86:89], v[146:149], v[208:211], 0
	v_mfma_f32_16x16x32_bf16 v[86:89], v[150:153], v[212:215], v[86:89]
	s_setprio 2
	s_barrier
	v_mfma_f32_16x16x32_bf16 v[82:85], v[154:157], v[208:211], 0
	v_mfma_f32_16x16x32_bf16 v[82:85], v[158:161], v[212:215], v[82:85]
	s_setprio 0
	ds_read_b128 v[170:173], v183 offset:16384
	ds_read_b128 v[188:191], v183 offset:17408
	ds_read_b128 v[192:195], v183 offset:18432
	ds_read_b128 v[196:199], v183 offset:19456
	ds_read_b128 v[200:203], v183 offset:20480
	ds_read_b128 v[204:207], v183 offset:21504
	ds_read_b128 v[208:211], v183 offset:22528
	ds_read_b128 v[212:215], v183 offset:23552
	s_mov_b32 s82, m0
	s_mov_b32 m0, s49
	s_nop 0
	global_load_lds_dwordx4 v176, s[36:37]
	s_mov_b32 m0, s82
	s_nop 0
	s_mov_b32 s82, m0
	s_mov_b32 m0, s56
	s_nop 0
	global_load_lds_dwordx4 v178, s[36:37]
	s_mov_b32 m0, s82
	s_add_u32 s82, s36, 0x80000
	s_addc_u32 s83, s37, 0
	s_mov_b32 s86, m0
	s_mov_b32 m0, s57
	s_nop 0
	global_load_lds_dwordx4 v176, s[82:83]
	s_mov_b32 m0, s86
	s_nop 0
	s_mov_b32 s86, m0
	s_mov_b32 m0, s58
	s_nop 0
	global_load_lds_dwordx4 v178, s[82:83]
	s_mov_b32 m0, s86
	s_waitcnt vmcnt(4)
	s_waitcnt lgkmcnt(0)
	s_barrier
	s_setprio 1
	.p2align 3
	v_mfma_f32_16x16x32_bf16 v[78:81], v[42:45], v[170:173], 0
	v_mfma_f32_16x16x32_bf16 v[78:81], v[46:49], v[188:191], v[78:81]
	v_mfma_f32_16x16x32_bf16 v[74:77], v[58:61], v[170:173], 0
	v_mfma_f32_16x16x32_bf16 v[74:77], v[62:65], v[188:191], v[74:77]
	v_mfma_f32_16x16x32_bf16 v[54:57], v[42:45], v[192:195], 0
	v_mfma_f32_16x16x32_bf16 v[54:57], v[46:49], v[196:199], v[54:57]
	v_mfma_f32_16x16x32_bf16 v[50:53], v[58:61], v[192:195], 0
	v_mfma_f32_16x16x32_bf16 v[50:53], v[62:65], v[196:199], v[50:53]
	v_mfma_f32_16x16x32_bf16 v[30:33], v[42:45], v[200:203], 0
	v_mfma_f32_16x16x32_bf16 v[30:33], v[46:49], v[204:207], v[30:33]
	v_mfma_f32_16x16x32_bf16 v[26:29], v[58:61], v[200:203], 0
	v_mfma_f32_16x16x32_bf16 v[26:29], v[62:65], v[204:207], v[26:29]
	v_mfma_f32_16x16x32_bf16 v[14:17], v[42:45], v[208:211], 0
	v_mfma_f32_16x16x32_bf16 v[14:17], v[46:49], v[212:215], v[14:17]
	v_mfma_f32_16x16x32_bf16 v[10:13], v[58:61], v[208:211], 0
	v_mfma_f32_16x16x32_bf16 v[10:13], v[62:65], v[212:215], v[10:13]
	s_setprio 0
	s_setprio 1
	v_mfma_f32_16x16x32_bf16 v[38:41], v[146:149], v[192:195], 0
	v_mfma_f32_16x16x32_bf16 v[38:41], v[150:153], v[196:199], v[38:41]
	v_mfma_f32_16x16x32_bf16 v[34:37], v[154:157], v[192:195], 0
	v_mfma_f32_16x16x32_bf16 v[34:37], v[158:161], v[196:199], v[34:37]
	v_mfma_f32_16x16x32_bf16 v[22:25], v[146:149], v[200:203], 0
	v_mfma_f32_16x16x32_bf16 v[22:25], v[150:153], v[204:207], v[22:25]
	v_mfma_f32_16x16x32_bf16 v[18:21], v[154:157], v[200:203], 0
	v_mfma_f32_16x16x32_bf16 v[18:21], v[158:161], v[204:207], v[18:21]
	v_mfma_f32_16x16x32_bf16 v[6:9], v[146:149], v[208:211], 0
	v_mfma_f32_16x16x32_bf16 v[6:9], v[150:153], v[212:215], v[6:9]
	v_mfma_f32_16x16x32_bf16 v[2:5], v[154:157], v[208:211], 0
	v_mfma_f32_16x16x32_bf16 v[2:5], v[158:161], v[212:215], v[2:5]
	v_mfma_f32_16x16x32_bf16 v[42:45], v[146:149], v[170:173], 0
	v_mfma_f32_16x16x32_bf16 v[42:45], v[150:153], v[188:191], v[42:45]
	s_setprio 2
	s_barrier
	v_mfma_f32_16x16x32_bf16 v[46:49], v[154:157], v[170:173], 0
	v_mfma_f32_16x16x32_bf16 v[46:49], v[158:161], v[188:191], v[46:49]
	s_setprio 0
	ds_read_b128 v[58:61], v184
	ds_read_b128 v[62:65], v184 offset:1024
	ds_read_b128 v[66:69], v184 offset:2048
	ds_read_b128 v[70:73], v184 offset:3072
	ds_read_b128 v[146:149], v185
	ds_read_b128 v[150:153], v185 offset:1024
	ds_read_b128 v[154:157], v185 offset:2048
	ds_read_b128 v[158:161], v185 offset:3072
	ds_read_b128 v[170:173], v183 offset:32768
	ds_read_b128 v[188:191], v183 offset:33792
	ds_read_b128 v[192:195], v183 offset:34816
	ds_read_b128 v[196:199], v183 offset:35840
	ds_read_b128 v[200:203], v183 offset:36864
	ds_read_b128 v[204:207], v183 offset:37888
	ds_read_b128 v[208:211], v183 offset:38912
	ds_read_b128 v[212:215], v183 offset:39936
	s_mov_b32 s82, m0
	s_mov_b32 m0, s48
	s_nop 0
	global_load_lds_dwordx4 v1, s[40:41]
	s_mov_b32 m0, s82
	s_nop 0
	s_mov_b32 s82, m0
	s_mov_b32 m0, s59
	s_nop 0
	global_load_lds_dwordx4 v177, s[40:41]
	s_mov_b32 m0, s82
	s_add_u32 s40, s40, 0x80000
	s_addc_u32 s41, s41, 0
	s_mov_b32 s82, m0
	s_mov_b32 m0, s62
	s_nop 0
	global_load_lds_dwordx4 v1, s[40:41]
	s_mov_b32 m0, s82
	s_nop 0
	s_mov_b32 s82, m0
	s_mov_b32 m0, s63
	s_nop 0
	global_load_lds_dwordx4 v177, s[40:41]
	s_mov_b32 m0, s82
	s_waitcnt vmcnt(8)
	s_waitcnt lgkmcnt(0)
	s_barrier
	s_setprio 1
	.p2align 3
	v_mfma_f32_16x16x32_bf16 v[142:145], v[58:61], v[170:173], v[142:145]
	v_mfma_f32_16x16x32_bf16 v[142:145], v[62:65], v[188:191], v[142:145]
	v_mfma_f32_16x16x32_bf16 v[138:141], v[66:69], v[170:173], v[138:141]
	v_mfma_f32_16x16x32_bf16 v[138:141], v[70:73], v[188:191], v[138:141]
	v_mfma_f32_16x16x32_bf16 v[126:129], v[58:61], v[192:195], v[126:129]
	v_mfma_f32_16x16x32_bf16 v[126:129], v[62:65], v[196:199], v[126:129]
	v_mfma_f32_16x16x32_bf16 v[122:125], v[66:69], v[192:195], v[122:125]
	v_mfma_f32_16x16x32_bf16 v[122:125], v[70:73], v[196:199], v[122:125]
	v_mfma_f32_16x16x32_bf16 v[110:113], v[58:61], v[200:203], v[110:113]
	v_mfma_f32_16x16x32_bf16 v[110:113], v[62:65], v[204:207], v[110:113]
	v_mfma_f32_16x16x32_bf16 v[106:109], v[66:69], v[200:203], v[106:109]
	v_mfma_f32_16x16x32_bf16 v[106:109], v[70:73], v[204:207], v[106:109]
	v_mfma_f32_16x16x32_bf16 v[94:97], v[58:61], v[208:211], v[94:97]
	v_mfma_f32_16x16x32_bf16 v[94:97], v[62:65], v[212:215], v[94:97]
	v_mfma_f32_16x16x32_bf16 v[90:93], v[66:69], v[208:211], v[90:93]
	v_mfma_f32_16x16x32_bf16 v[90:93], v[70:73], v[212:215], v[90:93]
	s_setprio 0
	s_setprio 1
	v_mfma_f32_16x16x32_bf16 v[134:137], v[146:149], v[170:173], v[134:137]
	v_mfma_f32_16x16x32_bf16 v[134:137], v[150:153], v[188:191], v[134:137]
	v_mfma_f32_16x16x32_bf16 v[130:133], v[154:157], v[170:173], v[130:133]
	v_mfma_f32_16x16x32_bf16 v[130:133], v[158:161], v[188:191], v[130:133]
	v_mfma_f32_16x16x32_bf16 v[118:121], v[146:149], v[192:195], v[118:121]
	v_mfma_f32_16x16x32_bf16 v[118:121], v[150:153], v[196:199], v[118:121]
	v_mfma_f32_16x16x32_bf16 v[114:117], v[154:157], v[192:195], v[114:117]
	v_mfma_f32_16x16x32_bf16 v[114:117], v[158:161], v[196:199], v[114:117]
	v_mfma_f32_16x16x32_bf16 v[102:105], v[146:149], v[200:203], v[102:105]
	v_mfma_f32_16x16x32_bf16 v[102:105], v[150:153], v[204:207], v[102:105]
	v_mfma_f32_16x16x32_bf16 v[98:101], v[154:157], v[200:203], v[98:101]
	v_mfma_f32_16x16x32_bf16 v[98:101], v[158:161], v[204:207], v[98:101]
	v_mfma_f32_16x16x32_bf16 v[86:89], v[146:149], v[208:211], v[86:89]
	v_mfma_f32_16x16x32_bf16 v[86:89], v[150:153], v[212:215], v[86:89]
	s_setprio 2
	s_barrier
	v_mfma_f32_16x16x32_bf16 v[82:85], v[154:157], v[208:211], v[82:85]
	v_mfma_f32_16x16x32_bf16 v[82:85], v[158:161], v[212:215], v[82:85]
	s_setprio 0
	ds_read_b128 v[170:173], v183 offset:49152
	ds_read_b128 v[188:191], v183 offset:50176
	ds_read_b128 v[192:195], v183 offset:51200
	ds_read_b128 v[196:199], v183 offset:52224
	ds_read_b128 v[200:203], v183 offset:53248
	ds_read_b128 v[204:207], v183 offset:54272
	ds_read_b128 v[208:211], v183 offset:55296
	ds_read_b128 v[212:215], v183 offset:56320
	s_add_u32 s40, s36, 0x80
	s_addc_u32 s41, s37, 0
	s_mov_b32 s82, m0
	s_mov_b32 m0, s64
	s_nop 0
	global_load_lds_dwordx4 v176, s[40:41]
	s_mov_b32 m0, s82
	s_add_u32 s36, s36, 0x80080
	s_mov_b32 s82, m0
	s_mov_b32 m0, s65
	s_nop 0
	global_load_lds_dwordx4 v178, s[40:41]
	s_mov_b32 m0, s82
	s_addc_u32 s37, s37, 0
	s_mov_b32 s40, m0
	s_mov_b32 m0, s66
	s_nop 0
	global_load_lds_dwordx4 v176, s[36:37]
	s_mov_b32 m0, s40
	s_nop 0
	s_mov_b32 s40, m0
	s_mov_b32 m0, s67
	s_nop 0
	global_load_lds_dwordx4 v178, s[36:37]
	s_mov_b32 m0, s40
	s_waitcnt vmcnt(4)
	s_waitcnt lgkmcnt(0)
	s_barrier
	s_setprio 1
	.p2align 3
	v_mfma_f32_16x16x32_bf16 v[78:81], v[58:61], v[170:173], v[78:81]
	v_mfma_f32_16x16x32_bf16 v[78:81], v[62:65], v[188:191], v[78:81]
	v_mfma_f32_16x16x32_bf16 v[74:77], v[66:69], v[170:173], v[74:77]
	v_mfma_f32_16x16x32_bf16 v[74:77], v[70:73], v[188:191], v[74:77]
	v_mfma_f32_16x16x32_bf16 v[54:57], v[58:61], v[192:195], v[54:57]
	v_mfma_f32_16x16x32_bf16 v[54:57], v[62:65], v[196:199], v[54:57]
	v_mfma_f32_16x16x32_bf16 v[50:53], v[66:69], v[192:195], v[50:53]
	v_mfma_f32_16x16x32_bf16 v[50:53], v[70:73], v[196:199], v[50:53]
	v_mfma_f32_16x16x32_bf16 v[30:33], v[58:61], v[200:203], v[30:33]
	v_mfma_f32_16x16x32_bf16 v[30:33], v[62:65], v[204:207], v[30:33]
	v_mfma_f32_16x16x32_bf16 v[26:29], v[66:69], v[200:203], v[26:29]
	v_mfma_f32_16x16x32_bf16 v[26:29], v[70:73], v[204:207], v[26:29]
	v_mfma_f32_16x16x32_bf16 v[14:17], v[58:61], v[208:211], v[14:17]
	v_mfma_f32_16x16x32_bf16 v[14:17], v[62:65], v[212:215], v[14:17]
	v_mfma_f32_16x16x32_bf16 v[10:13], v[66:69], v[208:211], v[10:13]
	v_mfma_f32_16x16x32_bf16 v[10:13], v[70:73], v[212:215], v[10:13]
	s_setprio 0
	s_setprio 1
	v_mfma_f32_16x16x32_bf16 v[42:45], v[146:149], v[170:173], v[42:45]
	v_mfma_f32_16x16x32_bf16 v[70:73], v[150:153], v[188:191], v[42:45]
	v_mfma_f32_16x16x32_bf16 v[42:45], v[154:157], v[170:173], v[46:49]
	v_mfma_f32_16x16x32_bf16 v[66:69], v[158:161], v[188:191], v[42:45]
	v_mfma_f32_16x16x32_bf16 v[38:41], v[146:149], v[192:195], v[38:41]
	v_mfma_f32_16x16x32_bf16 v[38:41], v[150:153], v[196:199], v[38:41]
	v_mfma_f32_16x16x32_bf16 v[34:37], v[154:157], v[192:195], v[34:37]
	v_mfma_f32_16x16x32_bf16 v[34:37], v[158:161], v[196:199], v[34:37]
	v_mfma_f32_16x16x32_bf16 v[22:25], v[146:149], v[200:203], v[22:25]
	v_mfma_f32_16x16x32_bf16 v[22:25], v[150:153], v[204:207], v[22:25]
	v_mfma_f32_16x16x32_bf16 v[18:21], v[154:157], v[200:203], v[18:21]
	v_mfma_f32_16x16x32_bf16 v[18:21], v[158:161], v[204:207], v[18:21]
	v_mfma_f32_16x16x32_bf16 v[6:9], v[146:149], v[208:211], v[6:9]
	v_mfma_f32_16x16x32_bf16 v[6:9], v[150:153], v[212:215], v[6:9]
	s_setprio 2
	s_barrier
	v_mfma_f32_16x16x32_bf16 v[2:5], v[154:157], v[208:211], v[2:5]
	v_mfma_f32_16x16x32_bf16 v[2:5], v[158:161], v[212:215], v[2:5]
	s_setprio 0
	s_add_i32 s81, s81, 2
	s_add_u32 s77, s77, 0x100
	s_addc_u32 s78, s78, 0
	s_add_u32 s34, s34, 0x100
	s_addc_u32 s35, s35, 0
	s_add_u32 s79, s79, 0x100
	s_addc_u32 s80, s80, 0
	s_cmp_gt_u32 s81, 29
	.p2align 6
.LBB0_2146:
	ds_read_b128 v[42:45], v181
	ds_read_b128 v[46:49], v181 offset:1024
	ds_read_b128 v[58:61], v181 offset:2048
	ds_read_b128 v[62:65], v181 offset:3072
	ds_read_b128 v[146:149], v182
	ds_read_b128 v[150:153], v182 offset:1024
	ds_read_b128 v[154:157], v182 offset:2048
	ds_read_b128 v[158:161], v182 offset:3072
	s_cmp_eq_u32 s81, 28
	s_cselect_b32 s37, s23, s78
	s_cselect_b32 s36, s31, s77
	s_cselect_b32 s41, s5, s80
	s_cselect_b32 s40, s25, s79
	ds_read_b128 v[170:173], v183
	ds_read_b128 v[188:191], v183 offset:1024
	ds_read_b128 v[192:195], v183 offset:2048
	ds_read_b128 v[196:199], v183 offset:3072
	ds_read_b128 v[200:203], v183 offset:4096
	ds_read_b128 v[204:207], v183 offset:5120
	ds_read_b128 v[208:211], v183 offset:6144
	ds_read_b128 v[212:215], v183 offset:7168
	s_add_u32 s82, s34, 0xfff80000
	s_addc_u32 s83, s35, -1
	s_mov_b32 s86, m0
	s_mov_b32 m0, s70
	s_nop 0
	global_load_lds_dwordx4 v1, s[82:83]
	s_mov_b32 m0, s86
	s_nop 0
	s_mov_b32 s86, m0
	s_mov_b32 m0, s73
	s_nop 0
	global_load_lds_dwordx4 v177, s[82:83]
	s_mov_b32 m0, s86
	s_mov_b32 s82, m0
	s_mov_b32 m0, s71
	s_nop 0
	global_load_lds_dwordx4 v1, s[34:35]
	s_mov_b32 m0, s82
	s_nop 0
	s_mov_b32 s82, m0
	s_mov_b32 m0, s74
	s_nop 0
	global_load_lds_dwordx4 v177, s[34:35]
	s_mov_b32 m0, s82
	s_waitcnt vmcnt(8)
	s_waitcnt lgkmcnt(0)
	s_barrier
	s_setprio 1
	.p2align 3
	v_mfma_f32_16x16x32_bf16 v[142:145], v[42:45], v[170:173], v[142:145]
	v_mfma_f32_16x16x32_bf16 v[142:145], v[46:49], v[188:191], v[142:145]
	v_mfma_f32_16x16x32_bf16 v[138:141], v[58:61], v[170:173], v[138:141]
	v_mfma_f32_16x16x32_bf16 v[138:141], v[62:65], v[188:191], v[138:141]
	v_mfma_f32_16x16x32_bf16 v[126:129], v[42:45], v[192:195], v[126:129]
	v_mfma_f32_16x16x32_bf16 v[126:129], v[46:49], v[196:199], v[126:129]
	v_mfma_f32_16x16x32_bf16 v[122:125], v[58:61], v[192:195], v[122:125]
	v_mfma_f32_16x16x32_bf16 v[122:125], v[62:65], v[196:199], v[122:125]
	v_mfma_f32_16x16x32_bf16 v[110:113], v[42:45], v[200:203], v[110:113]
	v_mfma_f32_16x16x32_bf16 v[110:113], v[46:49], v[204:207], v[110:113]
	v_mfma_f32_16x16x32_bf16 v[106:109], v[58:61], v[200:203], v[106:109]
	v_mfma_f32_16x16x32_bf16 v[106:109], v[62:65], v[204:207], v[106:109]
	v_mfma_f32_16x16x32_bf16 v[94:97], v[42:45], v[208:211], v[94:97]
	v_mfma_f32_16x16x32_bf16 v[94:97], v[46:49], v[212:215], v[94:97]
	v_mfma_f32_16x16x32_bf16 v[90:93], v[58:61], v[208:211], v[90:93]
	v_mfma_f32_16x16x32_bf16 v[90:93], v[62:65], v[212:215], v[90:93]
	s_setprio 0
	s_setprio 1
	v_mfma_f32_16x16x32_bf16 v[134:137], v[146:149], v[170:173], v[134:137]
	v_mfma_f32_16x16x32_bf16 v[134:137], v[150:153], v[188:191], v[134:137]
	v_mfma_f32_16x16x32_bf16 v[130:133], v[154:157], v[170:173], v[130:133]
	v_mfma_f32_16x16x32_bf16 v[130:133], v[158:161], v[188:191], v[130:133]
	v_mfma_f32_16x16x32_bf16 v[118:121], v[146:149], v[192:195], v[118:121]
	v_mfma_f32_16x16x32_bf16 v[118:121], v[150:153], v[196:199], v[118:121]
	v_mfma_f32_16x16x32_bf16 v[114:117], v[154:157], v[192:195], v[114:117]
	v_mfma_f32_16x16x32_bf16 v[114:117], v[158:161], v[196:199], v[114:117]
	v_mfma_f32_16x16x32_bf16 v[102:105], v[146:149], v[200:203], v[102:105]
	v_mfma_f32_16x16x32_bf16 v[102:105], v[150:153], v[204:207], v[102:105]
	v_mfma_f32_16x16x32_bf16 v[98:101], v[154:157], v[200:203], v[98:101]
	v_mfma_f32_16x16x32_bf16 v[98:101], v[158:161], v[204:207], v[98:101]
	v_mfma_f32_16x16x32_bf16 v[86:89], v[146:149], v[208:211], v[86:89]
	v_mfma_f32_16x16x32_bf16 v[86:89], v[150:153], v[212:215], v[86:89]
	s_setprio 2
	s_barrier
	v_mfma_f32_16x16x32_bf16 v[82:85], v[154:157], v[208:211], v[82:85]
	v_mfma_f32_16x16x32_bf16 v[82:85], v[158:161], v[212:215], v[82:85]
	s_setprio 0
	ds_read_b128 v[170:173], v183 offset:16384
	ds_read_b128 v[188:191], v183 offset:17408
	ds_read_b128 v[192:195], v183 offset:18432
	ds_read_b128 v[196:199], v183 offset:19456
	ds_read_b128 v[200:203], v183 offset:20480
	ds_read_b128 v[204:207], v183 offset:21504
	ds_read_b128 v[208:211], v183 offset:22528
	ds_read_b128 v[212:215], v183 offset:23552
	s_mov_b32 s82, m0
	s_mov_b32 m0, s49
	s_nop 0
	global_load_lds_dwordx4 v176, s[36:37]
	s_mov_b32 m0, s82
	s_nop 0
	s_mov_b32 s82, m0
	s_mov_b32 m0, s56
	s_nop 0
	global_load_lds_dwordx4 v178, s[36:37]
	s_mov_b32 m0, s82
	s_add_u32 s82, s36, 0x80000
	s_addc_u32 s83, s37, 0
	s_mov_b32 s86, m0
	s_mov_b32 m0, s57
	s_nop 0
	global_load_lds_dwordx4 v176, s[82:83]
	s_mov_b32 m0, s86
	s_nop 0
	s_mov_b32 s86, m0
	s_mov_b32 m0, s58
	s_nop 0
	global_load_lds_dwordx4 v178, s[82:83]
	s_mov_b32 m0, s86
	s_waitcnt vmcnt(4)
	s_waitcnt lgkmcnt(0)
	s_barrier
	s_setprio 1
	.p2align 3
	v_mfma_f32_16x16x32_bf16 v[78:81], v[42:45], v[170:173], v[78:81]
	v_mfma_f32_16x16x32_bf16 v[78:81], v[46:49], v[188:191], v[78:81]
	v_mfma_f32_16x16x32_bf16 v[74:77], v[58:61], v[170:173], v[74:77]
	v_mfma_f32_16x16x32_bf16 v[74:77], v[62:65], v[188:191], v[74:77]
	v_mfma_f32_16x16x32_bf16 v[54:57], v[42:45], v[192:195], v[54:57]
	v_mfma_f32_16x16x32_bf16 v[54:57], v[46:49], v[196:199], v[54:57]
	v_mfma_f32_16x16x32_bf16 v[50:53], v[58:61], v[192:195], v[50:53]
	v_mfma_f32_16x16x32_bf16 v[50:53], v[62:65], v[196:199], v[50:53]
	v_mfma_f32_16x16x32_bf16 v[30:33], v[42:45], v[200:203], v[30:33]
	v_mfma_f32_16x16x32_bf16 v[30:33], v[46:49], v[204:207], v[30:33]
	v_mfma_f32_16x16x32_bf16 v[26:29], v[58:61], v[200:203], v[26:29]
	v_mfma_f32_16x16x32_bf16 v[26:29], v[62:65], v[204:207], v[26:29]
	v_mfma_f32_16x16x32_bf16 v[14:17], v[42:45], v[208:211], v[14:17]
	v_mfma_f32_16x16x32_bf16 v[14:17], v[46:49], v[212:215], v[14:17]
	v_mfma_f32_16x16x32_bf16 v[10:13], v[58:61], v[208:211], v[10:13]
	v_mfma_f32_16x16x32_bf16 v[10:13], v[62:65], v[212:215], v[10:13]
	s_setprio 0
	s_setprio 1
	v_mfma_f32_16x16x32_bf16 v[38:41], v[146:149], v[192:195], v[38:41]
	v_mfma_f32_16x16x32_bf16 v[38:41], v[150:153], v[196:199], v[38:41]
	v_mfma_f32_16x16x32_bf16 v[34:37], v[154:157], v[192:195], v[34:37]
	v_mfma_f32_16x16x32_bf16 v[34:37], v[158:161], v[196:199], v[34:37]
	v_mfma_f32_16x16x32_bf16 v[22:25], v[146:149], v[200:203], v[22:25]
	v_mfma_f32_16x16x32_bf16 v[22:25], v[150:153], v[204:207], v[22:25]
	v_mfma_f32_16x16x32_bf16 v[18:21], v[154:157], v[200:203], v[18:21]
	v_mfma_f32_16x16x32_bf16 v[18:21], v[158:161], v[204:207], v[18:21]
	v_mfma_f32_16x16x32_bf16 v[6:9], v[146:149], v[208:211], v[6:9]
	v_mfma_f32_16x16x32_bf16 v[6:9], v[150:153], v[212:215], v[6:9]
	v_mfma_f32_16x16x32_bf16 v[2:5], v[154:157], v[208:211], v[2:5]
	v_mfma_f32_16x16x32_bf16 v[2:5], v[158:161], v[212:215], v[2:5]
	v_mfma_f32_16x16x32_bf16 v[42:45], v[146:149], v[170:173], v[70:73]
	v_mfma_f32_16x16x32_bf16 v[42:45], v[150:153], v[188:191], v[42:45]
	s_setprio 2
	s_barrier
	v_mfma_f32_16x16x32_bf16 v[46:49], v[154:157], v[170:173], v[66:69]
	v_mfma_f32_16x16x32_bf16 v[46:49], v[158:161], v[188:191], v[46:49]
	s_setprio 0
	ds_read_b128 v[58:61], v184
	ds_read_b128 v[62:65], v184 offset:1024
	ds_read_b128 v[66:69], v184 offset:2048
	ds_read_b128 v[70:73], v184 offset:3072
	ds_read_b128 v[146:149], v185
	ds_read_b128 v[150:153], v185 offset:1024
	ds_read_b128 v[154:157], v185 offset:2048
	ds_read_b128 v[158:161], v185 offset:3072
	ds_read_b128 v[170:173], v183 offset:32768
	ds_read_b128 v[188:191], v183 offset:33792
	ds_read_b128 v[192:195], v183 offset:34816
	ds_read_b128 v[196:199], v183 offset:35840
	ds_read_b128 v[200:203], v183 offset:36864
	ds_read_b128 v[204:207], v183 offset:37888
	ds_read_b128 v[208:211], v183 offset:38912
	ds_read_b128 v[212:215], v183 offset:39936
	s_mov_b32 s82, m0
	s_mov_b32 m0, s48
	s_nop 0
	global_load_lds_dwordx4 v1, s[40:41]
	s_mov_b32 m0, s82
	s_nop 0
	s_mov_b32 s82, m0
	s_mov_b32 m0, s59
	s_nop 0
	global_load_lds_dwordx4 v177, s[40:41]
	s_mov_b32 m0, s82
	s_add_u32 s40, s40, 0x80000
	s_addc_u32 s41, s41, 0
	s_mov_b32 s82, m0
	s_mov_b32 m0, s62
	s_nop 0
	global_load_lds_dwordx4 v1, s[40:41]
	s_mov_b32 m0, s82
	s_nop 0
	s_mov_b32 s82, m0
	s_mov_b32 m0, s63
	s_nop 0
	global_load_lds_dwordx4 v177, s[40:41]
	s_mov_b32 m0, s82
	s_waitcnt vmcnt(8)
	s_waitcnt lgkmcnt(0)
	s_barrier
	s_setprio 1
	.p2align 3
	v_mfma_f32_16x16x32_bf16 v[142:145], v[58:61], v[170:173], v[142:145]
	v_mfma_f32_16x16x32_bf16 v[142:145], v[62:65], v[188:191], v[142:145]
	v_mfma_f32_16x16x32_bf16 v[138:141], v[66:69], v[170:173], v[138:141]
	v_mfma_f32_16x16x32_bf16 v[138:141], v[70:73], v[188:191], v[138:141]
	v_mfma_f32_16x16x32_bf16 v[126:129], v[58:61], v[192:195], v[126:129]
	v_mfma_f32_16x16x32_bf16 v[126:129], v[62:65], v[196:199], v[126:129]
	v_mfma_f32_16x16x32_bf16 v[122:125], v[66:69], v[192:195], v[122:125]
	v_mfma_f32_16x16x32_bf16 v[122:125], v[70:73], v[196:199], v[122:125]
	v_mfma_f32_16x16x32_bf16 v[110:113], v[58:61], v[200:203], v[110:113]
	v_mfma_f32_16x16x32_bf16 v[110:113], v[62:65], v[204:207], v[110:113]
	v_mfma_f32_16x16x32_bf16 v[106:109], v[66:69], v[200:203], v[106:109]
	v_mfma_f32_16x16x32_bf16 v[106:109], v[70:73], v[204:207], v[106:109]
	v_mfma_f32_16x16x32_bf16 v[94:97], v[58:61], v[208:211], v[94:97]
	v_mfma_f32_16x16x32_bf16 v[94:97], v[62:65], v[212:215], v[94:97]
	v_mfma_f32_16x16x32_bf16 v[90:93], v[66:69], v[208:211], v[90:93]
	v_mfma_f32_16x16x32_bf16 v[90:93], v[70:73], v[212:215], v[90:93]
	s_setprio 0
	s_setprio 1
	v_mfma_f32_16x16x32_bf16 v[134:137], v[146:149], v[170:173], v[134:137]
	v_mfma_f32_16x16x32_bf16 v[134:137], v[150:153], v[188:191], v[134:137]
	v_mfma_f32_16x16x32_bf16 v[130:133], v[154:157], v[170:173], v[130:133]
	v_mfma_f32_16x16x32_bf16 v[130:133], v[158:161], v[188:191], v[130:133]
	v_mfma_f32_16x16x32_bf16 v[118:121], v[146:149], v[192:195], v[118:121]
	v_mfma_f32_16x16x32_bf16 v[118:121], v[150:153], v[196:199], v[118:121]
	v_mfma_f32_16x16x32_bf16 v[114:117], v[154:157], v[192:195], v[114:117]
	v_mfma_f32_16x16x32_bf16 v[114:117], v[158:161], v[196:199], v[114:117]
	v_mfma_f32_16x16x32_bf16 v[102:105], v[146:149], v[200:203], v[102:105]
	v_mfma_f32_16x16x32_bf16 v[102:105], v[150:153], v[204:207], v[102:105]
	v_mfma_f32_16x16x32_bf16 v[98:101], v[154:157], v[200:203], v[98:101]
	v_mfma_f32_16x16x32_bf16 v[98:101], v[158:161], v[204:207], v[98:101]
	v_mfma_f32_16x16x32_bf16 v[86:89], v[146:149], v[208:211], v[86:89]
	v_mfma_f32_16x16x32_bf16 v[86:89], v[150:153], v[212:215], v[86:89]
	s_setprio 2
	s_barrier
	v_mfma_f32_16x16x32_bf16 v[82:85], v[154:157], v[208:211], v[82:85]
	v_mfma_f32_16x16x32_bf16 v[82:85], v[158:161], v[212:215], v[82:85]
	s_setprio 0
	ds_read_b128 v[170:173], v183 offset:49152
	ds_read_b128 v[188:191], v183 offset:50176
	ds_read_b128 v[192:195], v183 offset:51200
	ds_read_b128 v[196:199], v183 offset:52224
	ds_read_b128 v[200:203], v183 offset:53248
	ds_read_b128 v[204:207], v183 offset:54272
	ds_read_b128 v[208:211], v183 offset:55296
	ds_read_b128 v[212:215], v183 offset:56320
	s_add_u32 s40, s36, 0x80
	s_addc_u32 s41, s37, 0
	s_mov_b32 s82, m0
	s_mov_b32 m0, s64
	s_nop 0
	global_load_lds_dwordx4 v176, s[40:41]
	s_mov_b32 m0, s82
	s_add_u32 s36, s36, 0x80080
	s_mov_b32 s82, m0
	s_mov_b32 m0, s65
	s_nop 0
	global_load_lds_dwordx4 v178, s[40:41]
	s_mov_b32 m0, s82
	s_addc_u32 s37, s37, 0
	s_mov_b32 s40, m0
	s_mov_b32 m0, s66
	s_nop 0
	global_load_lds_dwordx4 v176, s[36:37]
	s_mov_b32 m0, s40
	s_nop 0
	s_mov_b32 s40, m0
	s_mov_b32 m0, s67
	s_nop 0
	global_load_lds_dwordx4 v178, s[36:37]
	s_mov_b32 m0, s40
	s_waitcnt vmcnt(4)
	s_waitcnt lgkmcnt(0)
	s_barrier
	s_setprio 1
	.p2align 3
	v_mfma_f32_16x16x32_bf16 v[78:81], v[58:61], v[170:173], v[78:81]
	v_mfma_f32_16x16x32_bf16 v[78:81], v[62:65], v[188:191], v[78:81]
	v_mfma_f32_16x16x32_bf16 v[74:77], v[66:69], v[170:173], v[74:77]
	v_mfma_f32_16x16x32_bf16 v[74:77], v[70:73], v[188:191], v[74:77]
	v_mfma_f32_16x16x32_bf16 v[54:57], v[58:61], v[192:195], v[54:57]
	v_mfma_f32_16x16x32_bf16 v[54:57], v[62:65], v[196:199], v[54:57]
	v_mfma_f32_16x16x32_bf16 v[50:53], v[66:69], v[192:195], v[50:53]
	v_mfma_f32_16x16x32_bf16 v[50:53], v[70:73], v[196:199], v[50:53]
	v_mfma_f32_16x16x32_bf16 v[30:33], v[58:61], v[200:203], v[30:33]
	v_mfma_f32_16x16x32_bf16 v[30:33], v[62:65], v[204:207], v[30:33]
	v_mfma_f32_16x16x32_bf16 v[26:29], v[66:69], v[200:203], v[26:29]
	v_mfma_f32_16x16x32_bf16 v[26:29], v[70:73], v[204:207], v[26:29]
	v_mfma_f32_16x16x32_bf16 v[14:17], v[58:61], v[208:211], v[14:17]
	v_mfma_f32_16x16x32_bf16 v[14:17], v[62:65], v[212:215], v[14:17]
	v_mfma_f32_16x16x32_bf16 v[10:13], v[66:69], v[208:211], v[10:13]
	v_mfma_f32_16x16x32_bf16 v[10:13], v[70:73], v[212:215], v[10:13]
	s_setprio 0
	s_setprio 1
	v_mfma_f32_16x16x32_bf16 v[42:45], v[146:149], v[170:173], v[42:45]
	v_mfma_f32_16x16x32_bf16 v[70:73], v[150:153], v[188:191], v[42:45]
	v_mfma_f32_16x16x32_bf16 v[42:45], v[154:157], v[170:173], v[46:49]
	v_mfma_f32_16x16x32_bf16 v[66:69], v[158:161], v[188:191], v[42:45]
	v_mfma_f32_16x16x32_bf16 v[38:41], v[146:149], v[192:195], v[38:41]
	v_mfma_f32_16x16x32_bf16 v[38:41], v[150:153], v[196:199], v[38:41]
	v_mfma_f32_16x16x32_bf16 v[34:37], v[154:157], v[192:195], v[34:37]
	v_mfma_f32_16x16x32_bf16 v[34:37], v[158:161], v[196:199], v[34:37]
	v_mfma_f32_16x16x32_bf16 v[22:25], v[146:149], v[200:203], v[22:25]
	v_mfma_f32_16x16x32_bf16 v[22:25], v[150:153], v[204:207], v[22:25]
	v_mfma_f32_16x16x32_bf16 v[18:21], v[154:157], v[200:203], v[18:21]
	v_mfma_f32_16x16x32_bf16 v[18:21], v[158:161], v[204:207], v[18:21]
	v_mfma_f32_16x16x32_bf16 v[6:9], v[146:149], v[208:211], v[6:9]
	v_mfma_f32_16x16x32_bf16 v[6:9], v[150:153], v[212:215], v[6:9]
	s_setprio 2
	s_barrier
	v_mfma_f32_16x16x32_bf16 v[2:5], v[154:157], v[208:211], v[2:5]
	v_mfma_f32_16x16x32_bf16 v[2:5], v[158:161], v[212:215], v[2:5]
	s_setprio 0
	s_add_i32 s81, s81, 2
	s_add_u32 s77, s77, 0x100
	s_addc_u32 s78, s78, 0
	s_add_u32 s34, s34, 0x100
	s_addc_u32 s35, s35, 0
	s_add_u32 s79, s79, 0x100
	s_addc_u32 s80, s80, 0
	s_cmp_gt_u32 s81, 29
	s_cbranch_scc0 .LBB0_2146
	s_and_b64 vcc, exec, s[14:15]
	s_cbranch_vccz .LBB0_2149
	s_barrier

.LBB0_2409:
	s_ashr_i32 s17, s16, 31
	s_lshl_b64 s[18:19], s[16:17], 20
	s_add_u32 s18, s33, s18
	s_addc_u32 s19, s34, s19
	s_and_b64 s[20:21], s[2:3], exec
	s_cselect_b32 s17, s19, s27
	s_cselect_b32 s71, s18, s26
	s_ashr_i32 s15, s14, 31
	s_lshl_b64 s[20:21], s[14:15], 20
	s_add_u32 s20, s35, s20
	s_addc_u32 s21, s36, s21
	s_and_b64 s[28:29], s[2:3], exec
	s_cselect_b32 s15, s21, s25
	s_cselect_b32 s73, s20, s24
	s_add_u32 s74, s24, 0x100
	s_addc_u32 s75, s25, 0
	s_add_u32 s24, s26, 0x80080
	s_addc_u32 s25, s27, 0
	s_add_u32 s76, s26, 0x100
	s_addc_u32 s77, s27, 0
	s_mov_b32 s78, -2
	s_waitcnt vmcnt(25)
	s_waitcnt vmcnt(24)
	s_waitcnt vmcnt(4)
	s_waitcnt vmcnt(2)
	s_waitcnt vmcnt(1)
	s_waitcnt vmcnt(0)
	ds_read_b128 v[130:133], v181
	ds_read_b128 v[134:137], v181 offset:1024
	ds_read_b128 v[138:141], v181 offset:2048
	ds_read_b128 v[142:145], v181 offset:3072
	ds_read_b128 v[146:149], v182
	ds_read_b128 v[150:153], v182 offset:1024
	ds_read_b128 v[154:157], v182 offset:2048
	ds_read_b128 v[158:161], v182 offset:3072
	s_cmp_eq_u32 s78, 28
	s_cselect_b32 s27, s15, s75
	s_cselect_b32 s26, s73, s74
	s_cselect_b32 s29, s17, s77
	s_cselect_b32 s28, s71, s76
	ds_read_b128 v[166:169], v183
	ds_read_b128 v[170:173], v183 offset:1024
	ds_read_b128 v[186:189], v183 offset:2048
	ds_read_b128 v[190:193], v183 offset:3072
	ds_read_b128 v[194:197], v183 offset:4096
	ds_read_b128 v[198:201], v183 offset:5120
	ds_read_b128 v[202:205], v183 offset:6144
	ds_read_b128 v[206:209], v183 offset:7168
	s_add_u32 s80, s24, 0xfff80000
	s_addc_u32 s81, s25, -1
	s_mov_b32 s79, m0
	s_mov_b32 m0, s64
	s_nop 0
	global_load_lds_dwordx4 v1, s[80:81]
	s_mov_b32 m0, s79
	s_nop 0
	s_mov_b32 s79, m0
	s_mov_b32 m0, s66
	s_nop 0
	global_load_lds_dwordx4 v177, s[80:81]
	s_mov_b32 m0, s79
	s_nop 0
	s_mov_b32 s79, m0
	s_mov_b32 m0, s65
	s_nop 0
	global_load_lds_dwordx4 v1, s[24:25]
	s_mov_b32 m0, s79
	s_nop 0
	s_mov_b32 s79, m0
	s_mov_b32 m0, s67
	s_nop 0
	global_load_lds_dwordx4 v177, s[24:25]
	s_mov_b32 m0, s79
	s_waitcnt vmcnt(8)
	s_waitcnt lgkmcnt(0)
	s_barrier
	s_setprio 1
	.p2align 3
	v_mfma_f32_16x16x32_bf16 v[126:129], v[130:133], v[166:169], 0
	v_mfma_f32_16x16x32_bf16 v[126:129], v[134:137], v[170:173], v[126:129]
	v_mfma_f32_16x16x32_bf16 v[122:125], v[138:141], v[166:169], 0
	v_mfma_f32_16x16x32_bf16 v[122:125], v[142:145], v[170:173], v[122:125]
	v_mfma_f32_16x16x32_bf16 v[114:117], v[138:141], v[186:189], 0
	v_mfma_f32_16x16x32_bf16 v[114:117], v[142:145], v[190:193], v[114:117]
	v_mfma_f32_16x16x32_bf16 v[118:121], v[130:133], v[186:189], 0
	v_mfma_f32_16x16x32_bf16 v[118:121], v[134:137], v[190:193], v[118:121]
	v_mfma_f32_16x16x32_bf16 v[94:97], v[130:133], v[194:197], 0
	v_mfma_f32_16x16x32_bf16 v[94:97], v[134:137], v[198:201], v[94:97]
	v_mfma_f32_16x16x32_bf16 v[90:93], v[138:141], v[194:197], 0
	v_mfma_f32_16x16x32_bf16 v[90:93], v[142:145], v[198:201], v[90:93]
	v_mfma_f32_16x16x32_bf16 v[78:81], v[138:141], v[202:205], 0
	v_mfma_f32_16x16x32_bf16 v[78:81], v[142:145], v[206:209], v[78:81]
	v_mfma_f32_16x16x32_bf16 v[86:89], v[130:133], v[202:205], 0
	v_mfma_f32_16x16x32_bf16 v[86:89], v[134:137], v[206:209], v[86:89]
	s_setprio 0
	s_setprio 1
	v_mfma_f32_16x16x32_bf16 v[110:113], v[146:149], v[166:169], 0
	v_mfma_f32_16x16x32_bf16 v[110:113], v[150:153], v[170:173], v[110:113]
	v_mfma_f32_16x16x32_bf16 v[106:109], v[154:157], v[166:169], 0
	v_mfma_f32_16x16x32_bf16 v[106:109], v[158:161], v[170:173], v[106:109]
	v_mfma_f32_16x16x32_bf16 v[98:101], v[154:157], v[186:189], 0
	v_mfma_f32_16x16x32_bf16 v[98:101], v[158:161], v[190:193], v[98:101]
	v_mfma_f32_16x16x32_bf16 v[102:105], v[146:149], v[186:189], 0
	v_mfma_f32_16x16x32_bf16 v[102:105], v[150:153], v[190:193], v[102:105]
	v_mfma_f32_16x16x32_bf16 v[82:85], v[146:149], v[194:197], 0
	v_mfma_f32_16x16x32_bf16 v[82:85], v[150:153], v[198:201], v[82:85]
	v_mfma_f32_16x16x32_bf16 v[74:77], v[154:157], v[194:197], 0
	v_mfma_f32_16x16x32_bf16 v[74:77], v[158:161], v[198:201], v[74:77]
	v_mfma_f32_16x16x32_bf16 v[66:69], v[154:157], v[202:205], 0
	v_mfma_f32_16x16x32_bf16 v[66:69], v[158:161], v[206:209], v[66:69]
	s_setprio 2
	s_barrier
	v_mfma_f32_16x16x32_bf16 v[70:73], v[146:149], v[202:205], 0
	v_mfma_f32_16x16x32_bf16 v[70:73], v[150:153], v[206:209], v[70:73]
	s_setprio 0
	ds_read_b128 v[166:169], v183 offset:16384
	ds_read_b128 v[170:173], v183 offset:17408
	ds_read_b128 v[186:189], v183 offset:18432
	ds_read_b128 v[190:193], v183 offset:19456
	ds_read_b128 v[194:197], v183 offset:20480
	ds_read_b128 v[198:201], v183 offset:21504
	ds_read_b128 v[202:205], v183 offset:22528
	ds_read_b128 v[206:209], v183 offset:23552
	s_mov_b32 s79, m0
	s_mov_b32 m0, s41
	s_nop 0
	global_load_lds_dwordx4 v176, s[26:27]
	s_mov_b32 m0, s79
	s_add_u32 s80, s26, 0x80000
	s_mov_b32 s79, m0
	s_mov_b32 m0, s42
	s_nop 0
	global_load_lds_dwordx4 v178, s[26:27]
	s_mov_b32 m0, s79
	s_addc_u32 s81, s27, 0
	s_mov_b32 s79, m0
	s_mov_b32 m0, s43
	s_nop 0
	global_load_lds_dwordx4 v176, s[80:81]
	s_mov_b32 m0, s79
	s_nop 0
	s_mov_b32 s79, m0
	s_mov_b32 m0, s46
	s_nop 0
	global_load_lds_dwordx4 v178, s[80:81]
	s_mov_b32 m0, s79
	s_waitcnt vmcnt(4)
	s_waitcnt lgkmcnt(0)
	s_barrier
	s_setprio 1
	.p2align 3
	v_mfma_f32_16x16x32_bf16 v[62:65], v[130:133], v[166:169], 0
	v_mfma_f32_16x16x32_bf16 v[62:65], v[134:137], v[170:173], v[62:65]
	v_mfma_f32_16x16x32_bf16 v[58:61], v[138:141], v[166:169], 0
	v_mfma_f32_16x16x32_bf16 v[58:61], v[142:145], v[170:173], v[58:61]
	v_mfma_f32_16x16x32_bf16 v[42:45], v[138:141], v[186:189], 0
	v_mfma_f32_16x16x32_bf16 v[42:45], v[142:145], v[190:193], v[42:45]
	v_mfma_f32_16x16x32_bf16 v[46:49], v[130:133], v[186:189], 0
	v_mfma_f32_16x16x32_bf16 v[46:49], v[134:137], v[190:193], v[46:49]
	v_mfma_f32_16x16x32_bf16 v[30:33], v[130:133], v[194:197], 0
	v_mfma_f32_16x16x32_bf16 v[30:33], v[134:137], v[198:201], v[30:33]
	v_mfma_f32_16x16x32_bf16 v[26:29], v[138:141], v[194:197], 0
	v_mfma_f32_16x16x32_bf16 v[26:29], v[142:145], v[198:201], v[26:29]
	v_mfma_f32_16x16x32_bf16 v[10:13], v[138:141], v[202:205], 0
	v_mfma_f32_16x16x32_bf16 v[10:13], v[142:145], v[206:209], v[10:13]
	v_mfma_f32_16x16x32_bf16 v[14:17], v[130:133], v[202:205], 0
	v_mfma_f32_16x16x32_bf16 v[14:17], v[134:137], v[206:209], v[14:17]
	s_setprio 0
	s_setprio 1
	v_mfma_f32_16x16x32_bf16 v[54:57], v[146:149], v[166:169], 0
	v_mfma_f32_16x16x32_bf16 v[54:57], v[150:153], v[170:173], v[54:57]
	v_mfma_f32_16x16x32_bf16 v[50:53], v[154:157], v[166:169], 0
	v_mfma_f32_16x16x32_bf16 v[50:53], v[158:161], v[170:173], v[50:53]
	v_mfma_f32_16x16x32_bf16 v[34:37], v[154:157], v[186:189], 0
	v_mfma_f32_16x16x32_bf16 v[34:37], v[158:161], v[190:193], v[34:37]
	v_mfma_f32_16x16x32_bf16 v[38:41], v[146:149], v[186:189], 0
	v_mfma_f32_16x16x32_bf16 v[38:41], v[150:153], v[190:193], v[38:41]
	v_mfma_f32_16x16x32_bf16 v[22:25], v[146:149], v[194:197], 0
	v_mfma_f32_16x16x32_bf16 v[22:25], v[150:153], v[198:201], v[22:25]
	v_mfma_f32_16x16x32_bf16 v[18:21], v[154:157], v[194:197], 0
	v_mfma_f32_16x16x32_bf16 v[18:21], v[158:161], v[198:201], v[18:21]
	v_mfma_f32_16x16x32_bf16 v[2:5], v[154:157], v[202:205], 0
	v_mfma_f32_16x16x32_bf16 v[2:5], v[158:161], v[206:209], v[2:5]
	s_setprio 2
	s_barrier
	v_mfma_f32_16x16x32_bf16 v[6:9], v[146:149], v[202:205], 0
	v_mfma_f32_16x16x32_bf16 v[6:9], v[150:153], v[206:209], v[6:9]
	s_setprio 0
	ds_read_b128 v[130:133], v184
	ds_read_b128 v[134:137], v184 offset:1024
	ds_read_b128 v[138:141], v184 offset:2048
	ds_read_b128 v[142:145], v184 offset:3072
	ds_read_b128 v[146:149], v185
	ds_read_b128 v[150:153], v185 offset:1024
	ds_read_b128 v[154:157], v185 offset:2048
	ds_read_b128 v[158:161], v185 offset:3072
	ds_read_b128 v[166:169], v183 offset:32768
	ds_read_b128 v[170:173], v183 offset:33792
	ds_read_b128 v[186:189], v183 offset:34816
	ds_read_b128 v[190:193], v183 offset:35840
	ds_read_b128 v[194:197], v183 offset:36864
	ds_read_b128 v[198:201], v183 offset:37888
	ds_read_b128 v[202:205], v183 offset:38912
	ds_read_b128 v[206:209], v183 offset:39936
	s_mov_b32 s79, m0
	s_mov_b32 m0, s40
	s_nop 0
	global_load_lds_dwordx4 v1, s[28:29]
	s_mov_b32 m0, s79
	s_nop 0
	s_mov_b32 s79, m0
	s_mov_b32 m0, s47
	s_nop 0
	global_load_lds_dwordx4 v177, s[28:29]
	s_mov_b32 m0, s79
	s_add_u32 s28, s28, 0x80000
	s_addc_u32 s29, s29, 0
	s_mov_b32 s79, m0
	s_mov_b32 m0, s48
	s_nop 0
	global_load_lds_dwordx4 v1, s[28:29]
	s_mov_b32 m0, s79
	s_nop 0
	s_mov_b32 s79, m0
	s_mov_b32 m0, s49
	s_nop 0
	global_load_lds_dwordx4 v177, s[28:29]
	s_mov_b32 m0, s79
	s_waitcnt vmcnt(8)
	s_waitcnt lgkmcnt(0)
	s_barrier
	s_setprio 1
	.p2align 3
	v_mfma_f32_16x16x32_bf16 v[126:129], v[130:133], v[166:169], v[126:129]
	v_mfma_f32_16x16x32_bf16 v[126:129], v[134:137], v[170:173], v[126:129]
	v_mfma_f32_16x16x32_bf16 v[122:125], v[138:141], v[166:169], v[122:125]
	v_mfma_f32_16x16x32_bf16 v[122:125], v[142:145], v[170:173], v[122:125]
	v_mfma_f32_16x16x32_bf16 v[114:117], v[138:141], v[186:189], v[114:117]
	v_mfma_f32_16x16x32_bf16 v[114:117], v[142:145], v[190:193], v[114:117]
	v_mfma_f32_16x16x32_bf16 v[118:121], v[130:133], v[186:189], v[118:121]
	v_mfma_f32_16x16x32_bf16 v[118:121], v[134:137], v[190:193], v[118:121]
	v_mfma_f32_16x16x32_bf16 v[94:97], v[130:133], v[194:197], v[94:97]
	v_mfma_f32_16x16x32_bf16 v[94:97], v[134:137], v[198:201], v[94:97]
	v_mfma_f32_16x16x32_bf16 v[90:93], v[138:141], v[194:197], v[90:93]
	v_mfma_f32_16x16x32_bf16 v[90:93], v[142:145], v[198:201], v[90:93]
	v_mfma_f32_16x16x32_bf16 v[78:81], v[138:141], v[202:205], v[78:81]
	v_mfma_f32_16x16x32_bf16 v[78:81], v[142:145], v[206:209], v[78:81]
	v_mfma_f32_16x16x32_bf16 v[86:89], v[130:133], v[202:205], v[86:89]
	v_mfma_f32_16x16x32_bf16 v[86:89], v[134:137], v[206:209], v[86:89]
	s_setprio 0
	s_setprio 1
	v_mfma_f32_16x16x32_bf16 v[110:113], v[146:149], v[166:169], v[110:113]
	v_mfma_f32_16x16x32_bf16 v[110:113], v[150:153], v[170:173], v[110:113]
	v_mfma_f32_16x16x32_bf16 v[106:109], v[154:157], v[166:169], v[106:109]
	v_mfma_f32_16x16x32_bf16 v[106:109], v[158:161], v[170:173], v[106:109]
	v_mfma_f32_16x16x32_bf16 v[98:101], v[154:157], v[186:189], v[98:101]
	v_mfma_f32_16x16x32_bf16 v[98:101], v[158:161], v[190:193], v[98:101]
	v_mfma_f32_16x16x32_bf16 v[102:105], v[146:149], v[186:189], v[102:105]
	v_mfma_f32_16x16x32_bf16 v[102:105], v[150:153], v[190:193], v[102:105]
	v_mfma_f32_16x16x32_bf16 v[82:85], v[146:149], v[194:197], v[82:85]
	v_mfma_f32_16x16x32_bf16 v[82:85], v[150:153], v[198:201], v[82:85]
	v_mfma_f32_16x16x32_bf16 v[74:77], v[154:157], v[194:197], v[74:77]
	v_mfma_f32_16x16x32_bf16 v[74:77], v[158:161], v[198:201], v[74:77]
	v_mfma_f32_16x16x32_bf16 v[66:69], v[154:157], v[202:205], v[66:69]
	v_mfma_f32_16x16x32_bf16 v[66:69], v[158:161], v[206:209], v[66:69]
	s_setprio 2
	s_barrier
	v_mfma_f32_16x16x32_bf16 v[70:73], v[146:149], v[202:205], v[70:73]
	v_mfma_f32_16x16x32_bf16 v[70:73], v[150:153], v[206:209], v[70:73]
	s_setprio 0
	ds_read_b128 v[166:169], v183 offset:49152
	ds_read_b128 v[170:173], v183 offset:50176
	ds_read_b128 v[186:189], v183 offset:51200
	ds_read_b128 v[190:193], v183 offset:52224
	ds_read_b128 v[194:197], v183 offset:53248
	ds_read_b128 v[198:201], v183 offset:54272
	ds_read_b128 v[202:205], v183 offset:55296
	ds_read_b128 v[206:209], v183 offset:56320
	s_add_u32 s28, s26, 0x80
	s_addc_u32 s29, s27, 0
	s_mov_b32 s79, m0
	s_mov_b32 m0, s56
	s_nop 0
	global_load_lds_dwordx4 v176, s[28:29]
	s_mov_b32 m0, s79
	s_add_u32 s26, s26, 0x80080
	s_mov_b32 s79, m0
	s_mov_b32 m0, s57
	s_nop 0
	global_load_lds_dwordx4 v178, s[28:29]
	s_mov_b32 m0, s79
	s_addc_u32 s27, s27, 0
	s_mov_b32 s28, m0
	s_mov_b32 m0, s58
	s_nop 0
	global_load_lds_dwordx4 v176, s[26:27]
	s_mov_b32 m0, s28
	s_nop 0
	s_mov_b32 s28, m0
	s_mov_b32 m0, s59
	s_nop 0
	global_load_lds_dwordx4 v178, s[26:27]
	s_mov_b32 m0, s28
	s_waitcnt vmcnt(4)
	s_waitcnt lgkmcnt(0)
	s_barrier
	s_setprio 1
	.p2align 3
	v_mfma_f32_16x16x32_bf16 v[62:65], v[130:133], v[166:169], v[62:65]
	v_mfma_f32_16x16x32_bf16 v[62:65], v[134:137], v[170:173], v[62:65]
	v_mfma_f32_16x16x32_bf16 v[58:61], v[138:141], v[166:169], v[58:61]
	v_mfma_f32_16x16x32_bf16 v[58:61], v[142:145], v[170:173], v[58:61]
	v_mfma_f32_16x16x32_bf16 v[42:45], v[138:141], v[186:189], v[42:45]
	v_mfma_f32_16x16x32_bf16 v[42:45], v[142:145], v[190:193], v[42:45]
	v_mfma_f32_16x16x32_bf16 v[46:49], v[130:133], v[186:189], v[46:49]
	v_mfma_f32_16x16x32_bf16 v[46:49], v[134:137], v[190:193], v[46:49]
	v_mfma_f32_16x16x32_bf16 v[30:33], v[130:133], v[194:197], v[30:33]
	v_mfma_f32_16x16x32_bf16 v[30:33], v[134:137], v[198:201], v[30:33]
	v_mfma_f32_16x16x32_bf16 v[26:29], v[138:141], v[194:197], v[26:29]
	v_mfma_f32_16x16x32_bf16 v[26:29], v[142:145], v[198:201], v[26:29]
	v_mfma_f32_16x16x32_bf16 v[10:13], v[138:141], v[202:205], v[10:13]
	v_mfma_f32_16x16x32_bf16 v[10:13], v[142:145], v[206:209], v[10:13]
	v_mfma_f32_16x16x32_bf16 v[14:17], v[130:133], v[202:205], v[14:17]
	v_mfma_f32_16x16x32_bf16 v[14:17], v[134:137], v[206:209], v[14:17]
	s_setprio 0
	s_setprio 1
	v_mfma_f32_16x16x32_bf16 v[54:57], v[146:149], v[166:169], v[54:57]
	v_mfma_f32_16x16x32_bf16 v[54:57], v[150:153], v[170:173], v[54:57]
	v_mfma_f32_16x16x32_bf16 v[50:53], v[154:157], v[166:169], v[50:53]
	v_mfma_f32_16x16x32_bf16 v[50:53], v[158:161], v[170:173], v[50:53]
	v_mfma_f32_16x16x32_bf16 v[34:37], v[154:157], v[186:189], v[34:37]
	v_mfma_f32_16x16x32_bf16 v[34:37], v[158:161], v[190:193], v[34:37]
	v_mfma_f32_16x16x32_bf16 v[38:41], v[146:149], v[186:189], v[38:41]
	v_mfma_f32_16x16x32_bf16 v[38:41], v[150:153], v[190:193], v[38:41]
	v_mfma_f32_16x16x32_bf16 v[22:25], v[146:149], v[194:197], v[22:25]
	v_mfma_f32_16x16x32_bf16 v[22:25], v[150:153], v[198:201], v[22:25]
	v_mfma_f32_16x16x32_bf16 v[18:21], v[154:157], v[194:197], v[18:21]
	v_mfma_f32_16x16x32_bf16 v[18:21], v[158:161], v[198:201], v[18:21]
	v_mfma_f32_16x16x32_bf16 v[2:5], v[154:157], v[202:205], v[2:5]
	v_mfma_f32_16x16x32_bf16 v[2:5], v[158:161], v[206:209], v[2:5]
	s_setprio 2
	s_barrier
	v_mfma_f32_16x16x32_bf16 v[6:9], v[146:149], v[202:205], v[6:9]
	v_mfma_f32_16x16x32_bf16 v[6:9], v[150:153], v[206:209], v[6:9]
	s_setprio 0
	s_add_i32 s78, s78, 2
	s_add_u32 s74, s74, 0x100
	s_addc_u32 s75, s75, 0
	s_add_u32 s24, s24, 0x100
	s_addc_u32 s25, s25, 0
	s_add_u32 s76, s76, 0x100
	s_addc_u32 s77, s77, 0
	s_cmp_gt_u32 s78, 29
	.p2align 6
.LBB0_2410:
	ds_read_b128 v[130:133], v181
	ds_read_b128 v[134:137], v181 offset:1024
	ds_read_b128 v[138:141], v181 offset:2048
	ds_read_b128 v[142:145], v181 offset:3072
	ds_read_b128 v[146:149], v182
	ds_read_b128 v[150:153], v182 offset:1024
	ds_read_b128 v[154:157], v182 offset:2048
	ds_read_b128 v[158:161], v182 offset:3072
	s_cmp_eq_u32 s78, 28
	s_cselect_b32 s27, s15, s75
	s_cselect_b32 s26, s73, s74
	s_cselect_b32 s29, s17, s77
	s_cselect_b32 s28, s71, s76
	ds_read_b128 v[166:169], v183
	ds_read_b128 v[170:173], v183 offset:1024
	ds_read_b128 v[186:189], v183 offset:2048
	ds_read_b128 v[190:193], v183 offset:3072
	ds_read_b128 v[194:197], v183 offset:4096
	ds_read_b128 v[198:201], v183 offset:5120
	ds_read_b128 v[202:205], v183 offset:6144
	ds_read_b128 v[206:209], v183 offset:7168
	s_add_u32 s80, s24, 0xfff80000
	s_addc_u32 s81, s25, -1
	s_mov_b32 s79, m0
	s_mov_b32 m0, s64
	s_nop 0
	global_load_lds_dwordx4 v1, s[80:81]
	s_mov_b32 m0, s79
	s_nop 0
	s_mov_b32 s79, m0
	s_mov_b32 m0, s66
	s_nop 0
	global_load_lds_dwordx4 v177, s[80:81]
	s_mov_b32 m0, s79
	s_nop 0
	s_mov_b32 s79, m0
	s_mov_b32 m0, s65
	s_nop 0
	global_load_lds_dwordx4 v1, s[24:25]
	s_mov_b32 m0, s79
	s_nop 0
	s_mov_b32 s79, m0
	s_mov_b32 m0, s67
	s_nop 0
	global_load_lds_dwordx4 v177, s[24:25]
	s_mov_b32 m0, s79
	s_waitcnt vmcnt(8)
	s_waitcnt lgkmcnt(0)
	s_barrier
	s_setprio 1
	.p2align 3
	v_mfma_f32_16x16x32_bf16 v[126:129], v[130:133], v[166:169], v[126:129]
	v_mfma_f32_16x16x32_bf16 v[126:129], v[134:137], v[170:173], v[126:129]
	v_mfma_f32_16x16x32_bf16 v[122:125], v[138:141], v[166:169], v[122:125]
	v_mfma_f32_16x16x32_bf16 v[122:125], v[142:145], v[170:173], v[122:125]
	v_mfma_f32_16x16x32_bf16 v[114:117], v[138:141], v[186:189], v[114:117]
	v_mfma_f32_16x16x32_bf16 v[114:117], v[142:145], v[190:193], v[114:117]
	v_mfma_f32_16x16x32_bf16 v[118:121], v[130:133], v[186:189], v[118:121]
	v_mfma_f32_16x16x32_bf16 v[118:121], v[134:137], v[190:193], v[118:121]
	v_mfma_f32_16x16x32_bf16 v[94:97], v[130:133], v[194:197], v[94:97]
	v_mfma_f32_16x16x32_bf16 v[94:97], v[134:137], v[198:201], v[94:97]
	v_mfma_f32_16x16x32_bf16 v[90:93], v[138:141], v[194:197], v[90:93]
	v_mfma_f32_16x16x32_bf16 v[90:93], v[142:145], v[198:201], v[90:93]
	v_mfma_f32_16x16x32_bf16 v[78:81], v[138:141], v[202:205], v[78:81]
	v_mfma_f32_16x16x32_bf16 v[78:81], v[142:145], v[206:209], v[78:81]
	v_mfma_f32_16x16x32_bf16 v[86:89], v[130:133], v[202:205], v[86:89]
	v_mfma_f32_16x16x32_bf16 v[86:89], v[134:137], v[206:209], v[86:89]
	s_setprio 0
	s_setprio 1
	v_mfma_f32_16x16x32_bf16 v[110:113], v[146:149], v[166:169], v[110:113]
	v_mfma_f32_16x16x32_bf16 v[110:113], v[150:153], v[170:173], v[110:113]
	v_mfma_f32_16x16x32_bf16 v[106:109], v[154:157], v[166:169], v[106:109]
	v_mfma_f32_16x16x32_bf16 v[106:109], v[158:161], v[170:173], v[106:109]
	v_mfma_f32_16x16x32_bf16 v[98:101], v[154:157], v[186:189], v[98:101]
	v_mfma_f32_16x16x32_bf16 v[98:101], v[158:161], v[190:193], v[98:101]
	v_mfma_f32_16x16x32_bf16 v[102:105], v[146:149], v[186:189], v[102:105]
	v_mfma_f32_16x16x32_bf16 v[102:105], v[150:153], v[190:193], v[102:105]
	v_mfma_f32_16x16x32_bf16 v[82:85], v[146:149], v[194:197], v[82:85]
	v_mfma_f32_16x16x32_bf16 v[82:85], v[150:153], v[198:201], v[82:85]
	v_mfma_f32_16x16x32_bf16 v[74:77], v[154:157], v[194:197], v[74:77]
	v_mfma_f32_16x16x32_bf16 v[74:77], v[158:161], v[198:201], v[74:77]
	v_mfma_f32_16x16x32_bf16 v[66:69], v[154:157], v[202:205], v[66:69]
	v_mfma_f32_16x16x32_bf16 v[66:69], v[158:161], v[206:209], v[66:69]
	s_setprio 2
	s_barrier
	v_mfma_f32_16x16x32_bf16 v[70:73], v[146:149], v[202:205], v[70:73]
	v_mfma_f32_16x16x32_bf16 v[70:73], v[150:153], v[206:209], v[70:73]
	s_setprio 0
	ds_read_b128 v[166:169], v183 offset:16384
	ds_read_b128 v[170:173], v183 offset:17408
	ds_read_b128 v[186:189], v183 offset:18432
	ds_read_b128 v[190:193], v183 offset:19456
	ds_read_b128 v[194:197], v183 offset:20480
	ds_read_b128 v[198:201], v183 offset:21504
	ds_read_b128 v[202:205], v183 offset:22528
	ds_read_b128 v[206:209], v183 offset:23552
	s_mov_b32 s79, m0
	s_mov_b32 m0, s41
	s_nop 0
	global_load_lds_dwordx4 v176, s[26:27]
	s_mov_b32 m0, s79
	s_add_u32 s80, s26, 0x80000
	s_mov_b32 s79, m0
	s_mov_b32 m0, s42
	s_nop 0
	global_load_lds_dwordx4 v178, s[26:27]
	s_mov_b32 m0, s79
	s_addc_u32 s81, s27, 0
	s_mov_b32 s79, m0
	s_mov_b32 m0, s43
	s_nop 0
	global_load_lds_dwordx4 v176, s[80:81]
	s_mov_b32 m0, s79
	s_nop 0
	s_mov_b32 s79, m0
	s_mov_b32 m0, s46
	s_nop 0
	global_load_lds_dwordx4 v178, s[80:81]
	s_mov_b32 m0, s79
	s_waitcnt vmcnt(4)
	s_waitcnt lgkmcnt(0)
	s_barrier
	s_setprio 1
	.p2align 3
	v_mfma_f32_16x16x32_bf16 v[62:65], v[130:133], v[166:169], v[62:65]
	v_mfma_f32_16x16x32_bf16 v[62:65], v[134:137], v[170:173], v[62:65]
	v_mfma_f32_16x16x32_bf16 v[58:61], v[138:141], v[166:169], v[58:61]
	v_mfma_f32_16x16x32_bf16 v[58:61], v[142:145], v[170:173], v[58:61]
	v_mfma_f32_16x16x32_bf16 v[42:45], v[138:141], v[186:189], v[42:45]
	v_mfma_f32_16x16x32_bf16 v[42:45], v[142:145], v[190:193], v[42:45]
	v_mfma_f32_16x16x32_bf16 v[46:49], v[130:133], v[186:189], v[46:49]
	v_mfma_f32_16x16x32_bf16 v[46:49], v[134:137], v[190:193], v[46:49]
	v_mfma_f32_16x16x32_bf16 v[30:33], v[130:133], v[194:197], v[30:33]
	v_mfma_f32_16x16x32_bf16 v[30:33], v[134:137], v[198:201], v[30:33]
	v_mfma_f32_16x16x32_bf16 v[26:29], v[138:141], v[194:197], v[26:29]
	v_mfma_f32_16x16x32_bf16 v[26:29], v[142:145], v[198:201], v[26:29]
	v_mfma_f32_16x16x32_bf16 v[10:13], v[138:141], v[202:205], v[10:13]
	v_mfma_f32_16x16x32_bf16 v[10:13], v[142:145], v[206:209], v[10:13]
	v_mfma_f32_16x16x32_bf16 v[14:17], v[130:133], v[202:205], v[14:17]
	v_mfma_f32_16x16x32_bf16 v[14:17], v[134:137], v[206:209], v[14:17]
	s_setprio 0
	s_setprio 1
	v_mfma_f32_16x16x32_bf16 v[54:57], v[146:149], v[166:169], v[54:57]
	v_mfma_f32_16x16x32_bf16 v[54:57], v[150:153], v[170:173], v[54:57]
	v_mfma_f32_16x16x32_bf16 v[50:53], v[154:157], v[166:169], v[50:53]
	v_mfma_f32_16x16x32_bf16 v[50:53], v[158:161], v[170:173], v[50:53]
	v_mfma_f32_16x16x32_bf16 v[34:37], v[154:157], v[186:189], v[34:37]
	v_mfma_f32_16x16x32_bf16 v[34:37], v[158:161], v[190:193], v[34:37]
	v_mfma_f32_16x16x32_bf16 v[38:41], v[146:149], v[186:189], v[38:41]
	v_mfma_f32_16x16x32_bf16 v[38:41], v[150:153], v[190:193], v[38:41]
	v_mfma_f32_16x16x32_bf16 v[22:25], v[146:149], v[194:197], v[22:25]
	v_mfma_f32_16x16x32_bf16 v[22:25], v[150:153], v[198:201], v[22:25]
	v_mfma_f32_16x16x32_bf16 v[18:21], v[154:157], v[194:197], v[18:21]
	v_mfma_f32_16x16x32_bf16 v[18:21], v[158:161], v[198:201], v[18:21]
	v_mfma_f32_16x16x32_bf16 v[2:5], v[154:157], v[202:205], v[2:5]
	v_mfma_f32_16x16x32_bf16 v[2:5], v[158:161], v[206:209], v[2:5]
	s_setprio 2
	s_barrier
	v_mfma_f32_16x16x32_bf16 v[6:9], v[146:149], v[202:205], v[6:9]
	v_mfma_f32_16x16x32_bf16 v[6:9], v[150:153], v[206:209], v[6:9]
	s_setprio 0
	ds_read_b128 v[130:133], v184
	ds_read_b128 v[134:137], v184 offset:1024
	ds_read_b128 v[138:141], v184 offset:2048
	ds_read_b128 v[142:145], v184 offset:3072
	ds_read_b128 v[146:149], v185
	ds_read_b128 v[150:153], v185 offset:1024
	ds_read_b128 v[154:157], v185 offset:2048
	ds_read_b128 v[158:161], v185 offset:3072
	ds_read_b128 v[166:169], v183 offset:32768
	ds_read_b128 v[170:173], v183 offset:33792
	ds_read_b128 v[186:189], v183 offset:34816
	ds_read_b128 v[190:193], v183 offset:35840
	ds_read_b128 v[194:197], v183 offset:36864
	ds_read_b128 v[198:201], v183 offset:37888
	ds_read_b128 v[202:205], v183 offset:38912
	ds_read_b128 v[206:209], v183 offset:39936
	s_mov_b32 s79, m0
	s_mov_b32 m0, s40
	s_nop 0
	global_load_lds_dwordx4 v1, s[28:29]
	s_mov_b32 m0, s79
	s_nop 0
	s_mov_b32 s79, m0
	s_mov_b32 m0, s47
	s_nop 0
	global_load_lds_dwordx4 v177, s[28:29]
	s_mov_b32 m0, s79
	s_add_u32 s28, s28, 0x80000
	s_addc_u32 s29, s29, 0
	s_mov_b32 s79, m0
	s_mov_b32 m0, s48
	s_nop 0
	global_load_lds_dwordx4 v1, s[28:29]
	s_mov_b32 m0, s79
	s_nop 0
	s_mov_b32 s79, m0
	s_mov_b32 m0, s49
	s_nop 0
	global_load_lds_dwordx4 v177, s[28:29]
	s_mov_b32 m0, s79
	s_waitcnt vmcnt(8)
	s_waitcnt lgkmcnt(0)
	s_barrier
	s_setprio 1
	.p2align 3
	v_mfma_f32_16x16x32_bf16 v[126:129], v[130:133], v[166:169], v[126:129]
	v_mfma_f32_16x16x32_bf16 v[126:129], v[134:137], v[170:173], v[126:129]
	v_mfma_f32_16x16x32_bf16 v[122:125], v[138:141], v[166:169], v[122:125]
	v_mfma_f32_16x16x32_bf16 v[122:125], v[142:145], v[170:173], v[122:125]
	v_mfma_f32_16x16x32_bf16 v[114:117], v[138:141], v[186:189], v[114:117]
	v_mfma_f32_16x16x32_bf16 v[114:117], v[142:145], v[190:193], v[114:117]
	v_mfma_f32_16x16x32_bf16 v[118:121], v[130:133], v[186:189], v[118:121]
	v_mfma_f32_16x16x32_bf16 v[118:121], v[134:137], v[190:193], v[118:121]
	v_mfma_f32_16x16x32_bf16 v[94:97], v[130:133], v[194:197], v[94:97]
	v_mfma_f32_16x16x32_bf16 v[94:97], v[134:137], v[198:201], v[94:97]
	v_mfma_f32_16x16x32_bf16 v[90:93], v[138:141], v[194:197], v[90:93]
	v_mfma_f32_16x16x32_bf16 v[90:93], v[142:145], v[198:201], v[90:93]
	v_mfma_f32_16x16x32_bf16 v[78:81], v[138:141], v[202:205], v[78:81]
	v_mfma_f32_16x16x32_bf16 v[78:81], v[142:145], v[206:209], v[78:81]
	v_mfma_f32_16x16x32_bf16 v[86:89], v[130:133], v[202:205], v[86:89]
	v_mfma_f32_16x16x32_bf16 v[86:89], v[134:137], v[206:209], v[86:89]
	s_setprio 0
	s_setprio 1
	v_mfma_f32_16x16x32_bf16 v[110:113], v[146:149], v[166:169], v[110:113]
	v_mfma_f32_16x16x32_bf16 v[110:113], v[150:153], v[170:173], v[110:113]
	v_mfma_f32_16x16x32_bf16 v[106:109], v[154:157], v[166:169], v[106:109]
	v_mfma_f32_16x16x32_bf16 v[106:109], v[158:161], v[170:173], v[106:109]
	v_mfma_f32_16x16x32_bf16 v[98:101], v[154:157], v[186:189], v[98:101]
	v_mfma_f32_16x16x32_bf16 v[98:101], v[158:161], v[190:193], v[98:101]
	v_mfma_f32_16x16x32_bf16 v[102:105], v[146:149], v[186:189], v[102:105]
	v_mfma_f32_16x16x32_bf16 v[102:105], v[150:153], v[190:193], v[102:105]
	v_mfma_f32_16x16x32_bf16 v[82:85], v[146:149], v[194:197], v[82:85]
	v_mfma_f32_16x16x32_bf16 v[82:85], v[150:153], v[198:201], v[82:85]
	v_mfma_f32_16x16x32_bf16 v[74:77], v[154:157], v[194:197], v[74:77]
	v_mfma_f32_16x16x32_bf16 v[74:77], v[158:161], v[198:201], v[74:77]
	v_mfma_f32_16x16x32_bf16 v[66:69], v[154:157], v[202:205], v[66:69]
	v_mfma_f32_16x16x32_bf16 v[66:69], v[158:161], v[206:209], v[66:69]
	s_setprio 2
	s_barrier
	v_mfma_f32_16x16x32_bf16 v[70:73], v[146:149], v[202:205], v[70:73]
	v_mfma_f32_16x16x32_bf16 v[70:73], v[150:153], v[206:209], v[70:73]
	s_setprio 0
	ds_read_b128 v[166:169], v183 offset:49152
	ds_read_b128 v[170:173], v183 offset:50176
	ds_read_b128 v[186:189], v183 offset:51200
	ds_read_b128 v[190:193], v183 offset:52224
	ds_read_b128 v[194:197], v183 offset:53248
	ds_read_b128 v[198:201], v183 offset:54272
	ds_read_b128 v[202:205], v183 offset:55296
	ds_read_b128 v[206:209], v183 offset:56320
	s_add_u32 s28, s26, 0x80
	s_addc_u32 s29, s27, 0
	s_mov_b32 s79, m0
	s_mov_b32 m0, s56
	s_nop 0
	global_load_lds_dwordx4 v176, s[28:29]
	s_mov_b32 m0, s79
	s_add_u32 s26, s26, 0x80080
	s_mov_b32 s79, m0
	s_mov_b32 m0, s57
	s_nop 0
	global_load_lds_dwordx4 v178, s[28:29]
	s_mov_b32 m0, s79
	s_addc_u32 s27, s27, 0
	s_mov_b32 s28, m0
	s_mov_b32 m0, s58
	s_nop 0
	global_load_lds_dwordx4 v176, s[26:27]
	s_mov_b32 m0, s28
	s_nop 0
	s_mov_b32 s28, m0
	s_mov_b32 m0, s59
	s_nop 0
	global_load_lds_dwordx4 v178, s[26:27]
	s_mov_b32 m0, s28
	s_waitcnt vmcnt(4)
	s_waitcnt lgkmcnt(0)
	s_barrier
	s_setprio 1
	.p2align 3
	v_mfma_f32_16x16x32_bf16 v[62:65], v[130:133], v[166:169], v[62:65]
	v_mfma_f32_16x16x32_bf16 v[62:65], v[134:137], v[170:173], v[62:65]
	v_mfma_f32_16x16x32_bf16 v[58:61], v[138:141], v[166:169], v[58:61]
	v_mfma_f32_16x16x32_bf16 v[58:61], v[142:145], v[170:173], v[58:61]
	v_mfma_f32_16x16x32_bf16 v[42:45], v[138:141], v[186:189], v[42:45]
	v_mfma_f32_16x16x32_bf16 v[42:45], v[142:145], v[190:193], v[42:45]
	v_mfma_f32_16x16x32_bf16 v[46:49], v[130:133], v[186:189], v[46:49]
	v_mfma_f32_16x16x32_bf16 v[46:49], v[134:137], v[190:193], v[46:49]
	v_mfma_f32_16x16x32_bf16 v[30:33], v[130:133], v[194:197], v[30:33]
	v_mfma_f32_16x16x32_bf16 v[30:33], v[134:137], v[198:201], v[30:33]
	v_mfma_f32_16x16x32_bf16 v[26:29], v[138:141], v[194:197], v[26:29]
	v_mfma_f32_16x16x32_bf16 v[26:29], v[142:145], v[198:201], v[26:29]
	v_mfma_f32_16x16x32_bf16 v[10:13], v[138:141], v[202:205], v[10:13]
	v_mfma_f32_16x16x32_bf16 v[10:13], v[142:145], v[206:209], v[10:13]
	v_mfma_f32_16x16x32_bf16 v[14:17], v[130:133], v[202:205], v[14:17]
	v_mfma_f32_16x16x32_bf16 v[14:17], v[134:137], v[206:209], v[14:17]
	s_setprio 0
	s_setprio 1
	v_mfma_f32_16x16x32_bf16 v[54:57], v[146:149], v[166:169], v[54:57]
	v_mfma_f32_16x16x32_bf16 v[54:57], v[150:153], v[170:173], v[54:57]
	v_mfma_f32_16x16x32_bf16 v[50:53], v[154:157], v[166:169], v[50:53]
	v_mfma_f32_16x16x32_bf16 v[50:53], v[158:161], v[170:173], v[50:53]
	v_mfma_f32_16x16x32_bf16 v[34:37], v[154:157], v[186:189], v[34:37]
	v_mfma_f32_16x16x32_bf16 v[34:37], v[158:161], v[190:193], v[34:37]
	v_mfma_f32_16x16x32_bf16 v[38:41], v[146:149], v[186:189], v[38:41]
	v_mfma_f32_16x16x32_bf16 v[38:41], v[150:153], v[190:193], v[38:41]
	v_mfma_f32_16x16x32_bf16 v[22:25], v[146:149], v[194:197], v[22:25]
	v_mfma_f32_16x16x32_bf16 v[22:25], v[150:153], v[198:201], v[22:25]
	v_mfma_f32_16x16x32_bf16 v[18:21], v[154:157], v[194:197], v[18:21]
	v_mfma_f32_16x16x32_bf16 v[18:21], v[158:161], v[198:201], v[18:21]
	v_mfma_f32_16x16x32_bf16 v[2:5], v[154:157], v[202:205], v[2:5]
	v_mfma_f32_16x16x32_bf16 v[2:5], v[158:161], v[206:209], v[2:5]
	s_setprio 2
	s_barrier
	v_mfma_f32_16x16x32_bf16 v[6:9], v[146:149], v[202:205], v[6:9]
	v_mfma_f32_16x16x32_bf16 v[6:9], v[150:153], v[206:209], v[6:9]
	s_setprio 0
	s_add_i32 s78, s78, 2
	s_add_u32 s74, s74, 0x100
	s_addc_u32 s75, s75, 0
	s_add_u32 s24, s24, 0x100
	s_addc_u32 s25, s25, 0
	s_add_u32 s76, s76, 0x100
	s_addc_u32 s77, s77, 0
	s_cmp_gt_u32 s78, 29
	s_cbranch_scc0 .LBB0_2410
	s_and_b64 vcc, exec, s[8:9]
	s_cbranch_vccz .LBB0_2413
	s_barrier

.LBB0_2593:
	s_ashr_i32 s11, s10, 31
	s_lshl_b64 s[12:13], s[10:11], 20
	s_add_u32 s12, s26, s12
	s_addc_u32 s13, s27, s13
	s_and_b64 s[14:15], s[2:3], exec
	s_cselect_b32 s11, s13, s21
	s_cselect_b32 s62, s12, s20
	s_ashr_i32 s9, s8, 31
	s_lshl_b64 s[14:15], s[8:9], 20
	s_add_u32 s14, s28, s14
	s_addc_u32 s15, s29, s15
	s_and_b64 s[22:23], s[2:3], exec
	s_cselect_b32 s9, s15, s19
	s_cselect_b32 s63, s14, s18
	s_add_u32 s64, s18, 0x100
	s_addc_u32 s65, s19, 0
	s_add_u32 s18, s20, 0x80080
	s_addc_u32 s19, s21, 0
	s_add_u32 s66, s20, 0x100
	s_addc_u32 s67, s21, 0
	s_mov_b32 s70, -2
	ds_read_b128 v[148:151], v143
	ds_read_b128 v[152:155], v143 offset:1024
	ds_read_b128 v[156:159], v143 offset:2048
	ds_read_b128 v[160:163], v143 offset:3072
	ds_read_b128 v[164:167], v144
	ds_read_b128 v[168:171], v144 offset:1024
	ds_read_b128 v[172:175], v144 offset:2048
	ds_read_b128 v[176:179], v144 offset:3072
	s_cmp_eq_u32 s70, 28
	s_cselect_b32 s21, s9, s65
	s_cselect_b32 s20, s63, s64
	s_cselect_b32 s23, s11, s67
	s_cselect_b32 s22, s62, s66
	ds_read_b128 v[180:183], v145
	ds_read_b128 v[184:187], v145 offset:1024
	ds_read_b128 v[188:191], v145 offset:2048
	ds_read_b128 v[192:195], v145 offset:3072
	ds_read_b128 v[196:199], v145 offset:4096
	ds_read_b128 v[200:203], v145 offset:5120
	ds_read_b128 v[204:207], v145 offset:6144
	ds_read_b128 v[208:211], v145 offset:7168
	s_add_u32 s74, s18, 0xfff80000
	s_addc_u32 s75, s19, -1
	s_mov_b32 s71, m0
	s_mov_b32 m0, s48
	s_nop 0
	global_load_lds_dwordx4 v138, s[74:75]
	s_mov_b32 m0, s71
	s_nop 0
	s_mov_b32 s71, m0
	s_mov_b32 m0, s57
	s_nop 0
	global_load_lds_dwordx4 v140, s[74:75]
	s_mov_b32 m0, s71
	s_nop 0
	s_mov_b32 s71, m0
	s_mov_b32 m0, s49
	s_nop 0
	global_load_lds_dwordx4 v138, s[18:19]
	s_mov_b32 m0, s71
	s_nop 0
	s_mov_b32 s71, m0
	s_mov_b32 m0, s58
	s_nop 0
	global_load_lds_dwordx4 v140, s[18:19]
	s_mov_b32 m0, s71
	s_waitcnt vmcnt(8)
	s_waitcnt lgkmcnt(0)
	s_barrier
	s_setprio 1
	.p2align 3
	v_mfma_f32_16x16x32_bf16 v[126:129], v[148:151], v[180:183], 0
	v_mfma_f32_16x16x32_bf16 v[126:129], v[152:155], v[184:187], v[126:129]
	v_mfma_f32_16x16x32_bf16 v[122:125], v[156:159], v[180:183], 0
	v_mfma_f32_16x16x32_bf16 v[122:125], v[160:163], v[184:187], v[122:125]
	v_mfma_f32_16x16x32_bf16 v[106:109], v[156:159], v[188:191], 0
	v_mfma_f32_16x16x32_bf16 v[106:109], v[160:163], v[192:195], v[106:109]
	v_mfma_f32_16x16x32_bf16 v[110:113], v[148:151], v[188:191], 0
	v_mfma_f32_16x16x32_bf16 v[110:113], v[152:155], v[192:195], v[110:113]
	v_mfma_f32_16x16x32_bf16 v[94:97], v[148:151], v[196:199], 0
	v_mfma_f32_16x16x32_bf16 v[94:97], v[152:155], v[200:203], v[94:97]
	v_mfma_f32_16x16x32_bf16 v[90:93], v[156:159], v[196:199], 0
	v_mfma_f32_16x16x32_bf16 v[90:93], v[160:163], v[200:203], v[90:93]
	v_mfma_f32_16x16x32_bf16 v[74:77], v[156:159], v[204:207], 0
	v_mfma_f32_16x16x32_bf16 v[74:77], v[160:163], v[208:211], v[74:77]
	v_mfma_f32_16x16x32_bf16 v[78:81], v[148:151], v[204:207], 0
	v_mfma_f32_16x16x32_bf16 v[78:81], v[152:155], v[208:211], v[78:81]
	s_setprio 0
	s_setprio 1
	v_mfma_f32_16x16x32_bf16 v[118:121], v[164:167], v[180:183], 0
	v_mfma_f32_16x16x32_bf16 v[118:121], v[168:171], v[184:187], v[118:121]
	v_mfma_f32_16x16x32_bf16 v[114:117], v[172:175], v[180:183], 0
	v_mfma_f32_16x16x32_bf16 v[114:117], v[176:179], v[184:187], v[114:117]
	v_mfma_f32_16x16x32_bf16 v[98:101], v[172:175], v[188:191], 0
	v_mfma_f32_16x16x32_bf16 v[98:101], v[176:179], v[192:195], v[98:101]
	v_mfma_f32_16x16x32_bf16 v[102:105], v[164:167], v[188:191], 0
	v_mfma_f32_16x16x32_bf16 v[102:105], v[168:171], v[192:195], v[102:105]
	v_mfma_f32_16x16x32_bf16 v[86:89], v[164:167], v[196:199], 0
	v_mfma_f32_16x16x32_bf16 v[86:89], v[168:171], v[200:203], v[86:89]
	v_mfma_f32_16x16x32_bf16 v[82:85], v[172:175], v[196:199], 0
	v_mfma_f32_16x16x32_bf16 v[82:85], v[176:179], v[200:203], v[82:85]
	v_mfma_f32_16x16x32_bf16 v[66:69], v[172:175], v[204:207], 0
	v_mfma_f32_16x16x32_bf16 v[66:69], v[176:179], v[208:211], v[66:69]
	s_setprio 2
	s_barrier
	v_mfma_f32_16x16x32_bf16 v[70:73], v[164:167], v[204:207], 0
	v_mfma_f32_16x16x32_bf16 v[70:73], v[168:171], v[208:211], v[70:73]
	s_setprio 0
	ds_read_b128 v[180:183], v145 offset:16384
	ds_read_b128 v[184:187], v145 offset:17408
	ds_read_b128 v[188:191], v145 offset:18432
	ds_read_b128 v[192:195], v145 offset:19456
	ds_read_b128 v[196:199], v145 offset:20480
	ds_read_b128 v[200:203], v145 offset:21504
	ds_read_b128 v[204:207], v145 offset:22528
	ds_read_b128 v[208:211], v145 offset:23552
	s_mov_b32 s71, m0
	s_mov_b32 m0, s35
	s_nop 0
	global_load_lds_dwordx4 v139, s[20:21]
	s_mov_b32 m0, s71
	s_add_u32 s74, s20, 0x80000
	s_mov_b32 s71, m0
	s_mov_b32 m0, s36
	s_nop 0
	global_load_lds_dwordx4 v141, s[20:21]
	s_mov_b32 m0, s71
	s_addc_u32 s75, s21, 0
	s_mov_b32 s71, m0
	s_mov_b32 m0, s37
	s_nop 0
	global_load_lds_dwordx4 v139, s[74:75]
	s_mov_b32 m0, s71
	s_nop 0
	s_mov_b32 s71, m0
	s_mov_b32 m0, s40
	s_nop 0
	global_load_lds_dwordx4 v141, s[74:75]
	s_mov_b32 m0, s71
	s_waitcnt vmcnt(4)
	s_waitcnt lgkmcnt(0)
	s_barrier
	s_setprio 1
	.p2align 3
	v_mfma_f32_16x16x32_bf16 v[62:65], v[148:151], v[180:183], 0
	v_mfma_f32_16x16x32_bf16 v[62:65], v[152:155], v[184:187], v[62:65]
	v_mfma_f32_16x16x32_bf16 v[58:61], v[156:159], v[180:183], 0
	v_mfma_f32_16x16x32_bf16 v[58:61], v[160:163], v[184:187], v[58:61]
	v_mfma_f32_16x16x32_bf16 v[42:45], v[156:159], v[188:191], 0
	v_mfma_f32_16x16x32_bf16 v[42:45], v[160:163], v[192:195], v[42:45]
	v_mfma_f32_16x16x32_bf16 v[46:49], v[148:151], v[188:191], 0
	v_mfma_f32_16x16x32_bf16 v[46:49], v[152:155], v[192:195], v[46:49]
	v_mfma_f32_16x16x32_bf16 v[30:33], v[148:151], v[196:199], 0
	v_mfma_f32_16x16x32_bf16 v[30:33], v[152:155], v[200:203], v[30:33]
	v_mfma_f32_16x16x32_bf16 v[26:29], v[156:159], v[196:199], 0
	v_mfma_f32_16x16x32_bf16 v[26:29], v[160:163], v[200:203], v[26:29]
	v_mfma_f32_16x16x32_bf16 v[10:13], v[156:159], v[204:207], 0
	v_mfma_f32_16x16x32_bf16 v[10:13], v[160:163], v[208:211], v[10:13]
	v_mfma_f32_16x16x32_bf16 v[14:17], v[148:151], v[204:207], 0
	v_mfma_f32_16x16x32_bf16 v[14:17], v[152:155], v[208:211], v[14:17]
	s_setprio 0
	s_setprio 1
	v_mfma_f32_16x16x32_bf16 v[54:57], v[164:167], v[180:183], 0
	v_mfma_f32_16x16x32_bf16 v[54:57], v[168:171], v[184:187], v[54:57]
	v_mfma_f32_16x16x32_bf16 v[50:53], v[172:175], v[180:183], 0
	v_mfma_f32_16x16x32_bf16 v[50:53], v[176:179], v[184:187], v[50:53]
	v_mfma_f32_16x16x32_bf16 v[34:37], v[172:175], v[188:191], 0
	v_mfma_f32_16x16x32_bf16 v[34:37], v[176:179], v[192:195], v[34:37]
	v_mfma_f32_16x16x32_bf16 v[38:41], v[164:167], v[188:191], 0
	v_mfma_f32_16x16x32_bf16 v[38:41], v[168:171], v[192:195], v[38:41]
	v_mfma_f32_16x16x32_bf16 v[22:25], v[164:167], v[196:199], 0
	v_mfma_f32_16x16x32_bf16 v[22:25], v[168:171], v[200:203], v[22:25]
	v_mfma_f32_16x16x32_bf16 v[18:21], v[172:175], v[196:199], 0
	v_mfma_f32_16x16x32_bf16 v[18:21], v[176:179], v[200:203], v[18:21]
	v_mfma_f32_16x16x32_bf16 v[2:5], v[172:175], v[204:207], 0
	v_mfma_f32_16x16x32_bf16 v[2:5], v[176:179], v[208:211], v[2:5]
	s_setprio 2
	s_barrier
	v_mfma_f32_16x16x32_bf16 v[6:9], v[164:167], v[204:207], 0
	v_mfma_f32_16x16x32_bf16 v[6:9], v[168:171], v[208:211], v[6:9]
	s_setprio 0
	ds_read_b128 v[148:151], v146
	ds_read_b128 v[152:155], v146 offset:1024
	ds_read_b128 v[156:159], v146 offset:2048
	ds_read_b128 v[160:163], v146 offset:3072
	ds_read_b128 v[164:167], v147
	ds_read_b128 v[168:171], v147 offset:1024
	ds_read_b128 v[172:175], v147 offset:2048
	ds_read_b128 v[176:179], v147 offset:3072
	ds_read_b128 v[180:183], v145 offset:32768
	ds_read_b128 v[184:187], v145 offset:33792
	ds_read_b128 v[188:191], v145 offset:34816
	ds_read_b128 v[192:195], v145 offset:35840
	ds_read_b128 v[196:199], v145 offset:36864
	ds_read_b128 v[200:203], v145 offset:37888
	ds_read_b128 v[204:207], v145 offset:38912
	ds_read_b128 v[208:211], v145 offset:39936
	s_mov_b32 s71, m0
	s_mov_b32 m0, s31
	s_nop 0
	global_load_lds_dwordx4 v138, s[22:23]
	s_mov_b32 m0, s71
	s_nop 0
	s_mov_b32 s71, m0
	s_mov_b32 m0, s41
	s_nop 0
	global_load_lds_dwordx4 v140, s[22:23]
	s_mov_b32 m0, s71
	s_add_u32 s22, s22, 0x80000
	s_addc_u32 s23, s23, 0
	s_mov_b32 s71, m0
	s_mov_b32 m0, s42
	s_nop 0
	global_load_lds_dwordx4 v138, s[22:23]
	s_mov_b32 m0, s71
	s_nop 0
	s_mov_b32 s71, m0
	s_mov_b32 m0, s43
	s_nop 0
	global_load_lds_dwordx4 v140, s[22:23]
	s_mov_b32 m0, s71
	s_waitcnt vmcnt(8)
	s_waitcnt lgkmcnt(0)
	s_barrier
	s_setprio 1
	.p2align 3
	v_mfma_f32_16x16x32_bf16 v[126:129], v[148:151], v[180:183], v[126:129]
	v_mfma_f32_16x16x32_bf16 v[126:129], v[152:155], v[184:187], v[126:129]
	v_mfma_f32_16x16x32_bf16 v[122:125], v[156:159], v[180:183], v[122:125]
	v_mfma_f32_16x16x32_bf16 v[122:125], v[160:163], v[184:187], v[122:125]
	v_mfma_f32_16x16x32_bf16 v[106:109], v[156:159], v[188:191], v[106:109]
	v_mfma_f32_16x16x32_bf16 v[106:109], v[160:163], v[192:195], v[106:109]
	v_mfma_f32_16x16x32_bf16 v[110:113], v[148:151], v[188:191], v[110:113]
	v_mfma_f32_16x16x32_bf16 v[110:113], v[152:155], v[192:195], v[110:113]
	v_mfma_f32_16x16x32_bf16 v[94:97], v[148:151], v[196:199], v[94:97]
	v_mfma_f32_16x16x32_bf16 v[94:97], v[152:155], v[200:203], v[94:97]
	v_mfma_f32_16x16x32_bf16 v[90:93], v[156:159], v[196:199], v[90:93]
	v_mfma_f32_16x16x32_bf16 v[90:93], v[160:163], v[200:203], v[90:93]
	v_mfma_f32_16x16x32_bf16 v[74:77], v[156:159], v[204:207], v[74:77]
	v_mfma_f32_16x16x32_bf16 v[74:77], v[160:163], v[208:211], v[74:77]
	v_mfma_f32_16x16x32_bf16 v[78:81], v[148:151], v[204:207], v[78:81]
	v_mfma_f32_16x16x32_bf16 v[78:81], v[152:155], v[208:211], v[78:81]
	s_setprio 0
	s_setprio 1
	v_mfma_f32_16x16x32_bf16 v[118:121], v[164:167], v[180:183], v[118:121]
	v_mfma_f32_16x16x32_bf16 v[118:121], v[168:171], v[184:187], v[118:121]
	v_mfma_f32_16x16x32_bf16 v[114:117], v[172:175], v[180:183], v[114:117]
	v_mfma_f32_16x16x32_bf16 v[114:117], v[176:179], v[184:187], v[114:117]
	v_mfma_f32_16x16x32_bf16 v[98:101], v[172:175], v[188:191], v[98:101]
	v_mfma_f32_16x16x32_bf16 v[98:101], v[176:179], v[192:195], v[98:101]
	v_mfma_f32_16x16x32_bf16 v[102:105], v[164:167], v[188:191], v[102:105]
	v_mfma_f32_16x16x32_bf16 v[102:105], v[168:171], v[192:195], v[102:105]
	v_mfma_f32_16x16x32_bf16 v[86:89], v[164:167], v[196:199], v[86:89]
	v_mfma_f32_16x16x32_bf16 v[86:89], v[168:171], v[200:203], v[86:89]
	v_mfma_f32_16x16x32_bf16 v[82:85], v[172:175], v[196:199], v[82:85]
	v_mfma_f32_16x16x32_bf16 v[82:85], v[176:179], v[200:203], v[82:85]
	v_mfma_f32_16x16x32_bf16 v[66:69], v[172:175], v[204:207], v[66:69]
	v_mfma_f32_16x16x32_bf16 v[66:69], v[176:179], v[208:211], v[66:69]
	s_setprio 2
	s_barrier
	v_mfma_f32_16x16x32_bf16 v[70:73], v[164:167], v[204:207], v[70:73]
	v_mfma_f32_16x16x32_bf16 v[70:73], v[168:171], v[208:211], v[70:73]
	s_setprio 0
	ds_read_b128 v[180:183], v145 offset:49152
	ds_read_b128 v[184:187], v145 offset:50176
	ds_read_b128 v[188:191], v145 offset:51200
	ds_read_b128 v[192:195], v145 offset:52224
	ds_read_b128 v[196:199], v145 offset:53248
	ds_read_b128 v[200:203], v145 offset:54272
	ds_read_b128 v[204:207], v145 offset:55296
	ds_read_b128 v[208:211], v145 offset:56320
	s_add_u32 s22, s20, 0x80
	s_addc_u32 s23, s21, 0
	s_mov_b32 s71, m0
	s_mov_b32 m0, s44
	s_nop 0
	global_load_lds_dwordx4 v139, s[22:23]
	s_mov_b32 m0, s71
	s_add_u32 s20, s20, 0x80080
	s_mov_b32 s71, m0
	s_mov_b32 m0, s45
	s_nop 0
	global_load_lds_dwordx4 v141, s[22:23]
	s_mov_b32 m0, s71
	s_addc_u32 s21, s21, 0
	s_mov_b32 s22, m0
	s_mov_b32 m0, s46
	s_nop 0
	global_load_lds_dwordx4 v139, s[20:21]
	s_mov_b32 m0, s22
	s_nop 0
	s_mov_b32 s22, m0
	s_mov_b32 m0, s47
	s_nop 0
	global_load_lds_dwordx4 v141, s[20:21]
	s_mov_b32 m0, s22
	s_waitcnt vmcnt(4)
	s_waitcnt lgkmcnt(0)
	s_barrier
	s_setprio 1
	.p2align 3
	v_mfma_f32_16x16x32_bf16 v[62:65], v[148:151], v[180:183], v[62:65]
	v_mfma_f32_16x16x32_bf16 v[62:65], v[152:155], v[184:187], v[62:65]
	v_mfma_f32_16x16x32_bf16 v[58:61], v[156:159], v[180:183], v[58:61]
	v_mfma_f32_16x16x32_bf16 v[58:61], v[160:163], v[184:187], v[58:61]
	v_mfma_f32_16x16x32_bf16 v[42:45], v[156:159], v[188:191], v[42:45]
	v_mfma_f32_16x16x32_bf16 v[42:45], v[160:163], v[192:195], v[42:45]
	v_mfma_f32_16x16x32_bf16 v[46:49], v[148:151], v[188:191], v[46:49]
	v_mfma_f32_16x16x32_bf16 v[46:49], v[152:155], v[192:195], v[46:49]
	v_mfma_f32_16x16x32_bf16 v[30:33], v[148:151], v[196:199], v[30:33]
	v_mfma_f32_16x16x32_bf16 v[30:33], v[152:155], v[200:203], v[30:33]
	v_mfma_f32_16x16x32_bf16 v[26:29], v[156:159], v[196:199], v[26:29]
	v_mfma_f32_16x16x32_bf16 v[26:29], v[160:163], v[200:203], v[26:29]
	v_mfma_f32_16x16x32_bf16 v[10:13], v[156:159], v[204:207], v[10:13]
	v_mfma_f32_16x16x32_bf16 v[10:13], v[160:163], v[208:211], v[10:13]
	v_mfma_f32_16x16x32_bf16 v[14:17], v[148:151], v[204:207], v[14:17]
	v_mfma_f32_16x16x32_bf16 v[14:17], v[152:155], v[208:211], v[14:17]
	s_setprio 0
	s_setprio 1
	v_mfma_f32_16x16x32_bf16 v[54:57], v[164:167], v[180:183], v[54:57]
	v_mfma_f32_16x16x32_bf16 v[54:57], v[168:171], v[184:187], v[54:57]
	v_mfma_f32_16x16x32_bf16 v[50:53], v[172:175], v[180:183], v[50:53]
	v_mfma_f32_16x16x32_bf16 v[50:53], v[176:179], v[184:187], v[50:53]
	v_mfma_f32_16x16x32_bf16 v[34:37], v[172:175], v[188:191], v[34:37]
	v_mfma_f32_16x16x32_bf16 v[34:37], v[176:179], v[192:195], v[34:37]
	v_mfma_f32_16x16x32_bf16 v[38:41], v[164:167], v[188:191], v[38:41]
	v_mfma_f32_16x16x32_bf16 v[38:41], v[168:171], v[192:195], v[38:41]
	v_mfma_f32_16x16x32_bf16 v[22:25], v[164:167], v[196:199], v[22:25]
	v_mfma_f32_16x16x32_bf16 v[22:25], v[168:171], v[200:203], v[22:25]
	v_mfma_f32_16x16x32_bf16 v[18:21], v[172:175], v[196:199], v[18:21]
	v_mfma_f32_16x16x32_bf16 v[18:21], v[176:179], v[200:203], v[18:21]
	v_mfma_f32_16x16x32_bf16 v[2:5], v[172:175], v[204:207], v[2:5]
	v_mfma_f32_16x16x32_bf16 v[2:5], v[176:179], v[208:211], v[2:5]
	s_setprio 2
	s_barrier
	v_mfma_f32_16x16x32_bf16 v[6:9], v[164:167], v[204:207], v[6:9]
	v_mfma_f32_16x16x32_bf16 v[6:9], v[168:171], v[208:211], v[6:9]
	s_setprio 0
	s_add_i32 s70, s70, 2
	s_add_u32 s64, s64, 0x100
	s_addc_u32 s65, s65, 0
	s_add_u32 s18, s18, 0x100
	s_addc_u32 s19, s19, 0
	s_add_u32 s66, s66, 0x100
	s_addc_u32 s67, s67, 0
	s_cmp_gt_u32 s70, 29
	.p2align 6
.LBB0_2594:
	ds_read_b128 v[148:151], v143
	ds_read_b128 v[152:155], v143 offset:1024
	ds_read_b128 v[156:159], v143 offset:2048
	ds_read_b128 v[160:163], v143 offset:3072
	ds_read_b128 v[164:167], v144
	ds_read_b128 v[168:171], v144 offset:1024
	ds_read_b128 v[172:175], v144 offset:2048
	ds_read_b128 v[176:179], v144 offset:3072
	s_cmp_eq_u32 s70, 28
	s_cselect_b32 s21, s9, s65
	s_cselect_b32 s20, s63, s64
	s_cselect_b32 s23, s11, s67
	s_cselect_b32 s22, s62, s66
	ds_read_b128 v[180:183], v145
	ds_read_b128 v[184:187], v145 offset:1024
	ds_read_b128 v[188:191], v145 offset:2048
	ds_read_b128 v[192:195], v145 offset:3072
	ds_read_b128 v[196:199], v145 offset:4096
	ds_read_b128 v[200:203], v145 offset:5120
	ds_read_b128 v[204:207], v145 offset:6144
	ds_read_b128 v[208:211], v145 offset:7168
	s_add_u32 s74, s18, 0xfff80000
	s_addc_u32 s75, s19, -1
	s_mov_b32 s71, m0
	s_mov_b32 m0, s48
	s_nop 0
	global_load_lds_dwordx4 v138, s[74:75]
	s_mov_b32 m0, s71
	s_nop 0
	s_mov_b32 s71, m0
	s_mov_b32 m0, s57
	s_nop 0
	global_load_lds_dwordx4 v140, s[74:75]
	s_mov_b32 m0, s71
	s_nop 0
	s_mov_b32 s71, m0
	s_mov_b32 m0, s49
	s_nop 0
	global_load_lds_dwordx4 v138, s[18:19]
	s_mov_b32 m0, s71
	s_nop 0
	s_mov_b32 s71, m0
	s_mov_b32 m0, s58
	s_nop 0
	global_load_lds_dwordx4 v140, s[18:19]
	s_mov_b32 m0, s71
	s_waitcnt vmcnt(8)
	s_waitcnt lgkmcnt(0)
	s_barrier
	s_setprio 1
	.p2align 3
	v_mfma_f32_16x16x32_bf16 v[126:129], v[148:151], v[180:183], v[126:129]
	v_mfma_f32_16x16x32_bf16 v[126:129], v[152:155], v[184:187], v[126:129]
	v_mfma_f32_16x16x32_bf16 v[122:125], v[156:159], v[180:183], v[122:125]
	v_mfma_f32_16x16x32_bf16 v[122:125], v[160:163], v[184:187], v[122:125]
	v_mfma_f32_16x16x32_bf16 v[106:109], v[156:159], v[188:191], v[106:109]
	v_mfma_f32_16x16x32_bf16 v[106:109], v[160:163], v[192:195], v[106:109]
	v_mfma_f32_16x16x32_bf16 v[110:113], v[148:151], v[188:191], v[110:113]
	v_mfma_f32_16x16x32_bf16 v[110:113], v[152:155], v[192:195], v[110:113]
	v_mfma_f32_16x16x32_bf16 v[94:97], v[148:151], v[196:199], v[94:97]
	v_mfma_f32_16x16x32_bf16 v[94:97], v[152:155], v[200:203], v[94:97]
	v_mfma_f32_16x16x32_bf16 v[90:93], v[156:159], v[196:199], v[90:93]
	v_mfma_f32_16x16x32_bf16 v[90:93], v[160:163], v[200:203], v[90:93]
	v_mfma_f32_16x16x32_bf16 v[74:77], v[156:159], v[204:207], v[74:77]
	v_mfma_f32_16x16x32_bf16 v[74:77], v[160:163], v[208:211], v[74:77]
	v_mfma_f32_16x16x32_bf16 v[78:81], v[148:151], v[204:207], v[78:81]
	v_mfma_f32_16x16x32_bf16 v[78:81], v[152:155], v[208:211], v[78:81]
	s_setprio 0
	s_setprio 1
	v_mfma_f32_16x16x32_bf16 v[118:121], v[164:167], v[180:183], v[118:121]
	v_mfma_f32_16x16x32_bf16 v[118:121], v[168:171], v[184:187], v[118:121]
	v_mfma_f32_16x16x32_bf16 v[114:117], v[172:175], v[180:183], v[114:117]
	v_mfma_f32_16x16x32_bf16 v[114:117], v[176:179], v[184:187], v[114:117]
	v_mfma_f32_16x16x32_bf16 v[98:101], v[172:175], v[188:191], v[98:101]
	v_mfma_f32_16x16x32_bf16 v[98:101], v[176:179], v[192:195], v[98:101]
	v_mfma_f32_16x16x32_bf16 v[102:105], v[164:167], v[188:191], v[102:105]
	v_mfma_f32_16x16x32_bf16 v[102:105], v[168:171], v[192:195], v[102:105]
	v_mfma_f32_16x16x32_bf16 v[86:89], v[164:167], v[196:199], v[86:89]
	v_mfma_f32_16x16x32_bf16 v[86:89], v[168:171], v[200:203], v[86:89]
	v_mfma_f32_16x16x32_bf16 v[82:85], v[172:175], v[196:199], v[82:85]
	v_mfma_f32_16x16x32_bf16 v[82:85], v[176:179], v[200:203], v[82:85]
	v_mfma_f32_16x16x32_bf16 v[66:69], v[172:175], v[204:207], v[66:69]
	v_mfma_f32_16x16x32_bf16 v[66:69], v[176:179], v[208:211], v[66:69]
	s_setprio 2
	s_barrier
	v_mfma_f32_16x16x32_bf16 v[70:73], v[164:167], v[204:207], v[70:73]
	v_mfma_f32_16x16x32_bf16 v[70:73], v[168:171], v[208:211], v[70:73]
	s_setprio 0
	ds_read_b128 v[180:183], v145 offset:16384
	ds_read_b128 v[184:187], v145 offset:17408
	ds_read_b128 v[188:191], v145 offset:18432
	ds_read_b128 v[192:195], v145 offset:19456
	ds_read_b128 v[196:199], v145 offset:20480
	ds_read_b128 v[200:203], v145 offset:21504
	ds_read_b128 v[204:207], v145 offset:22528
	ds_read_b128 v[208:211], v145 offset:23552
	s_mov_b32 s71, m0
	s_mov_b32 m0, s35
	s_nop 0
	global_load_lds_dwordx4 v139, s[20:21]
	s_mov_b32 m0, s71
	s_add_u32 s74, s20, 0x80000
	s_mov_b32 s71, m0
	s_mov_b32 m0, s36
	s_nop 0
	global_load_lds_dwordx4 v141, s[20:21]
	s_mov_b32 m0, s71
	s_addc_u32 s75, s21, 0
	s_mov_b32 s71, m0
	s_mov_b32 m0, s37
	s_nop 0
	global_load_lds_dwordx4 v139, s[74:75]
	s_mov_b32 m0, s71
	s_nop 0
	s_mov_b32 s71, m0
	s_mov_b32 m0, s40
	s_nop 0
	global_load_lds_dwordx4 v141, s[74:75]
	s_mov_b32 m0, s71
	s_waitcnt vmcnt(4)
	s_waitcnt lgkmcnt(0)
	s_barrier
	s_setprio 1
	.p2align 3
	v_mfma_f32_16x16x32_bf16 v[62:65], v[148:151], v[180:183], v[62:65]
	v_mfma_f32_16x16x32_bf16 v[62:65], v[152:155], v[184:187], v[62:65]
	v_mfma_f32_16x16x32_bf16 v[58:61], v[156:159], v[180:183], v[58:61]
	v_mfma_f32_16x16x32_bf16 v[58:61], v[160:163], v[184:187], v[58:61]
	v_mfma_f32_16x16x32_bf16 v[42:45], v[156:159], v[188:191], v[42:45]
	v_mfma_f32_16x16x32_bf16 v[42:45], v[160:163], v[192:195], v[42:45]
	v_mfma_f32_16x16x32_bf16 v[46:49], v[148:151], v[188:191], v[46:49]
	v_mfma_f32_16x16x32_bf16 v[46:49], v[152:155], v[192:195], v[46:49]
	v_mfma_f32_16x16x32_bf16 v[30:33], v[148:151], v[196:199], v[30:33]
	v_mfma_f32_16x16x32_bf16 v[30:33], v[152:155], v[200:203], v[30:33]
	v_mfma_f32_16x16x32_bf16 v[26:29], v[156:159], v[196:199], v[26:29]
	v_mfma_f32_16x16x32_bf16 v[26:29], v[160:163], v[200:203], v[26:29]
	v_mfma_f32_16x16x32_bf16 v[10:13], v[156:159], v[204:207], v[10:13]
	v_mfma_f32_16x16x32_bf16 v[10:13], v[160:163], v[208:211], v[10:13]
	v_mfma_f32_16x16x32_bf16 v[14:17], v[148:151], v[204:207], v[14:17]
	v_mfma_f32_16x16x32_bf16 v[14:17], v[152:155], v[208:211], v[14:17]
	s_setprio 0
	s_setprio 1
	v_mfma_f32_16x16x32_bf16 v[54:57], v[164:167], v[180:183], v[54:57]
	v_mfma_f32_16x16x32_bf16 v[54:57], v[168:171], v[184:187], v[54:57]
	v_mfma_f32_16x16x32_bf16 v[50:53], v[172:175], v[180:183], v[50:53]
	v_mfma_f32_16x16x32_bf16 v[50:53], v[176:179], v[184:187], v[50:53]
	v_mfma_f32_16x16x32_bf16 v[34:37], v[172:175], v[188:191], v[34:37]
	v_mfma_f32_16x16x32_bf16 v[34:37], v[176:179], v[192:195], v[34:37]
	v_mfma_f32_16x16x32_bf16 v[38:41], v[164:167], v[188:191], v[38:41]
	v_mfma_f32_16x16x32_bf16 v[38:41], v[168:171], v[192:195], v[38:41]
	v_mfma_f32_16x16x32_bf16 v[22:25], v[164:167], v[196:199], v[22:25]
	v_mfma_f32_16x16x32_bf16 v[22:25], v[168:171], v[200:203], v[22:25]
	v_mfma_f32_16x16x32_bf16 v[18:21], v[172:175], v[196:199], v[18:21]
	v_mfma_f32_16x16x32_bf16 v[18:21], v[176:179], v[200:203], v[18:21]
	v_mfma_f32_16x16x32_bf16 v[2:5], v[172:175], v[204:207], v[2:5]
	v_mfma_f32_16x16x32_bf16 v[2:5], v[176:179], v[208:211], v[2:5]
	s_setprio 2
	s_barrier
	v_mfma_f32_16x16x32_bf16 v[6:9], v[164:167], v[204:207], v[6:9]
	v_mfma_f32_16x16x32_bf16 v[6:9], v[168:171], v[208:211], v[6:9]
	s_setprio 0
	ds_read_b128 v[148:151], v146
	ds_read_b128 v[152:155], v146 offset:1024
	ds_read_b128 v[156:159], v146 offset:2048
	ds_read_b128 v[160:163], v146 offset:3072
	ds_read_b128 v[164:167], v147
	ds_read_b128 v[168:171], v147 offset:1024
	ds_read_b128 v[172:175], v147 offset:2048
	ds_read_b128 v[176:179], v147 offset:3072
	ds_read_b128 v[180:183], v145 offset:32768
	ds_read_b128 v[184:187], v145 offset:33792
	ds_read_b128 v[188:191], v145 offset:34816
	ds_read_b128 v[192:195], v145 offset:35840
	ds_read_b128 v[196:199], v145 offset:36864
	ds_read_b128 v[200:203], v145 offset:37888
	ds_read_b128 v[204:207], v145 offset:38912
	ds_read_b128 v[208:211], v145 offset:39936
	s_mov_b32 s71, m0
	s_mov_b32 m0, s31
	s_nop 0
	global_load_lds_dwordx4 v138, s[22:23]
	s_mov_b32 m0, s71
	s_nop 0
	s_mov_b32 s71, m0
	s_mov_b32 m0, s41
	s_nop 0
	global_load_lds_dwordx4 v140, s[22:23]
	s_mov_b32 m0, s71
	s_add_u32 s22, s22, 0x80000
	s_addc_u32 s23, s23, 0
	s_mov_b32 s71, m0
	s_mov_b32 m0, s42
	s_nop 0
	global_load_lds_dwordx4 v138, s[22:23]
	s_mov_b32 m0, s71
	s_nop 0
	s_mov_b32 s71, m0
	s_mov_b32 m0, s43
	s_nop 0
	global_load_lds_dwordx4 v140, s[22:23]
	s_mov_b32 m0, s71
	s_waitcnt vmcnt(8)
	s_waitcnt lgkmcnt(0)
	s_barrier
	s_setprio 1
	.p2align 3
	v_mfma_f32_16x16x32_bf16 v[126:129], v[148:151], v[180:183], v[126:129]
	v_mfma_f32_16x16x32_bf16 v[126:129], v[152:155], v[184:187], v[126:129]
	v_mfma_f32_16x16x32_bf16 v[122:125], v[156:159], v[180:183], v[122:125]
	v_mfma_f32_16x16x32_bf16 v[122:125], v[160:163], v[184:187], v[122:125]
	v_mfma_f32_16x16x32_bf16 v[106:109], v[156:159], v[188:191], v[106:109]
	v_mfma_f32_16x16x32_bf16 v[106:109], v[160:163], v[192:195], v[106:109]
	v_mfma_f32_16x16x32_bf16 v[110:113], v[148:151], v[188:191], v[110:113]
	v_mfma_f32_16x16x32_bf16 v[110:113], v[152:155], v[192:195], v[110:113]
	v_mfma_f32_16x16x32_bf16 v[94:97], v[148:151], v[196:199], v[94:97]
	v_mfma_f32_16x16x32_bf16 v[94:97], v[152:155], v[200:203], v[94:97]
	v_mfma_f32_16x16x32_bf16 v[90:93], v[156:159], v[196:199], v[90:93]
	v_mfma_f32_16x16x32_bf16 v[90:93], v[160:163], v[200:203], v[90:93]
	v_mfma_f32_16x16x32_bf16 v[74:77], v[156:159], v[204:207], v[74:77]
	v_mfma_f32_16x16x32_bf16 v[74:77], v[160:163], v[208:211], v[74:77]
	v_mfma_f32_16x16x32_bf16 v[78:81], v[148:151], v[204:207], v[78:81]
	v_mfma_f32_16x16x32_bf16 v[78:81], v[152:155], v[208:211], v[78:81]
	s_setprio 0
	s_setprio 1
	v_mfma_f32_16x16x32_bf16 v[118:121], v[164:167], v[180:183], v[118:121]
	v_mfma_f32_16x16x32_bf16 v[118:121], v[168:171], v[184:187], v[118:121]
	v_mfma_f32_16x16x32_bf16 v[114:117], v[172:175], v[180:183], v[114:117]
	v_mfma_f32_16x16x32_bf16 v[114:117], v[176:179], v[184:187], v[114:117]
	v_mfma_f32_16x16x32_bf16 v[98:101], v[172:175], v[188:191], v[98:101]
	v_mfma_f32_16x16x32_bf16 v[98:101], v[176:179], v[192:195], v[98:101]
	v_mfma_f32_16x16x32_bf16 v[102:105], v[164:167], v[188:191], v[102:105]
	v_mfma_f32_16x16x32_bf16 v[102:105], v[168:171], v[192:195], v[102:105]
	v_mfma_f32_16x16x32_bf16 v[86:89], v[164:167], v[196:199], v[86:89]
	v_mfma_f32_16x16x32_bf16 v[86:89], v[168:171], v[200:203], v[86:89]
	v_mfma_f32_16x16x32_bf16 v[82:85], v[172:175], v[196:199], v[82:85]
	v_mfma_f32_16x16x32_bf16 v[82:85], v[176:179], v[200:203], v[82:85]
	v_mfma_f32_16x16x32_bf16 v[66:69], v[172:175], v[204:207], v[66:69]
	v_mfma_f32_16x16x32_bf16 v[66:69], v[176:179], v[208:211], v[66:69]
	s_setprio 2
	s_barrier
	v_mfma_f32_16x16x32_bf16 v[70:73], v[164:167], v[204:207], v[70:73]
	v_mfma_f32_16x16x32_bf16 v[70:73], v[168:171], v[208:211], v[70:73]
	s_setprio 0
	ds_read_b128 v[180:183], v145 offset:49152
	ds_read_b128 v[184:187], v145 offset:50176
	ds_read_b128 v[188:191], v145 offset:51200
	ds_read_b128 v[192:195], v145 offset:52224
	ds_read_b128 v[196:199], v145 offset:53248
	ds_read_b128 v[200:203], v145 offset:54272
	ds_read_b128 v[204:207], v145 offset:55296
	ds_read_b128 v[208:211], v145 offset:56320
	s_add_u32 s22, s20, 0x80
	s_addc_u32 s23, s21, 0
	s_mov_b32 s71, m0
	s_mov_b32 m0, s44
	s_nop 0
	global_load_lds_dwordx4 v139, s[22:23]
	s_mov_b32 m0, s71
	s_add_u32 s20, s20, 0x80080
	s_mov_b32 s71, m0
	s_mov_b32 m0, s45
	s_nop 0
	global_load_lds_dwordx4 v141, s[22:23]
	s_mov_b32 m0, s71
	s_addc_u32 s21, s21, 0
	s_mov_b32 s22, m0
	s_mov_b32 m0, s46
	s_nop 0
	global_load_lds_dwordx4 v139, s[20:21]
	s_mov_b32 m0, s22
	s_nop 0
	s_mov_b32 s22, m0
	s_mov_b32 m0, s47
	s_nop 0
	global_load_lds_dwordx4 v141, s[20:21]
	s_mov_b32 m0, s22
	s_waitcnt vmcnt(4)
	s_waitcnt lgkmcnt(0)
	s_barrier
	s_setprio 1
	.p2align 3
	v_mfma_f32_16x16x32_bf16 v[62:65], v[148:151], v[180:183], v[62:65]
	v_mfma_f32_16x16x32_bf16 v[62:65], v[152:155], v[184:187], v[62:65]
	v_mfma_f32_16x16x32_bf16 v[58:61], v[156:159], v[180:183], v[58:61]
	v_mfma_f32_16x16x32_bf16 v[58:61], v[160:163], v[184:187], v[58:61]
	v_mfma_f32_16x16x32_bf16 v[42:45], v[156:159], v[188:191], v[42:45]
	v_mfma_f32_16x16x32_bf16 v[42:45], v[160:163], v[192:195], v[42:45]
	v_mfma_f32_16x16x32_bf16 v[46:49], v[148:151], v[188:191], v[46:49]
	v_mfma_f32_16x16x32_bf16 v[46:49], v[152:155], v[192:195], v[46:49]
	v_mfma_f32_16x16x32_bf16 v[30:33], v[148:151], v[196:199], v[30:33]
	v_mfma_f32_16x16x32_bf16 v[30:33], v[152:155], v[200:203], v[30:33]
	v_mfma_f32_16x16x32_bf16 v[26:29], v[156:159], v[196:199], v[26:29]
	v_mfma_f32_16x16x32_bf16 v[26:29], v[160:163], v[200:203], v[26:29]
	v_mfma_f32_16x16x32_bf16 v[10:13], v[156:159], v[204:207], v[10:13]
	v_mfma_f32_16x16x32_bf16 v[10:13], v[160:163], v[208:211], v[10:13]
	v_mfma_f32_16x16x32_bf16 v[14:17], v[148:151], v[204:207], v[14:17]
	v_mfma_f32_16x16x32_bf16 v[14:17], v[152:155], v[208:211], v[14:17]
	s_setprio 0
	s_setprio 1
	v_mfma_f32_16x16x32_bf16 v[54:57], v[164:167], v[180:183], v[54:57]
	v_mfma_f32_16x16x32_bf16 v[54:57], v[168:171], v[184:187], v[54:57]
	v_mfma_f32_16x16x32_bf16 v[50:53], v[172:175], v[180:183], v[50:53]
	v_mfma_f32_16x16x32_bf16 v[50:53], v[176:179], v[184:187], v[50:53]
	v_mfma_f32_16x16x32_bf16 v[34:37], v[172:175], v[188:191], v[34:37]
	v_mfma_f32_16x16x32_bf16 v[34:37], v[176:179], v[192:195], v[34:37]
	v_mfma_f32_16x16x32_bf16 v[38:41], v[164:167], v[188:191], v[38:41]
	v_mfma_f32_16x16x32_bf16 v[38:41], v[168:171], v[192:195], v[38:41]
	v_mfma_f32_16x16x32_bf16 v[22:25], v[164:167], v[196:199], v[22:25]
	v_mfma_f32_16x16x32_bf16 v[22:25], v[168:171], v[200:203], v[22:25]
	v_mfma_f32_16x16x32_bf16 v[18:21], v[172:175], v[196:199], v[18:21]
	v_mfma_f32_16x16x32_bf16 v[18:21], v[176:179], v[200:203], v[18:21]
	v_mfma_f32_16x16x32_bf16 v[2:5], v[172:175], v[204:207], v[2:5]
	v_mfma_f32_16x16x32_bf16 v[2:5], v[176:179], v[208:211], v[2:5]
	s_setprio 2
	s_barrier
	v_mfma_f32_16x16x32_bf16 v[6:9], v[164:167], v[204:207], v[6:9]
	v_mfma_f32_16x16x32_bf16 v[6:9], v[168:171], v[208:211], v[6:9]
	s_setprio 0
	s_add_i32 s70, s70, 2
	s_add_u32 s64, s64, 0x100
	s_addc_u32 s65, s65, 0
	s_add_u32 s18, s18, 0x100
	s_addc_u32 s19, s19, 0
	s_add_u32 s66, s66, 0x100
	s_addc_u32 s67, s67, 0
	s_cmp_gt_u32 s70, 29
	s_cbranch_scc0 .LBB0_2594
	s_and_b64 vcc, exec, s[6:7]
	s_cbranch_vccz .LBB0_2597
	s_barrier

.LBB0_2791:
	s_ashr_i32 s21, s20, 31
	s_lshl_b64 s[22:23], s[20:21], 15
	s_add_u32 s22, s37, s22
	s_addc_u32 s23, s40, s23
	s_and_b64 s[24:25], s[2:3], exec
	s_cselect_b32 s21, s23, s31
	s_cselect_b32 s63, s22, s30
	s_ashr_i32 s19, s18, 31
	s_lshl_b64 s[24:25], s[18:19], 15
	s_add_u32 s24, s41, s24
	s_addc_u32 s25, s42, s25
	s_and_b64 s[34:35], s[2:3], exec
	s_cselect_b32 s19, s25, s29
	s_cselect_b32 s64, s24, s28
	s_add_u32 s65, s28, 0x80000
	s_addc_u32 s66, s29, 0
	s_add_u32 s28, s30, 0x204000
	s_addc_u32 s29, s31, 0
	s_add_u32 s67, s30, 0x400000
	s_addc_u32 s68, s31, 0
	s_mov_b32 s69, -2
	s_waitcnt vmcnt(25)
	s_waitcnt vmcnt(24)
	s_waitcnt vmcnt(4)
	s_waitcnt vmcnt(2)
	s_waitcnt vmcnt(1)
	s_waitcnt vmcnt(0)
	ds_read_b128 v[130:133], v181
	ds_read_b128 v[134:137], v181 offset:1024
	ds_read_b128 v[138:141], v181 offset:2048
	ds_read_b128 v[142:145], v181 offset:3072
	ds_read_b128 v[150:153], v182
	ds_read_b128 v[154:157], v182 offset:1024
	ds_read_b128 v[158:161], v182 offset:2048
	ds_read_b128 v[162:165], v182 offset:3072
	s_cmpk_eq_i32 s69, 0x52
	s_cselect_b32 s31, s19, s66
	s_cselect_b32 s30, s64, s65
	s_cselect_b32 s35, s21, s68
	s_cselect_b32 s34, s63, s67
	ds_read_b128 v[166:169], v183
	ds_read_b128 v[170:173], v183 offset:1024
	ds_read_b128 v[186:189], v183 offset:2048
	ds_read_b128 v[190:193], v183 offset:3072
	ds_read_b128 v[194:197], v183 offset:4096
	ds_read_b128 v[198:201], v183 offset:5120
	ds_read_b128 v[202:205], v183 offset:6144
	ds_read_b128 v[206:209], v183 offset:7168
	s_add_u32 s70, s28, 0xffffc000
	s_addc_u32 s71, s29, -1
	s_mov_b32 s73, m0
	s_mov_b32 m0, s57
	s_nop 0
	global_load_lds_dwordx4 v1, s[70:71]
	s_mov_b32 m0, s73
	s_nop 0
	s_mov_b32 s73, m0
	s_mov_b32 m0, s59
	s_nop 0
	global_load_lds_dwordx4 v177, s[70:71]
	s_mov_b32 m0, s73
	s_mov_b32 s70, m0
	s_mov_b32 m0, s58
	s_nop 0
	global_load_lds_dwordx4 v1, s[28:29]
	s_mov_b32 m0, s70
	s_nop 0
	s_mov_b32 s70, m0
	s_mov_b32 m0, s60
	s_nop 0
	global_load_lds_dwordx4 v177, s[28:29]
	s_mov_b32 m0, s70
	s_waitcnt vmcnt(8)
	s_waitcnt lgkmcnt(0)
	s_barrier
	s_setprio 1
	.p2align 3
	v_mfma_f32_16x16x32_bf16 v[126:129], v[130:133], v[166:169], 0
	v_mfma_f32_16x16x32_bf16 v[126:129], v[134:137], v[170:173], v[126:129]
	v_mfma_f32_16x16x32_bf16 v[122:125], v[138:141], v[166:169], 0
	v_mfma_f32_16x16x32_bf16 v[122:125], v[142:145], v[170:173], v[122:125]
	v_mfma_f32_16x16x32_bf16 v[110:113], v[138:141], v[186:189], 0
	v_mfma_f32_16x16x32_bf16 v[110:113], v[142:145], v[190:193], v[110:113]
	v_mfma_f32_16x16x32_bf16 v[118:121], v[130:133], v[186:189], 0
	v_mfma_f32_16x16x32_bf16 v[118:121], v[134:137], v[190:193], v[118:121]
	v_mfma_f32_16x16x32_bf16 v[94:97], v[130:133], v[194:197], 0
	v_mfma_f32_16x16x32_bf16 v[94:97], v[134:137], v[198:201], v[94:97]
	v_mfma_f32_16x16x32_bf16 v[90:93], v[138:141], v[194:197], 0
	v_mfma_f32_16x16x32_bf16 v[90:93], v[142:145], v[198:201], v[90:93]
	v_mfma_f32_16x16x32_bf16 v[78:81], v[138:141], v[202:205], 0
	v_mfma_f32_16x16x32_bf16 v[78:81], v[142:145], v[206:209], v[78:81]
	v_mfma_f32_16x16x32_bf16 v[86:89], v[130:133], v[202:205], 0
	v_mfma_f32_16x16x32_bf16 v[86:89], v[134:137], v[206:209], v[86:89]
	s_setprio 0
	s_setprio 1
	v_mfma_f32_16x16x32_bf16 v[114:117], v[150:153], v[166:169], 0
	v_mfma_f32_16x16x32_bf16 v[114:117], v[154:157], v[170:173], v[114:117]
	v_mfma_f32_16x16x32_bf16 v[106:109], v[158:161], v[166:169], 0
	v_mfma_f32_16x16x32_bf16 v[106:109], v[162:165], v[170:173], v[106:109]
	v_mfma_f32_16x16x32_bf16 v[98:101], v[158:161], v[186:189], 0
	v_mfma_f32_16x16x32_bf16 v[98:101], v[162:165], v[190:193], v[98:101]
	v_mfma_f32_16x16x32_bf16 v[102:105], v[150:153], v[186:189], 0
	v_mfma_f32_16x16x32_bf16 v[102:105], v[154:157], v[190:193], v[102:105]
	v_mfma_f32_16x16x32_bf16 v[82:85], v[150:153], v[194:197], 0
	v_mfma_f32_16x16x32_bf16 v[82:85], v[154:157], v[198:201], v[82:85]
	v_mfma_f32_16x16x32_bf16 v[74:77], v[158:161], v[194:197], 0
	v_mfma_f32_16x16x32_bf16 v[74:77], v[162:165], v[198:201], v[74:77]
	v_mfma_f32_16x16x32_bf16 v[66:69], v[158:161], v[202:205], 0
	v_mfma_f32_16x16x32_bf16 v[66:69], v[162:165], v[206:209], v[66:69]
	s_setprio 2
	s_barrier
	v_mfma_f32_16x16x32_bf16 v[70:73], v[150:153], v[202:205], 0
	v_mfma_f32_16x16x32_bf16 v[70:73], v[154:157], v[206:209], v[70:73]
	s_setprio 0
	ds_read_b128 v[166:169], v183 offset:16384
	ds_read_b128 v[170:173], v183 offset:17408
	ds_read_b128 v[186:189], v183 offset:18432
	ds_read_b128 v[190:193], v183 offset:19456
	ds_read_b128 v[194:197], v183 offset:20480
	ds_read_b128 v[198:201], v183 offset:21504
	ds_read_b128 v[202:205], v183 offset:22528
	ds_read_b128 v[206:209], v183 offset:23552
	s_mov_b32 s70, m0
	s_mov_b32 m0, s27
	s_nop 0
	global_load_lds_dwordx4 v176, s[30:31]
	s_mov_b32 m0, s70
	s_nop 0
	s_mov_b32 s70, m0
	s_mov_b32 m0, s45
	s_nop 0
	global_load_lds_dwordx4 v178, s[30:31]
	s_mov_b32 m0, s70
	s_add_u32 s70, s30, 0x4000
	s_addc_u32 s71, s31, 0
	s_mov_b32 s73, m0
	s_mov_b32 m0, s46
	s_nop 0
	global_load_lds_dwordx4 v176, s[70:71]
	s_mov_b32 m0, s73
	s_nop 0
	s_mov_b32 s73, m0
	s_mov_b32 m0, s47
	s_nop 0
	global_load_lds_dwordx4 v178, s[70:71]
	s_mov_b32 m0, s73
	s_waitcnt vmcnt(4)
	s_waitcnt lgkmcnt(0)
	s_barrier
	s_setprio 1
	.p2align 3
	v_mfma_f32_16x16x32_bf16 v[62:65], v[130:133], v[166:169], 0
	v_mfma_f32_16x16x32_bf16 v[62:65], v[134:137], v[170:173], v[62:65]
	v_mfma_f32_16x16x32_bf16 v[58:61], v[138:141], v[166:169], 0
	v_mfma_f32_16x16x32_bf16 v[58:61], v[142:145], v[170:173], v[58:61]
	v_mfma_f32_16x16x32_bf16 v[42:45], v[138:141], v[186:189], 0
	v_mfma_f32_16x16x32_bf16 v[42:45], v[142:145], v[190:193], v[42:45]
	v_mfma_f32_16x16x32_bf16 v[46:49], v[130:133], v[186:189], 0
	v_mfma_f32_16x16x32_bf16 v[46:49], v[134:137], v[190:193], v[46:49]
	v_mfma_f32_16x16x32_bf16 v[30:33], v[130:133], v[194:197], 0
	v_mfma_f32_16x16x32_bf16 v[30:33], v[134:137], v[198:201], v[30:33]
	v_mfma_f32_16x16x32_bf16 v[26:29], v[138:141], v[194:197], 0
	v_mfma_f32_16x16x32_bf16 v[26:29], v[142:145], v[198:201], v[26:29]
	v_mfma_f32_16x16x32_bf16 v[10:13], v[138:141], v[202:205], 0
	v_mfma_f32_16x16x32_bf16 v[10:13], v[142:145], v[206:209], v[10:13]
	v_mfma_f32_16x16x32_bf16 v[14:17], v[130:133], v[202:205], 0
	v_mfma_f32_16x16x32_bf16 v[14:17], v[134:137], v[206:209], v[14:17]
	s_setprio 0
	s_setprio 1
	v_mfma_f32_16x16x32_bf16 v[54:57], v[150:153], v[166:169], 0
	v_mfma_f32_16x16x32_bf16 v[54:57], v[154:157], v[170:173], v[54:57]
	v_mfma_f32_16x16x32_bf16 v[50:53], v[158:161], v[166:169], 0
	v_mfma_f32_16x16x32_bf16 v[50:53], v[162:165], v[170:173], v[50:53]
	v_mfma_f32_16x16x32_bf16 v[34:37], v[158:161], v[186:189], 0
	v_mfma_f32_16x16x32_bf16 v[34:37], v[162:165], v[190:193], v[34:37]
	v_mfma_f32_16x16x32_bf16 v[38:41], v[150:153], v[186:189], 0
	v_mfma_f32_16x16x32_bf16 v[38:41], v[154:157], v[190:193], v[38:41]
	v_mfma_f32_16x16x32_bf16 v[22:25], v[150:153], v[194:197], 0
	v_mfma_f32_16x16x32_bf16 v[22:25], v[154:157], v[198:201], v[22:25]
	v_mfma_f32_16x16x32_bf16 v[18:21], v[158:161], v[194:197], 0
	v_mfma_f32_16x16x32_bf16 v[18:21], v[162:165], v[198:201], v[18:21]
	v_mfma_f32_16x16x32_bf16 v[2:5], v[158:161], v[202:205], 0
	v_mfma_f32_16x16x32_bf16 v[2:5], v[162:165], v[206:209], v[2:5]
	s_setprio 2
	s_barrier
	v_mfma_f32_16x16x32_bf16 v[6:9], v[150:153], v[202:205], 0
	v_mfma_f32_16x16x32_bf16 v[6:9], v[154:157], v[206:209], v[6:9]
	s_setprio 0
	ds_read_b128 v[130:133], v184
	ds_read_b128 v[134:137], v184 offset:1024
	ds_read_b128 v[138:141], v184 offset:2048
	ds_read_b128 v[142:145], v184 offset:3072
	ds_read_b128 v[150:153], v185
	ds_read_b128 v[154:157], v185 offset:1024
	ds_read_b128 v[158:161], v185 offset:2048
	ds_read_b128 v[162:165], v185 offset:3072
	ds_read_b128 v[166:169], v183 offset:32768
	ds_read_b128 v[170:173], v183 offset:33792
	ds_read_b128 v[186:189], v183 offset:34816
	ds_read_b128 v[190:193], v183 offset:35840
	ds_read_b128 v[194:197], v183 offset:36864
	ds_read_b128 v[198:201], v183 offset:37888
	ds_read_b128 v[202:205], v183 offset:38912
	ds_read_b128 v[206:209], v183 offset:39936
	s_mov_b32 s70, m0
	s_mov_b32 m0, s44
	s_nop 0
	global_load_lds_dwordx4 v1, s[34:35]
	s_mov_b32 m0, s70
	s_nop 0
	s_mov_b32 s70, m0
	s_mov_b32 m0, s48
	s_nop 0
	global_load_lds_dwordx4 v177, s[34:35]
	s_mov_b32 m0, s70
	s_add_u32 s34, s34, 0x4000
	s_addc_u32 s35, s35, 0
	s_mov_b32 s70, m0
	s_mov_b32 m0, s49
	s_nop 0
	global_load_lds_dwordx4 v1, s[34:35]
	s_mov_b32 m0, s70
	s_nop 0
	s_mov_b32 s70, m0
	s_mov_b32 m0, s50
	s_nop 0
	global_load_lds_dwordx4 v177, s[34:35]
	s_mov_b32 m0, s70
	s_waitcnt vmcnt(8)
	s_waitcnt lgkmcnt(0)
	s_barrier
	s_setprio 1
	.p2align 3
	v_mfma_f32_16x16x32_bf16 v[126:129], v[130:133], v[166:169], v[126:129]
	v_mfma_f32_16x16x32_bf16 v[126:129], v[134:137], v[170:173], v[126:129]
	v_mfma_f32_16x16x32_bf16 v[122:125], v[138:141], v[166:169], v[122:125]
	v_mfma_f32_16x16x32_bf16 v[122:125], v[142:145], v[170:173], v[122:125]
	v_mfma_f32_16x16x32_bf16 v[110:113], v[138:141], v[186:189], v[110:113]
	v_mfma_f32_16x16x32_bf16 v[110:113], v[142:145], v[190:193], v[110:113]
	v_mfma_f32_16x16x32_bf16 v[118:121], v[130:133], v[186:189], v[118:121]
	v_mfma_f32_16x16x32_bf16 v[118:121], v[134:137], v[190:193], v[118:121]
	v_mfma_f32_16x16x32_bf16 v[94:97], v[130:133], v[194:197], v[94:97]
	v_mfma_f32_16x16x32_bf16 v[94:97], v[134:137], v[198:201], v[94:97]
	v_mfma_f32_16x16x32_bf16 v[90:93], v[138:141], v[194:197], v[90:93]
	v_mfma_f32_16x16x32_bf16 v[90:93], v[142:145], v[198:201], v[90:93]
	v_mfma_f32_16x16x32_bf16 v[78:81], v[138:141], v[202:205], v[78:81]
	v_mfma_f32_16x16x32_bf16 v[78:81], v[142:145], v[206:209], v[78:81]
	v_mfma_f32_16x16x32_bf16 v[86:89], v[130:133], v[202:205], v[86:89]
	v_mfma_f32_16x16x32_bf16 v[86:89], v[134:137], v[206:209], v[86:89]
	s_setprio 0
	s_setprio 1
	v_mfma_f32_16x16x32_bf16 v[114:117], v[150:153], v[166:169], v[114:117]
	v_mfma_f32_16x16x32_bf16 v[114:117], v[154:157], v[170:173], v[114:117]
	v_mfma_f32_16x16x32_bf16 v[106:109], v[158:161], v[166:169], v[106:109]
	v_mfma_f32_16x16x32_bf16 v[106:109], v[162:165], v[170:173], v[106:109]
	v_mfma_f32_16x16x32_bf16 v[98:101], v[158:161], v[186:189], v[98:101]
	v_mfma_f32_16x16x32_bf16 v[98:101], v[162:165], v[190:193], v[98:101]
	v_mfma_f32_16x16x32_bf16 v[102:105], v[150:153], v[186:189], v[102:105]
	v_mfma_f32_16x16x32_bf16 v[102:105], v[154:157], v[190:193], v[102:105]
	v_mfma_f32_16x16x32_bf16 v[82:85], v[150:153], v[194:197], v[82:85]
	v_mfma_f32_16x16x32_bf16 v[82:85], v[154:157], v[198:201], v[82:85]
	v_mfma_f32_16x16x32_bf16 v[74:77], v[158:161], v[194:197], v[74:77]
	v_mfma_f32_16x16x32_bf16 v[74:77], v[162:165], v[198:201], v[74:77]
	v_mfma_f32_16x16x32_bf16 v[66:69], v[158:161], v[202:205], v[66:69]
	v_mfma_f32_16x16x32_bf16 v[66:69], v[162:165], v[206:209], v[66:69]
	s_setprio 2
	s_barrier
	v_mfma_f32_16x16x32_bf16 v[70:73], v[150:153], v[202:205], v[70:73]
	v_mfma_f32_16x16x32_bf16 v[70:73], v[154:157], v[206:209], v[70:73]
	s_setprio 0
	ds_read_b128 v[166:169], v183 offset:49152
	ds_read_b128 v[170:173], v183 offset:50176
	ds_read_b128 v[186:189], v183 offset:51200
	ds_read_b128 v[190:193], v183 offset:52224
	ds_read_b128 v[194:197], v183 offset:53248
	ds_read_b128 v[198:201], v183 offset:54272
	ds_read_b128 v[202:205], v183 offset:55296
	ds_read_b128 v[206:209], v183 offset:56320
	s_add_u32 s34, s30, 0x40000
	s_addc_u32 s35, s31, 0
	s_mov_b32 s70, m0
	s_mov_b32 m0, s51
	s_nop 0
	global_load_lds_dwordx4 v176, s[34:35]
	s_mov_b32 m0, s70
	s_add_u32 s30, s30, 0x44000
	s_mov_b32 s70, m0
	s_mov_b32 m0, s52
	s_nop 0
	global_load_lds_dwordx4 v178, s[34:35]
	s_mov_b32 m0, s70
	s_addc_u32 s31, s31, 0
	s_mov_b32 s34, m0
	s_mov_b32 m0, s53
	s_nop 0
	global_load_lds_dwordx4 v176, s[30:31]
	s_mov_b32 m0, s34
	s_nop 0
	s_mov_b32 s34, m0
	s_mov_b32 m0, s54
	s_nop 0
	global_load_lds_dwordx4 v178, s[30:31]
	s_mov_b32 m0, s34
	s_waitcnt vmcnt(4)
	s_waitcnt lgkmcnt(0)
	s_barrier
	s_setprio 1
	.p2align 3
	v_mfma_f32_16x16x32_bf16 v[62:65], v[130:133], v[166:169], v[62:65]
	v_mfma_f32_16x16x32_bf16 v[62:65], v[134:137], v[170:173], v[62:65]
	v_mfma_f32_16x16x32_bf16 v[58:61], v[138:141], v[166:169], v[58:61]
	v_mfma_f32_16x16x32_bf16 v[58:61], v[142:145], v[170:173], v[58:61]
	v_mfma_f32_16x16x32_bf16 v[42:45], v[138:141], v[186:189], v[42:45]
	v_mfma_f32_16x16x32_bf16 v[42:45], v[142:145], v[190:193], v[42:45]
	v_mfma_f32_16x16x32_bf16 v[46:49], v[130:133], v[186:189], v[46:49]
	v_mfma_f32_16x16x32_bf16 v[46:49], v[134:137], v[190:193], v[46:49]
	v_mfma_f32_16x16x32_bf16 v[30:33], v[130:133], v[194:197], v[30:33]
	v_mfma_f32_16x16x32_bf16 v[30:33], v[134:137], v[198:201], v[30:33]
	v_mfma_f32_16x16x32_bf16 v[26:29], v[138:141], v[194:197], v[26:29]
	v_mfma_f32_16x16x32_bf16 v[26:29], v[142:145], v[198:201], v[26:29]
	v_mfma_f32_16x16x32_bf16 v[10:13], v[138:141], v[202:205], v[10:13]
	v_mfma_f32_16x16x32_bf16 v[10:13], v[142:145], v[206:209], v[10:13]
	v_mfma_f32_16x16x32_bf16 v[14:17], v[130:133], v[202:205], v[14:17]
	v_mfma_f32_16x16x32_bf16 v[14:17], v[134:137], v[206:209], v[14:17]
	s_setprio 0
	s_setprio 1
	v_mfma_f32_16x16x32_bf16 v[54:57], v[150:153], v[166:169], v[54:57]
	v_mfma_f32_16x16x32_bf16 v[54:57], v[154:157], v[170:173], v[54:57]
	v_mfma_f32_16x16x32_bf16 v[50:53], v[158:161], v[166:169], v[50:53]
	v_mfma_f32_16x16x32_bf16 v[50:53], v[162:165], v[170:173], v[50:53]
	v_mfma_f32_16x16x32_bf16 v[34:37], v[158:161], v[186:189], v[34:37]
	v_mfma_f32_16x16x32_bf16 v[34:37], v[162:165], v[190:193], v[34:37]
	v_mfma_f32_16x16x32_bf16 v[38:41], v[150:153], v[186:189], v[38:41]
	v_mfma_f32_16x16x32_bf16 v[38:41], v[154:157], v[190:193], v[38:41]
	v_mfma_f32_16x16x32_bf16 v[22:25], v[150:153], v[194:197], v[22:25]
	v_mfma_f32_16x16x32_bf16 v[22:25], v[154:157], v[198:201], v[22:25]
	v_mfma_f32_16x16x32_bf16 v[18:21], v[158:161], v[194:197], v[18:21]
	v_mfma_f32_16x16x32_bf16 v[18:21], v[162:165], v[198:201], v[18:21]
	v_mfma_f32_16x16x32_bf16 v[2:5], v[158:161], v[202:205], v[2:5]
	v_mfma_f32_16x16x32_bf16 v[2:5], v[162:165], v[206:209], v[2:5]
	s_setprio 2
	s_barrier
	v_mfma_f32_16x16x32_bf16 v[6:9], v[150:153], v[202:205], v[6:9]
	v_mfma_f32_16x16x32_bf16 v[6:9], v[154:157], v[206:209], v[6:9]
	s_setprio 0
	s_add_i32 s69, s69, 2
	s_add_u32 s65, s65, 0x80000
	s_addc_u32 s66, s66, 0
	s_add_u32 s28, s28, 0x400000
	s_addc_u32 s29, s29, 0
	s_add_u32 s67, s67, 0x400000
	s_addc_u32 s68, s68, 0
	s_cmpk_gt_u32 s69, 0x53
	.p2align 6
.LBB0_2792:
	ds_read_b128 v[130:133], v181
	ds_read_b128 v[134:137], v181 offset:1024
	ds_read_b128 v[138:141], v181 offset:2048
	ds_read_b128 v[142:145], v181 offset:3072
	ds_read_b128 v[150:153], v182
	ds_read_b128 v[154:157], v182 offset:1024
	ds_read_b128 v[158:161], v182 offset:2048
	ds_read_b128 v[162:165], v182 offset:3072
	s_cmpk_eq_i32 s69, 0x52
	s_cselect_b32 s31, s19, s66
	s_cselect_b32 s30, s64, s65
	s_cselect_b32 s35, s21, s68
	s_cselect_b32 s34, s63, s67
	ds_read_b128 v[166:169], v183
	ds_read_b128 v[170:173], v183 offset:1024
	ds_read_b128 v[186:189], v183 offset:2048
	ds_read_b128 v[190:193], v183 offset:3072
	ds_read_b128 v[194:197], v183 offset:4096
	ds_read_b128 v[198:201], v183 offset:5120
	ds_read_b128 v[202:205], v183 offset:6144
	ds_read_b128 v[206:209], v183 offset:7168
	s_add_u32 s70, s28, 0xffffc000
	s_addc_u32 s71, s29, -1
	s_mov_b32 s73, m0
	s_mov_b32 m0, s57
	s_nop 0
	global_load_lds_dwordx4 v1, s[70:71]
	s_mov_b32 m0, s73
	s_nop 0
	s_mov_b32 s73, m0
	s_mov_b32 m0, s59
	s_nop 0
	global_load_lds_dwordx4 v177, s[70:71]
	s_mov_b32 m0, s73
	s_mov_b32 s70, m0
	s_mov_b32 m0, s58
	s_nop 0
	global_load_lds_dwordx4 v1, s[28:29]
	s_mov_b32 m0, s70
	s_nop 0
	s_mov_b32 s70, m0
	s_mov_b32 m0, s60
	s_nop 0
	global_load_lds_dwordx4 v177, s[28:29]
	s_mov_b32 m0, s70
	s_waitcnt vmcnt(8)
	s_waitcnt lgkmcnt(0)
	s_barrier
	s_setprio 1
	.p2align 3
	v_mfma_f32_16x16x32_bf16 v[126:129], v[130:133], v[166:169], v[126:129]
	v_mfma_f32_16x16x32_bf16 v[126:129], v[134:137], v[170:173], v[126:129]
	v_mfma_f32_16x16x32_bf16 v[122:125], v[138:141], v[166:169], v[122:125]
	v_mfma_f32_16x16x32_bf16 v[122:125], v[142:145], v[170:173], v[122:125]
	v_mfma_f32_16x16x32_bf16 v[110:113], v[138:141], v[186:189], v[110:113]
	v_mfma_f32_16x16x32_bf16 v[110:113], v[142:145], v[190:193], v[110:113]
	v_mfma_f32_16x16x32_bf16 v[118:121], v[130:133], v[186:189], v[118:121]
	v_mfma_f32_16x16x32_bf16 v[118:121], v[134:137], v[190:193], v[118:121]
	v_mfma_f32_16x16x32_bf16 v[94:97], v[130:133], v[194:197], v[94:97]
	v_mfma_f32_16x16x32_bf16 v[94:97], v[134:137], v[198:201], v[94:97]
	v_mfma_f32_16x16x32_bf16 v[90:93], v[138:141], v[194:197], v[90:93]
	v_mfma_f32_16x16x32_bf16 v[90:93], v[142:145], v[198:201], v[90:93]
	v_mfma_f32_16x16x32_bf16 v[78:81], v[138:141], v[202:205], v[78:81]
	v_mfma_f32_16x16x32_bf16 v[78:81], v[142:145], v[206:209], v[78:81]
	v_mfma_f32_16x16x32_bf16 v[86:89], v[130:133], v[202:205], v[86:89]
	v_mfma_f32_16x16x32_bf16 v[86:89], v[134:137], v[206:209], v[86:89]
	s_setprio 0
	s_setprio 1
	v_mfma_f32_16x16x32_bf16 v[114:117], v[150:153], v[166:169], v[114:117]
	v_mfma_f32_16x16x32_bf16 v[114:117], v[154:157], v[170:173], v[114:117]
	v_mfma_f32_16x16x32_bf16 v[106:109], v[158:161], v[166:169], v[106:109]
	v_mfma_f32_16x16x32_bf16 v[106:109], v[162:165], v[170:173], v[106:109]
	v_mfma_f32_16x16x32_bf16 v[98:101], v[158:161], v[186:189], v[98:101]
	v_mfma_f32_16x16x32_bf16 v[98:101], v[162:165], v[190:193], v[98:101]
	v_mfma_f32_16x16x32_bf16 v[102:105], v[150:153], v[186:189], v[102:105]
	v_mfma_f32_16x16x32_bf16 v[102:105], v[154:157], v[190:193], v[102:105]
	v_mfma_f32_16x16x32_bf16 v[82:85], v[150:153], v[194:197], v[82:85]
	v_mfma_f32_16x16x32_bf16 v[82:85], v[154:157], v[198:201], v[82:85]
	v_mfma_f32_16x16x32_bf16 v[74:77], v[158:161], v[194:197], v[74:77]
	v_mfma_f32_16x16x32_bf16 v[74:77], v[162:165], v[198:201], v[74:77]
	v_mfma_f32_16x16x32_bf16 v[66:69], v[158:161], v[202:205], v[66:69]
	v_mfma_f32_16x16x32_bf16 v[66:69], v[162:165], v[206:209], v[66:69]
	s_setprio 2
	s_barrier
	v_mfma_f32_16x16x32_bf16 v[70:73], v[150:153], v[202:205], v[70:73]
	v_mfma_f32_16x16x32_bf16 v[70:73], v[154:157], v[206:209], v[70:73]
	s_setprio 0
	ds_read_b128 v[166:169], v183 offset:16384
	ds_read_b128 v[170:173], v183 offset:17408
	ds_read_b128 v[186:189], v183 offset:18432
	ds_read_b128 v[190:193], v183 offset:19456
	ds_read_b128 v[194:197], v183 offset:20480
	ds_read_b128 v[198:201], v183 offset:21504
	ds_read_b128 v[202:205], v183 offset:22528
	ds_read_b128 v[206:209], v183 offset:23552
	s_mov_b32 s70, m0
	s_mov_b32 m0, s27
	s_nop 0
	global_load_lds_dwordx4 v176, s[30:31]
	s_mov_b32 m0, s70
	s_nop 0
	s_mov_b32 s70, m0
	s_mov_b32 m0, s45
	s_nop 0
	global_load_lds_dwordx4 v178, s[30:31]
	s_mov_b32 m0, s70
	s_add_u32 s70, s30, 0x4000
	s_addc_u32 s71, s31, 0
	s_mov_b32 s73, m0
	s_mov_b32 m0, s46
	s_nop 0
	global_load_lds_dwordx4 v176, s[70:71]
	s_mov_b32 m0, s73
	s_nop 0
	s_mov_b32 s73, m0
	s_mov_b32 m0, s47
	s_nop 0
	global_load_lds_dwordx4 v178, s[70:71]
	s_mov_b32 m0, s73
	s_waitcnt vmcnt(4)
	s_waitcnt lgkmcnt(0)
	s_barrier
	s_setprio 1
	.p2align 3
	v_mfma_f32_16x16x32_bf16 v[62:65], v[130:133], v[166:169], v[62:65]
	v_mfma_f32_16x16x32_bf16 v[62:65], v[134:137], v[170:173], v[62:65]
	v_mfma_f32_16x16x32_bf16 v[58:61], v[138:141], v[166:169], v[58:61]
	v_mfma_f32_16x16x32_bf16 v[58:61], v[142:145], v[170:173], v[58:61]
	v_mfma_f32_16x16x32_bf16 v[42:45], v[138:141], v[186:189], v[42:45]
	v_mfma_f32_16x16x32_bf16 v[42:45], v[142:145], v[190:193], v[42:45]
	v_mfma_f32_16x16x32_bf16 v[46:49], v[130:133], v[186:189], v[46:49]
	v_mfma_f32_16x16x32_bf16 v[46:49], v[134:137], v[190:193], v[46:49]
	v_mfma_f32_16x16x32_bf16 v[30:33], v[130:133], v[194:197], v[30:33]
	v_mfma_f32_16x16x32_bf16 v[30:33], v[134:137], v[198:201], v[30:33]
	v_mfma_f32_16x16x32_bf16 v[26:29], v[138:141], v[194:197], v[26:29]
	v_mfma_f32_16x16x32_bf16 v[26:29], v[142:145], v[198:201], v[26:29]
	v_mfma_f32_16x16x32_bf16 v[10:13], v[138:141], v[202:205], v[10:13]
	v_mfma_f32_16x16x32_bf16 v[10:13], v[142:145], v[206:209], v[10:13]
	v_mfma_f32_16x16x32_bf16 v[14:17], v[130:133], v[202:205], v[14:17]
	v_mfma_f32_16x16x32_bf16 v[14:17], v[134:137], v[206:209], v[14:17]
	s_setprio 0
	s_setprio 1
	v_mfma_f32_16x16x32_bf16 v[54:57], v[150:153], v[166:169], v[54:57]
	v_mfma_f32_16x16x32_bf16 v[54:57], v[154:157], v[170:173], v[54:57]
	v_mfma_f32_16x16x32_bf16 v[50:53], v[158:161], v[166:169], v[50:53]
	v_mfma_f32_16x16x32_bf16 v[50:53], v[162:165], v[170:173], v[50:53]
	v_mfma_f32_16x16x32_bf16 v[34:37], v[158:161], v[186:189], v[34:37]
	v_mfma_f32_16x16x32_bf16 v[34:37], v[162:165], v[190:193], v[34:37]
	v_mfma_f32_16x16x32_bf16 v[38:41], v[150:153], v[186:189], v[38:41]
	v_mfma_f32_16x16x32_bf16 v[38:41], v[154:157], v[190:193], v[38:41]
	v_mfma_f32_16x16x32_bf16 v[22:25], v[150:153], v[194:197], v[22:25]
	v_mfma_f32_16x16x32_bf16 v[22:25], v[154:157], v[198:201], v[22:25]
	v_mfma_f32_16x16x32_bf16 v[18:21], v[158:161], v[194:197], v[18:21]
	v_mfma_f32_16x16x32_bf16 v[18:21], v[162:165], v[198:201], v[18:21]
	v_mfma_f32_16x16x32_bf16 v[2:5], v[158:161], v[202:205], v[2:5]
	v_mfma_f32_16x16x32_bf16 v[2:5], v[162:165], v[206:209], v[2:5]
	s_setprio 2
	s_barrier
	v_mfma_f32_16x16x32_bf16 v[6:9], v[150:153], v[202:205], v[6:9]
	v_mfma_f32_16x16x32_bf16 v[6:9], v[154:157], v[206:209], v[6:9]
	s_setprio 0
	ds_read_b128 v[130:133], v184
	ds_read_b128 v[134:137], v184 offset:1024
	ds_read_b128 v[138:141], v184 offset:2048
	ds_read_b128 v[142:145], v184 offset:3072
	ds_read_b128 v[150:153], v185
	ds_read_b128 v[154:157], v185 offset:1024
	ds_read_b128 v[158:161], v185 offset:2048
	ds_read_b128 v[162:165], v185 offset:3072
	ds_read_b128 v[166:169], v183 offset:32768
	ds_read_b128 v[170:173], v183 offset:33792
	ds_read_b128 v[186:189], v183 offset:34816
	ds_read_b128 v[190:193], v183 offset:35840
	ds_read_b128 v[194:197], v183 offset:36864
	ds_read_b128 v[198:201], v183 offset:37888
	ds_read_b128 v[202:205], v183 offset:38912
	ds_read_b128 v[206:209], v183 offset:39936
	s_mov_b32 s70, m0
	s_mov_b32 m0, s44
	s_nop 0
	global_load_lds_dwordx4 v1, s[34:35]
	s_mov_b32 m0, s70
	s_nop 0
	s_mov_b32 s70, m0
	s_mov_b32 m0, s48
	s_nop 0
	global_load_lds_dwordx4 v177, s[34:35]
	s_mov_b32 m0, s70
	s_add_u32 s34, s34, 0x4000
	s_addc_u32 s35, s35, 0
	s_mov_b32 s70, m0
	s_mov_b32 m0, s49
	s_nop 0
	global_load_lds_dwordx4 v1, s[34:35]
	s_mov_b32 m0, s70
	s_nop 0
	s_mov_b32 s70, m0
	s_mov_b32 m0, s50
	s_nop 0
	global_load_lds_dwordx4 v177, s[34:35]
	s_mov_b32 m0, s70
	s_waitcnt vmcnt(8)
	s_waitcnt lgkmcnt(0)
	s_barrier
	s_setprio 1
	.p2align 3
	v_mfma_f32_16x16x32_bf16 v[126:129], v[130:133], v[166:169], v[126:129]
	v_mfma_f32_16x16x32_bf16 v[126:129], v[134:137], v[170:173], v[126:129]
	v_mfma_f32_16x16x32_bf16 v[122:125], v[138:141], v[166:169], v[122:125]
	v_mfma_f32_16x16x32_bf16 v[122:125], v[142:145], v[170:173], v[122:125]
	v_mfma_f32_16x16x32_bf16 v[110:113], v[138:141], v[186:189], v[110:113]
	v_mfma_f32_16x16x32_bf16 v[110:113], v[142:145], v[190:193], v[110:113]
	v_mfma_f32_16x16x32_bf16 v[118:121], v[130:133], v[186:189], v[118:121]
	v_mfma_f32_16x16x32_bf16 v[118:121], v[134:137], v[190:193], v[118:121]
	v_mfma_f32_16x16x32_bf16 v[94:97], v[130:133], v[194:197], v[94:97]
	v_mfma_f32_16x16x32_bf16 v[94:97], v[134:137], v[198:201], v[94:97]
	v_mfma_f32_16x16x32_bf16 v[90:93], v[138:141], v[194:197], v[90:93]
	v_mfma_f32_16x16x32_bf16 v[90:93], v[142:145], v[198:201], v[90:93]
	v_mfma_f32_16x16x32_bf16 v[78:81], v[138:141], v[202:205], v[78:81]
	v_mfma_f32_16x16x32_bf16 v[78:81], v[142:145], v[206:209], v[78:81]
	v_mfma_f32_16x16x32_bf16 v[86:89], v[130:133], v[202:205], v[86:89]
	v_mfma_f32_16x16x32_bf16 v[86:89], v[134:137], v[206:209], v[86:89]
	s_setprio 0
	s_setprio 1
	v_mfma_f32_16x16x32_bf16 v[114:117], v[150:153], v[166:169], v[114:117]
	v_mfma_f32_16x16x32_bf16 v[114:117], v[154:157], v[170:173], v[114:117]
	v_mfma_f32_16x16x32_bf16 v[106:109], v[158:161], v[166:169], v[106:109]
	v_mfma_f32_16x16x32_bf16 v[106:109], v[162:165], v[170:173], v[106:109]
	v_mfma_f32_16x16x32_bf16 v[98:101], v[158:161], v[186:189], v[98:101]
	v_mfma_f32_16x16x32_bf16 v[98:101], v[162:165], v[190:193], v[98:101]
	v_mfma_f32_16x16x32_bf16 v[102:105], v[150:153], v[186:189], v[102:105]
	v_mfma_f32_16x16x32_bf16 v[102:105], v[154:157], v[190:193], v[102:105]
	v_mfma_f32_16x16x32_bf16 v[82:85], v[150:153], v[194:197], v[82:85]
	v_mfma_f32_16x16x32_bf16 v[82:85], v[154:157], v[198:201], v[82:85]
	v_mfma_f32_16x16x32_bf16 v[74:77], v[158:161], v[194:197], v[74:77]
	v_mfma_f32_16x16x32_bf16 v[74:77], v[162:165], v[198:201], v[74:77]
	v_mfma_f32_16x16x32_bf16 v[66:69], v[158:161], v[202:205], v[66:69]
	v_mfma_f32_16x16x32_bf16 v[66:69], v[162:165], v[206:209], v[66:69]
	s_setprio 2
	s_barrier
	v_mfma_f32_16x16x32_bf16 v[70:73], v[150:153], v[202:205], v[70:73]
	v_mfma_f32_16x16x32_bf16 v[70:73], v[154:157], v[206:209], v[70:73]
	s_setprio 0
	ds_read_b128 v[166:169], v183 offset:49152
	ds_read_b128 v[170:173], v183 offset:50176
	ds_read_b128 v[186:189], v183 offset:51200
	ds_read_b128 v[190:193], v183 offset:52224
	ds_read_b128 v[194:197], v183 offset:53248
	ds_read_b128 v[198:201], v183 offset:54272
	ds_read_b128 v[202:205], v183 offset:55296
	ds_read_b128 v[206:209], v183 offset:56320
	s_add_u32 s34, s30, 0x40000
	s_addc_u32 s35, s31, 0
	s_mov_b32 s70, m0
	s_mov_b32 m0, s51
	s_nop 0
	global_load_lds_dwordx4 v176, s[34:35]
	s_mov_b32 m0, s70
	s_add_u32 s30, s30, 0x44000
	s_mov_b32 s70, m0
	s_mov_b32 m0, s52
	s_nop 0
	global_load_lds_dwordx4 v178, s[34:35]
	s_mov_b32 m0, s70
	s_addc_u32 s31, s31, 0
	s_mov_b32 s34, m0
	s_mov_b32 m0, s53
	s_nop 0
	global_load_lds_dwordx4 v176, s[30:31]
	s_mov_b32 m0, s34
	s_nop 0
	s_mov_b32 s34, m0
	s_mov_b32 m0, s54
	s_nop 0
	global_load_lds_dwordx4 v178, s[30:31]
	s_mov_b32 m0, s34
	s_waitcnt vmcnt(4)
	s_waitcnt lgkmcnt(0)
	s_barrier
	s_setprio 1
	.p2align 3
	v_mfma_f32_16x16x32_bf16 v[62:65], v[130:133], v[166:169], v[62:65]
	v_mfma_f32_16x16x32_bf16 v[62:65], v[134:137], v[170:173], v[62:65]
	v_mfma_f32_16x16x32_bf16 v[58:61], v[138:141], v[166:169], v[58:61]
	v_mfma_f32_16x16x32_bf16 v[58:61], v[142:145], v[170:173], v[58:61]
	v_mfma_f32_16x16x32_bf16 v[42:45], v[138:141], v[186:189], v[42:45]
	v_mfma_f32_16x16x32_bf16 v[42:45], v[142:145], v[190:193], v[42:45]
	v_mfma_f32_16x16x32_bf16 v[46:49], v[130:133], v[186:189], v[46:49]
	v_mfma_f32_16x16x32_bf16 v[46:49], v[134:137], v[190:193], v[46:49]
	v_mfma_f32_16x16x32_bf16 v[30:33], v[130:133], v[194:197], v[30:33]
	v_mfma_f32_16x16x32_bf16 v[30:33], v[134:137], v[198:201], v[30:33]
	v_mfma_f32_16x16x32_bf16 v[26:29], v[138:141], v[194:197], v[26:29]
	v_mfma_f32_16x16x32_bf16 v[26:29], v[142:145], v[198:201], v[26:29]
	v_mfma_f32_16x16x32_bf16 v[10:13], v[138:141], v[202:205], v[10:13]
	v_mfma_f32_16x16x32_bf16 v[10:13], v[142:145], v[206:209], v[10:13]
	v_mfma_f32_16x16x32_bf16 v[14:17], v[130:133], v[202:205], v[14:17]
	v_mfma_f32_16x16x32_bf16 v[14:17], v[134:137], v[206:209], v[14:17]
	s_setprio 0
	s_setprio 1
	v_mfma_f32_16x16x32_bf16 v[54:57], v[150:153], v[166:169], v[54:57]
	v_mfma_f32_16x16x32_bf16 v[54:57], v[154:157], v[170:173], v[54:57]
	v_mfma_f32_16x16x32_bf16 v[50:53], v[158:161], v[166:169], v[50:53]
	v_mfma_f32_16x16x32_bf16 v[50:53], v[162:165], v[170:173], v[50:53]
	v_mfma_f32_16x16x32_bf16 v[34:37], v[158:161], v[186:189], v[34:37]
	v_mfma_f32_16x16x32_bf16 v[34:37], v[162:165], v[190:193], v[34:37]
	v_mfma_f32_16x16x32_bf16 v[38:41], v[150:153], v[186:189], v[38:41]
	v_mfma_f32_16x16x32_bf16 v[38:41], v[154:157], v[190:193], v[38:41]
	v_mfma_f32_16x16x32_bf16 v[22:25], v[150:153], v[194:197], v[22:25]
	v_mfma_f32_16x16x32_bf16 v[22:25], v[154:157], v[198:201], v[22:25]
	v_mfma_f32_16x16x32_bf16 v[18:21], v[158:161], v[194:197], v[18:21]
	v_mfma_f32_16x16x32_bf16 v[18:21], v[162:165], v[198:201], v[18:21]
	v_mfma_f32_16x16x32_bf16 v[2:5], v[158:161], v[202:205], v[2:5]
	v_mfma_f32_16x16x32_bf16 v[2:5], v[162:165], v[206:209], v[2:5]
	s_setprio 2
	s_barrier
	v_mfma_f32_16x16x32_bf16 v[6:9], v[150:153], v[202:205], v[6:9]
	v_mfma_f32_16x16x32_bf16 v[6:9], v[154:157], v[206:209], v[6:9]
	s_setprio 0
	s_add_i32 s69, s69, 2
	s_add_u32 s65, s65, 0x80000
	s_addc_u32 s66, s66, 0
	s_add_u32 s28, s28, 0x400000
	s_addc_u32 s29, s29, 0
	s_add_u32 s67, s67, 0x400000
	s_addc_u32 s68, s68, 0
	s_cmpk_gt_u32 s69, 0x53
	s_cbranch_scc0 .LBB0_2792
	s_and_b64 vcc, exec, s[8:9]
	s_cbranch_vccz .LBB0_2795
	s_barrier
